# hg_m3 y stores paired into dwordx4 via v_permlane16_swap; hazard nops of the removed softplus chains merged
# speedup vs baseline: 1.0090x; 1.0090x over previous
; __device__ __forceinline__ void ld8bf(const bf16_t* p, float (&o)[8]) { unpack8(*(const u32x4*)p, o); }
; __device__ __forceinline__ float sigmoidf_(float x) { return __builtin_amdgcn_rcpf(1.0f + __expf(-x)); }
; __device__ __forceinline__ bf16x8 pack_frag(const float (&v)[8]) { return __builtin_bit_cast(bf16x8, pack8(v)); }
; template <int KIND>
; __device__ __forceinline__ void w_m3_core(const bf16x8 (&Qf)[4][2], const bf16x8 (&Kf)[4][2], const bf16x8 (&Sf)[4][2], const LAS bf16_t* vT, float lg,
;                                           const bf16_t* gsrc, const float* nw, bf16_t* ydst, int lo, int fq) {
;     ...
;             const unsigned long long gw_ = *(const unsigned long long*)(gsrc + n * NIN + e0); const f32x4 w4 = *(const f32x4*)(nw + e0);
; __device__ __forceinline__ void w_hg_m3(const Args& a, int l, unsigned char* ws, const bf16_t* proj, bf16_t* y, LAS unsigned char* wl, int b, int ck_, int h, int lane) {
;     ...
;         for (int tb = 0; tb < 4; ++tb) { float fp[8], qv[8], a1[8], a2[8];
;             ld8bf(fsrc + (size_t)(16 * tb + lo) * NIN, fp); ld8bf(proj + (size_t)(row0 + 16 * tb + lo) * NIN + C_HQ + 64 * h + 32 * kk + 8 * fq, qv);
; #pragma unroll
;             for (int j = 0; j < 8; ++j) { float lf, key; hg_lf_key(fp[j], lbv[j], lf, key);
;                 const float q = qv[j] * sigmoidf_(qv[j]); a1[j] = q * __expf(bb[tb][j] - r31[j]); a2[j] = key * __expf(r31[j] - bb[tb][j]); }
;             Qf[tb][kk] = pack_frag(a1); Kf[tb][kk] = pack_frag(a2); }
.LBB0_189:
	s_or_b64 exec, exec, s[34:35]
	v_and_b32_e32 v196, 15, v132
	v_lshrrev_b32_e32 v197, 4, v132
	v_mul_u32_u24_e32 v196, 0x1800, v196
	v_lshl_add_u32 v196, v197, 3, v196
	v_add_u32_e32 v196, s88, v196
	v_add_u32_e32 v196, 0x1600, v196
	v_mov_b32_e32 v197, 0
	v_mov_b32_e32 v198, s67
	v_mov_b32_e32 v199, s68
	v_lshl_add_u64 v[198:199], v[198:199], 0, v[196:197]
	global_load_dwordx2 v[222:223], v[198:199], off
	global_load_dwordx2 v[224:225], v[198:199], off offset:32
	global_load_dwordx2 v[226:227], v[198:199], off offset:64
	global_load_dwordx2 v[228:229], v[198:199], off offset:96
	v_add_u32_e32 v196, 0x18000, v196
	v_mov_b32_e32 v198, s67
	v_mov_b32_e32 v199, s68
	v_lshl_add_u64 v[198:199], v[198:199], 0, v[196:197]
	global_load_dwordx2 v[230:231], v[198:199], off
	global_load_dwordx2 v[232:233], v[198:199], off offset:32
	global_load_dwordx2 v[234:235], v[198:199], off offset:64
	global_load_dwordx2 v[236:237], v[198:199], off offset:96
	v_add_u32_e32 v196, 0x18000, v196
	v_mov_b32_e32 v198, s67
	v_mov_b32_e32 v199, s68
	v_lshl_add_u64 v[198:199], v[198:199], 0, v[196:197]
	global_load_dwordx2 v[238:239], v[198:199], off
	global_load_dwordx2 v[240:241], v[198:199], off offset:32
	global_load_dwordx2 v[242:243], v[198:199], off offset:64
	global_load_dwordx2 v[244:245], v[198:199], off offset:96
	v_add_u32_e32 v196, 0x18000, v196
	v_mov_b32_e32 v198, s67
	v_mov_b32_e32 v199, s68
	v_lshl_add_u64 v[198:199], v[198:199], 0, v[196:197]
	global_load_dwordx2 v[246:247], v[198:199], off
	global_load_dwordx2 v[248:249], v[198:199], off offset:32
	global_load_dwordx2 v[250:251], v[198:199], off offset:64
	global_load_dwordx2 v[252:253], v[198:199], off offset:96
	s_mov_b64 s[20:21], 0x1000
	v_lshl_add_u64 v[38:39], v[64:65], 0, s[20:21]
	v_lshl_add_u64 v[64:65], v[66:67], 0, s[20:21]
	v_mul_f32_e32 v52, 0x3fb8aa3b, v98
	v_lshlrev_b32_e32 v67, 16, v4
	v_or_b32_e32 v186, 60, v70
	v_lshl_add_u64 v[70:71], v[54:55], 0, s[20:21]
	v_exp_f32_e32 v81, v52
	v_mul_f32_e32 v52, 0x3fb8aa3b, v97
	v_and_b32_e32 v4, 0xffff0000, v4
	v_mul_f32_e64 v54, |v67|, s26
	v_exp_f32_e32 v80, v52
	v_mul_f32_e32 v52, 0x3fb8aa3b, v94
	v_exp_f32_e32 v54, v54
	v_mul_f32_e64 v55, |v4|, s26
	v_exp_f32_e32 v83, v52
	v_mul_f32_e32 v52, 0x3fb8aa3b, v93
	v_exp_f32_e32 v55, v55
	v_exp_f32_e32 v82, v52
	v_mul_f32_e32 v52, 0x3fb8aa3b, v90
	v_exp_f32_e32 v85, v52
	v_mul_f32_e32 v52, 0x3fb8aa3b, v89
	v_add_f32_e32 v53, v151, v153
	v_exp_f32_e32 v84, v52
	v_mul_f32_e32 v52, 0x3fb8aa3b, v74
	v_add_f32_e32 v145, v53, v145
	v_add_f32_e32 v53, 1.0, v54
	v_lshl_add_u64 v[78:79], v[62:63], 0, s[20:21]
	v_exp_f32_e32 v87, v52
	v_mul_f32_e32 v52, 0x3fb8aa3b, v73
	v_rcp_f32_e32 v62, v53
	v_add_f32_e32 v53, 1.0, v55
	v_exp_f32_e32 v86, v52
	v_add_f32_e32 v52, v152, v154
	v_rcp_f32_e32 v63, v53
	v_add_f32_e32 v66, v52, v146
	v_sub_f32_e32 v52, v73, v66
	v_sub_f32_e32 v53, v74, v145
	v_mul_f32_e32 v52, 0x3fb8aa3b, v52
	v_mul_f32_e32 v53, 0x3fb8aa3b, v53
	v_exp_f32_e32 v52, v52
	v_exp_f32_e32 v53, v53
	v_pk_mul_f32 v[54:55], v[54:55], v[62:63]
	v_cmp_le_f32_e32 vcc, 0, v4
	v_pk_add_f32 v[42:43], v[42:43], 1.0 op_sel_hi:[1,0] neg_lo:[1,0] neg_hi:[1,0]
	s_lshl_b32 s20, s90, 2
	v_cndmask_b32_e32 v55, v63, v55, vcc
	v_cmp_le_f32_e32 vcc, 0, v67
	s_lshl_b32 s21, s71, 9
	s_add_i32 s20, s20, s21
	v_cndmask_b32_e32 v54, v62, v54, vcc
	v_pk_mul_f32 v[54:55], v[42:43], v[54:55]
	s_mov_b64 s[34:35], 0x18000
	v_pk_mul_f32 v[52:53], v[52:53], v[54:55]
	s_add_i32 s20, s20, s70
	v_cvt_pk_bf16_f32 v4, v52, v53
	v_pk_add_f32 v[52:53], v[44:45], 1.0 op_sel_hi:[1,0] neg_lo:[1,0] neg_hi:[1,0]
	v_add_f32_e32 v44, v148, v150
	v_add_f32_e32 v67, v44, v139
	v_lshlrev_b32_e32 v139, 16, v5
	v_and_b32_e32 v5, 0xffff0000, v5
	v_mul_f32_e64 v54, |v139|, s26
	v_exp_f32_e32 v54, v54
	v_mul_f32_e64 v55, |v5|, s26
	v_exp_f32_e32 v55, v55
	v_add_f32_e32 v45, v147, v149
	v_add_f32_e32 v138, v45, v138
	v_add_f32_e32 v45, 1.0, v54
	v_rcp_f32_e32 v62, v45
	v_add_f32_e32 v45, 1.0, v55
	v_rcp_f32_e32 v63, v45
	v_sub_f32_e32 v44, v89, v67
	v_sub_f32_e32 v45, v90, v138
	v_mul_f32_e32 v44, 0x3fb8aa3b, v44
	v_mul_f32_e32 v45, 0x3fb8aa3b, v45
	v_exp_f32_e32 v44, v44
	v_exp_f32_e32 v45, v45
	v_pk_mul_f32 v[54:55], v[54:55], v[62:63]
	v_cmp_le_f32_e32 vcc, 0, v5
	v_lshl_add_u64 v[36:37], v[48:49], 0, s[34:35]
	s_mov_b64 s[34:35], 0x30000
	v_cndmask_b32_e32 v55, v63, v55, vcc
	v_cmp_le_f32_e32 vcc, 0, v139
	v_lshlrev_b32_e32 v139, 16, v6
	v_and_b32_e32 v6, 0xffff0000, v6
	v_cndmask_b32_e32 v54, v62, v54, vcc
	v_pk_mul_f32 v[54:55], v[52:53], v[54:55]
	v_cmp_le_f32_e32 vcc, 0, v6
	v_pk_mul_f32 v[44:45], v[44:45], v[54:55]
	v_pk_add_f32 v[54:55], v[46:47], 1.0 op_sel_hi:[1,0] neg_lo:[1,0] neg_hi:[1,0]
	v_mul_f32_e64 v46, |v139|, s26
	v_exp_f32_e32 v46, v46
	v_mul_f32_e64 v47, |v6|, s26
	v_exp_f32_e32 v47, v47
	v_cvt_pk_bf16_f32 v5, v44, v45
	v_add_f32_e32 v45, v140, v142
	v_add_f32_e32 v131, v45, v131
	v_add_f32_e32 v45, 1.0, v46
	v_rcp_f32_e32 v62, v45
	v_add_f32_e32 v45, 1.0, v47
	v_add_f32_e32 v44, v141, v143
	v_rcp_f32_e32 v63, v45
	v_add_f32_e32 v133, v44, v133
	v_sub_f32_e32 v44, v93, v133
	v_sub_f32_e32 v45, v94, v131
	v_mul_f32_e32 v44, 0x3fb8aa3b, v44
	v_mul_f32_e32 v45, 0x3fb8aa3b, v45
	v_exp_f32_e32 v44, v44
	v_exp_f32_e32 v45, v45
	v_pk_mul_f32 v[46:47], v[46:47], v[62:63]
	s_ashr_i32 s21, s20, 31
	v_cndmask_b32_e32 v47, v63, v47, vcc
	v_cmp_le_f32_e32 vcc, 0, v139
	v_lshl_add_u64 v[76:77], v[48:49], 0, s[34:35]
	v_or_b32_e32 v128, 16, v114
	v_cndmask_b32_e32 v46, v62, v46, vcc
	v_pk_mul_f32 v[46:47], v[54:55], v[46:47]
	v_or_b32_e32 v127, 32, v114
	v_pk_mul_f32 v[44:45], v[44:45], v[46:47]
	v_or_b32_e32 v126, 48, v114
; __device__ __forceinline__ void ld8bf(const bf16_t* p, float (&o)[8]) { unpack8(*(const u32x4*)p, o); }
; __device__ __forceinline__ float sigmoidf_(float x) { return __builtin_amdgcn_rcpf(1.0f + __expf(-x)); }
; __device__ __forceinline__ bf16x8 pack_frag(const float (&v)[8]) { return __builtin_bit_cast(bf16x8, pack8(v)); }
; __device__ __forceinline__ void w_hg_m3(const Args& a, int l, unsigned char* ws, const bf16_t* proj, bf16_t* y, LAS unsigned char* wl, int b, int ck_, int h, int lane) {
;     ...
;         for (int tb = 0; tb < 4; ++tb) { float fp[8], qv[8], a1[8], a2[8];
;             ld8bf(fsrc + (size_t)(16 * tb + lo) * NIN, fp); ld8bf(proj + (size_t)(row0 + 16 * tb + lo) * NIN + C_HQ + 64 * h + 32 * kk + 8 * fq, qv);
; #pragma unroll
;             for (int j = 0; j < 8; ++j) { float lf, key; hg_lf_key(fp[j], lbv[j], lf, key);
;                 const float q = qv[j] * sigmoidf_(qv[j]); a1[j] = q * __expf(bb[tb][j] - r31[j]); a2[j] = key * __expf(r31[j] - bb[tb][j]); }
;             Qf[tb][kk] = pack_frag(a1); Kf[tb][kk] = pack_frag(a2); }
	v_cvt_pk_bf16_f32 v6, v44, v45
	v_add_f32_e32 v45, v134, v136
	v_lshlrev_b32_e32 v134, 16, v7
	v_and_b32_e32 v7, 0xffff0000, v7
	v_mul_f32_e64 v46, |v134|, s26
	v_exp_f32_e32 v46, v46
	v_mul_f32_e64 v47, |v7|, s26
	v_exp_f32_e32 v47, v47
	v_add_f32_e32 v125, v45, v125
	v_add_f32_e32 v45, 1.0, v46
	v_rcp_f32_e32 v62, v45
	v_add_f32_e32 v45, 1.0, v47
	v_add_f32_e32 v44, v135, v137
	v_rcp_f32_e32 v63, v45
	v_add_f32_e32 v129, v44, v129
	v_sub_f32_e32 v44, v97, v129
	v_sub_f32_e32 v45, v98, v125
	v_mul_f32_e32 v44, 0x3fb8aa3b, v44
	v_mul_f32_e32 v45, 0x3fb8aa3b, v45
	v_exp_f32_e32 v44, v44
	v_exp_f32_e32 v45, v45
	v_pk_mul_f32 v[46:47], v[46:47], v[62:63]
	v_cmp_le_f32_e32 vcc, 0, v7
	s_lshl_b64 s[40:41], s[20:21], 13
	s_nop 0
	v_cndmask_b32_e32 v47, v63, v47, vcc
	v_cmp_le_f32_e32 vcc, 0, v134
	s_nop 1
	v_cndmask_b32_e32 v46, v62, v46, vcc
	v_pk_mul_f32 v[46:47], v[40:41], v[46:47]
	s_nop 0
	v_pk_mul_f32 v[44:45], v[44:45], v[46:47]
	s_nop 0
	v_cvt_pk_bf16_f32 v7, v44, v45
	v_sub_f32_e32 v44, v66, v73
	v_mul_f32_e32 v46, 0x3fb8aa3b, v44
	v_lshlrev_b32_e32 v44, 16, v8
	v_and_b32_e32 v45, 0xffff0000, v8
	v_mul_f32_e32 v8, 0xbfb8aa3b, v44
	v_exp_f32_e32 v8, v8
	v_mul_f32_e32 v47, 0xbfb8aa3b, v45
	v_exp_f32_e32 v47, v47
	v_lshlrev_b32_e32 v66, 16, v9
	v_add_f32_e32 v8, 1.0, v8
	v_rcp_f32_e32 v62, v8
	v_add_f32_e32 v8, 1.0, v47
	v_rcp_f32_e32 v63, v8
	v_sub_f32_e32 v8, v145, v74
	v_mul_f32_e32 v8, 0x3fb8aa3b, v8
	v_exp_f32_e32 v47, v8
	v_sub_f32_e32 v8, v67, v89
	v_and_b32_e32 v67, 0xffff0000, v9
	v_mul_f32_e32 v9, 0xbfb8aa3b, v66
	v_pk_mul_f32 v[44:45], v[62:63], v[44:45]
	v_exp_f32_e32 v9, v9
	v_mul_f32_e32 v63, 0xbfb8aa3b, v67
	v_exp_f32_e32 v63, v63
	v_mul_f32_e32 v8, 0x3fb8aa3b, v8
	v_add_f32_e32 v9, 1.0, v9
	v_exp_f32_e32 v62, v8
	v_sub_f32_e32 v8, v138, v90
	v_rcp_f32_e32 v134, v9
	v_add_f32_e32 v9, 1.0, v63
	v_exp_f32_e32 v46, v46
	v_mul_f32_e32 v8, 0x3fb8aa3b, v8
	v_rcp_f32_e32 v135, v9
	v_exp_f32_e32 v63, v8
	v_pk_mul_f32 v[8:9], v[46:47], v[44:45]
	v_pk_mul_f32 v[44:45], v[134:135], v[66:67]
	s_nop 0
	v_pk_mul_f32 v[44:45], v[62:63], v[44:45]
	v_cvt_pk_bf16_f32 v8, v8, v9
	v_cvt_pk_bf16_f32 v9, v44, v45
	v_sub_f32_e32 v44, v133, v93
	v_mul_f32_e32 v46, 0x3fb8aa3b, v44
	v_lshlrev_b32_e32 v44, 16, v10
	v_and_b32_e32 v45, 0xffff0000, v10
	v_mul_f32_e32 v10, 0xbfb8aa3b, v44
	v_exp_f32_e32 v10, v10
	v_mul_f32_e32 v47, 0xbfb8aa3b, v45
	v_exp_f32_e32 v47, v47
	v_lshlrev_b32_e32 v66, 16, v11
	v_add_f32_e32 v10, 1.0, v10
	v_rcp_f32_e32 v62, v10
	v_add_f32_e32 v10, 1.0, v47
	v_rcp_f32_e32 v63, v10
	v_and_b32_e32 v67, 0xffff0000, v11
	v_mul_f32_e32 v11, 0xbfb8aa3b, v66
	v_exp_f32_e32 v11, v11
	v_pk_mul_f32 v[44:45], v[62:63], v[44:45]
	v_mul_f32_e32 v63, 0xbfb8aa3b, v67
	v_sub_f32_e32 v10, v131, v94
	v_exp_f32_e32 v63, v63
	v_mul_f32_e32 v10, 0x3fb8aa3b, v10
	v_exp_f32_e32 v47, v10
	v_sub_f32_e32 v10, v129, v97
	v_mul_f32_e32 v10, 0x3fb8aa3b, v10
	v_add_f32_e32 v11, 1.0, v11
	v_exp_f32_e32 v62, v10
	v_sub_f32_e32 v10, v125, v98
	v_rcp_f32_e32 v134, v11
	v_add_f32_e32 v11, 1.0, v63
	v_exp_f32_e32 v46, v46
	v_mul_f32_e32 v10, 0x3fb8aa3b, v10
	v_rcp_f32_e32 v135, v11
	v_exp_f32_e32 v63, v10
	v_pk_mul_f32 v[10:11], v[46:47], v[44:45]
	v_pk_mul_f32 v[44:45], v[134:135], v[66:67]
	s_nop 0
	v_pk_mul_f32 v[44:45], v[62:63], v[44:45]
	v_cvt_pk_bf16_f32 v10, v10, v11
	v_cvt_pk_bf16_f32 v11, v44, v45
	v_sub_f32_e32 v44, v97, v121
	v_lshlrev_b32_e32 v66, 16, v31
	v_mul_f32_e32 v46, 0x3fb8aa3b, v44
	v_and_b32_e32 v31, 0xffff0000, v31
	v_mul_f32_e64 v44, |v66|, s26
	v_exp_f32_e32 v44, v44
	v_mul_f32_e64 v45, |v31|, s26
	v_exp_f32_e32 v45, v45
	v_cmp_le_f32_e32 vcc, 0, v31
	v_add_f32_e32 v47, 1.0, v44
	v_rcp_f32_e32 v62, v47
	v_add_f32_e32 v47, 1.0, v45
	v_rcp_f32_e32 v63, v47
	v_and_b32_e32 v67, 0xffff0000, v15
	v_sub_f32_e32 v31, v121, v97
	v_sub_f32_e32 v47, v98, v122
	v_pk_mul_f32 v[44:45], v[44:45], v[62:63]
	v_mul_f32_e32 v31, 0x3fb8aa3b, v31
	v_cndmask_b32_e32 v45, v63, v45, vcc
	v_cmp_le_f32_e32 vcc, 0, v66
	v_lshlrev_b32_e32 v66, 16, v15
	v_mul_f32_e32 v15, 0xbfb8aa3b, v66
	v_exp_f32_e32 v15, v15
	v_mul_f32_e32 v63, 0xbfb8aa3b, v67
	v_exp_f32_e32 v63, v63
	v_mul_f32_e32 v47, 0x3fb8aa3b, v47
	v_add_f32_e32 v15, 1.0, v15
	v_cndmask_b32_e32 v44, v62, v44, vcc
	v_exp_f32_e32 v62, v31
	v_sub_f32_e32 v31, v122, v98
	v_rcp_f32_e32 v134, v15
	v_add_f32_e32 v15, 1.0, v63
	v_lshlrev_b32_e32 v121, 16, v30
	v_exp_f32_e32 v46, v46
	v_exp_f32_e32 v47, v47
	v_mul_f32_e32 v31, 0x3fb8aa3b, v31
	v_rcp_f32_e32 v135, v15
	v_and_b32_e32 v122, 0xffff0000, v30
	v_mul_f32_e64 v30, |v121|, s26
	v_exp_f32_e32 v63, v31
	v_exp_f32_e32 v30, v30
	v_mul_f32_e64 v31, |v122|, s26
	v_exp_f32_e32 v31, v31
	v_pk_mul_f32 v[44:45], v[40:41], v[44:45]
	v_sub_f32_e32 v15, v93, v118
	v_pk_mul_f32 v[44:45], v[46:47], v[44:45]
	v_pk_mul_f32 v[46:47], v[134:135], v[66:67]
	v_mul_f32_e32 v15, 0x3fb8aa3b, v15
	v_pk_mul_f32 v[46:47], v[62:63], v[46:47]
	v_exp_f32_e32 v62, v15
	v_add_f32_e32 v15, 1.0, v30
	v_rcp_f32_e32 v66, v15
	v_add_f32_e32 v15, 1.0, v31
	v_rcp_f32_e32 v67, v15
	v_sub_f32_e32 v15, v94, v119
	v_mul_f32_e32 v15, 0x3fb8aa3b, v15
	v_exp_f32_e32 v63, v15
	v_pk_mul_f32 v[30:31], v[30:31], v[66:67]
	v_cmp_le_f32_e32 vcc, 0, v122
	v_sub_f32_e32 v15, v118, v93
	v_mul_f32_e32 v15, 0x3fb8aa3b, v15
	v_cndmask_b32_e32 v31, v67, v31, vcc
	v_cmp_le_f32_e32 vcc, 0, v121
	v_lshlrev_b32_e32 v118, 16, v14
	v_lshlrev_b32_e32 v134, 16, v13
	v_cndmask_b32_e32 v30, v66, v30, vcc
	v_exp_f32_e32 v66, v15
	v_sub_f32_e32 v15, v119, v94
	v_and_b32_e32 v119, 0xffff0000, v14
	v_mul_f32_e32 v14, 0xbfb8aa3b, v118
	v_mul_f32_e32 v67, 0xbfb8aa3b, v119
	v_exp_f32_e32 v14, v14
	v_exp_f32_e32 v67, v67
; __device__ __forceinline__ void ld8bf(const bf16_t* p, float (&o)[8]) { unpack8(*(const u32x4*)p, o); }
; __device__ __forceinline__ float sigmoidf_(float x) { return __builtin_amdgcn_rcpf(1.0f + __expf(-x)); }
; __device__ __forceinline__ bf16x8 pack_frag(const float (&v)[8]) { return __builtin_bit_cast(bf16x8, pack8(v)); }
; __device__ __forceinline__ void w_hg_m3(const Args& a, int l, unsigned char* ws, const bf16_t* proj, bf16_t* y, LAS unsigned char* wl, int b, int ck_, int h, int lane) {
;     ...
;         for (int tb = 0; tb < 4; ++tb) { float fp[8], qv[8], a1[8], a2[8];
;             ld8bf(fsrc + (size_t)(16 * tb + lo) * NIN, fp); ld8bf(proj + (size_t)(row0 + 16 * tb + lo) * NIN + C_HQ + 64 * h + 32 * kk + 8 * fq, qv);
; #pragma unroll
;             for (int j = 0; j < 8; ++j) { float lf, key; hg_lf_key(fp[j], lbv[j], lf, key);
;                 const float q = qv[j] * sigmoidf_(qv[j]); a1[j] = q * __expf(bb[tb][j] - r31[j]); a2[j] = key * __expf(r31[j] - bb[tb][j]); }
;             Qf[tb][kk] = pack_frag(a1); Kf[tb][kk] = pack_frag(a2); }
	v_mul_f32_e32 v121, 0x3fb8aa3b, v15
	v_pk_mul_f32 v[30:31], v[54:55], v[30:31]
	v_add_f32_e32 v14, 1.0, v14
	v_add_f32_e32 v15, 1.0, v67
	v_rcp_f32_e32 v14, v14
	v_rcp_f32_e32 v15, v15
	v_exp_f32_e32 v67, v121
	v_pk_mul_f32 v[30:31], v[62:63], v[30:31]
	v_lshlrev_b32_e32 v121, 16, v29
	v_pk_mul_f32 v[14:15], v[14:15], v[118:119]
	v_and_b32_e32 v29, 0xffff0000, v29
	v_pk_mul_f32 v[62:63], v[66:67], v[14:15]
	v_sub_f32_e32 v14, v89, v115
	v_mul_f32_e32 v66, 0x3fb8aa3b, v14
	v_mul_f32_e64 v14, |v121|, s26
	v_exp_f32_e32 v14, v14
	v_mul_f32_e64 v15, |v29|, s26
	v_exp_f32_e32 v15, v15
	v_and_b32_e32 v135, 0xffff0000, v13
	v_add_f32_e32 v67, 1.0, v14
	v_rcp_f32_e32 v118, v67
	v_add_f32_e32 v67, 1.0, v15
	v_rcp_f32_e32 v119, v67
	v_mul_f32_e32 v13, 0xbfb8aa3b, v134
	v_cmp_le_f32_e32 vcc, 0, v29
	v_sub_f32_e32 v29, v115, v89
	v_exp_f32_e32 v13, v13
	v_mul_f32_e32 v115, 0xbfb8aa3b, v135
	v_exp_f32_e32 v115, v115
	v_pk_mul_f32 v[14:15], v[14:15], v[118:119]
	v_sub_f32_e32 v67, v90, v116
	v_cndmask_b32_e32 v15, v119, v15, vcc
	v_cmp_le_f32_e32 vcc, 0, v121
	v_mul_f32_e32 v29, 0x3fb8aa3b, v29
	v_add_f32_e32 v13, 1.0, v13
	v_mul_f32_e32 v67, 0x3fb8aa3b, v67
	v_cndmask_b32_e32 v14, v118, v14, vcc
	v_exp_f32_e32 v118, v29
	v_sub_f32_e32 v29, v116, v90
	v_rcp_f32_e32 v136, v13
	v_add_f32_e32 v13, 1.0, v115
	v_lshlrev_b32_e32 v115, 16, v28
	v_exp_f32_e32 v66, v66
	v_exp_f32_e32 v67, v67
	v_mul_f32_e32 v29, 0x3fb8aa3b, v29
	v_rcp_f32_e32 v137, v13
	v_and_b32_e32 v116, 0xffff0000, v28
	v_mul_f32_e64 v28, |v115|, s26
	v_exp_f32_e32 v119, v29
	v_exp_f32_e32 v28, v28
	v_mul_f32_e64 v29, |v116|, s26
	v_exp_f32_e32 v29, v29
	v_pk_mul_f32 v[14:15], v[52:53], v[14:15]
	v_sub_f32_e32 v13, v73, v111
	v_pk_mul_f32 v[14:15], v[66:67], v[14:15]
	v_pk_mul_f32 v[66:67], v[136:137], v[134:135]
	v_mul_f32_e32 v13, 0x3fb8aa3b, v13
	v_pk_mul_f32 v[66:67], v[118:119], v[66:67]
	v_exp_f32_e32 v118, v13
	v_add_f32_e32 v13, 1.0, v28
	v_rcp_f32_e32 v134, v13
	v_add_f32_e32 v13, 1.0, v29
	v_rcp_f32_e32 v135, v13
	v_sub_f32_e32 v13, v74, v112
	v_mul_f32_e32 v13, 0x3fb8aa3b, v13
	v_lshlrev_b32_e32 v136, 16, v12
	v_and_b32_e32 v137, 0xffff0000, v12
	v_exp_f32_e32 v119, v13
	v_sub_f32_e32 v13, v111, v73
	v_mul_f32_e32 v12, 0xbfb8aa3b, v136
	v_mul_f32_e32 v111, 0xbfb8aa3b, v137
	v_exp_f32_e32 v12, v12
	v_exp_f32_e32 v111, v111
	v_pk_mul_f32 v[28:29], v[28:29], v[134:135]
	v_cmp_le_f32_e32 vcc, 0, v116
	v_mul_f32_e32 v13, 0x3fb8aa3b, v13
	v_add_f32_e32 v12, 1.0, v12
	v_cndmask_b32_e32 v29, v135, v29, vcc
	v_cmp_le_f32_e32 vcc, 0, v115
	v_rcp_f32_e32 v12, v12
	s_nop 0
	v_cndmask_b32_e32 v28, v134, v28, vcc
	v_exp_f32_e32 v134, v13
	v_sub_f32_e32 v13, v112, v74
	v_mul_f32_e32 v112, 0x3fb8aa3b, v13
	v_add_f32_e32 v13, 1.0, v111
	v_rcp_f32_e32 v13, v13
	v_exp_f32_e32 v135, v112
	v_pk_mul_f32 v[28:29], v[42:43], v[28:29]
	v_pk_mul_f32 v[12:13], v[12:13], v[136:137]
	v_pk_mul_f32 v[28:29], v[118:119], v[28:29]
	v_pk_mul_f32 v[118:119], v[134:135], v[12:13]
	v_cvt_pk_bf16_f32 v12, v28, v29
	v_cvt_pk_bf16_f32 v13, v14, v15
	v_cvt_pk_bf16_f32 v15, v44, v45
	v_cvt_pk_bf16_f32 v29, v66, v67
	v_sub_f32_e32 v44, v97, v107
	v_lshlrev_b32_e32 v66, 16, v35
	v_cvt_pk_bf16_f32 v14, v30, v31
	v_cvt_pk_bf16_f32 v31, v46, v47
	v_mul_f32_e32 v46, 0x3fb8aa3b, v44
	v_and_b32_e32 v35, 0xffff0000, v35
	v_mul_f32_e64 v44, |v66|, s26
	v_exp_f32_e32 v44, v44
	v_mul_f32_e64 v45, |v35|, s26
	v_exp_f32_e32 v45, v45
	v_cvt_pk_bf16_f32 v30, v62, v63
	v_add_f32_e32 v47, 1.0, v44
	v_rcp_f32_e32 v62, v47
	v_add_f32_e32 v47, 1.0, v45
	v_rcp_f32_e32 v63, v47
	v_cmp_le_f32_e32 vcc, 0, v35
	v_and_b32_e32 v67, 0xffff0000, v19
	v_sub_f32_e32 v35, v107, v97
	v_pk_mul_f32 v[44:45], v[44:45], v[62:63]
	v_sub_f32_e32 v47, v98, v109
	v_cndmask_b32_e32 v45, v63, v45, vcc
	v_cmp_le_f32_e32 vcc, 0, v66
	v_lshlrev_b32_e32 v66, 16, v19
	v_mul_f32_e32 v19, 0xbfb8aa3b, v66
	v_exp_f32_e32 v19, v19
	v_mul_f32_e32 v63, 0xbfb8aa3b, v67
	v_exp_f32_e32 v63, v63
	v_mul_f32_e32 v35, 0x3fb8aa3b, v35
	v_add_f32_e32 v19, 1.0, v19
	v_cvt_pk_bf16_f32 v28, v118, v119
	v_mul_f32_e32 v47, 0x3fb8aa3b, v47
	v_cndmask_b32_e32 v44, v62, v44, vcc
	v_exp_f32_e32 v62, v35
	v_sub_f32_e32 v35, v109, v98
	v_rcp_f32_e32 v118, v19
	v_add_f32_e32 v19, 1.0, v63
	v_lshlrev_b32_e32 v107, 16, v34
	v_exp_f32_e32 v46, v46
	v_exp_f32_e32 v47, v47
	v_mul_f32_e32 v35, 0x3fb8aa3b, v35
	v_rcp_f32_e32 v119, v19
	v_and_b32_e32 v109, 0xffff0000, v34
	v_mul_f32_e64 v34, |v107|, s26
	v_exp_f32_e32 v63, v35
	v_exp_f32_e32 v34, v34
	v_mul_f32_e64 v35, |v109|, s26
	v_exp_f32_e32 v35, v35
	v_pk_mul_f32 v[44:45], v[40:41], v[44:45]
	v_sub_f32_e32 v19, v93, v104
	v_pk_mul_f32 v[44:45], v[46:47], v[44:45]
	v_pk_mul_f32 v[46:47], v[118:119], v[66:67]
	v_mul_f32_e32 v19, 0x3fb8aa3b, v19
	v_pk_mul_f32 v[62:63], v[62:63], v[46:47]
	v_exp_f32_e32 v46, v19
	v_add_f32_e32 v19, 1.0, v34
	v_rcp_f32_e32 v66, v19
	v_add_f32_e32 v19, 1.0, v35
	v_rcp_f32_e32 v67, v19
	v_sub_f32_e32 v19, v94, v105
	v_mul_f32_e32 v19, 0x3fb8aa3b, v19
	v_exp_f32_e32 v47, v19
	v_pk_mul_f32 v[34:35], v[34:35], v[66:67]
	v_cmp_le_f32_e32 vcc, 0, v109
	v_sub_f32_e32 v19, v104, v93
	v_mul_f32_e32 v19, 0x3fb8aa3b, v19
	v_cndmask_b32_e32 v35, v67, v35, vcc
	v_cmp_le_f32_e32 vcc, 0, v107
	v_lshlrev_b32_e32 v104, 16, v18
	v_lshlrev_b32_e32 v118, 16, v17
	v_cndmask_b32_e32 v34, v66, v34, vcc
	v_exp_f32_e32 v66, v19
	v_sub_f32_e32 v19, v105, v94
	v_and_b32_e32 v105, 0xffff0000, v18
	v_mul_f32_e32 v18, 0xbfb8aa3b, v104
	v_mul_f32_e32 v67, 0xbfb8aa3b, v105
	v_exp_f32_e32 v18, v18
	v_exp_f32_e32 v67, v67
	v_mul_f32_e32 v107, 0x3fb8aa3b, v19
	v_pk_mul_f32 v[34:35], v[54:55], v[34:35]
	v_add_f32_e32 v18, 1.0, v18
	v_add_f32_e32 v19, 1.0, v67
; __device__ __forceinline__ void ld8bf(const bf16_t* p, float (&o)[8]) { unpack8(*(const u32x4*)p, o); }
; __device__ __forceinline__ float sigmoidf_(float x) { return __builtin_amdgcn_rcpf(1.0f + __expf(-x)); }
; __device__ __forceinline__ bf16x8 pack_frag(const float (&v)[8]) { return __builtin_bit_cast(bf16x8, pack8(v)); }
; __device__ __forceinline__ void w_hg_m3(const Args& a, int l, unsigned char* ws, const bf16_t* proj, bf16_t* y, LAS unsigned char* wl, int b, int ck_, int h, int lane) {
;     ...
;         for (int tb = 0; tb < 4; ++tb) { float fp[8], qv[8], a1[8], a2[8];
;             ld8bf(fsrc + (size_t)(16 * tb + lo) * NIN, fp); ld8bf(proj + (size_t)(row0 + 16 * tb + lo) * NIN + C_HQ + 64 * h + 32 * kk + 8 * fq, qv);
; #pragma unroll
;             for (int j = 0; j < 8; ++j) { float lf, key; hg_lf_key(fp[j], lbv[j], lf, key);
;                 const float q = qv[j] * sigmoidf_(qv[j]); a1[j] = q * __expf(bb[tb][j] - r31[j]); a2[j] = key * __expf(r31[j] - bb[tb][j]); }
;             Qf[tb][kk] = pack_frag(a1); Kf[tb][kk] = pack_frag(a2); }
	v_rcp_f32_e32 v18, v18
	v_rcp_f32_e32 v19, v19
	v_exp_f32_e32 v67, v107
	v_pk_mul_f32 v[34:35], v[46:47], v[34:35]
	v_lshlrev_b32_e32 v107, 16, v33
	v_pk_mul_f32 v[18:19], v[18:19], v[104:105]
	v_and_b32_e32 v33, 0xffff0000, v33
	v_pk_mul_f32 v[46:47], v[66:67], v[18:19]
	v_sub_f32_e32 v18, v89, v101
	v_mul_f32_e32 v66, 0x3fb8aa3b, v18
	v_mul_f32_e64 v18, |v107|, s26
	v_exp_f32_e32 v18, v18
	v_mul_f32_e64 v19, |v33|, s26
	v_exp_f32_e32 v19, v19
	v_and_b32_e32 v119, 0xffff0000, v17
	v_add_f32_e32 v67, 1.0, v18
	v_rcp_f32_e32 v104, v67
	v_add_f32_e32 v67, 1.0, v19
	v_rcp_f32_e32 v105, v67
	v_mul_f32_e32 v17, 0xbfb8aa3b, v118
	v_cmp_le_f32_e32 vcc, 0, v33
	v_sub_f32_e32 v33, v101, v89
	v_exp_f32_e32 v17, v17
	v_mul_f32_e32 v101, 0xbfb8aa3b, v119
	v_exp_f32_e32 v101, v101
	v_pk_mul_f32 v[18:19], v[18:19], v[104:105]
	v_sub_f32_e32 v67, v90, v102
	v_cndmask_b32_e32 v19, v105, v19, vcc
	v_cmp_le_f32_e32 vcc, 0, v107
	v_mul_f32_e32 v33, 0x3fb8aa3b, v33
	v_add_f32_e32 v17, 1.0, v17
	v_mul_f32_e32 v67, 0x3fb8aa3b, v67
	v_cndmask_b32_e32 v18, v104, v18, vcc
	v_exp_f32_e32 v104, v33
	v_sub_f32_e32 v33, v102, v90
	v_rcp_f32_e32 v134, v17
	v_add_f32_e32 v17, 1.0, v101
	v_lshlrev_b32_e32 v101, 16, v32
	v_exp_f32_e32 v66, v66
	v_exp_f32_e32 v67, v67
	v_mul_f32_e32 v33, 0x3fb8aa3b, v33
	v_rcp_f32_e32 v135, v17
	v_and_b32_e32 v102, 0xffff0000, v32
	v_mul_f32_e64 v32, |v101|, s26
	v_exp_f32_e32 v105, v33
	v_exp_f32_e32 v32, v32
	v_mul_f32_e64 v33, |v102|, s26
	v_exp_f32_e32 v33, v33
	v_pk_mul_f32 v[18:19], v[52:53], v[18:19]
	v_sub_f32_e32 v17, v73, v99
	v_pk_mul_f32 v[18:19], v[66:67], v[18:19]
	v_pk_mul_f32 v[66:67], v[134:135], v[118:119]
	v_mul_f32_e32 v17, 0x3fb8aa3b, v17
	v_pk_mul_f32 v[66:67], v[104:105], v[66:67]
	v_exp_f32_e32 v104, v17
	v_add_f32_e32 v17, 1.0, v32
	v_rcp_f32_e32 v118, v17
	v_add_f32_e32 v17, 1.0, v33
	v_rcp_f32_e32 v119, v17
	v_sub_f32_e32 v17, v74, v100
	v_mul_f32_e32 v17, 0x3fb8aa3b, v17
	v_exp_f32_e32 v105, v17
	v_pk_mul_f32 v[32:33], v[32:33], v[118:119]
	v_cmp_le_f32_e32 vcc, 0, v102
	v_sub_f32_e32 v17, v99, v73
	v_mul_f32_e32 v17, 0x3fb8aa3b, v17
	v_cndmask_b32_e32 v33, v119, v33, vcc
	v_cmp_le_f32_e32 vcc, 0, v101
	v_and_b32_e32 v101, 0xffff0000, v16
	v_mul_f32_e32 v99, 0xbfb8aa3b, v101
	v_cndmask_b32_e32 v32, v118, v32, vcc
	v_exp_f32_e32 v118, v17
	v_sub_f32_e32 v17, v100, v74
	v_lshlrev_b32_e32 v100, 16, v16
	v_mul_f32_e32 v16, 0xbfb8aa3b, v100
	v_exp_f32_e32 v16, v16
	v_exp_f32_e32 v99, v99
	v_mul_f32_e32 v102, 0x3fb8aa3b, v17
	v_exp_f32_e32 v119, v102
	v_add_f32_e32 v16, 1.0, v16
	v_add_f32_e32 v17, 1.0, v99
	v_rcp_f32_e32 v16, v16
	v_rcp_f32_e32 v17, v17
	v_pk_mul_f32 v[32:33], v[42:43], v[32:33]
	v_cvt_pk_bf16_f32 v46, v46, v47
	v_pk_mul_f32 v[32:33], v[104:105], v[32:33]
	v_pk_mul_f32 v[16:17], v[16:17], v[100:101]
	v_cvt_pk_bf16_f32 v47, v62, v63
	v_pk_mul_f32 v[100:101], v[118:119], v[16:17]
	v_cvt_pk_bf16_f32 v16, v32, v33
	v_cvt_pk_bf16_f32 v17, v18, v19
	v_cvt_pk_bf16_f32 v19, v44, v45
	v_cvt_pk_bf16_f32 v45, v66, v67
	v_sub_f32_e32 v32, v97, v95
	v_lshlrev_b32_e32 v66, 16, v27
	v_cvt_pk_bf16_f32 v18, v34, v35
	v_mul_f32_e32 v34, 0x3fb8aa3b, v32
	v_and_b32_e32 v27, 0xffff0000, v27
	v_mul_f32_e64 v32, |v66|, s26
	v_exp_f32_e32 v32, v32
	v_mul_f32_e64 v33, |v27|, s26
	v_exp_f32_e32 v33, v33
	v_cmp_le_f32_e32 vcc, 0, v27
	v_add_f32_e32 v35, 1.0, v32
	v_rcp_f32_e32 v62, v35
	v_add_f32_e32 v35, 1.0, v33
	v_rcp_f32_e32 v63, v35
	v_and_b32_e32 v67, 0xffff0000, v23
	v_sub_f32_e32 v27, v95, v97
	v_sub_f32_e32 v35, v98, v96
	v_pk_mul_f32 v[32:33], v[32:33], v[62:63]
	v_mul_f32_e32 v27, 0x3fb8aa3b, v27
	v_cndmask_b32_e32 v33, v63, v33, vcc
	v_cmp_le_f32_e32 vcc, 0, v66
	v_lshlrev_b32_e32 v66, 16, v23
	v_mul_f32_e32 v23, 0xbfb8aa3b, v66
	v_exp_f32_e32 v23, v23
	v_mul_f32_e32 v63, 0xbfb8aa3b, v67
	v_exp_f32_e32 v63, v63
	v_mul_f32_e32 v35, 0x3fb8aa3b, v35
	v_add_f32_e32 v23, 1.0, v23
	v_cndmask_b32_e32 v32, v62, v32, vcc
	v_exp_f32_e32 v62, v27
	v_sub_f32_e32 v27, v96, v98
	v_rcp_f32_e32 v96, v23
	v_add_f32_e32 v23, 1.0, v63
	v_exp_f32_e32 v34, v34
	v_exp_f32_e32 v35, v35
	v_rcp_f32_e32 v97, v23
	v_pk_mul_f32 v[32:33], v[40:41], v[32:33]
	v_mul_f32_e32 v27, 0x3fb8aa3b, v27
	v_pk_mul_f32 v[32:33], v[34:35], v[32:33]
	v_pk_mul_f32 v[34:35], v[96:97], v[66:67]
	v_lshlrev_b32_e32 v66, 16, v26
	v_and_b32_e32 v67, 0xffff0000, v26
	v_mul_f32_e64 v26, |v66|, s26
	v_exp_f32_e32 v63, v27
	v_exp_f32_e32 v26, v26
	v_mul_f32_e64 v27, |v67|, s26
	v_exp_f32_e32 v27, v27
	v_sub_f32_e32 v23, v93, v91
	v_mul_f32_e32 v23, 0x3fb8aa3b, v23
	v_exp_f32_e32 v40, v23
	v_add_f32_e32 v23, 1.0, v26
	v_pk_mul_f32 v[34:35], v[62:63], v[34:35]
	v_rcp_f32_e32 v62, v23
	v_add_f32_e32 v23, 1.0, v27
	v_rcp_f32_e32 v63, v23
	v_cmp_le_f32_e32 vcc, 0, v67
	v_and_b32_e32 v67, 0xffff0000, v22
	v_sub_f32_e32 v23, v94, v92
	v_pk_mul_f32 v[26:27], v[26:27], v[62:63]
	v_mul_f32_e32 v23, 0x3fb8aa3b, v23
	v_cndmask_b32_e32 v27, v63, v27, vcc
	v_cmp_le_f32_e32 vcc, 0, v66
	v_lshlrev_b32_e32 v66, 16, v22
	v_mul_f32_e32 v22, 0xbfb8aa3b, v66
	v_mul_f32_e32 v63, 0xbfb8aa3b, v67
	v_exp_f32_e32 v22, v22
	v_exp_f32_e32 v63, v63
	v_exp_f32_e32 v41, v23
	v_sub_f32_e32 v23, v91, v93
	v_mul_f32_e32 v23, 0x3fb8aa3b, v23
	v_cndmask_b32_e32 v26, v62, v26, vcc
	v_exp_f32_e32 v62, v23
	v_sub_f32_e32 v23, v92, v94
	v_mul_f32_e32 v91, 0x3fb8aa3b, v23
	v_add_f32_e32 v22, 1.0, v22
	v_add_f32_e32 v23, 1.0, v63
	v_rcp_f32_e32 v22, v22
	v_rcp_f32_e32 v23, v23
	v_exp_f32_e32 v63, v91
	v_pk_mul_f32 v[26:27], v[54:55], v[26:27]
	v_cvt_pk_bf16_f32 v44, v100, v101
	v_pk_mul_f32 v[22:23], v[22:23], v[66:67]
	v_pk_mul_f32 v[26:27], v[40:41], v[26:27]
	v_pk_mul_f32 v[40:41], v[62:63], v[22:23]
; __device__ __forceinline__ void ld8bf(const bf16_t* p, float (&o)[8]) { unpack8(*(const u32x4*)p, o); }
; __device__ __forceinline__ float sigmoidf_(float x) { return __builtin_amdgcn_rcpf(1.0f + __expf(-x)); }
; __device__ __forceinline__ bf16x8 pack_frag(const float (&v)[8]) { return __builtin_bit_cast(bf16x8, pack8(v)); }
; __device__ __forceinline__ float row_sum_incl(float v) { v += dpp_shr0<1>(v); v += dpp_shr0<2>(v); v += dpp_shr0<4>(v); v += dpp_shr0<8>(v); return v; }
; __device__ __forceinline__ float bcast15(float v, int lane) { return bperm_f((lane & 48) | 15, v); }
; __device__ __forceinline__ void w_hg_scan(const float (&lbv)[8], const bf16_t* fsrc, int lane, float (&bb)[4][8], float (&r31)[8], float (&r63)[8]) {
;     ...
;     for (int tb = 0; tb < 4; ++tb) {
; #pragma unroll
;         for (int j = 0; j < 8; ++j) { const float v = row_sum_incl(bb[tb][j]) + carry[j]; bb[tb][j] = v; carry[j] = bcast15(v, lane); if (tb == 1) r31[j] = carry[j]; if (tb == 3) r63[j] = carry[j]; }
;         __builtin_amdgcn_sched_barrier(0);
;     }
; __device__ __forceinline__ void w_hg_m3(const Args& a, int l, unsigned char* ws, const bf16_t* proj, bf16_t* y, LAS unsigned char* wl, int b, int ck_, int h, int lane) {
;     ...
;         for (int tb = 0; tb < 4; ++tb) { float fp[8], qv[8], a1[8], a2[8];
;             ld8bf(fsrc + (size_t)(16 * tb + lo) * NIN, fp); ld8bf(proj + (size_t)(row0 + 16 * tb + lo) * NIN + C_HQ + 64 * h + 32 * kk + 8 * fq, qv);
; #pragma unroll
;             for (int j = 0; j < 8; ++j) { float lf, key; hg_lf_key(fp[j], lbv[j], lf, key);
;                 const float q = qv[j] * sigmoidf_(qv[j]); a1[j] = q * __expf(bb[tb][j] - r31[j]); a2[j] = key * __expf(r31[j] - bb[tb][j]); }
;             Qf[tb][kk] = pack_frag(a1); Kf[tb][kk] = pack_frag(a2); }
	v_sub_f32_e32 v22, v89, v75
	v_lshlrev_b32_e32 v66, 16, v25
	v_mul_f32_e32 v54, 0x3fb8aa3b, v22
	v_and_b32_e32 v25, 0xffff0000, v25
	v_mul_f32_e64 v22, |v66|, s26
	v_exp_f32_e32 v22, v22
	v_mul_f32_e64 v23, |v25|, s26
	v_exp_f32_e32 v23, v23
	v_cmp_le_f32_e32 vcc, 0, v25
	v_add_f32_e32 v55, 1.0, v22
	v_rcp_f32_e32 v62, v55
	v_add_f32_e32 v55, 1.0, v23
	v_rcp_f32_e32 v63, v55
	v_and_b32_e32 v67, 0xffff0000, v21
	v_sub_f32_e32 v25, v75, v89
	v_mul_f32_e32 v25, 0x3fb8aa3b, v25
	v_pk_mul_f32 v[22:23], v[22:23], v[62:63]
	v_sub_f32_e32 v55, v90, v88
	v_cndmask_b32_e32 v23, v63, v23, vcc
	v_cmp_le_f32_e32 vcc, 0, v66
	v_lshlrev_b32_e32 v66, 16, v21
	v_mul_f32_e32 v21, 0xbfb8aa3b, v66
	v_exp_f32_e32 v21, v21
	v_mul_f32_e32 v63, 0xbfb8aa3b, v67
	v_exp_f32_e32 v63, v63
	v_cndmask_b32_e32 v22, v62, v22, vcc
	v_add_f32_e32 v21, 1.0, v21
	v_exp_f32_e32 v62, v25
	v_sub_f32_e32 v25, v88, v90
	v_rcp_f32_e32 v88, v21
	v_add_f32_e32 v21, 1.0, v63
	v_rcp_f32_e32 v89, v21
	v_pk_mul_f32 v[22:23], v[52:53], v[22:23]
	v_mul_f32_e32 v55, 0x3fb8aa3b, v55
	v_mul_f32_e32 v25, 0x3fb8aa3b, v25
	v_pk_mul_f32 v[52:53], v[88:89], v[66:67]
	v_lshlrev_b32_e32 v66, 16, v24
	v_and_b32_e32 v67, 0xffff0000, v24
	v_mul_f32_e64 v24, |v66|, s26
	v_exp_f32_e32 v54, v54
	v_exp_f32_e32 v55, v55
	v_exp_f32_e32 v63, v25
	v_exp_f32_e32 v24, v24
	v_mul_f32_e64 v25, |v67|, s26
	v_exp_f32_e32 v25, v25
	v_sub_f32_e32 v21, v73, v2
	v_mul_f32_e32 v21, 0x3fb8aa3b, v21
	v_pk_mul_f32 v[22:23], v[54:55], v[22:23]
	v_pk_mul_f32 v[54:55], v[62:63], v[52:53]
	v_exp_f32_e32 v52, v21
	v_add_f32_e32 v21, 1.0, v24
	v_rcp_f32_e32 v62, v21
	v_add_f32_e32 v21, 1.0, v25
	v_rcp_f32_e32 v63, v21
	v_sub_f32_e32 v21, v74, v72
	v_cmp_le_f32_e32 vcc, 0, v67
	v_mul_f32_e32 v21, 0x3fb8aa3b, v21
	v_pk_mul_f32 v[24:25], v[24:25], v[62:63]
	v_and_b32_e32 v67, 0xffff0000, v20
	v_cndmask_b32_e32 v25, v63, v25, vcc
	v_cmp_le_f32_e32 vcc, 0, v66
	v_lshlrev_b32_e32 v66, 16, v20
	v_exp_f32_e32 v53, v21
	v_mul_f32_e32 v20, 0xbfb8aa3b, v66
	v_mul_f32_e32 v21, 0xbfb8aa3b, v67
	v_exp_f32_e32 v20, v20
	v_exp_f32_e32 v21, v21
	v_sub_f32_e32 v2, v2, v73
	v_mul_f32_e32 v2, 0x3fb8aa3b, v2
	v_cndmask_b32_e32 v24, v62, v24, vcc
	v_exp_f32_e32 v62, v2
	v_sub_f32_e32 v2, v72, v74
	v_add_f32_e32 v20, 1.0, v20
	v_add_f32_e32 v21, 1.0, v21
	v_mul_f32_e32 v2, 0x3fb8aa3b, v2
	v_rcp_f32_e32 v20, v20
	v_rcp_f32_e32 v21, v21
	v_exp_f32_e32 v63, v2
	v_pk_mul_f32 v[24:25], v[42:43], v[24:25]
	v_add_f32_dpp v2, v103, v103 row_shr:1 row_mask:0xf bank_mask:0xf bound_ctrl:1
	v_pk_mul_f32 v[24:25], v[52:53], v[24:25]
	v_pk_mul_f32 v[20:21], v[20:21], v[66:67]
	v_cvt_pk_bf16_f32 v53, v54, v55
	v_pk_mul_f32 v[42:43], v[62:63], v[20:21]
	v_cvt_pk_bf16_f32 v20, v24, v25
	v_cvt_pk_bf16_f32 v21, v22, v23
	v_cvt_pk_bf16_f32 v22, v26, v27
	v_cvt_pk_bf16_f32 v23, v32, v33
	v_cvt_pk_bf16_f32 v55, v34, v35
	v_add_f32_dpp v24, v106, v106 row_shr:1 row_mask:0xf bank_mask:0xf bound_ctrl:1
	v_add_f32_dpp v25, v110, v110 row_shr:1 row_mask:0xf bank_mask:0xf bound_ctrl:1
	v_add_f32_dpp v26, v113, v113 row_shr:1 row_mask:0xf bank_mask:0xf bound_ctrl:1
	v_add_f32_dpp v27, v117, v117 row_shr:1 row_mask:0xf bank_mask:0xf bound_ctrl:1
	v_add_f32_dpp v32, v120, v120 row_shr:1 row_mask:0xf bank_mask:0xf bound_ctrl:1
	v_add_f32_dpp v33, v123, v123 row_shr:1 row_mask:0xf bank_mask:0xf bound_ctrl:1
	v_add_f32_dpp v34, v124, v124 row_shr:1 row_mask:0xf bank_mask:0xf bound_ctrl:1
	v_add_f32_dpp v2, v2, v2 row_shr:2 row_mask:0xf bank_mask:0xf bound_ctrl:1
	v_add_f32_dpp v24, v24, v24 row_shr:2 row_mask:0xf bank_mask:0xf bound_ctrl:1
	v_add_f32_dpp v25, v25, v25 row_shr:2 row_mask:0xf bank_mask:0xf bound_ctrl:1
	v_add_f32_dpp v26, v26, v26 row_shr:2 row_mask:0xf bank_mask:0xf bound_ctrl:1
	v_add_f32_dpp v27, v27, v27 row_shr:2 row_mask:0xf bank_mask:0xf bound_ctrl:1
	v_add_f32_dpp v32, v32, v32 row_shr:2 row_mask:0xf bank_mask:0xf bound_ctrl:1
	v_add_f32_dpp v33, v33, v33 row_shr:2 row_mask:0xf bank_mask:0xf bound_ctrl:1
	v_add_f32_dpp v34, v34, v34 row_shr:2 row_mask:0xf bank_mask:0xf bound_ctrl:1
	v_add_f32_dpp v2, v2, v2 row_shr:4 row_mask:0xf bank_mask:0xf bound_ctrl:1
	v_add_f32_dpp v24, v24, v24 row_shr:4 row_mask:0xf bank_mask:0xf bound_ctrl:1
	v_add_f32_dpp v25, v25, v25 row_shr:4 row_mask:0xf bank_mask:0xf bound_ctrl:1
	v_add_f32_dpp v26, v26, v26 row_shr:4 row_mask:0xf bank_mask:0xf bound_ctrl:1
	v_add_f32_dpp v27, v27, v27 row_shr:4 row_mask:0xf bank_mask:0xf bound_ctrl:1
	v_add_f32_dpp v32, v32, v32 row_shr:4 row_mask:0xf bank_mask:0xf bound_ctrl:1
	v_add_f32_dpp v33, v33, v33 row_shr:4 row_mask:0xf bank_mask:0xf bound_ctrl:1
	v_add_f32_dpp v34, v34, v34 row_shr:4 row_mask:0xf bank_mask:0xf bound_ctrl:1
	v_add_f32_dpp v2, v2, v2 row_shr:8 row_mask:0xf bank_mask:0xf bound_ctrl:1
	v_add_f32_dpp v24, v24, v24 row_shr:8 row_mask:0xf bank_mask:0xf bound_ctrl:1
	v_add_f32_dpp v25, v25, v25 row_shr:8 row_mask:0xf bank_mask:0xf bound_ctrl:1
	v_add_f32_dpp v26, v26, v26 row_shr:8 row_mask:0xf bank_mask:0xf bound_ctrl:1
	v_add_f32_dpp v27, v27, v27 row_shr:8 row_mask:0xf bank_mask:0xf bound_ctrl:1
	v_add_f32_dpp v32, v32, v32 row_shr:8 row_mask:0xf bank_mask:0xf bound_ctrl:1
	v_add_f32_dpp v33, v33, v33 row_shr:8 row_mask:0xf bank_mask:0xf bound_ctrl:1
	v_add_f32_dpp v34, v34, v34 row_shr:8 row_mask:0xf bank_mask:0xf bound_ctrl:1
	v_cvt_pk_bf16_f32 v52, v42, v43
	v_cvt_pk_bf16_f32 v54, v40, v41
	v_add_f32_e32 v41, 0, v2
	v_add_f32_e32 v43, 0, v24
	v_add_f32_e32 v74, 0, v25
	v_add_f32_e32 v75, 0, v26
	v_add_f32_e32 v121, 0, v27
	v_add_f32_e32 v119, 0, v32
	v_add_f32_e32 v63, 0, v33
	v_add_f32_e32 v62, 0, v34
	ds_bpermute_b32 v2, v186, v41
	ds_bpermute_b32 v24, v186, v43
	ds_bpermute_b32 v25, v186, v74
	ds_bpermute_b32 v26, v186, v75
	ds_bpermute_b32 v27, v186, v121
	ds_bpermute_b32 v32, v186, v119
	ds_bpermute_b32 v33, v186, v63
	ds_bpermute_b32 v34, v186, v62
	v_add_f32_dpp v35, v130, v130 row_shr:1 row_mask:0xf bank_mask:0xf bound_ctrl:1
	s_nop 1
	v_add_f32_dpp v35, v35, v35 row_shr:2 row_mask:0xf bank_mask:0xf bound_ctrl:1
	s_nop 1
	v_add_f32_dpp v35, v35, v35 row_shr:4 row_mask:0xf bank_mask:0xf bound_ctrl:1
	s_nop 1
	v_add_f32_dpp v35, v35, v35 row_shr:8 row_mask:0xf bank_mask:0xf bound_ctrl:1
	s_waitcnt lgkmcnt(7)
; __device__ __forceinline__ float row_sum_incl(float v) { v += dpp_shr0<1>(v); v += dpp_shr0<2>(v); v += dpp_shr0<4>(v); v += dpp_shr0<8>(v); return v; }
; __device__ __forceinline__ float bcast15(float v, int lane) { return bperm_f((lane & 48) | 15, v); }
; __device__ __forceinline__ void w_hg_scan(const float (&lbv)[8], const bf16_t* fsrc, int lane, float (&bb)[4][8], float (&r31)[8], float (&r63)[8]) {
;     ...
;     for (int tb = 0; tb < 4; ++tb) {
; #pragma unroll
;         for (int j = 0; j < 8; ++j) { const float v = row_sum_incl(bb[tb][j]) + carry[j]; bb[tb][j] = v; carry[j] = bcast15(v, lane); if (tb == 1) r31[j] = carry[j]; if (tb == 3) r63[j] = carry[j]; }
;         __builtin_amdgcn_sched_barrier(0);
;     }
	v_add_f32_e32 v118, v35, v2
	ds_bpermute_b32 v2, v186, v118
	v_add_f32_dpp v35, v144, v144 row_shr:1 row_mask:0xf bank_mask:0xf bound_ctrl:1
	s_nop 1
	v_add_f32_dpp v35, v35, v35 row_shr:2 row_mask:0xf bank_mask:0xf bound_ctrl:1
	s_nop 1
	v_add_f32_dpp v35, v35, v35 row_shr:4 row_mask:0xf bank_mask:0xf bound_ctrl:1
	s_nop 1
	v_add_f32_dpp v35, v35, v35 row_shr:8 row_mask:0xf bank_mask:0xf bound_ctrl:1
	s_waitcnt lgkmcnt(7)
	v_add_f32_e32 v117, v35, v24
	v_add_f32_dpp v24, v155, v155 row_shr:1 row_mask:0xf bank_mask:0xf bound_ctrl:1
	ds_bpermute_b32 v88, v186, v117
	s_nop 0
	v_add_f32_dpp v24, v24, v24 row_shr:2 row_mask:0xf bank_mask:0xf bound_ctrl:1
	s_nop 1
	v_add_f32_dpp v24, v24, v24 row_shr:4 row_mask:0xf bank_mask:0xf bound_ctrl:1
	s_nop 1
	v_add_f32_dpp v24, v24, v24 row_shr:8 row_mask:0xf bank_mask:0xf bound_ctrl:1
	s_waitcnt lgkmcnt(7)
	v_add_f32_e32 v116, v24, v25
	ds_bpermute_b32 v89, v186, v116
	v_add_f32_dpp v24, v156, v156 row_shr:1 row_mask:0xf bank_mask:0xf bound_ctrl:1
	s_nop 1
	v_add_f32_dpp v24, v24, v24 row_shr:2 row_mask:0xf bank_mask:0xf bound_ctrl:1
	s_nop 1
	v_add_f32_dpp v24, v24, v24 row_shr:4 row_mask:0xf bank_mask:0xf bound_ctrl:1
	s_nop 1
	v_add_f32_dpp v24, v24, v24 row_shr:8 row_mask:0xf bank_mask:0xf bound_ctrl:1
	s_waitcnt lgkmcnt(7)
	v_add_f32_e32 v115, v24, v26
	ds_bpermute_b32 v90, v186, v115
	v_add_f32_dpp v24, v157, v157 row_shr:1 row_mask:0xf bank_mask:0xf bound_ctrl:1
	s_nop 1
	v_add_f32_dpp v24, v24, v24 row_shr:2 row_mask:0xf bank_mask:0xf bound_ctrl:1
	s_nop 1
	v_add_f32_dpp v24, v24, v24 row_shr:4 row_mask:0xf bank_mask:0xf bound_ctrl:1
	s_nop 1
	v_add_f32_dpp v24, v24, v24 row_shr:8 row_mask:0xf bank_mask:0xf bound_ctrl:1
	s_waitcnt lgkmcnt(7)
	v_add_f32_e32 v113, v24, v27
	ds_bpermute_b32 v91, v186, v113
	v_add_f32_dpp v24, v158, v158 row_shr:1 row_mask:0xf bank_mask:0xf bound_ctrl:1
	s_nop 1
	v_add_f32_dpp v24, v24, v24 row_shr:2 row_mask:0xf bank_mask:0xf bound_ctrl:1
	s_nop 1
	v_add_f32_dpp v24, v24, v24 row_shr:4 row_mask:0xf bank_mask:0xf bound_ctrl:1
	s_nop 1
	v_add_f32_dpp v24, v24, v24 row_shr:8 row_mask:0xf bank_mask:0xf bound_ctrl:1
	s_waitcnt lgkmcnt(7)
	v_add_f32_e32 v112, v24, v32
	ds_bpermute_b32 v92, v186, v112
	v_add_f32_dpp v24, v159, v159 row_shr:1 row_mask:0xf bank_mask:0xf bound_ctrl:1
	s_nop 1
	v_add_f32_dpp v24, v24, v24 row_shr:2 row_mask:0xf bank_mask:0xf bound_ctrl:1
	s_nop 1
	v_add_f32_dpp v24, v24, v24 row_shr:4 row_mask:0xf bank_mask:0xf bound_ctrl:1
	s_nop 1
	v_add_f32_dpp v24, v24, v24 row_shr:8 row_mask:0xf bank_mask:0xf bound_ctrl:1
	s_waitcnt lgkmcnt(7)
	v_add_f32_e32 v111, v24, v33
	ds_bpermute_b32 v93, v186, v111
	v_add_f32_dpp v24, v160, v160 row_shr:1 row_mask:0xf bank_mask:0xf bound_ctrl:1
	s_nop 1
	v_add_f32_dpp v24, v24, v24 row_shr:2 row_mask:0xf bank_mask:0xf bound_ctrl:1
	s_nop 1
	v_add_f32_dpp v24, v24, v24 row_shr:4 row_mask:0xf bank_mask:0xf bound_ctrl:1
	s_nop 1
	v_add_f32_dpp v24, v24, v24 row_shr:8 row_mask:0xf bank_mask:0xf bound_ctrl:1
	s_waitcnt lgkmcnt(7)
	v_add_f32_e32 v110, v24, v34
	ds_bpermute_b32 v94, v186, v110
	v_add_f32_dpp v24, v161, v161 row_shr:1 row_mask:0xf bank_mask:0xf bound_ctrl:1
	v_add_f32_dpp v25, v162, v162 row_shr:1 row_mask:0xf bank_mask:0xf bound_ctrl:1
	v_add_f32_dpp v26, v163, v163 row_shr:1 row_mask:0xf bank_mask:0xf bound_ctrl:1
	v_add_f32_dpp v27, v169, v169 row_shr:1 row_mask:0xf bank_mask:0xf bound_ctrl:1
	v_add_f32_dpp v32, v174, v174 row_shr:1 row_mask:0xf bank_mask:0xf bound_ctrl:1
	v_add_f32_dpp v33, v175, v175 row_shr:1 row_mask:0xf bank_mask:0xf bound_ctrl:1
	v_add_f32_dpp v34, v176, v176 row_shr:1 row_mask:0xf bank_mask:0xf bound_ctrl:1
	v_add_f32_dpp v35, v177, v177 row_shr:1 row_mask:0xf bank_mask:0xf bound_ctrl:1
	v_add_f32_dpp v24, v24, v24 row_shr:2 row_mask:0xf bank_mask:0xf bound_ctrl:1
	v_add_f32_dpp v25, v25, v25 row_shr:2 row_mask:0xf bank_mask:0xf bound_ctrl:1
	v_add_f32_dpp v26, v26, v26 row_shr:2 row_mask:0xf bank_mask:0xf bound_ctrl:1
	v_add_f32_dpp v27, v27, v27 row_shr:2 row_mask:0xf bank_mask:0xf bound_ctrl:1
	v_add_f32_dpp v32, v32, v32 row_shr:2 row_mask:0xf bank_mask:0xf bound_ctrl:1
	v_add_f32_dpp v33, v33, v33 row_shr:2 row_mask:0xf bank_mask:0xf bound_ctrl:1
	v_add_f32_dpp v34, v34, v34 row_shr:2 row_mask:0xf bank_mask:0xf bound_ctrl:1
	v_add_f32_dpp v35, v35, v35 row_shr:2 row_mask:0xf bank_mask:0xf bound_ctrl:1
	v_add_f32_dpp v24, v24, v24 row_shr:4 row_mask:0xf bank_mask:0xf bound_ctrl:1
	v_add_f32_dpp v25, v25, v25 row_shr:4 row_mask:0xf bank_mask:0xf bound_ctrl:1
	v_add_f32_dpp v26, v26, v26 row_shr:4 row_mask:0xf bank_mask:0xf bound_ctrl:1
	v_add_f32_dpp v27, v27, v27 row_shr:4 row_mask:0xf bank_mask:0xf bound_ctrl:1
	v_add_f32_dpp v32, v32, v32 row_shr:4 row_mask:0xf bank_mask:0xf bound_ctrl:1
	v_add_f32_dpp v33, v33, v33 row_shr:4 row_mask:0xf bank_mask:0xf bound_ctrl:1
	v_add_f32_dpp v34, v34, v34 row_shr:4 row_mask:0xf bank_mask:0xf bound_ctrl:1
	v_add_f32_dpp v35, v35, v35 row_shr:4 row_mask:0xf bank_mask:0xf bound_ctrl:1
	v_add_f32_dpp v24, v24, v24 row_shr:8 row_mask:0xf bank_mask:0xf bound_ctrl:1
	v_add_f32_dpp v25, v25, v25 row_shr:8 row_mask:0xf bank_mask:0xf bound_ctrl:1
	v_add_f32_dpp v26, v26, v26 row_shr:8 row_mask:0xf bank_mask:0xf bound_ctrl:1
	v_add_f32_dpp v27, v27, v27 row_shr:8 row_mask:0xf bank_mask:0xf bound_ctrl:1
	v_add_f32_dpp v32, v32, v32 row_shr:8 row_mask:0xf bank_mask:0xf bound_ctrl:1
	v_add_f32_dpp v33, v33, v33 row_shr:8 row_mask:0xf bank_mask:0xf bound_ctrl:1
	v_add_f32_dpp v34, v34, v34 row_shr:8 row_mask:0xf bank_mask:0xf bound_ctrl:1
	v_add_f32_dpp v35, v35, v35 row_shr:8 row_mask:0xf bank_mask:0xf bound_ctrl:1
	s_waitcnt lgkmcnt(7)
; __device__ __forceinline__ void ld8bf(const bf16_t* p, float (&o)[8]) { unpack8(*(const u32x4*)p, o); }
; __device__ __forceinline__ float sigmoidf_(float x) { return __builtin_amdgcn_rcpf(1.0f + __expf(-x)); }
; __device__ __forceinline__ float row_sum_incl(float v) { v += dpp_shr0<1>(v); v += dpp_shr0<2>(v); v += dpp_shr0<4>(v); v += dpp_shr0<8>(v); return v; }
; __device__ __forceinline__ float bcast15(float v, int lane) { return bperm_f((lane & 48) | 15, v); }
; __device__ __forceinline__ void w_hg_scan(const float (&lbv)[8], const bf16_t* fsrc, int lane, float (&bb)[4][8], float (&r31)[8], float (&r63)[8]) {
;     ...
;     for (int tb = 0; tb < 4; ++tb) {
; #pragma unroll
;         for (int j = 0; j < 8; ++j) { const float v = row_sum_incl(bb[tb][j]) + carry[j]; bb[tb][j] = v; carry[j] = bcast15(v, lane); if (tb == 1) r31[j] = carry[j]; if (tb == 3) r63[j] = carry[j]; }
;         __builtin_amdgcn_sched_barrier(0);
;     }
; __device__ __forceinline__ void w_hg_m3(const Args& a, int l, unsigned char* ws, const bf16_t* proj, bf16_t* y, LAS unsigned char* wl, int b, int ck_, int h, int lane) {
;     ...
;         for (int tb = 0; tb < 4; ++tb) { float fp[8], qv[8], a1[8], a2[8];
;             ld8bf(fsrc + (size_t)(16 * tb + lo) * NIN, fp); ld8bf(proj + (size_t)(row0 + 16 * tb + lo) * NIN + C_HQ + 64 * h + 32 * kk + 8 * fq, qv);
; #pragma unroll
;             for (int j = 0; j < 8; ++j) { float lf, key; hg_lf_key(fp[j], lbv[j], lf, key);
;                 const float q = qv[j] * sigmoidf_(qv[j]); a1[j] = q * __expf(bb[tb][j] - r31[j]); a2[j] = key * __expf(r31[j] - bb[tb][j]); }
	v_add_f32_e32 v109, v24, v2
	s_waitcnt lgkmcnt(6)
	v_add_f32_e32 v107, v25, v88
	s_waitcnt lgkmcnt(5)
	v_add_f32_e32 v106, v26, v89
	s_waitcnt lgkmcnt(4)
	v_add_f32_e32 v105, v27, v90
	s_waitcnt lgkmcnt(3)
	v_add_f32_e32 v104, v32, v91
	s_waitcnt lgkmcnt(2)
	v_add_f32_e32 v103, v33, v92
	s_waitcnt lgkmcnt(1)
	v_add_f32_e32 v67, v34, v93
	s_waitcnt lgkmcnt(0)
	v_add_f32_e32 v66, v35, v94
	ds_bpermute_b32 v24, v186, v109
	ds_bpermute_b32 v25, v186, v107
	ds_bpermute_b32 v26, v186, v106
	ds_bpermute_b32 v27, v186, v105
	ds_bpermute_b32 v32, v186, v104
	ds_bpermute_b32 v33, v186, v103
	ds_bpermute_b32 v34, v186, v67
	ds_bpermute_b32 v35, v186, v66
	v_add_f32_dpp v40, v178, v178 row_shr:1 row_mask:0xf bank_mask:0xf bound_ctrl:1
	s_nop 1
	v_add_f32_dpp v40, v40, v40 row_shr:2 row_mask:0xf bank_mask:0xf bound_ctrl:1
	s_nop 1
	v_add_f32_dpp v40, v40, v40 row_shr:4 row_mask:0xf bank_mask:0xf bound_ctrl:1
	s_nop 1
	v_add_f32_dpp v40, v40, v40 row_shr:8 row_mask:0xf bank_mask:0xf bound_ctrl:1
	s_waitcnt lgkmcnt(7)
	v_add_f32_e32 v102, v40, v24
	v_add_f32_dpp v24, v179, v179 row_shr:1 row_mask:0xf bank_mask:0xf bound_ctrl:1
	s_nop 1
	v_add_f32_dpp v24, v24, v24 row_shr:2 row_mask:0xf bank_mask:0xf bound_ctrl:1
	s_nop 1
	v_add_f32_dpp v24, v24, v24 row_shr:4 row_mask:0xf bank_mask:0xf bound_ctrl:1
	s_nop 1
	v_add_f32_dpp v24, v24, v24 row_shr:8 row_mask:0xf bank_mask:0xf bound_ctrl:1
	s_waitcnt lgkmcnt(6)
	v_add_f32_e32 v101, v24, v25
	v_add_f32_dpp v24, v180, v180 row_shr:1 row_mask:0xf bank_mask:0xf bound_ctrl:1
	s_nop 1
	v_add_f32_dpp v24, v24, v24 row_shr:2 row_mask:0xf bank_mask:0xf bound_ctrl:1
	s_nop 1
	v_add_f32_dpp v24, v24, v24 row_shr:4 row_mask:0xf bank_mask:0xf bound_ctrl:1
	s_nop 1
	v_add_f32_dpp v24, v24, v24 row_shr:8 row_mask:0xf bank_mask:0xf bound_ctrl:1
	s_waitcnt lgkmcnt(5)
	v_add_f32_e32 v100, v24, v26
	v_add_f32_dpp v24, v181, v181 row_shr:1 row_mask:0xf bank_mask:0xf bound_ctrl:1
	s_nop 1
	v_add_f32_dpp v24, v24, v24 row_shr:2 row_mask:0xf bank_mask:0xf bound_ctrl:1
	s_nop 1
	v_add_f32_dpp v24, v24, v24 row_shr:4 row_mask:0xf bank_mask:0xf bound_ctrl:1
	s_nop 1
	v_add_f32_dpp v24, v24, v24 row_shr:8 row_mask:0xf bank_mask:0xf bound_ctrl:1
	s_waitcnt lgkmcnt(4)
	v_add_f32_e32 v99, v24, v27
	v_add_f32_dpp v24, v182, v182 row_shr:1 row_mask:0xf bank_mask:0xf bound_ctrl:1
	s_nop 1
	v_add_f32_dpp v24, v24, v24 row_shr:2 row_mask:0xf bank_mask:0xf bound_ctrl:1
	s_nop 1
	v_add_f32_dpp v24, v24, v24 row_shr:4 row_mask:0xf bank_mask:0xf bound_ctrl:1
	s_nop 1
	v_add_f32_dpp v24, v24, v24 row_shr:8 row_mask:0xf bank_mask:0xf bound_ctrl:1
	s_waitcnt lgkmcnt(3)
	v_add_f32_e32 v98, v24, v32
	v_add_f32_dpp v24, v183, v183 row_shr:1 row_mask:0xf bank_mask:0xf bound_ctrl:1
	s_nop 1
	v_add_f32_dpp v24, v24, v24 row_shr:2 row_mask:0xf bank_mask:0xf bound_ctrl:1
	s_nop 1
	v_add_f32_dpp v24, v24, v24 row_shr:4 row_mask:0xf bank_mask:0xf bound_ctrl:1
	s_nop 1
	v_add_f32_dpp v24, v24, v24 row_shr:8 row_mask:0xf bank_mask:0xf bound_ctrl:1
	s_waitcnt lgkmcnt(2)
	v_add_f32_e32 v97, v24, v33
	v_add_f32_dpp v24, v184, v184 row_shr:1 row_mask:0xf bank_mask:0xf bound_ctrl:1
	s_nop 1
	v_add_f32_dpp v24, v24, v24 row_shr:2 row_mask:0xf bank_mask:0xf bound_ctrl:1
	s_nop 1
	v_add_f32_dpp v24, v24, v24 row_shr:4 row_mask:0xf bank_mask:0xf bound_ctrl:1
	s_nop 1
	v_add_f32_dpp v24, v24, v24 row_shr:8 row_mask:0xf bank_mask:0xf bound_ctrl:1
	s_waitcnt lgkmcnt(1)
	v_add_f32_e32 v96, v24, v34
	v_add_f32_dpp v24, v185, v185 row_shr:1 row_mask:0xf bank_mask:0xf bound_ctrl:1
	s_nop 1
	v_add_f32_dpp v24, v24, v24 row_shr:2 row_mask:0xf bank_mask:0xf bound_ctrl:1
	s_nop 1
	v_add_f32_dpp v24, v24, v24 row_shr:4 row_mask:0xf bank_mask:0xf bound_ctrl:1
	s_nop 1
	v_add_f32_dpp v24, v24, v24 row_shr:8 row_mask:0xf bank_mask:0xf bound_ctrl:1
	s_waitcnt lgkmcnt(0)
	v_add_f32_e32 v95, v24, v35
	global_load_dwordx4 v[24:27], v[60:61], off
	global_load_dwordx4 v[32:35], v[70:71], off offset:64
	global_load_dwordx4 v[134:137], v[48:49], off offset:64
	global_load_dwordx4 v[138:141], v[78:79], off offset:64
	global_load_dwordx4 v[142:145], v[36:37], off offset:64
	global_load_dwordx4 v[146:149], v[38:39], off offset:64
	global_load_dwordx4 v[150:153], v[76:77], off offset:64
	global_load_dwordx4 v[122:125], v[64:65], off offset:64
	v_pk_add_f32 v[70:71], v[56:57], 1.0 op_sel_hi:[1,0] neg_lo:[1,0] neg_hi:[1,0]
	v_sub_f32_e32 v40, v41, v2
	v_sub_f32_e32 v41, v2, v41
	v_mul_f32_e32 v41, 0x3fb8aa3b, v41
	v_exp_f32_e32 v42, v41
	v_sub_f32_e32 v41, v43, v88
	v_mul_f32_e32 v40, 0x3fb8aa3b, v40
	v_mul_f32_e32 v41, 0x3fb8aa3b, v41
	v_exp_f32_e32 v40, v40
	v_exp_f32_e32 v41, v41
	v_pk_add_f32 v[72:73], v[58:59], 1.0 op_sel_hi:[1,0] neg_lo:[1,0] neg_hi:[1,0]
	s_waitcnt vmcnt(0) lgkmcnt(0)
; __device__ __forceinline__ void ld8bf(const bf16_t* p, float (&o)[8]) { unpack8(*(const u32x4*)p, o); }
; __device__ __forceinline__ float sigmoidf_(float x) { return __builtin_amdgcn_rcpf(1.0f + __expf(-x)); }
; __device__ __forceinline__ bf16x8 pack_frag(const float (&v)[8]) { return __builtin_bit_cast(bf16x8, pack8(v)); }
; __device__ __forceinline__ void w_hg_m3(const Args& a, int l, unsigned char* ws, const bf16_t* proj, bf16_t* y, LAS unsigned char* wl, int b, int ck_, int h, int lane) {
;     ...
;         for (int tb = 0; tb < 4; ++tb) { float fp[8], qv[8], a1[8], a2[8];
;             ld8bf(fsrc + (size_t)(16 * tb + lo) * NIN, fp); ld8bf(proj + (size_t)(row0 + 16 * tb + lo) * NIN + C_HQ + 64 * h + 32 * kk + 8 * fq, qv);
; #pragma unroll
;             for (int j = 0; j < 8; ++j) { float lf, key; hg_lf_key(fp[j], lbv[j], lf, key);
;                 const float q = qv[j] * sigmoidf_(qv[j]); a1[j] = q * __expf(bb[tb][j] - r31[j]); a2[j] = key * __expf(r31[j] - bb[tb][j]); }
;             Qf[tb][kk] = pack_frag(a1); Kf[tb][kk] = pack_frag(a2); }
	v_lshlrev_b32_e32 v56, 16, v32
	v_and_b32_e32 v57, 0xffff0000, v32
	v_mul_f32_e32 v32, 0xbfb8aa3b, v56
	v_exp_f32_e32 v32, v32
	s_nop 0
	v_add_f32_e32 v32, 1.0, v32
	v_rcp_f32_e32 v60, v32
	v_mul_f32_e32 v32, 0xbfb8aa3b, v57
	v_exp_f32_e32 v32, v32
	s_nop 0
	v_add_f32_e32 v32, 1.0, v32
	v_rcp_f32_e32 v61, v32
	v_sub_f32_e32 v32, v88, v43
	v_mul_f32_e32 v32, 0x3fb8aa3b, v32
	v_exp_f32_e32 v43, v32
	v_pk_mul_f32 v[56:57], v[60:61], v[56:57]
	v_lshlrev_b32_e32 v32, 16, v24
	v_pk_mul_f32 v[40:41], v[40:41], v[56:57]
	v_mul_f32_e64 v56, |v32|, s26
	v_exp_f32_e32 v56, v56
	v_and_b32_e32 v24, 0xffff0000, v24
	v_cmp_le_f32_e32 vcc, 0, v32
	v_cmp_le_f32_e64 s[38:39], 0, v24
	v_add_f32_e32 v57, 1.0, v56
	v_rcp_f32_e32 v60, v57
	v_mul_f32_e64 v57, |v24|, s26
	v_exp_f32_e32 v57, v57
	v_sub_f32_e32 v24, v74, v89
	v_mul_f32_e32 v24, 0x3fb8aa3b, v24
	v_lshlrev_b32_e32 v32, 16, v33
	v_add_f32_e32 v61, 1.0, v57
	v_rcp_f32_e32 v61, v61
	v_and_b32_e32 v33, 0xffff0000, v33
	v_pk_mul_f32 v[56:57], v[56:57], v[60:61]
	s_nop 0
	v_cndmask_b32_e64 v57, v61, v57, s[38:39]
	v_cndmask_b32_e32 v56, v60, v56, vcc
	v_pk_mul_f32 v[56:57], v[70:71], v[56:57]
	s_nop 0
	v_pk_mul_f32 v[42:43], v[42:43], v[56:57]
	v_exp_f32_e32 v56, v24
	v_sub_f32_e32 v24, v89, v74
	v_mul_f32_e32 v24, 0x3fb8aa3b, v24
	v_exp_f32_e32 v58, v24
	v_sub_f32_e32 v24, v75, v90
	v_mul_f32_e32 v24, 0x3fb8aa3b, v24
	v_exp_f32_e32 v57, v24
	v_mul_f32_e32 v24, 0xbfb8aa3b, v32
	v_exp_f32_e32 v24, v24
	s_nop 0
	v_add_f32_e32 v24, 1.0, v24
	v_rcp_f32_e32 v60, v24
	v_mul_f32_e32 v24, 0xbfb8aa3b, v33
	v_exp_f32_e32 v24, v24
	s_nop 0
	v_add_f32_e32 v24, 1.0, v24
	v_rcp_f32_e32 v61, v24
	v_sub_f32_e32 v24, v90, v75
	v_mul_f32_e32 v24, 0x3fb8aa3b, v24
	v_exp_f32_e32 v59, v24
	v_pk_mul_f32 v[32:33], v[60:61], v[32:33]
	v_lshlrev_b32_e32 v60, 16, v25
	v_mul_f32_e64 v24, |v60|, s26
	v_exp_f32_e32 v24, v24
	v_and_b32_e32 v61, 0xffff0000, v25
	v_pk_mul_f32 v[32:33], v[56:57], v[32:33]
	v_cmp_le_f32_e32 vcc, 0, v60
	v_add_f32_e32 v25, 1.0, v24
	v_rcp_f32_e32 v56, v25
	v_mul_f32_e64 v25, |v61|, s26
	v_exp_f32_e32 v25, v25
	v_cmp_le_f32_e64 s[38:39], 0, v61
	v_pk_add_f32 v[74:75], v[50:51], 1.0 op_sel_hi:[1,0] neg_lo:[1,0] neg_hi:[1,0]
	v_add_f32_e32 v57, 1.0, v25
	v_rcp_f32_e32 v57, v57
	s_nop 0
	v_pk_mul_f32 v[24:25], v[24:25], v[56:57]
	s_nop 0
	v_cndmask_b32_e64 v25, v57, v25, s[38:39]
	v_cndmask_b32_e32 v24, v56, v24, vcc
	v_pk_mul_f32 v[24:25], v[72:73], v[24:25]
	s_nop 0
	v_pk_mul_f32 v[56:57], v[58:59], v[24:25]
	v_lshlrev_b32_e32 v58, 16, v34
	v_and_b32_e32 v59, 0xffff0000, v34
	v_mul_f32_e32 v34, 0xbfb8aa3b, v58
	v_exp_f32_e32 v34, v34
	v_sub_f32_e32 v25, v91, v121
	v_mul_f32_e32 v25, 0x3fb8aa3b, v25
	v_sub_f32_e32 v24, v121, v91
	v_add_f32_e32 v34, 1.0, v34
	v_rcp_f32_e32 v60, v34
	v_mul_f32_e32 v34, 0xbfb8aa3b, v59
	v_exp_f32_e32 v34, v34
	v_exp_f32_e32 v50, v25
	v_sub_f32_e32 v25, v119, v92
	v_mul_f32_e32 v24, 0x3fb8aa3b, v24
	v_add_f32_e32 v34, 1.0, v34
	v_mul_f32_e32 v25, 0x3fb8aa3b, v25
	v_rcp_f32_e32 v61, v34
	v_exp_f32_e32 v24, v24
	v_exp_f32_e32 v25, v25
	v_sub_f32_e32 v34, v92, v119
	v_mul_f32_e32 v34, 0x3fb8aa3b, v34
	v_pk_mul_f32 v[58:59], v[60:61], v[58:59]
	v_exp_f32_e32 v51, v34
	v_lshlrev_b32_e32 v34, 16, v26
	v_pk_mul_f32 v[24:25], v[24:25], v[58:59]
	v_mul_f32_e64 v58, |v34|, s26
	v_exp_f32_e32 v58, v58
	v_and_b32_e32 v26, 0xffff0000, v26
	v_cmp_le_f32_e32 vcc, 0, v34
	v_cmp_le_f32_e64 s[38:39], 0, v26
	v_add_f32_e32 v59, 1.0, v58
	v_rcp_f32_e32 v60, v59
	v_mul_f32_e64 v59, |v26|, s26
	v_exp_f32_e32 v59, v59
	v_sub_f32_e32 v26, v63, v93
	v_mul_f32_e32 v26, 0x3fb8aa3b, v26
	v_add_f32_e32 v61, 1.0, v59
	v_rcp_f32_e32 v61, v61
	s_nop 0
	v_pk_mul_f32 v[58:59], v[58:59], v[60:61]
	s_nop 0
	v_cndmask_b32_e64 v59, v61, v59, s[38:39]
	v_cndmask_b32_e32 v58, v60, v58, vcc
	v_pk_mul_f32 v[58:59], v[74:75], v[58:59]
	v_lshlrev_b32_e32 v60, 16, v35
	v_pk_mul_f32 v[50:51], v[50:51], v[58:59]
	v_exp_f32_e32 v58, v26
	v_sub_f32_e32 v26, v93, v63
	v_mul_f32_e32 v26, 0x3fb8aa3b, v26
	v_exp_f32_e32 v34, v26
	v_sub_f32_e32 v26, v62, v94
	v_mul_f32_e32 v26, 0x3fb8aa3b, v26
	v_exp_f32_e32 v59, v26
	v_mul_f32_e32 v26, 0xbfb8aa3b, v60
	v_exp_f32_e32 v26, v26
	v_and_b32_e32 v61, 0xffff0000, v35
	v_and_b32_e32 v63, 0xffff0000, v27
	v_cmp_le_f32_e64 s[38:39], 0, v63
	v_add_f32_e32 v26, 1.0, v26
	v_rcp_f32_e32 v120, v26
	v_mul_f32_e32 v26, 0xbfb8aa3b, v61
	v_exp_f32_e32 v26, v26
	s_nop 0
	v_add_f32_e32 v26, 1.0, v26
	v_rcp_f32_e32 v121, v26
	v_sub_f32_e32 v26, v94, v62
	v_mul_f32_e32 v26, 0x3fb8aa3b, v26
	v_lshlrev_b32_e32 v62, 16, v27
	v_exp_f32_e32 v35, v26
	v_mul_f32_e64 v26, |v62|, s26
	v_exp_f32_e32 v26, v26
	v_pk_mul_f32 v[60:61], v[120:121], v[60:61]
	v_cmp_le_f32_e32 vcc, 0, v62
	v_pk_mul_f32 v[58:59], v[58:59], v[60:61]
	v_add_f32_e32 v27, 1.0, v26
	v_rcp_f32_e32 v60, v27
	v_mul_f32_e64 v27, |v63|, s26
	v_exp_f32_e32 v27, v27
	v_cvt_pk_bf16_f32 v62, v24, v25
	v_cvt_pk_bf16_f32 v24, v42, v43
	v_cvt_pk_bf16_f32 v25, v56, v57
	v_add_f32_e32 v61, 1.0, v27
	v_rcp_f32_e32 v61, v61
	v_cvt_pk_bf16_f32 v63, v58, v59
	v_pk_mul_f32 v[26:27], v[26:27], v[60:61]
	s_nop 0
	v_cndmask_b32_e64 v27, v61, v27, s[38:39]
	v_cndmask_b32_e32 v26, v60, v26, vcc
	v_pk_mul_f32 v[26:27], v[68:69], v[26:27]
	v_cvt_pk_bf16_f32 v60, v40, v41
	v_pk_mul_f32 v[34:35], v[34:35], v[26:27]
	v_cvt_pk_bf16_f32 v61, v32, v33
	v_cvt_pk_bf16_f32 v27, v34, v35
	v_mov_b64_e32 v[32:33], v[134:135]
	v_mov_b64_e32 v[34:35], v[136:137]
	v_mov_b64_e32 v[40:41], v[138:139]
	v_mov_b64_e32 v[42:43], v[140:141]
	v_sub_f32_e32 v49, v2, v118
	v_mul_f32_e32 v49, 0x3fb8aa3b, v49
	v_cvt_pk_bf16_f32 v26, v50, v51
	v_sub_f32_e32 v48, v118, v2
	v_exp_f32_e32 v50, v49
	v_sub_f32_e32 v49, v117, v88
	v_mul_f32_e32 v48, 0x3fb8aa3b, v48
	v_mul_f32_e32 v49, 0x3fb8aa3b, v49
	v_exp_f32_e32 v48, v48
	v_exp_f32_e32 v49, v49
	s_waitcnt vmcnt(0) lgkmcnt(0)
; __device__ __forceinline__ void ld8bf(const bf16_t* p, float (&o)[8]) { unpack8(*(const u32x4*)p, o); }
; __device__ __forceinline__ float sigmoidf_(float x) { return __builtin_amdgcn_rcpf(1.0f + __expf(-x)); }
; __device__ __forceinline__ bf16x8 pack_frag(const float (&v)[8]) { return __builtin_bit_cast(bf16x8, pack8(v)); }
; __device__ __forceinline__ void w_hg_m3(const Args& a, int l, unsigned char* ws, const bf16_t* proj, bf16_t* y, LAS unsigned char* wl, int b, int ck_, int h, int lane) {
;     ...
;         for (int tb = 0; tb < 4; ++tb) { float fp[8], qv[8], a1[8], a2[8];
;             ld8bf(fsrc + (size_t)(16 * tb + lo) * NIN, fp); ld8bf(proj + (size_t)(row0 + 16 * tb + lo) * NIN + C_HQ + 64 * h + 32 * kk + 8 * fq, qv);
; #pragma unroll
;             for (int j = 0; j < 8; ++j) { float lf, key; hg_lf_key(fp[j], lbv[j], lf, key);
;                 const float q = qv[j] * sigmoidf_(qv[j]); a1[j] = q * __expf(bb[tb][j] - r31[j]); a2[j] = key * __expf(r31[j] - bb[tb][j]); }
;             Qf[tb][kk] = pack_frag(a1); Kf[tb][kk] = pack_frag(a2); }
	v_lshlrev_b32_e32 v56, 16, v40
	v_and_b32_e32 v57, 0xffff0000, v40
	v_mul_f32_e32 v40, 0xbfb8aa3b, v56
	v_exp_f32_e32 v40, v40
	s_nop 0
	v_add_f32_e32 v40, 1.0, v40
	v_rcp_f32_e32 v58, v40
	v_mul_f32_e32 v40, 0xbfb8aa3b, v57
	v_exp_f32_e32 v40, v40
	s_nop 0
	v_add_f32_e32 v40, 1.0, v40
	v_rcp_f32_e32 v59, v40
	v_sub_f32_e32 v40, v88, v117
	v_mul_f32_e32 v40, 0x3fb8aa3b, v40
	v_exp_f32_e32 v51, v40
	v_pk_mul_f32 v[56:57], v[58:59], v[56:57]
	v_lshlrev_b32_e32 v40, 16, v32
	v_pk_mul_f32 v[48:49], v[48:49], v[56:57]
	v_mul_f32_e64 v56, |v40|, s26
	v_exp_f32_e32 v56, v56
	v_and_b32_e32 v32, 0xffff0000, v32
	v_cmp_le_f32_e32 vcc, 0, v40
	v_cmp_le_f32_e64 s[38:39], 0, v32
	v_add_f32_e32 v57, 1.0, v56
	v_rcp_f32_e32 v58, v57
	v_mul_f32_e64 v57, |v32|, s26
	v_exp_f32_e32 v57, v57
	v_sub_f32_e32 v32, v116, v89
	v_mul_f32_e32 v32, 0x3fb8aa3b, v32
	v_cvt_pk_bf16_f32 v48, v48, v49
	v_add_f32_e32 v59, 1.0, v57
	v_rcp_f32_e32 v59, v59
	s_nop 0
	v_pk_mul_f32 v[56:57], v[56:57], v[58:59]
	s_nop 0
	v_cndmask_b32_e64 v57, v59, v57, s[38:39]
	v_cndmask_b32_e32 v56, v58, v56, vcc
	v_pk_mul_f32 v[56:57], v[70:71], v[56:57]
	v_lshlrev_b32_e32 v58, 16, v41
	v_pk_mul_f32 v[56:57], v[50:51], v[56:57]
	v_exp_f32_e32 v50, v32
	v_sub_f32_e32 v32, v89, v116
	v_mul_f32_e32 v32, 0x3fb8aa3b, v32
	v_exp_f32_e32 v40, v32
	v_sub_f32_e32 v32, v115, v90
	v_mul_f32_e32 v32, 0x3fb8aa3b, v32
	v_exp_f32_e32 v51, v32
	v_mul_f32_e32 v32, 0xbfb8aa3b, v58
	v_exp_f32_e32 v32, v32
	v_and_b32_e32 v59, 0xffff0000, v41
	v_add_f32_e32 v32, 1.0, v32
	v_rcp_f32_e32 v78, v32
	v_mul_f32_e32 v32, 0xbfb8aa3b, v59
	v_exp_f32_e32 v32, v32
	s_nop 0
	v_add_f32_e32 v32, 1.0, v32
	v_rcp_f32_e32 v79, v32
	v_sub_f32_e32 v32, v90, v115
	v_mul_f32_e32 v32, 0x3fb8aa3b, v32
	v_exp_f32_e32 v41, v32
	v_pk_mul_f32 v[58:59], v[78:79], v[58:59]
	v_lshlrev_b32_e32 v78, 16, v33
	v_mul_f32_e64 v32, |v78|, s26
	v_exp_f32_e32 v32, v32
	v_and_b32_e32 v79, 0xffff0000, v33
	v_pk_mul_f32 v[50:51], v[50:51], v[58:59]
	v_cmp_le_f32_e32 vcc, 0, v78
	v_add_f32_e32 v33, 1.0, v32
	v_rcp_f32_e32 v58, v33
	v_mul_f32_e64 v33, |v79|, s26
	v_exp_f32_e32 v33, v33
	v_lshlrev_b32_e32 v78, 16, v42
	v_cmp_le_f32_e64 s[38:39], 0, v79
	v_and_b32_e32 v79, 0xffff0000, v42
	v_mul_f32_e32 v42, 0xbfb8aa3b, v78
	v_add_f32_e32 v59, 1.0, v33
	v_exp_f32_e32 v42, v42
	v_rcp_f32_e32 v59, v59
	v_cvt_pk_bf16_f32 v49, v50, v51
	v_add_f32_e32 v42, 1.0, v42
	v_pk_mul_f32 v[32:33], v[32:33], v[58:59]
	v_rcp_f32_e32 v116, v42
	v_mul_f32_e32 v42, 0xbfb8aa3b, v79
	v_cndmask_b32_e64 v33, v59, v33, s[38:39]
	v_cndmask_b32_e32 v32, v58, v32, vcc
	v_exp_f32_e32 v42, v42
	v_pk_mul_f32 v[32:33], v[72:73], v[32:33]
	v_add_f32_e32 v42, 1.0, v42
	v_pk_mul_f32 v[40:41], v[40:41], v[32:33]
	v_sub_f32_e32 v33, v91, v113
	v_mul_f32_e32 v33, 0x3fb8aa3b, v33
	v_sub_f32_e32 v32, v113, v91
	v_exp_f32_e32 v58, v33
	v_sub_f32_e32 v33, v112, v92
	v_mul_f32_e32 v32, 0x3fb8aa3b, v32
	v_mul_f32_e32 v33, 0x3fb8aa3b, v33
	v_rcp_f32_e32 v117, v42
	v_exp_f32_e32 v32, v32
	v_exp_f32_e32 v33, v33
	v_sub_f32_e32 v42, v92, v112
	v_mul_f32_e32 v42, 0x3fb8aa3b, v42
	v_pk_mul_f32 v[78:79], v[116:117], v[78:79]
	v_exp_f32_e32 v59, v42
	v_lshlrev_b32_e32 v42, 16, v34
	v_pk_mul_f32 v[32:33], v[32:33], v[78:79]
	v_mul_f32_e64 v78, |v42|, s26
	v_exp_f32_e32 v78, v78
	v_and_b32_e32 v34, 0xffff0000, v34
	v_cmp_le_f32_e32 vcc, 0, v42
	v_cmp_le_f32_e64 s[38:39], 0, v34
	v_add_f32_e32 v79, 1.0, v78
	v_rcp_f32_e32 v112, v79
	v_mul_f32_e64 v79, |v34|, s26
	v_exp_f32_e32 v79, v79
	v_sub_f32_e32 v34, v111, v93
	v_mul_f32_e32 v34, 0x3fb8aa3b, v34
	v_cvt_pk_bf16_f32 v50, v32, v33
	v_add_f32_e32 v113, 1.0, v79
	v_rcp_f32_e32 v113, v113
	v_cvt_pk_bf16_f32 v33, v40, v41
	v_cvt_pk_bf16_f32 v32, v56, v57
	v_sub_f32_e32 v57, v2, v109
	v_pk_mul_f32 v[78:79], v[78:79], v[112:113]
	v_mul_f32_e32 v57, 0x3fb8aa3b, v57
	v_cndmask_b32_e64 v79, v113, v79, s[38:39]
	v_cndmask_b32_e32 v78, v112, v78, vcc
	v_pk_mul_f32 v[78:79], v[74:75], v[78:79]
	v_lshlrev_b32_e32 v112, 16, v43
	v_pk_mul_f32 v[58:59], v[58:59], v[78:79]
	v_exp_f32_e32 v78, v34
	v_sub_f32_e32 v34, v93, v111
	v_mul_f32_e32 v34, 0x3fb8aa3b, v34
	v_exp_f32_e32 v42, v34
	v_sub_f32_e32 v34, v110, v94
	v_mul_f32_e32 v34, 0x3fb8aa3b, v34
	v_exp_f32_e32 v79, v34
	v_mul_f32_e32 v34, 0xbfb8aa3b, v112
	v_exp_f32_e32 v34, v34
	v_and_b32_e32 v113, 0xffff0000, v43
	v_sub_f32_e32 v56, v109, v2
	v_mul_f32_e32 v56, 0x3fb8aa3b, v56
	v_add_f32_e32 v34, 1.0, v34
	v_rcp_f32_e32 v116, v34
	v_mul_f32_e32 v34, 0xbfb8aa3b, v113
	v_exp_f32_e32 v34, v34
	v_exp_f32_e32 v56, v56
	v_add_f32_e32 v34, 1.0, v34
	v_rcp_f32_e32 v117, v34
	v_sub_f32_e32 v34, v94, v110
	v_mul_f32_e32 v34, 0x3fb8aa3b, v34
	v_exp_f32_e32 v43, v34
	v_pk_mul_f32 v[112:113], v[116:117], v[112:113]
	s_nop 0
	v_pk_mul_f32 v[78:79], v[78:79], v[112:113]
	v_lshlrev_b32_e32 v112, 16, v35
	v_mul_f32_e64 v34, |v112|, s26
	v_exp_f32_e32 v34, v34
	v_and_b32_e32 v113, 0xffff0000, v35
	v_cmp_le_f32_e32 vcc, 0, v112
	v_cmp_le_f32_e64 s[38:39], 0, v113
	v_add_f32_e32 v35, 1.0, v34
	v_rcp_f32_e32 v110, v35
	v_mul_f32_e64 v35, |v113|, s26
	v_exp_f32_e32 v35, v35
	v_cvt_pk_bf16_f32 v51, v78, v79
	v_add_f32_e32 v111, 1.0, v35
	v_rcp_f32_e32 v111, v111
	s_nop 0
	v_pk_mul_f32 v[34:35], v[34:35], v[110:111]
	s_nop 0
	v_cndmask_b32_e64 v35, v111, v35, s[38:39]
	v_cndmask_b32_e32 v34, v110, v34, vcc
	v_pk_mul_f32 v[34:35], v[68:69], v[34:35]
	s_nop 0
	v_pk_mul_f32 v[42:43], v[42:43], v[34:35]
	v_cvt_pk_bf16_f32 v34, v58, v59
	v_cvt_pk_bf16_f32 v35, v42, v43
	v_mov_b64_e32 v[40:41], v[142:143]
	v_mov_b64_e32 v[42:43], v[144:145]
	s_nop 0
	v_mov_b64_e32 v[36:37], v[146:147]
	v_mov_b64_e32 v[38:39], v[148:149]
	v_exp_f32_e32 v58, v57
	v_sub_f32_e32 v57, v107, v88
	v_mul_f32_e32 v57, 0x3fb8aa3b, v57
	v_exp_f32_e32 v57, v57
	s_waitcnt vmcnt(0) lgkmcnt(0)
; __device__ __forceinline__ void ld8bf(const bf16_t* p, float (&o)[8]) { unpack8(*(const u32x4*)p, o); }
; __device__ __forceinline__ float sigmoidf_(float x) { return __builtin_amdgcn_rcpf(1.0f + __expf(-x)); }
; __device__ __forceinline__ bf16x8 pack_frag(const float (&v)[8]) { return __builtin_bit_cast(bf16x8, pack8(v)); }
; __device__ __forceinline__ void w_hg_m3(const Args& a, int l, unsigned char* ws, const bf16_t* proj, bf16_t* y, LAS unsigned char* wl, int b, int ck_, int h, int lane) {
;     ...
;         for (int tb = 0; tb < 4; ++tb) { float fp[8], qv[8], a1[8], a2[8];
;             ld8bf(fsrc + (size_t)(16 * tb + lo) * NIN, fp); ld8bf(proj + (size_t)(row0 + 16 * tb + lo) * NIN + C_HQ + 64 * h + 32 * kk + 8 * fq, qv);
; #pragma unroll
;             for (int j = 0; j < 8; ++j) { float lf, key; hg_lf_key(fp[j], lbv[j], lf, key);
;                 const float q = qv[j] * sigmoidf_(qv[j]); a1[j] = q * __expf(bb[tb][j] - r31[j]); a2[j] = key * __expf(r31[j] - bb[tb][j]); }
;             Qf[tb][kk] = pack_frag(a1); Kf[tb][kk] = pack_frag(a2); }
	v_and_b32_e32 v109, 0xffff0000, v41
	v_lshlrev_b32_e32 v78, 16, v36
	v_and_b32_e32 v79, 0xffff0000, v36
	v_mul_f32_e32 v36, 0xbfb8aa3b, v78
	v_exp_f32_e32 v36, v36
	s_nop 0
	v_add_f32_e32 v36, 1.0, v36
	v_rcp_f32_e32 v110, v36
	v_mul_f32_e32 v36, 0xbfb8aa3b, v79
	v_exp_f32_e32 v36, v36
	s_nop 0
	v_add_f32_e32 v36, 1.0, v36
	v_rcp_f32_e32 v111, v36
	v_sub_f32_e32 v36, v88, v107
	v_mul_f32_e32 v36, 0x3fb8aa3b, v36
	v_exp_f32_e32 v59, v36
	v_pk_mul_f32 v[78:79], v[110:111], v[78:79]
	v_lshlrev_b32_e32 v36, 16, v40
	v_pk_mul_f32 v[56:57], v[56:57], v[78:79]
	v_mul_f32_e64 v78, |v36|, s26
	v_exp_f32_e32 v78, v78
	v_and_b32_e32 v40, 0xffff0000, v40
	v_cmp_le_f32_e32 vcc, 0, v36
	v_cmp_le_f32_e64 s[38:39], 0, v40
	v_add_f32_e32 v79, 1.0, v78
	v_rcp_f32_e32 v110, v79
	v_mul_f32_e64 v79, |v40|, s26
	v_exp_f32_e32 v79, v79
	v_sub_f32_e32 v36, v106, v89
	v_mul_f32_e32 v36, 0x3fb8aa3b, v36
	v_sub_f32_e32 v40, v105, v90
	v_add_f32_e32 v107, 1.0, v79
	v_rcp_f32_e32 v111, v107
	v_and_b32_e32 v107, 0xffff0000, v37
	v_mul_f32_e32 v40, 0x3fb8aa3b, v40
	v_pk_mul_f32 v[78:79], v[78:79], v[110:111]
	s_nop 0
	v_cndmask_b32_e64 v79, v111, v79, s[38:39]
	v_cndmask_b32_e32 v78, v110, v78, vcc
	v_pk_mul_f32 v[78:79], v[70:71], v[78:79]
	v_cmp_le_f32_e64 s[38:39], 0, v109
	v_pk_mul_f32 v[58:59], v[58:59], v[78:79]
	v_exp_f32_e32 v78, v36
	v_sub_f32_e32 v36, v89, v106
	v_lshlrev_b32_e32 v106, 16, v37
	v_mul_f32_e32 v37, 0xbfb8aa3b, v106
	v_exp_f32_e32 v37, v37
	v_exp_f32_e32 v79, v40
	v_mul_f32_e32 v36, 0x3fb8aa3b, v36
	v_exp_f32_e32 v36, v36
	v_add_f32_e32 v37, 1.0, v37
	v_rcp_f32_e32 v110, v37
	v_mul_f32_e32 v37, 0xbfb8aa3b, v107
	v_exp_f32_e32 v37, v37
	s_nop 0
	v_add_f32_e32 v37, 1.0, v37
	v_rcp_f32_e32 v111, v37
	v_sub_f32_e32 v37, v90, v105
	v_lshlrev_b32_e32 v105, 16, v41
	v_mul_f32_e64 v40, |v105|, s26
	v_exp_f32_e32 v40, v40
	v_pk_mul_f32 v[106:107], v[110:111], v[106:107]
	v_mul_f32_e32 v37, 0x3fb8aa3b, v37
	v_pk_mul_f32 v[78:79], v[78:79], v[106:107]
	v_add_f32_e32 v41, 1.0, v40
	v_rcp_f32_e32 v106, v41
	v_mul_f32_e64 v41, |v109|, s26
	v_exp_f32_e32 v41, v41
	v_exp_f32_e32 v37, v37
	v_cmp_le_f32_e32 vcc, 0, v105
	v_and_b32_e32 v105, 0xffff0000, v38
	v_add_f32_e32 v107, 1.0, v41
	v_rcp_f32_e32 v107, v107
	s_nop 0
	v_pk_mul_f32 v[40:41], v[40:41], v[106:107]
	s_nop 0
	v_cndmask_b32_e64 v41, v107, v41, s[38:39]
	v_cndmask_b32_e32 v40, v106, v40, vcc
	v_pk_mul_f32 v[40:41], v[72:73], v[40:41]
	s_nop 0
	v_pk_mul_f32 v[106:107], v[36:37], v[40:41]
	v_sub_f32_e32 v36, v104, v91
	v_sub_f32_e32 v37, v91, v104
	v_lshlrev_b32_e32 v104, 16, v38
	v_mul_f32_e32 v38, 0xbfb8aa3b, v104
	v_exp_f32_e32 v38, v38
	v_mul_f32_e32 v37, 0x3fb8aa3b, v37
	v_exp_f32_e32 v40, v37
	v_sub_f32_e32 v37, v103, v92
	v_add_f32_e32 v38, 1.0, v38
	v_rcp_f32_e32 v110, v38
	v_mul_f32_e32 v38, 0xbfb8aa3b, v105
	v_exp_f32_e32 v38, v38
	v_mul_f32_e32 v36, 0x3fb8aa3b, v36
	v_mul_f32_e32 v37, 0x3fb8aa3b, v37
	v_exp_f32_e32 v36, v36
	v_add_f32_e32 v38, 1.0, v38
	v_rcp_f32_e32 v111, v38
	v_exp_f32_e32 v37, v37
	v_sub_f32_e32 v38, v92, v103
	v_mul_f32_e32 v38, 0x3fb8aa3b, v38
	v_exp_f32_e32 v41, v38
	v_lshlrev_b32_e32 v38, 16, v42
	v_pk_mul_f32 v[104:105], v[110:111], v[104:105]
	v_mul_f32_e64 v103, |v38|, s26
	v_pk_mul_f32 v[36:37], v[36:37], v[104:105]
	v_exp_f32_e32 v104, v103
	v_and_b32_e32 v42, 0xffff0000, v42
	v_cmp_le_f32_e32 vcc, 0, v38
	v_cmp_le_f32_e64 s[38:39], 0, v42
	v_add_f32_e32 v103, 1.0, v104
	v_rcp_f32_e32 v110, v103
	v_mul_f32_e64 v103, |v42|, s26
	v_exp_f32_e32 v105, v103
	v_sub_f32_e32 v38, v67, v93
	v_mul_f32_e32 v38, 0x3fb8aa3b, v38
	v_add_f32_e32 v103, 1.0, v105
	v_rcp_f32_e32 v111, v103
	s_nop 0
	v_pk_mul_f32 v[104:105], v[104:105], v[110:111]
	s_nop 0
	v_cndmask_b32_e32 v104, v110, v104, vcc
	v_lshlrev_b32_e32 v110, 16, v39
	v_cndmask_b32_e64 v105, v111, v105, s[38:39]
	v_and_b32_e32 v111, 0xffff0000, v39
	v_mul_f32_e32 v39, 0xbfb8aa3b, v110
	v_exp_f32_e32 v39, v39
	v_pk_mul_f32 v[104:105], v[74:75], v[104:105]
	v_add_f32_e32 v39, 1.0, v39
	v_rcp_f32_e32 v112, v39
	v_mul_f32_e32 v39, 0xbfb8aa3b, v111
	v_exp_f32_e32 v39, v39
	v_pk_mul_f32 v[104:105], v[40:41], v[104:105]
	v_sub_f32_e32 v41, v66, v94
	v_mul_f32_e32 v41, 0x3fb8aa3b, v41
	v_add_f32_e32 v39, 1.0, v39
	v_rcp_f32_e32 v113, v39
	v_exp_f32_e32 v40, v38
	v_exp_f32_e32 v41, v41
	v_sub_f32_e32 v39, v94, v66
	v_pk_mul_f32 v[110:111], v[112:113], v[110:111]
	v_lshlrev_b32_e32 v66, 16, v43
	v_pk_mul_f32 v[110:111], v[40:41], v[110:111]
	v_mul_f32_e64 v40, |v66|, s26
	v_exp_f32_e32 v40, v40
	v_sub_f32_e32 v38, v93, v67
	v_and_b32_e32 v67, 0xffff0000, v43
	v_mul_f32_e32 v38, 0x3fb8aa3b, v38
	v_add_f32_e32 v41, 1.0, v40
	v_rcp_f32_e32 v42, v41
	v_mul_f32_e64 v41, |v67|, s26
	v_exp_f32_e32 v41, v41
	v_mul_f32_e32 v39, 0x3fb8aa3b, v39
	v_exp_f32_e32 v38, v38
	v_exp_f32_e32 v39, v39
	v_add_f32_e32 v43, 1.0, v41
	v_rcp_f32_e32 v43, v43
	v_cmp_le_f32_e32 vcc, 0, v66
	v_cmp_le_f32_e64 s[38:39], 0, v67
	v_pk_mul_f32 v[40:41], v[40:41], v[42:43]
	s_nop 0
	v_cndmask_b32_e64 v41, v43, v41, s[38:39]
	v_cndmask_b32_e32 v40, v42, v40, vcc
	v_pk_mul_f32 v[40:41], v[68:69], v[40:41]
	v_cvt_pk_bf16_f32 v42, v36, v37
	v_pk_mul_f32 v[66:67], v[38:39], v[40:41]
	v_cvt_pk_bf16_f32 v40, v56, v57
	v_cvt_pk_bf16_f32 v36, v58, v59
	v_cvt_pk_bf16_f32 v39, v66, v67
	v_mov_b64_e32 v[56:57], v[150:151]
	v_mov_b64_e32 v[58:59], v[152:153]
	s_nop 0
	v_mov_b64_e32 v[64:65], v[122:123]
	v_mov_b64_e32 v[66:67], v[124:125]
	v_sub_f32_e32 v76, v102, v2
	v_sub_f32_e32 v77, v2, v102
	v_cvt_pk_bf16_f32 v38, v104, v105
	v_mul_f32_e32 v77, 0x3fb8aa3b, v77
	v_cvt_pk_bf16_f32 v41, v78, v79
	v_exp_f32_e32 v78, v77
	v_sub_f32_e32 v77, v101, v88
	v_mul_f32_e32 v76, 0x3fb8aa3b, v76
	v_mul_f32_e32 v77, 0x3fb8aa3b, v77
	v_exp_f32_e32 v76, v76
	v_exp_f32_e32 v77, v77
	v_mul_f32_e32 v2, 0x3fb8aa3b, v2
	v_cvt_pk_bf16_f32 v37, v106, v107
	v_cvt_pk_bf16_f32 v43, v110, v111
	s_waitcnt vmcnt(0) lgkmcnt(0)
; __device__ __forceinline__ void ld8bf(const bf16_t* p, float (&o)[8]) { unpack8(*(const u32x4*)p, o); }
; __device__ __forceinline__ float sigmoidf_(float x) { return __builtin_amdgcn_rcpf(1.0f + __expf(-x)); }
; __device__ __forceinline__ bf16x8 pack_frag(const float (&v)[8]) { return __builtin_bit_cast(bf16x8, pack8(v)); }
; __device__ __forceinline__ void w_hg_m3(const Args& a, int l, unsigned char* ws, const bf16_t* proj, bf16_t* y, LAS unsigned char* wl, int b, int ck_, int h, int lane) {
;     ...
;         for (int tb = 0; tb < 4; ++tb) { float fp[8], qv[8], a1[8], a2[8];
;             ld8bf(fsrc + (size_t)(16 * tb + lo) * NIN, fp); ld8bf(proj + (size_t)(row0 + 16 * tb + lo) * NIN + C_HQ + 64 * h + 32 * kk + 8 * fq, qv);
; #pragma unroll
;             for (int j = 0; j < 8; ++j) { float lf, key; hg_lf_key(fp[j], lbv[j], lf, key);
;                 const float q = qv[j] * sigmoidf_(qv[j]); a1[j] = q * __expf(bb[tb][j] - r31[j]); a2[j] = key * __expf(r31[j] - bb[tb][j]); }
;             Qf[tb][kk] = pack_frag(a1); Kf[tb][kk] = pack_frag(a2); }
; #pragma unroll
;         for (int j = 0; j < 8; ++j) er[kk][j] = __expf(r31[j]);
;         __builtin_amdgcn_sched_barrier(0);
;     }
; #pragma unroll
;     for (int kk = 0; kk < 2; ++kk)
; #pragma unroll
;         for (int eb = 0; eb < 4; ++eb) { float sv[8]; ld8bf(Sb + (16 * eb + lo) * 64 + 32 * kk + 8 * fq, sv);
; #pragma unroll
;             for (int j = 0; j < 8; ++j) sv[j] *= er[kk][j];
;             Sf[eb][kk] = pack_frag(sv); }
	v_lshlrev_b32_e32 v102, 16, v64
	v_and_b32_e32 v103, 0xffff0000, v64
	v_mul_f32_e32 v64, 0xbfb8aa3b, v102
	v_exp_f32_e32 v64, v64
	s_nop 0
	v_add_f32_e32 v64, 1.0, v64
	v_rcp_f32_e32 v104, v64
	v_mul_f32_e32 v64, 0xbfb8aa3b, v103
	v_exp_f32_e32 v64, v64
	s_nop 0
	v_add_f32_e32 v64, 1.0, v64
	v_rcp_f32_e32 v105, v64
	v_sub_f32_e32 v64, v88, v101
	v_mul_f32_e32 v64, 0x3fb8aa3b, v64
	v_exp_f32_e32 v79, v64
	v_lshlrev_b32_e32 v64, 16, v56
	v_pk_mul_f32 v[102:103], v[104:105], v[102:103]
	v_mul_f32_e64 v101, |v64|, s26
	v_pk_mul_f32 v[76:77], v[76:77], v[102:103]
	v_exp_f32_e32 v102, v101
	v_and_b32_e32 v56, 0xffff0000, v56
	v_cmp_le_f32_e32 vcc, 0, v64
	v_cmp_le_f32_e64 s[38:39], 0, v56
	v_add_f32_e32 v101, 1.0, v102
	v_rcp_f32_e32 v104, v101
	v_mul_f32_e64 v101, |v56|, s26
	v_exp_f32_e32 v103, v101
	v_sub_f32_e32 v56, v100, v89
	v_mul_f32_e32 v56, 0x3fb8aa3b, v56
	v_lshlrev_b32_e32 v64, 16, v65
	v_add_f32_e32 v101, 1.0, v103
	v_rcp_f32_e32 v105, v101
	v_and_b32_e32 v65, 0xffff0000, v65
	v_pk_mul_f32 v[102:103], v[102:103], v[104:105]
	s_nop 0
	v_cndmask_b32_e64 v103, v105, v103, s[38:39]
	v_cndmask_b32_e32 v102, v104, v102, vcc
	v_pk_mul_f32 v[70:71], v[70:71], v[102:103]
	s_nop 0
	v_pk_mul_f32 v[70:71], v[78:79], v[70:71]
	v_exp_f32_e32 v78, v56
	v_sub_f32_e32 v56, v89, v100
	v_mul_f32_e32 v56, 0x3fb8aa3b, v56
	v_exp_f32_e32 v100, v56
	v_sub_f32_e32 v56, v99, v90
	v_mul_f32_e32 v56, 0x3fb8aa3b, v56
	v_exp_f32_e32 v79, v56
	v_mul_f32_e32 v56, 0xbfb8aa3b, v64
	v_exp_f32_e32 v56, v56
	s_nop 0
	v_add_f32_e32 v56, 1.0, v56
	v_rcp_f32_e32 v102, v56
	v_mul_f32_e32 v56, 0xbfb8aa3b, v65
	v_exp_f32_e32 v56, v56
	s_nop 0
	v_add_f32_e32 v56, 1.0, v56
	v_rcp_f32_e32 v103, v56
	v_sub_f32_e32 v56, v90, v99
	v_mul_f32_e32 v56, 0x3fb8aa3b, v56
	v_lshlrev_b32_e32 v99, 16, v57
	v_exp_f32_e32 v101, v56
	v_mul_f32_e64 v56, |v99|, s26
	v_exp_f32_e32 v56, v56
	v_pk_mul_f32 v[64:65], v[102:103], v[64:65]
	v_and_b32_e32 v102, 0xffff0000, v57
	v_pk_mul_f32 v[64:65], v[78:79], v[64:65]
	v_add_f32_e32 v57, 1.0, v56
	v_rcp_f32_e32 v78, v57
	v_mul_f32_e64 v57, |v102|, s26
	v_exp_f32_e32 v57, v57
	v_cmp_le_f32_e32 vcc, 0, v99
	v_cmp_le_f32_e64 s[38:39], 0, v102
	v_and_b32_e32 v99, 0xffff0000, v66
	v_add_f32_e32 v79, 1.0, v57
	v_rcp_f32_e32 v79, v79
	s_nop 0
	v_pk_mul_f32 v[56:57], v[56:57], v[78:79]
	s_nop 0
	v_cndmask_b32_e64 v57, v79, v57, s[38:39]
	v_cndmask_b32_e32 v56, v78, v56, vcc
	v_pk_mul_f32 v[56:57], v[72:73], v[56:57]
	s_nop 0
	v_pk_mul_f32 v[72:73], v[100:101], v[56:57]
	v_sub_f32_e32 v56, v98, v91
	v_sub_f32_e32 v57, v91, v98
	v_lshlrev_b32_e32 v98, 16, v66
	v_mul_f32_e32 v66, 0xbfb8aa3b, v98
	v_exp_f32_e32 v66, v66
	v_mul_f32_e32 v57, 0x3fb8aa3b, v57
	v_exp_f32_e32 v78, v57
	v_sub_f32_e32 v57, v97, v92
	v_add_f32_e32 v66, 1.0, v66
	v_rcp_f32_e32 v100, v66
	v_mul_f32_e32 v66, 0xbfb8aa3b, v99
	v_exp_f32_e32 v66, v66
	v_mul_f32_e32 v56, 0x3fb8aa3b, v56
	v_mul_f32_e32 v57, 0x3fb8aa3b, v57
	v_exp_f32_e32 v56, v56
	v_add_f32_e32 v66, 1.0, v66
	v_rcp_f32_e32 v101, v66
	v_exp_f32_e32 v57, v57
	v_lshlrev_b32_e32 v66, 16, v58
	v_and_b32_e32 v58, 0xffff0000, v58
	v_pk_mul_f32 v[98:99], v[100:101], v[98:99]
	v_cmp_le_f32_e32 vcc, 0, v66
	v_pk_mul_f32 v[98:99], v[56:57], v[98:99]
	v_sub_f32_e32 v56, v92, v97
	v_mul_f32_e32 v56, 0x3fb8aa3b, v56
	v_exp_f32_e32 v79, v56
	v_mul_f32_e64 v56, |v66|, s26
	v_exp_f32_e32 v56, v56
	v_cmp_le_f32_e64 s[38:39], 0, v58
	v_add_f32_e32 v57, 1.0, v56
	v_rcp_f32_e32 v100, v57
	v_mul_f32_e64 v57, |v58|, s26
	v_exp_f32_e32 v57, v57
	s_nop 0
	v_add_f32_e32 v97, 1.0, v57
	v_rcp_f32_e32 v101, v97
	s_nop 0
	v_pk_mul_f32 v[56:57], v[56:57], v[100:101]
	s_nop 0
	v_cndmask_b32_e64 v57, v101, v57, s[38:39]
	v_cndmask_b32_e32 v56, v100, v56, vcc
	v_pk_mul_f32 v[56:57], v[74:75], v[56:57]
	v_exp_f32_e32 v100, v2
	v_pk_mul_f32 v[74:75], v[78:79], v[56:57]
	v_lshlrev_b32_e32 v78, 16, v67
	v_mul_f32_e32 v58, 0xbfb8aa3b, v78
	v_exp_f32_e32 v58, v58
	v_and_b32_e32 v79, 0xffff0000, v67
	v_sub_f32_e32 v56, v96, v93
	v_sub_f32_e32 v57, v93, v96
	v_add_f32_e32 v58, 1.0, v58
	v_rcp_f32_e32 v96, v58
	v_mul_f32_e32 v58, 0xbfb8aa3b, v79
	v_exp_f32_e32 v58, v58
	v_mul_f32_e32 v57, 0x3fb8aa3b, v57
	v_exp_f32_e32 v66, v57
	v_sub_f32_e32 v57, v95, v94
	v_add_f32_e32 v58, 1.0, v58
	v_mul_f32_e32 v56, 0x3fb8aa3b, v56
	v_mul_f32_e32 v57, 0x3fb8aa3b, v57
	v_rcp_f32_e32 v97, v58
	v_exp_f32_e32 v56, v56
	v_exp_f32_e32 v57, v57
	v_mul_f32_e32 v2, 0x3fb8aa3b, v88
	v_pk_mul_f32 v[78:79], v[96:97], v[78:79]
	v_and_b32_e32 v96, 0xffff0000, v59
	v_pk_mul_f32 v[78:79], v[56:57], v[78:79]
	v_sub_f32_e32 v56, v94, v95
	v_mul_f32_e32 v56, 0x3fb8aa3b, v56
	v_lshlrev_b32_e32 v95, 16, v59
	v_exp_f32_e32 v67, v56
	v_mul_f32_e64 v56, |v95|, s26
	v_exp_f32_e32 v56, v56
	v_exp_f32_e32 v101, v2
	v_mul_f32_e32 v2, 0x3fb8aa3b, v89
	v_exp_f32_e32 v102, v2
	v_add_f32_e32 v57, 1.0, v56
	v_rcp_f32_e32 v58, v57
	v_mul_f32_e64 v57, |v96|, s26
	v_exp_f32_e32 v57, v57
	v_mul_f32_e32 v2, 0x3fb8aa3b, v90
	v_cmp_le_f32_e32 vcc, 0, v95
	v_cmp_le_f32_e64 s[38:39], 0, v96
	v_add_f32_e32 v59, 1.0, v57
	v_rcp_f32_e32 v59, v59
	v_exp_f32_e32 v103, v2
	v_mul_f32_e32 v2, 0x3fb8aa3b, v91
	v_exp_f32_e32 v104, v2
	v_pk_mul_f32 v[56:57], v[56:57], v[58:59]
	v_mul_f32_e32 v2, 0x3fb8aa3b, v92
	v_cndmask_b32_e64 v57, v59, v57, s[38:39]
	v_cndmask_b32_e32 v56, v58, v56, vcc
	v_pk_mul_f32 v[56:57], v[68:69], v[56:57]
	v_exp_f32_e32 v105, v2
	v_mul_f32_e32 v2, 0x3fb8aa3b, v93
	v_pk_mul_f32 v[66:67], v[66:67], v[56:57]
	v_exp_f32_e32 v106, v2
	v_mul_f32_e32 v2, 0x3fb8aa3b, v94
	v_cvt_pk_bf16_f32 v56, v76, v77
	v_cvt_pk_bf16_f32 v57, v64, v65
	v_cvt_pk_bf16_f32 v58, v98, v99
	v_cvt_pk_bf16_f32 v59, v78, v79
	v_cvt_pk_bf16_f32 v68, v70, v71
	v_cvt_pk_bf16_f32 v69, v72, v73
	v_cvt_pk_bf16_f32 v70, v74, v75
	v_cvt_pk_bf16_f32 v71, v66, v67
	v_exp_f32_e32 v107, v2
	s_add_u32 s20, s80, s40
	s_addc_u32 s21, s81, s41
	v_lshl_add_u64 v[94:95], v[0:1], 1, s[20:21]
	v_lshlrev_b32_e32 v2, 7, v114
	v_lshl_add_u64 v[0:1], v[94:95], 0, v[2:3]
	global_load_dwordx4 v[146:149], v[0:1], off
	global_load_dwordx4 v[150:153], v[0:1], off offset:2048
	global_load_dwordx4 v[122:125], v[0:1], off offset:64
	global_load_dwordx4 v[134:137], v[0:1], off offset:2112
	v_mov_b32_e32 v130, 0x1000
	v_mov_b32_e32 v131, 0
	v_lshl_add_u64 v[186:187], v[0:1], 0, v[130:131]
	global_load_dwordx4 v[188:191], v[186:187], off
	global_load_dwordx4 v[192:195], v[186:187], off offset:2048
	global_load_dwordx4 v[196:199], v[186:187], off offset:64
	v_or_b32_e32 v92, 0x1000, v2
	v_mov_b32_e32 v93, v3
	v_or_b32_e32 v2, 0x1800, v2
	s_add_u32 s20, s67, s88
	v_lshlrev_b32_e32 v120, 2, v108
	s_addc_u32 s21, s68, 0
	v_cmp_gt_i32_e64 s[40:41], v120, v114
	s_add_u32 s48, s20, 0x1600
	s_mov_b32 s20, 12
	s_addc_u32 s49, s21, 0
	v_cmp_lt_i32_e64 s[42:43], v120, v114
	v_ashrrev_i32_e32 v121, 31, v120
	s_waitcnt vmcnt(0)
; __device__ __forceinline__ void ld8bf(const bf16_t* p, float (&o)[8]) { unpack8(*(const u32x4*)p, o); }
; __device__ __forceinline__ bf16x8 pack_frag(const float (&v)[8]) { return __builtin_bit_cast(bf16x8, pack8(v)); }
; template <int KIND>
; __device__ __forceinline__ void w_m3_core(const bf16x8 (&Qf)[4][2], const bf16x8 (&Kf)[4][2], const bf16x8 (&Sf)[4][2], const LAS bf16_t* vT, float lg,
;                                           const bf16_t* gsrc, const float* nw, bf16_t* ydst, int lo, int fq) {
;     ...
;                     s = __builtin_amdgcn_mfma_f32_16x16x32_bf16(Kf[mb][0], Qf[nb][0], s, 0, 0, 0); s = __builtin_amdgcn_mfma_f32_16x16x32_bf16(Kf[mb][1], Qf[nb][1], s, 0, 0, 0);
;     ...
;             const unsigned long long gw_ = *(const unsigned long long*)(gsrc + n * NIN + e0); const f32x4 w4 = *(const f32x4*)(nw + e0);
; __device__ __forceinline__ void w_hg_m3(const Args& a, int l, unsigned char* ws, const bf16_t* proj, bf16_t* y, LAS unsigned char* wl, int b, int ck_, int h, int lane) {
;     ...
; #pragma unroll
;     for (int kk = 0; kk < 2; ++kk)
; #pragma unroll
;         for (int eb = 0; eb < 4; ++eb) { float sv[8]; ld8bf(Sb + (16 * eb + lo) * 64 + 32 * kk + 8 * fq, sv);
; #pragma unroll
;             for (int j = 0; j < 8; ++j) sv[j] *= er[kk][j];
;             Sf[eb][kk] = pack_frag(sv); }
	v_mov_b64_e32 v[64:65], v[146:147]
	v_mov_b64_e32 v[66:67], v[148:149]
	v_lshlrev_b32_e32 v72, 16, v64
	v_and_b32_e32 v73, 0xffff0000, v64
	v_lshlrev_b32_e32 v64, 16, v65
	v_and_b32_e32 v65, 0xffff0000, v65
	v_pk_mul_f32 v[74:75], v[84:85], v[64:65]
	v_lshlrev_b32_e32 v64, 16, v66
	v_and_b32_e32 v65, 0xffff0000, v66
	v_pk_mul_f32 v[72:73], v[86:87], v[72:73]
	v_pk_mul_f32 v[76:77], v[82:83], v[64:65]
	v_lshlrev_b32_e32 v64, 16, v67
	v_and_b32_e32 v65, 0xffff0000, v67
	v_pk_mul_f32 v[78:79], v[80:81], v[64:65]
	v_cvt_pk_bf16_f32 v64, v72, v73
	v_cvt_pk_bf16_f32 v65, v74, v75
	v_mov_b64_e32 v[72:73], v[150:151]
	v_mov_b64_e32 v[74:75], v[152:153]
	v_cvt_pk_bf16_f32 v66, v76, v77
	v_cvt_pk_bf16_f32 v67, v78, v79
	s_waitcnt vmcnt(0)
	v_lshlrev_b32_e32 v76, 16, v72
	v_and_b32_e32 v77, 0xffff0000, v72
	v_lshlrev_b32_e32 v72, 16, v73
	v_and_b32_e32 v73, 0xffff0000, v73
	v_pk_mul_f32 v[78:79], v[84:85], v[72:73]
	v_lshlrev_b32_e32 v72, 16, v74
	v_and_b32_e32 v73, 0xffff0000, v74
	v_pk_mul_f32 v[76:77], v[86:87], v[76:77]
	v_pk_mul_f32 v[88:89], v[82:83], v[72:73]
	v_lshlrev_b32_e32 v72, 16, v75
	v_and_b32_e32 v73, 0xffff0000, v75
	v_pk_mul_f32 v[90:91], v[80:81], v[72:73]
	v_cvt_pk_bf16_f32 v72, v76, v77
	v_lshl_add_u64 v[76:77], v[94:95], 0, v[92:93]
	v_cvt_pk_bf16_f32 v73, v78, v79
	v_mov_b64_e32 v[76:77], v[188:189]
	v_mov_b64_e32 v[78:79], v[190:191]
	v_cvt_pk_bf16_f32 v74, v88, v89
	v_cvt_pk_bf16_f32 v75, v90, v91
	s_waitcnt vmcnt(0)
	v_lshlrev_b32_e32 v88, 16, v76
	v_and_b32_e32 v89, 0xffff0000, v76
	v_lshlrev_b32_e32 v76, 16, v77
	v_and_b32_e32 v77, 0xffff0000, v77
	v_pk_mul_f32 v[90:91], v[84:85], v[76:77]
	v_lshlrev_b32_e32 v76, 16, v78
	v_and_b32_e32 v77, 0xffff0000, v78
	v_pk_mul_f32 v[88:89], v[86:87], v[88:89]
	v_pk_mul_f32 v[96:97], v[82:83], v[76:77]
	v_lshlrev_b32_e32 v76, 16, v79
	v_and_b32_e32 v77, 0xffff0000, v79
	v_pk_mul_f32 v[98:99], v[80:81], v[76:77]
	v_cvt_pk_bf16_f32 v76, v88, v89
	v_lshl_add_u64 v[88:89], v[94:95], 0, v[2:3]
	v_cvt_pk_bf16_f32 v77, v90, v91
	v_mov_b64_e32 v[88:89], v[192:193]
	v_mov_b64_e32 v[90:91], v[194:195]
	v_cvt_pk_bf16_f32 v78, v96, v97
	v_cvt_pk_bf16_f32 v79, v98, v99
	v_mfma_f32_16x16x32_bf16 v[116:119], v[72:75], v[52:55], 0
	s_waitcnt vmcnt(0)
	v_lshlrev_b32_e32 v96, 16, v88
	v_and_b32_e32 v97, 0xffff0000, v88
	v_lshlrev_b32_e32 v88, 16, v89
	v_and_b32_e32 v89, 0xffff0000, v89
	v_pk_mul_f32 v[84:85], v[84:85], v[88:89]
	v_lshlrev_b32_e32 v88, 16, v90
	v_and_b32_e32 v89, 0xffff0000, v90
	v_pk_mul_f32 v[86:87], v[86:87], v[96:97]
	v_pk_mul_f32 v[82:83], v[82:83], v[88:89]
	v_lshlrev_b32_e32 v88, 16, v91
	v_and_b32_e32 v89, 0xffff0000, v91
	v_pk_mul_f32 v[88:89], v[80:81], v[88:89]
	v_cvt_pk_bf16_f32 v80, v86, v87
	v_cvt_pk_bf16_f32 v81, v84, v85
	v_mov_b64_e32 v[84:85], v[122:123]
	v_mov_b64_e32 v[86:87], v[124:125]
	v_cvt_pk_bf16_f32 v82, v82, v83
	v_cvt_pk_bf16_f32 v83, v88, v89
	v_lshl_add_u64 v[96:97], v[94:95], 0, 64
	v_mfma_f32_16x16x32_bf16 v[138:141], v[76:79], v[52:55], 0
	s_waitcnt vmcnt(0)
	v_lshlrev_b32_e32 v88, 16, v84
	v_and_b32_e32 v89, 0xffff0000, v84
	v_lshlrev_b32_e32 v84, 16, v85
	v_and_b32_e32 v85, 0xffff0000, v85
	v_pk_mul_f32 v[90:91], v[102:103], v[84:85]
	v_lshlrev_b32_e32 v84, 16, v86
	v_and_b32_e32 v85, 0xffff0000, v86
	v_pk_mul_f32 v[88:89], v[100:101], v[88:89]
	v_pk_mul_f32 v[94:95], v[104:105], v[84:85]
	v_lshlrev_b32_e32 v84, 16, v87
	v_and_b32_e32 v85, 0xffff0000, v87
	v_pk_mul_f32 v[98:99], v[106:107], v[84:85]
	v_cvt_pk_bf16_f32 v84, v88, v89
	v_cvt_pk_bf16_f32 v85, v90, v91
	v_mov_b64_e32 v[88:89], v[134:135]
	v_mov_b64_e32 v[90:91], v[136:137]
	v_cvt_pk_bf16_f32 v86, v94, v95
	v_cvt_pk_bf16_f32 v87, v98, v99
	s_waitcnt vmcnt(0)
	v_lshlrev_b32_e32 v0, 16, v88
	v_and_b32_e32 v1, 0xffff0000, v88
	v_lshlrev_b32_e32 v88, 16, v89
	v_and_b32_e32 v89, 0xffff0000, v89
	v_pk_mul_f32 v[94:95], v[102:103], v[88:89]
	v_lshlrev_b32_e32 v88, 16, v90
	v_and_b32_e32 v89, 0xffff0000, v90
	v_pk_mul_f32 v[0:1], v[100:101], v[0:1]
	v_pk_mul_f32 v[98:99], v[104:105], v[88:89]
	v_lshlrev_b32_e32 v88, 16, v91
	v_and_b32_e32 v89, 0xffff0000, v91
	v_pk_mul_f32 v[110:111], v[106:107], v[88:89]
	v_cvt_pk_bf16_f32 v88, v0, v1
	v_lshl_add_u64 v[0:1], v[96:97], 0, v[92:93]
	v_cvt_pk_bf16_f32 v89, v94, v95
	v_mov_b64_e32 v[92:93], v[196:197]
	v_mov_b64_e32 v[94:95], v[198:199]
	v_cvt_pk_bf16_f32 v90, v98, v99
	v_cvt_pk_bf16_f32 v91, v110, v111
	s_waitcnt vmcnt(0)
	v_lshlrev_b32_e32 v0, 16, v92
	v_and_b32_e32 v1, 0xffff0000, v92
	v_lshlrev_b32_e32 v92, 16, v93
	v_and_b32_e32 v93, 0xffff0000, v93
	v_pk_mul_f32 v[98:99], v[102:103], v[92:93]
	v_lshlrev_b32_e32 v92, 16, v94
	v_and_b32_e32 v93, 0xffff0000, v94
	v_pk_mul_f32 v[0:1], v[100:101], v[0:1]
	v_pk_mul_f32 v[110:111], v[104:105], v[92:93]
	v_lshlrev_b32_e32 v92, 16, v95
	v_and_b32_e32 v93, 0xffff0000, v95
	v_pk_mul_f32 v[112:113], v[106:107], v[92:93]
	v_cvt_pk_bf16_f32 v92, v0, v1
	v_lshl_add_u64 v[0:1], v[96:97], 0, v[2:3]
	v_cvt_pk_bf16_f32 v93, v98, v99
	global_load_dwordx4 v[96:99], v[0:1], off
	v_or_b32_e32 v2, 2, v120
	s_waitcnt lgkmcnt(0)
	s_ashr_i32 s21, s20, 31
	v_cmp_gt_i32_e64 s[38:39], v2, v114
	s_lshl_b64 s[20:21], s[20:21], 3
	s_add_u32 s20, s0, s20
	s_addc_u32 s21, s1, s21
	v_cvt_pk_bf16_f32 v94, v110, v111
	s_load_dwordx2 s[20:21], s[20:21], 0x0
	v_cvt_pk_bf16_f32 v95, v112, v113
	v_mfma_f32_16x16x32_bf16 v[142:145], v[88:91], v[60:63], v[116:119]
	s_lshl_b64 s[34:35], s[36:37], 2
	s_waitcnt lgkmcnt(0)
; __device__ __forceinline__ float bperm_f(int src_lane, float v) { return __builtin_bit_cast(float, __builtin_amdgcn_ds_bpermute(src_lane << 2, __builtin_bit_cast(int, v))); }
; template <int KIND>
; __device__ __forceinline__ void w_m3_core(const bf16x8 (&Qf)[4][2], const bf16x8 (&Kf)[4][2], const bf16x8 (&Sf)[4][2], const LAS bf16_t* vT, float lg,
;                                           const bf16_t* gsrc, const float* nw, bf16_t* ydst, int lo, int fq) {
;     ...
;             float pv[8];
; #pragma unroll
;             for (int hh = 0; hh < 2; ++hh) { const int mb = 2 * kk2 + hh;
;                 if (mb <= nb) { f32x4 s = {0.f, 0.f, 0.f, 0.f};
;                     s = __builtin_amdgcn_mfma_f32_16x16x32_bf16(Kf[mb][0], Qf[nb][0], s, 0, 0, 0); s = __builtin_amdgcn_mfma_f32_16x16x32_bf16(Kf[mb][1], Qf[nb][1], s, 0, 0, 0);
; #pragma unroll
;                     for (int r = 0; r < 4; ++r) { const int m = 16 * mb + 4 * fq + r, n = 16 * nb + lo; float v = s[r];
;                         if (KIND == 0) v *= __expf((float)(n - m) * lg);
;                         if (mb == nb) v = (m <= n) ? v : 0.f;
;                         pv[4 * hh + r] = v; }
;                 } else {
; #pragma unroll
;                     for (int r = 0; r < 4; ++r) pv[4 * hh + r] = 0.f; }
;             }
;             const bf16x8 Pf = pack_frag(pv);
; #pragma unroll
;             for (int eb = 0; eb < 4; ++eb)
;                 O[eb] = __builtin_amdgcn_mfma_f32_16x16x32_bf16(tr_frag(vT, 32 * kk2 + 4 * fq, 32 * kk2 + 16 + 4 * fq, 16 * eb, lo), Pf, O[eb], 0, 0, 0);
;         }
; #pragma unroll
;         for (int kk = 0; kk < 2; ++kk)
; #pragma unroll
;             for (int eb = 0; eb < 4; ++eb) O2[eb] = __builtin_amdgcn_mfma_f32_16x16x32_bf16(Sf[eb][kk], Qf[nb][kk], O2[eb], 0, 0, 0);
;         const float osc = KIND == 0 ? __expf((float)(16 * nb + lo + 1) * lg) : 1.0f;
; #pragma unroll
;         for (int eb = 0; eb < 4; ++eb) O[eb] = O[eb] + O2[eb] * osc;
;         float ss = 0.f;
; #pragma unroll
;         for (int eb = 0; eb < 4; ++eb) ss += (O[eb][0] * O[eb][0] + O[eb][1] * O[eb][1]) + (O[eb][2] * O[eb][2] + O[eb][3] * O[eb][3]);
;         { const int ln = (fq << 4) | lo; ss += bperm_f(ln ^ 16, ss); ss += bperm_f(ln ^ 32, ss); }
;         const float rs = rsqrtf(ss * (1.0f / 64.0f) + EPS);
	s_add_u32 s27, s20, s34
	v_mfma_f32_16x16x32_bf16 v[138:141], v[92:95], v[60:63], v[138:141]
	s_addc_u32 s35, s21, s35
	s_lshl_b64 s[20:21], s[24:25], 2
	s_add_u32 s34, s27, s20
	s_addc_u32 s35, s35, s21
	v_lshl_add_u64 v[186:187], v[120:121], 2, s[34:35]
	global_load_dwordx4 v[146:149], v[186:187], off
	global_load_dwordx4 v[150:153], v[186:187], off offset:64
	global_load_dwordx4 v[188:191], v[186:187], off offset:128
	global_load_dwordx4 v[192:195], v[186:187], off offset:192
	s_lshl_b64 s[20:21], s[86:87], 11
	s_add_u32 s20, s10, s20
	s_addc_u32 s21, s11, s21
	s_add_u32 s46, s20, s88
	s_addc_u32 s47, s21, 0
	s_waitcnt vmcnt(0)
	v_lshlrev_b32_e32 v0, 16, v96
	v_and_b32_e32 v1, 0xffff0000, v96
	v_lshlrev_b32_e32 v96, 16, v97
	v_and_b32_e32 v97, 0xffff0000, v97
	v_pk_mul_f32 v[0:1], v[100:101], v[0:1]
	v_pk_mul_f32 v[100:101], v[102:103], v[96:97]
	v_lshlrev_b32_e32 v96, 16, v98
	v_and_b32_e32 v97, 0xffff0000, v98
	v_pk_mul_f32 v[102:103], v[104:105], v[96:97]
	v_lshlrev_b32_e32 v96, 16, v99
	v_and_b32_e32 v97, 0xffff0000, v99
	v_pk_mul_f32 v[104:105], v[106:107], v[96:97]
	v_cvt_pk_bf16_f32 v97, v100, v101
	v_cvt_pk_bf16_f32 v98, v102, v103
	v_mfma_f32_16x16x32_bf16 v[100:103], v[20:23], v[52:55], 0
	v_cvt_pk_bf16_f32 v96, v0, v1
	v_lshrrev_b32_e32 v0, 2, v114
	v_lshlrev_b32_e32 v1, 3, v114
	v_mfma_f32_16x16x32_bf16 v[100:103], v[24:27], v[60:63], v[100:103]
	v_cvt_pk_bf16_f32 v99, v104, v105
	v_or_b32_e32 v104, v120, v0
	v_lshlrev_b32_e32 v0, 2, v114
	v_and_b32_e32 v105, 24, v1
	v_lshlrev_b32_e32 v1, 6, v108
	v_bitop3_b32 v130, v1, 64, v0 bitop3:0x36
	v_bitop3_b32 v129, v1, s96, v0 bitop3:0x36
	s_nop 0
	v_cndmask_b32_e64 v0, v100, 0, s[40:41]
	v_or_b32_e32 v100, 3, v120
	v_cmp_gt_i32_e32 vcc, v100, v114
	v_cndmask_b32_e64 v1, 0, v101, s[42:43]
	v_cndmask_b32_e64 v2, v102, 0, s[38:39]
	v_cndmask_b32_e64 v100, v103, 0, vcc
	v_cvt_pk_bf16_f32 v0, v0, v1
	v_cvt_pk_bf16_f32 v1, v2, v100
	v_mul_lo_u32 v100, v104, s23
	v_add3_u32 v131, s2, v105, v100
	ds_read_b64_tr_b16 v[102:103], v131 offset:2304
	ds_read_b64_tr_b16 v[100:101], v131
	ds_read_b64_tr_b16 v[104:105], v131 offset:32
	ds_read_b64_tr_b16 v[106:107], v131 offset:2336
	ds_read_b64_tr_b16 v[108:109], v131 offset:64
	ds_read_b64_tr_b16 v[110:111], v131 offset:2368
	v_mov_b32_e32 v2, v3
	s_waitcnt lgkmcnt(0)
	s_nop 0
	v_mfma_f32_16x16x32_bf16 v[122:125], v[108:111], v[0:3], 0
	ds_read_b64_tr_b16 v[108:109], v131 offset:96
	ds_read_b64_tr_b16 v[110:111], v131 offset:2400
	s_waitcnt lgkmcnt(0)
	v_mfma_f32_16x16x32_bf16 v[134:137], v[108:111], v[0:3], 0
	v_mfma_f32_16x16x32_bf16 v[108:111], v[64:67], v[52:55], 0
	v_mfma_f32_16x16x32_bf16 v[52:55], v[80:83], v[52:55], 0
	v_mfma_f32_16x16x32_bf16 v[100:103], v[100:103], v[0:3], 0
	v_mfma_f32_16x16x32_bf16 v[108:111], v[84:87], v[60:63], v[108:111]
	v_mfma_f32_16x16x32_bf16 v[104:107], v[104:107], v[0:3], 0
	v_mfma_f32_16x16x32_bf16 v[52:55], v[96:99], v[60:63], v[52:55]
	s_nop 5
	v_add_f32_e64 v116, v102, v110
	v_add_f32_e64 v117, v103, v111
	v_pk_add_f32 v[118:119], v[100:101], v[108:109]
	v_pk_add_f32 v[112:113], v[104:105], v[142:143]
	v_pk_add_f32 v[110:111], v[106:107], v[144:145]
	v_pk_add_f32 v[108:109], v[122:123], v[138:139]
	v_pk_add_f32 v[0:1], v[136:137], v[54:55]
	v_pk_add_f32 v[104:105], v[134:135], v[52:53]
	v_pk_mul_f32 v[52:53], v[116:117], v[116:117]
	v_pk_mul_f32 v[54:55], v[118:119], v[118:119]
	v_mul_f32_e32 v2, v104, v104
	v_pk_mov_b32 v[60:61], v[54:55], v[52:53] op_sel:[1,0]
	v_mov_b32_e32 v55, v53
	v_pk_add_f32 v[52:53], v[60:61], v[54:55]
	v_pk_mul_f32 v[54:55], v[110:111], v[110:111]
	v_pk_mul_f32 v[60:61], v[112:113], v[112:113]
	v_pk_add_f32 v[52:53], v[52:53], v[52:53] op_sel:[0,1] op_sel_hi:[1,0]
	v_pk_mov_b32 v[62:63], v[60:61], v[54:55] op_sel:[1,0]
	v_mov_b32_e32 v61, v55
	v_pk_add_f32 v[54:55], v[62:63], v[60:61]
	v_mul_f32_e32 v60, v105, v105
	v_pk_add_f32 v[54:55], v[54:55], v[54:55] op_sel:[0,1] op_sel_hi:[1,0]
	v_pk_add_f32 v[106:107], v[124:125], v[140:141]
	v_mov_b32_e32 v53, v2
	v_mov_b32_e32 v55, v60
	v_mul_f32_e32 v2, v109, v109
	v_mul_f32_e32 v61, v0, v0
	v_pk_add_f32 v[52:53], v[52:53], v[54:55]
	v_pk_fma_f32 v[54:55], v[108:109], v[108:109], v[2:3] op_sel_hi:[1,1,0]
	v_mul_f32_e32 v2, v107, v107
	v_mul_f32_e32 v62, v1, v1
	v_mov_b32_e32 v55, v61
	v_pk_fma_f32 v[60:61], v[106:107], v[106:107], v[2:3] op_sel_hi:[1,1,0]
	v_mov_b64_e32 v[100:101], s[48:49]
	v_mov_b32_e32 v61, v62
	v_pk_add_f32 v[54:55], v[54:55], v[60:61]
	v_lshlrev_b64 v[62:63], 1, v[120:121]
	v_pk_add_f32 v[52:53], v[52:53], v[54:55]
	v_lshl_add_u64 v[60:61], v[120:121], 2, s[34:35]
	v_add_f32_e32 v2, v52, v53
	ds_bpermute_b32 v52, v130, v2
	s_waitcnt lgkmcnt(0)
	v_add_f32_e32 v2, v2, v52
	ds_bpermute_b32 v52, v129, v2
	s_waitcnt lgkmcnt(0)
	v_add_f32_e32 v2, v2, v52
	v_fmamk_f32 v2, v2, 0x3c800000, v200
	v_cmp_gt_f32_e64 s[44:45], s29, v2
	v_mul_f32_e32 v52, 0x4b800000, v2
	s_nop 0
	v_cndmask_b32_e64 v2, v2, v52, s[44:45]
	v_rsq_f32_e32 v2, v2
	s_nop 0
	v_mul_f32_e32 v52, 0x45800000, v2
	v_cndmask_b32_e64 v102, v2, v52, s[44:45]
	v_mad_u64_u32 v[52:53], s[20:21], v114, s72, v[100:101]
	v_lshlrev_b32_e32 v2, 11, v114
	v_lshl_add_u64 v[114:115], v[52:53], 0, v[62:63]
	v_mov_b64_e32 v[124:125], v[222:223]
	v_mov_b64_e32 v[52:53], v[146:147]
	v_mov_b64_e32 v[54:55], v[148:149]
	v_lshl_add_u64 v[122:123], s[46:47], 0, v[2:3]
	v_pk_mul_f32 v[118:119], v[118:119], v[102:103] op_sel_hi:[1,0]
	v_pk_mul_f32 v[116:117], v[116:117], v[102:103] op_sel_hi:[1,0]
	v_pk_mul_f32 v[112:113], v[112:113], v[102:103] op_sel_hi:[1,0]
	v_pk_mul_f32 v[110:111], v[110:111], v[102:103] op_sel_hi:[1,0]
	s_waitcnt lgkmcnt(0)
; __device__ __forceinline__ unsigned pk2(float lo, float hi) { const f32x2_t v = {lo, hi}; const bf16x2_t b = __builtin_convertvector(v, bf16x2_t); return __builtin_bit_cast(unsigned, b); }
; __device__ __forceinline__ float sigmoidf_(float x) { return __builtin_amdgcn_rcpf(1.0f + __expf(-x)); }
; template <int KIND>
; __device__ __forceinline__ void w_m3_core(const bf16x8 (&Qf)[4][2], const bf16x8 (&Kf)[4][2], const bf16x8 (&Sf)[4][2], const LAS bf16_t* vT, float lg,
;                                           const bf16_t* gsrc, const float* nw, bf16_t* ydst, int lo, int fq) {
;     ...
;         const size_t n = 16 * nb + lo;
; #pragma unroll
;         for (int eb = 0; eb < 4; ++eb) { const int e0 = 16 * eb + 4 * fq;
;             const unsigned long long gw_ = *(const unsigned long long*)(gsrc + n * NIN + e0); const f32x4 w4 = *(const f32x4*)(nw + e0);
;             const float g0 = __uint_as_float((unsigned)gw_ << 16), g1 = __uint_as_float((unsigned)gw_ & 0xffff0000u), g2 = __uint_as_float((unsigned)(gw_ >> 32) << 16), g3 = __uint_as_float((unsigned)(gw_ >> 32) & 0xffff0000u);
;             const float o0 = O[eb][0] * rs * w4[0] * (g0 * sigmoidf_(g0)), o1 = O[eb][1] * rs * w4[1] * (g1 * sigmoidf_(g1));
;             const float o2 = O[eb][2] * rs * w4[2] * (g2 * sigmoidf_(g2)), o3 = O[eb][3] * rs * w4[3] * (g3 * sigmoidf_(g3));
;             *(unsigned long long*)(ydst + n * DM + e0) = (unsigned long long)pk2(o0, o1) | ((unsigned long long)pk2(o2, o3) << 32); }
	v_lshlrev_b32_e32 v120, 16, v124
	v_mul_f32_e32 v2, 0xbfb8aa3b, v120
	v_exp_f32_e32 v2, v2
	v_and_b32_e32 v121, 0xffff0000, v124
	v_lshlrev_b32_e32 v124, 16, v125
	v_and_b32_e32 v125, 0xffff0000, v125
	v_add_f32_e32 v2, 1.0, v2
	v_rcp_f32_e32 v134, v2
	v_mul_f32_e32 v2, 0xbfb8aa3b, v121
	v_exp_f32_e32 v2, v2
	v_pk_mul_f32 v[52:53], v[52:53], v[118:119]
	v_pk_mul_f32 v[54:55], v[54:55], v[116:117]
	v_add_f32_e32 v2, 1.0, v2
	v_rcp_f32_e32 v135, v2
	v_mul_f32_e32 v2, 0xbfb8aa3b, v124
	v_exp_f32_e32 v2, v2
	v_pk_mul_f32 v[118:119], v[134:135], v[120:121]
	s_nop 0
	v_pk_mul_f32 v[52:53], v[118:119], v[52:53]
	v_add_f32_e32 v2, 1.0, v2
	v_rcp_f32_e32 v118, v2
	v_mul_f32_e32 v2, 0xbfb8aa3b, v125
	v_exp_f32_e32 v2, v2
	s_nop 0
	v_add_f32_e32 v2, 1.0, v2
	v_rcp_f32_e32 v119, v2
	s_nop 0
	v_pk_mul_f32 v[116:117], v[118:119], v[124:125]
	s_nop 0
	v_pk_mul_f32 v[54:55], v[116:117], v[54:55]
	v_cvt_pk_bf16_f32 v116, v52, v53
	v_cvt_pk_bf16_f32 v117, v54, v55
	v_lshl_add_u64 v[52:53], v[122:123], 0, v[62:63]
	v_and_b32_e32 v142, 16, v132
	v_lshrrev_b32_e32 v143, 1, v142
	v_add_u32_e32 v142, v142, v143
	v_mov_b32_e32 v143, 0
	v_lshl_add_u64 v[52:53], v[52:53], 0, v[142:143]
	v_mov_b64_e32 v[196:197], v[116:117]
	v_mov_b64_e32 v[54:55], v[224:225]
	s_nop 0
	v_mov_b64_e32 v[116:117], v[150:151]
	v_mov_b64_e32 v[118:119], v[152:153]
	s_waitcnt lgkmcnt(0)
	v_lshlrev_b32_e32 v120, 16, v54
	v_mul_f32_e32 v2, 0xbfb8aa3b, v120
	v_exp_f32_e32 v2, v2
	v_and_b32_e32 v121, 0xffff0000, v54
	v_lshlrev_b32_e32 v54, 16, v55
	v_and_b32_e32 v55, 0xffff0000, v55
	v_add_f32_e32 v2, 1.0, v2
	v_rcp_f32_e32 v122, v2
	v_mul_f32_e32 v2, 0xbfb8aa3b, v121
	v_exp_f32_e32 v2, v2
	v_pk_mul_f32 v[112:113], v[116:117], v[112:113]
	v_pk_mul_f32 v[110:111], v[118:119], v[110:111]
	v_mul_f32_e32 v118, v109, v102
	v_add_f32_e32 v2, 1.0, v2
	v_rcp_f32_e32 v123, v2
	v_mul_f32_e32 v2, 0xbfb8aa3b, v54
	v_exp_f32_e32 v2, v2
	v_pk_mul_f32 v[116:117], v[122:123], v[120:121]
	s_nop 0
	v_pk_mul_f32 v[112:113], v[116:117], v[112:113]
	v_add_f32_e32 v2, 1.0, v2
	v_rcp_f32_e32 v116, v2
	v_mul_f32_e32 v2, 0xbfb8aa3b, v55
	v_exp_f32_e32 v2, v2
	v_mul_f32_e32 v120, v106, v102
	v_add_f32_e32 v2, 1.0, v2
	v_rcp_f32_e32 v117, v2
	s_nop 0
	v_pk_mul_f32 v[54:55], v[116:117], v[54:55]
	s_nop 0
	v_pk_mul_f32 v[54:55], v[54:55], v[110:111]
	v_cvt_pk_bf16_f32 v110, v112, v113
	v_cvt_pk_bf16_f32 v111, v54, v55
	v_mov_b64_e32 v[198:199], v[110:111]
	s_nop 1
	v_permlane16_swap_b32_e32 v196, v198
	v_permlane16_swap_b32_e32 v197, v199
	global_store_dwordx4 v[52:53], v[196:199], off offset:1536
	v_mov_b64_e32 v[54:55], v[226:227]
	s_nop 0
	v_mov_b64_e32 v[110:111], v[188:189]
	v_mov_b64_e32 v[112:113], v[190:191]
	v_mul_f32_e32 v116, v108, v102
	s_waitcnt lgkmcnt(0)
	v_lshlrev_b32_e32 v117, 16, v54
	v_mul_f32_e32 v2, 0xbfb8aa3b, v117
	v_exp_f32_e32 v2, v2
	v_and_b32_e32 v119, 0xffff0000, v54
	v_lshlrev_b32_e32 v121, 16, v55
	v_and_b32_e32 v55, 0xffff0000, v55
	v_add_f32_e32 v2, 1.0, v2
	v_rcp_f32_e32 v123, v2
	v_mul_f32_e32 v2, 0xbfb8aa3b, v119
	v_exp_f32_e32 v2, v2
	v_mov_b32_e32 v108, v111
	v_mul_f32_e32 v54, v107, v102
	v_mov_b32_e32 v122, v110
	v_add_f32_e32 v2, 1.0, v2
	v_rcp_f32_e32 v109, v2
	v_mul_f32_e32 v2, 0xbfb8aa3b, v121
	v_exp_f32_e32 v2, v2
	v_pk_mul_f32 v[116:117], v[122:123], v[116:117]
	v_pk_mul_f32 v[108:109], v[108:109], v[118:119]
	v_mov_b32_e32 v110, v112
	v_add_f32_e32 v2, 1.0, v2
	v_rcp_f32_e32 v111, v2
	v_mul_f32_e32 v2, 0xbfb8aa3b, v55
	v_exp_f32_e32 v2, v2
	v_mov_b32_e32 v106, v113
	v_pk_mul_f32 v[110:111], v[110:111], v[120:121]
	v_mul_f32_e32 v112, v105, v102
	v_add_f32_e32 v2, 1.0, v2
	v_rcp_f32_e32 v107, v2
	s_nop 0
	v_pk_mul_f32 v[54:55], v[106:107], v[54:55]
	v_mov_b32_e32 v106, v116
	v_mov_b32_e32 v107, v108
	v_mov_b32_e32 v108, v117
	v_pk_mul_f32 v[106:107], v[106:107], v[108:109]
	v_mov_b32_e32 v108, v110
	v_mov_b32_e32 v109, v54
	v_mov_b32_e32 v54, v111
	v_pk_mul_f32 v[54:55], v[108:109], v[54:55]
	v_cvt_pk_bf16_f32 v106, v106, v107
	v_cvt_pk_bf16_f32 v107, v54, v55
	v_mov_b64_e32 v[196:197], v[106:107]
	v_mov_b64_e32 v[54:55], v[228:229]
	s_nop 0
	v_mov_b64_e32 v[106:107], v[192:193]
	v_mov_b64_e32 v[108:109], v[194:195]
	v_mul_f32_e32 v114, v0, v102
	v_mul_f32_e32 v110, v104, v102
	s_waitcnt lgkmcnt(0)
	v_lshlrev_b32_e32 v111, 16, v54
	v_lshlrev_b32_e32 v115, 16, v55
	v_mul_f32_e32 v2, 0xbfb8aa3b, v111
	v_mul_f32_e32 v0, 0xbfb8aa3b, v115
	v_exp_f32_e32 v2, v2
	v_exp_f32_e32 v0, v0
	v_and_b32_e32 v113, 0xffff0000, v54
	v_and_b32_e32 v55, 0xffff0000, v55
	v_add_f32_e32 v2, 1.0, v2
	v_add_f32_e32 v0, 1.0, v0
	v_rcp_f32_e32 v117, v2
	v_mul_f32_e32 v2, 0xbfb8aa3b, v113
	v_mov_b32_e32 v104, v107
	v_rcp_f32_e32 v107, v0
	v_mul_f32_e32 v0, 0xbfb8aa3b, v55
	v_exp_f32_e32 v2, v2
	v_exp_f32_e32 v0, v0
	v_mul_f32_e32 v54, v1, v102
	v_mov_b32_e32 v116, v106
	v_add_f32_e32 v2, 1.0, v2
	v_add_f32_e32 v0, 1.0, v0
	v_rcp_f32_e32 v105, v2
	v_rcp_f32_e32 v1, v0
	v_mov_b32_e32 v106, v108
	v_mov_b32_e32 v0, v109
	v_pk_mul_f32 v[110:111], v[116:117], v[110:111]
	v_pk_mul_f32 v[104:105], v[104:105], v[112:113]
	v_pk_mul_f32 v[106:107], v[106:107], v[114:115]
	v_pk_mul_f32 v[0:1], v[0:1], v[54:55]
	v_mov_b32_e32 v54, v110
	v_mov_b32_e32 v55, v104
	v_mov_b32_e32 v104, v111
	v_mov_b32_e32 v102, v106
	v_mov_b32_e32 v103, v0
	v_mov_b32_e32 v0, v107
	v_pk_mul_f32 v[54:55], v[54:55], v[104:105]
	v_pk_mul_f32 v[0:1], v[102:103], v[0:1]
	v_cvt_pk_bf16_f32 v54, v54, v55
	v_cvt_pk_bf16_f32 v55, v0, v1
	v_mov_b64_e32 v[198:199], v[54:55]
	s_nop 1
	v_permlane16_swap_b32_e32 v196, v198
	v_permlane16_swap_b32_e32 v197, v199
	global_store_dwordx4 v[52:53], v[196:199], off offset:1600
	v_mfma_f32_16x16x32_bf16 v[102:105], v[16:19], v[44:47], 0
	v_mfma_f32_16x16x32_bf16 v[52:55], v[20:23], v[44:47], 0
	v_mfma_f32_16x16x32_bf16 v[102:105], v[32:35], v[48:51], v[102:105]
	v_mfma_f32_16x16x32_bf16 v[52:55], v[24:27], v[48:51], v[52:55]
	v_mfma_f32_16x16x32_bf16 v[134:137], v[76:79], v[44:47], 0
	s_nop 5
	v_cndmask_b32_e64 v0, v102, 0, s[40:41]
	v_cndmask_b32_e64 v2, v104, 0, s[38:39]
	v_cndmask_b32_e64 v102, v105, 0, vcc
	v_cndmask_b32_e64 v1, 0, v103, s[42:43]
	v_cvt_pk_bf16_f32 v52, v52, v53
	v_cvt_pk_bf16_f32 v53, v54, v55
	v_cvt_pk_bf16_f32 v55, v2, v102
	ds_read_b64_tr_b16 v[104:105], v131 offset:2304
	ds_read_b64_tr_b16 v[102:103], v131
	ds_read_b64_tr_b16 v[106:107], v131 offset:32
	ds_read_b64_tr_b16 v[108:109], v131 offset:2336
	v_cvt_pk_bf16_f32 v54, v0, v1
	v_mfma_f32_16x16x32_bf16 v[134:137], v[92:95], v[48:51], v[134:137]
	s_waitcnt lgkmcnt(0)
; template <int KIND>
; __device__ __forceinline__ void w_m3_core(const bf16x8 (&Qf)[4][2], const bf16x8 (&Kf)[4][2], const bf16x8 (&Sf)[4][2], const LAS bf16_t* vT, float lg,
;                                           const bf16_t* gsrc, const float* nw, bf16_t* ydst, int lo, int fq) {
;     ...
;             float pv[8];
; #pragma unroll
;             for (int hh = 0; hh < 2; ++hh) { const int mb = 2 * kk2 + hh;
;                 if (mb <= nb) { f32x4 s = {0.f, 0.f, 0.f, 0.f};
;                     s = __builtin_amdgcn_mfma_f32_16x16x32_bf16(Kf[mb][0], Qf[nb][0], s, 0, 0, 0); s = __builtin_amdgcn_mfma_f32_16x16x32_bf16(Kf[mb][1], Qf[nb][1], s, 0, 0, 0);
; #pragma unroll
;                     for (int r = 0; r < 4; ++r) { const int m = 16 * mb + 4 * fq + r, n = 16 * nb + lo; float v = s[r];
;                         if (KIND == 0) v *= __expf((float)(n - m) * lg);
;                         if (mb == nb) v = (m <= n) ? v : 0.f;
;                         pv[4 * hh + r] = v; }
;                 } else {
; #pragma unroll
;                     for (int r = 0; r < 4; ++r) pv[4 * hh + r] = 0.f; }
;             }
;             const bf16x8 Pf = pack_frag(pv);
; #pragma unroll
;             for (int eb = 0; eb < 4; ++eb)
;                 O[eb] = __builtin_amdgcn_mfma_f32_16x16x32_bf16(tr_frag(vT, 32 * kk2 + 4 * fq, 32 * kk2 + 16 + 4 * fq, 16 * eb, lo), Pf, O[eb], 0, 0, 0);
;         }
; #pragma unroll
;         for (int kk = 0; kk < 2; ++kk)
; #pragma unroll
;             for (int eb = 0; eb < 4; ++eb) O2[eb] = __builtin_amdgcn_mfma_f32_16x16x32_bf16(Sf[eb][kk], Qf[nb][kk], O2[eb], 0, 0, 0);
;         const float osc = KIND == 0 ? __expf((float)(16 * nb + lo + 1) * lg) : 1.0f;
; #pragma unroll
;         for (int eb = 0; eb < 4; ++eb) O[eb] = O[eb] + O2[eb] * osc;
;         float ss = 0.f;
; #pragma unroll
;         for (int eb = 0; eb < 4; ++eb) ss += (O[eb][0] * O[eb][0] + O[eb][1] * O[eb][1]) + (O[eb][2] * O[eb][2] + O[eb][3] * O[eb][3]);
;         { const int ln = (fq << 4) | lo; ss += bperm_f(ln ^ 16, ss); ss += bperm_f(ln ^ 32, ss); }
;         const float rs = rsqrtf(ss * (1.0f / 64.0f) + EPS);
;         const size_t n = 16 * nb + lo;
; #pragma unroll
;         for (int eb = 0; eb < 4; ++eb) { const int e0 = 16 * eb + 4 * fq;
;             const unsigned long long gw_ = *(const unsigned long long*)(gsrc + n * NIN + e0); const f32x4 w4 = *(const f32x4*)(nw + e0);
	v_mfma_f32_16x16x32_bf16 v[112:115], v[106:109], v[52:55], 0
	ds_read_b64_tr_b16 v[106:107], v131 offset:64
	ds_read_b64_tr_b16 v[108:109], v131 offset:2368
	s_waitcnt lgkmcnt(0)
	v_mfma_f32_16x16x32_bf16 v[116:119], v[106:109], v[52:55], 0
	ds_read_b64_tr_b16 v[106:107], v131 offset:96
	ds_read_b64_tr_b16 v[108:109], v131 offset:2400
	v_mfma_f32_16x16x32_bf16 v[102:105], v[102:105], v[52:55], 0
	s_waitcnt lgkmcnt(0)
	v_mfma_f32_16x16x32_bf16 v[120:123], v[106:109], v[52:55], 0
	v_mfma_f32_16x16x32_bf16 v[52:55], v[64:67], v[44:47], 0
	v_mfma_f32_16x16x32_bf16 v[106:109], v[72:75], v[44:47], 0
	v_mfma_f32_16x16x32_bf16 v[44:47], v[80:83], v[44:47], 0
	v_mfma_f32_16x16x32_bf16 v[52:55], v[84:87], v[48:51], v[52:55]
	v_mfma_f32_16x16x32_bf16 v[44:47], v[96:99], v[48:51], v[44:47]
	v_mfma_f32_16x16x32_bf16 v[138:141], v[88:91], v[48:51], v[106:109]
	s_nop 5
	v_add_f32_e64 v110, v102, v52
	v_add_f32_e64 v111, v103, v53
	v_pk_add_f32 v[0:1], v[122:123], v[46:47]
	v_pk_add_f32 v[50:51], v[120:121], v[44:45]
	v_pk_add_f32 v[108:109], v[104:105], v[54:55]
	v_pk_mul_f32 v[46:47], v[110:111], v[110:111]
	v_pk_mul_f32 v[44:45], v[108:109], v[108:109]
	v_pk_add_f32 v[104:105], v[114:115], v[140:141]
	v_pk_add_f32 v[106:107], v[112:113], v[138:139]
	v_pk_mov_b32 v[48:49], v[46:47], v[44:45] op_sel:[1,0]
	v_mov_b32_e32 v47, v45
	v_pk_add_f32 v[44:45], v[48:49], v[46:47]
	v_pk_mul_f32 v[46:47], v[104:105], v[104:105]
	v_pk_mul_f32 v[48:49], v[106:107], v[106:107]
	v_pk_add_f32 v[54:55], v[116:117], v[134:135]
	v_pk_mov_b32 v[102:103], v[48:49], v[46:47] op_sel:[1,0]
	v_mov_b32_e32 v49, v47
	v_pk_add_f32 v[46:47], v[102:103], v[48:49]
	v_mul_f32_e32 v2, v50, v50
	v_mul_f32_e32 v48, v51, v51
	v_pk_add_f32 v[44:45], v[44:45], v[44:45] op_sel:[0,1] op_sel_hi:[1,0]
	v_pk_add_f32 v[46:47], v[46:47], v[46:47] op_sel:[0,1] op_sel_hi:[1,0]
	v_pk_add_f32 v[52:53], v[118:119], v[136:137]
	v_mov_b32_e32 v45, v2
	v_mov_b32_e32 v47, v48
	v_mul_f32_e32 v2, v55, v55
	v_mul_f32_e32 v49, v0, v0
	v_pk_add_f32 v[44:45], v[44:45], v[46:47]
	v_pk_fma_f32 v[46:47], v[54:55], v[54:55], v[2:3] op_sel_hi:[1,1,0]
	v_mul_f32_e32 v2, v53, v53
	v_mul_f32_e32 v102, v1, v1
	v_mov_b32_e32 v47, v49
	v_pk_fma_f32 v[48:49], v[52:53], v[52:53], v[2:3] op_sel_hi:[1,1,0]
	s_nop 0
	v_mov_b32_e32 v49, v102
	v_pk_add_f32 v[46:47], v[46:47], v[48:49]
	s_nop 0
	v_pk_add_f32 v[44:45], v[44:45], v[46:47]
	s_nop 0
	v_add_f32_e32 v2, v44, v45
	ds_bpermute_b32 v44, v130, v2
	s_waitcnt lgkmcnt(0)
	v_add_f32_e32 v2, v2, v44
	ds_bpermute_b32 v44, v129, v2
	s_waitcnt lgkmcnt(0)
	v_add_f32_e32 v2, v2, v44
	v_fmamk_f32 v2, v2, 0x3c800000, v200
	v_cmp_gt_f32_e64 s[44:45], s29, v2
	v_mul_f32_e32 v44, 0x4b800000, v2
	s_nop 0
	v_cndmask_b32_e64 v2, v2, v44, s[44:45]
	v_rsq_f32_e32 v2, v2
	s_nop 0
	v_mul_f32_e32 v44, 0x45800000, v2
	v_cndmask_b32_e64 v48, v2, v44, s[44:45]
	v_mad_u64_u32 v[44:45], s[20:21], v128, s72, v[100:101]
	v_lshl_add_u64 v[102:103], v[44:45], 0, v[62:63]
	v_mov_b64_e32 v[114:115], v[230:231]
	v_mov_b64_e32 v[44:45], v[146:147]
	v_mov_b64_e32 v[46:47], v[148:149]
	v_lshlrev_b32_e32 v2, 11, v128
	v_lshl_add_u64 v[112:113], s[46:47], 0, v[2:3]
	v_pk_mul_f32 v[110:111], v[110:111], v[48:49] op_sel_hi:[1,0]
	v_pk_mul_f32 v[108:109], v[108:109], v[48:49] op_sel_hi:[1,0]
	v_pk_mul_f32 v[106:107], v[106:107], v[48:49] op_sel_hi:[1,0]
	v_pk_mul_f32 v[104:105], v[104:105], v[48:49] op_sel_hi:[1,0]
	s_waitcnt lgkmcnt(0)
	v_lshlrev_b32_e32 v116, 16, v114
	v_mul_f32_e32 v2, 0xbfb8aa3b, v116
	v_exp_f32_e32 v2, v2
	v_and_b32_e32 v117, 0xffff0000, v114
	v_lshlrev_b32_e32 v114, 16, v115
	v_and_b32_e32 v115, 0xffff0000, v115
	v_add_f32_e32 v2, 1.0, v2
	v_rcp_f32_e32 v118, v2
	v_mul_f32_e32 v2, 0xbfb8aa3b, v117
	v_exp_f32_e32 v2, v2
	v_pk_mul_f32 v[44:45], v[44:45], v[110:111]
	v_pk_mul_f32 v[46:47], v[46:47], v[108:109]
	v_add_f32_e32 v2, 1.0, v2
	v_rcp_f32_e32 v119, v2
	v_mul_f32_e32 v2, 0xbfb8aa3b, v114
	v_exp_f32_e32 v2, v2
	v_pk_mul_f32 v[110:111], v[118:119], v[116:117]
	s_nop 0
	v_pk_mul_f32 v[44:45], v[110:111], v[44:45]
	v_add_f32_e32 v2, 1.0, v2
	v_rcp_f32_e32 v110, v2
	v_mul_f32_e32 v2, 0xbfb8aa3b, v115
	v_exp_f32_e32 v2, v2
	s_nop 0
	v_add_f32_e32 v2, 1.0, v2
	v_rcp_f32_e32 v111, v2
	s_nop 0
	v_pk_mul_f32 v[108:109], v[110:111], v[114:115]
	s_nop 0
	v_pk_mul_f32 v[46:47], v[108:109], v[46:47]
	v_cvt_pk_bf16_f32 v108, v44, v45
	v_cvt_pk_bf16_f32 v109, v46, v47
	v_lshl_add_u64 v[44:45], v[112:113], 0, v[62:63]
	v_lshl_add_u64 v[44:45], v[44:45], 0, v[142:143]
	v_mov_b64_e32 v[196:197], v[108:109]
	v_mov_b64_e32 v[46:47], v[232:233]
	s_nop 0
	v_mov_b64_e32 v[108:109], v[150:151]
	v_mov_b64_e32 v[110:111], v[152:153]
	s_waitcnt lgkmcnt(0)
	v_lshlrev_b32_e32 v112, 16, v46
	v_mul_f32_e32 v2, 0xbfb8aa3b, v112
	v_exp_f32_e32 v2, v2
	v_and_b32_e32 v113, 0xffff0000, v46
	v_lshlrev_b32_e32 v46, 16, v47
	v_and_b32_e32 v47, 0xffff0000, v47
	v_add_f32_e32 v2, 1.0, v2
	v_rcp_f32_e32 v114, v2
	v_mul_f32_e32 v2, 0xbfb8aa3b, v113
	v_exp_f32_e32 v2, v2
	v_pk_mul_f32 v[106:107], v[108:109], v[106:107]
	v_pk_mul_f32 v[104:105], v[110:111], v[104:105]
	v_mul_f32_e32 v110, v55, v48
	v_add_f32_e32 v2, 1.0, v2
	v_rcp_f32_e32 v115, v2
	v_mul_f32_e32 v2, 0xbfb8aa3b, v46
	v_exp_f32_e32 v2, v2
	v_pk_mul_f32 v[108:109], v[114:115], v[112:113]
	s_nop 0
	v_pk_mul_f32 v[106:107], v[108:109], v[106:107]
	v_add_f32_e32 v2, 1.0, v2
	v_rcp_f32_e32 v108, v2
	v_mul_f32_e32 v2, 0xbfb8aa3b, v47
	v_exp_f32_e32 v2, v2
	v_mul_f32_e32 v112, v52, v48
	v_add_f32_e32 v2, 1.0, v2
	v_rcp_f32_e32 v109, v2
	s_nop 0
	v_pk_mul_f32 v[46:47], v[108:109], v[46:47]
	s_nop 0
	v_pk_mul_f32 v[46:47], v[46:47], v[104:105]
	v_cvt_pk_bf16_f32 v104, v106, v107
	v_cvt_pk_bf16_f32 v105, v46, v47
	v_mov_b64_e32 v[198:199], v[104:105]
	s_nop 1
	v_permlane16_swap_b32_e32 v196, v198
	v_permlane16_swap_b32_e32 v197, v199
	global_store_dwordx4 v[44:45], v[196:199], off offset:1536
	v_mov_b64_e32 v[46:47], v[234:235]
	s_nop 0
	v_mov_b64_e32 v[104:105], v[188:189]
	v_mov_b64_e32 v[106:107], v[190:191]
	v_mul_f32_e32 v108, v54, v48
	s_waitcnt lgkmcnt(0)
; template <int KIND>
; __device__ __forceinline__ void w_m3_core(const bf16x8 (&Qf)[4][2], const bf16x8 (&Kf)[4][2], const bf16x8 (&Sf)[4][2], const LAS bf16_t* vT, float lg,
;                                           const bf16_t* gsrc, const float* nw, bf16_t* ydst, int lo, int fq) {
;     ...
; #pragma unroll
;         for (int kk2 = 0; kk2 < 2; ++kk2) {
;             if (2 * kk2 > nb) continue;
;             float pv[8];
; #pragma unroll
;             for (int hh = 0; hh < 2; ++hh) { const int mb = 2 * kk2 + hh;
;                 if (mb <= nb) { f32x4 s = {0.f, 0.f, 0.f, 0.f};
;                     s = __builtin_amdgcn_mfma_f32_16x16x32_bf16(Kf[mb][0], Qf[nb][0], s, 0, 0, 0); s = __builtin_amdgcn_mfma_f32_16x16x32_bf16(Kf[mb][1], Qf[nb][1], s, 0, 0, 0);
; #pragma unroll
;                     for (int r = 0; r < 4; ++r) { const int m = 16 * mb + 4 * fq + r, n = 16 * nb + lo; float v = s[r];
;                         if (KIND == 0) v *= __expf((float)(n - m) * lg);
;                         if (mb == nb) v = (m <= n) ? v : 0.f;
;                         pv[4 * hh + r] = v; }
;                 } else {
; #pragma unroll
;                     for (int r = 0; r < 4; ++r) pv[4 * hh + r] = 0.f; }
;             }
;             const bf16x8 Pf = pack_frag(pv);
; #pragma unroll
;             for (int eb = 0; eb < 4; ++eb)
;                 O[eb] = __builtin_amdgcn_mfma_f32_16x16x32_bf16(tr_frag(vT, 32 * kk2 + 4 * fq, 32 * kk2 + 16 + 4 * fq, 16 * eb, lo), Pf, O[eb], 0, 0, 0);
;     ...
;         for (int eb = 0; eb < 4; ++eb) { const int e0 = 16 * eb + 4 * fq;
;             const unsigned long long gw_ = *(const unsigned long long*)(gsrc + n * NIN + e0); const f32x4 w4 = *(const f32x4*)(nw + e0);
;             const float g0 = __uint_as_float((unsigned)gw_ << 16), g1 = __uint_as_float((unsigned)gw_ & 0xffff0000u), g2 = __uint_as_float((unsigned)(gw_ >> 32) << 16), g3 = __uint_as_float((unsigned)(gw_ >> 32) & 0xffff0000u);
;             const float o0 = O[eb][0] * rs * w4[0] * (g0 * sigmoidf_(g0)), o1 = O[eb][1] * rs * w4[1] * (g1 * sigmoidf_(g1));
;             const float o2 = O[eb][2] * rs * w4[2] * (g2 * sigmoidf_(g2)), o3 = O[eb][3] * rs * w4[3] * (g3 * sigmoidf_(g3));
;             *(unsigned long long*)(ydst + n * DM + e0) = (unsigned long long)pk2(o0, o1) | ((unsigned long long)pk2(o2, o3) << 32); }
	v_lshlrev_b32_e32 v109, 16, v46
	v_mul_f32_e32 v2, 0xbfb8aa3b, v109
	v_exp_f32_e32 v2, v2
	v_and_b32_e32 v111, 0xffff0000, v46
	v_lshlrev_b32_e32 v113, 16, v47
	v_and_b32_e32 v47, 0xffff0000, v47
	v_add_f32_e32 v2, 1.0, v2
	v_rcp_f32_e32 v115, v2
	v_mul_f32_e32 v2, 0xbfb8aa3b, v111
	v_exp_f32_e32 v2, v2
	v_mov_b32_e32 v54, v105
	v_mul_f32_e32 v46, v53, v48
	v_mov_b32_e32 v114, v104
	v_add_f32_e32 v2, 1.0, v2
	v_rcp_f32_e32 v55, v2
	v_mul_f32_e32 v2, 0xbfb8aa3b, v113
	v_exp_f32_e32 v2, v2
	v_pk_mul_f32 v[108:109], v[114:115], v[108:109]
	v_pk_mul_f32 v[54:55], v[54:55], v[110:111]
	v_mov_b32_e32 v104, v106
	v_add_f32_e32 v2, 1.0, v2
	v_rcp_f32_e32 v105, v2
	v_mul_f32_e32 v2, 0xbfb8aa3b, v47
	v_exp_f32_e32 v2, v2
	v_mov_b32_e32 v52, v107
	v_pk_mul_f32 v[104:105], v[104:105], v[112:113]
	v_mul_f32_e32 v106, v0, v48
	v_add_f32_e32 v2, 1.0, v2
	v_rcp_f32_e32 v53, v2
	s_nop 0
	v_pk_mul_f32 v[46:47], v[52:53], v[46:47]
	v_mov_b32_e32 v52, v108
	v_mov_b32_e32 v53, v54
	v_mov_b32_e32 v54, v109
	v_pk_mul_f32 v[52:53], v[52:53], v[54:55]
	v_mov_b32_e32 v54, v104
	v_mov_b32_e32 v55, v46
	v_mov_b32_e32 v46, v105
	v_pk_mul_f32 v[46:47], v[54:55], v[46:47]
	v_cvt_pk_bf16_f32 v52, v52, v53
	v_cvt_pk_bf16_f32 v53, v46, v47
	v_mov_b64_e32 v[196:197], v[52:53]
	v_mov_b64_e32 v[46:47], v[236:237]
	s_nop 0
	v_mov_b64_e32 v[52:53], v[192:193]
	v_mov_b64_e32 v[54:55], v[194:195]
	v_mul_f32_e32 v102, v50, v48
	v_mul_f32_e32 v104, v51, v48
	s_waitcnt lgkmcnt(0)
	v_lshlrev_b32_e32 v103, 16, v46
	v_lshlrev_b32_e32 v107, 16, v47
	v_mul_f32_e32 v2, 0xbfb8aa3b, v103
	v_mul_f32_e32 v0, 0xbfb8aa3b, v107
	v_exp_f32_e32 v2, v2
	v_exp_f32_e32 v0, v0
	v_and_b32_e32 v105, 0xffff0000, v46
	v_and_b32_e32 v47, 0xffff0000, v47
	v_add_f32_e32 v2, 1.0, v2
	v_add_f32_e32 v0, 1.0, v0
	v_rcp_f32_e32 v109, v2
	v_mul_f32_e32 v2, 0xbfb8aa3b, v105
	v_mov_b32_e32 v50, v53
	v_rcp_f32_e32 v53, v0
	v_mul_f32_e32 v0, 0xbfb8aa3b, v47
	v_exp_f32_e32 v2, v2
	v_exp_f32_e32 v0, v0
	v_mul_f32_e32 v46, v1, v48
	v_mov_b32_e32 v108, v52
	v_add_f32_e32 v2, 1.0, v2
	v_add_f32_e32 v0, 1.0, v0
	v_rcp_f32_e32 v51, v2
	v_rcp_f32_e32 v1, v0
	v_mov_b32_e32 v52, v54
	v_mov_b32_e32 v0, v55
	v_pk_mul_f32 v[102:103], v[108:109], v[102:103]
	v_pk_mul_f32 v[50:51], v[50:51], v[104:105]
	v_pk_mul_f32 v[52:53], v[52:53], v[106:107]
	v_pk_mul_f32 v[0:1], v[0:1], v[46:47]
	v_mov_b32_e32 v46, v102
	v_mov_b32_e32 v47, v50
	v_mov_b32_e32 v50, v103
	v_mov_b32_e32 v48, v52
	v_mov_b32_e32 v49, v0
	v_mov_b32_e32 v0, v53
	v_pk_mul_f32 v[46:47], v[46:47], v[50:51]
	v_pk_mul_f32 v[0:1], v[48:49], v[0:1]
	v_cvt_pk_bf16_f32 v46, v46, v47
	v_cvt_pk_bf16_f32 v47, v0, v1
	v_mov_b64_e32 v[198:199], v[46:47]
	s_nop 1
	v_permlane16_swap_b32_e32 v196, v198
	v_permlane16_swap_b32_e32 v197, v199
	global_store_dwordx4 v[44:45], v[196:199], off offset:1600
	v_mfma_f32_16x16x32_bf16 v[44:47], v[20:23], v[28:31], 0
	v_mfma_f32_16x16x32_bf16 v[48:51], v[16:19], v[28:31], 0
	v_mfma_f32_16x16x32_bf16 v[44:47], v[24:27], v[40:43], v[44:47]
	v_mfma_f32_16x16x32_bf16 v[48:51], v[32:35], v[40:43], v[48:51]
	s_nop 6
	v_cvt_pk_bf16_f32 v44, v44, v45
	v_cvt_pk_bf16_f32 v45, v46, v47
	v_cvt_pk_bf16_f32 v46, v48, v49
	v_cvt_pk_bf16_f32 v47, v50, v51
	ds_read_b64_tr_b16 v[50:51], v131 offset:2304
	ds_read_b64_tr_b16 v[48:49], v131
	ds_read_b64_tr_b16 v[52:53], v131 offset:32
	ds_read_b64_tr_b16 v[54:55], v131 offset:2336
	ds_read_b64_tr_b16 v[102:103], v131 offset:64
	ds_read_b64_tr_b16 v[104:105], v131 offset:2368
	ds_read_b64_tr_b16 v[106:107], v131 offset:96
	ds_read_b64_tr_b16 v[108:109], v131 offset:2400
	s_waitcnt lgkmcnt(0)
	v_mfma_f32_16x16x32_bf16 v[48:51], v[48:51], v[44:47], 0
	v_mfma_f32_16x16x32_bf16 v[52:55], v[52:55], v[44:47], 0
	v_mfma_f32_16x16x32_bf16 v[102:105], v[102:105], v[44:47], 0
	v_mfma_f32_16x16x32_bf16 v[44:47], v[106:109], v[44:47], 0
	v_mfma_f32_16x16x32_bf16 v[106:109], v[12:15], v[28:31], 0
	v_mfma_f32_16x16x32_bf16 v[106:109], v[36:39], v[40:43], v[106:109]
	s_nop 7
	v_cndmask_b32_e64 v0, v106, 0, s[40:41]
	v_cndmask_b32_e64 v1, 0, v107, s[42:43]
	v_cndmask_b32_e64 v2, v108, 0, s[38:39]
	v_cndmask_b32_e64 v106, v109, 0, vcc
	v_cvt_pk_bf16_f32 v0, v0, v1
	v_cvt_pk_bf16_f32 v1, v2, v106
	ds_read_b64_tr_b16 v[106:107], v131 offset:4608
	ds_read_b64_tr_b16 v[108:109], v131 offset:6912
	v_mov_b32_e32 v2, v3
	s_waitcnt lgkmcnt(0)
	s_nop 0
	v_mfma_f32_16x16x32_bf16 v[48:51], v[106:109], v[0:3], v[48:51]
	ds_read_b64_tr_b16 v[106:107], v131 offset:4640
	ds_read_b64_tr_b16 v[108:109], v131 offset:6944
	s_waitcnt lgkmcnt(0)
	v_mfma_f32_16x16x32_bf16 v[106:109], v[106:109], v[0:3], v[52:55]
	s_nop 2
	ds_read_b64_tr_b16 v[52:53], v131 offset:4672
	ds_read_b64_tr_b16 v[54:55], v131 offset:6976
	s_waitcnt lgkmcnt(0)
	v_mfma_f32_16x16x32_bf16 v[110:113], v[52:55], v[0:3], v[102:105]
	ds_read_b64_tr_b16 v[52:53], v131 offset:4704
	ds_read_b64_tr_b16 v[54:55], v131 offset:7008
	s_waitcnt lgkmcnt(0)
; template <int KIND>
; __device__ __forceinline__ void w_m3_core(const bf16x8 (&Qf)[4][2], const bf16x8 (&Kf)[4][2], const bf16x8 (&Sf)[4][2], const LAS bf16_t* vT, float lg,
;                                           const bf16_t* gsrc, const float* nw, bf16_t* ydst, int lo, int fq) {
;     ...
;             float pv[8];
; #pragma unroll
;             for (int hh = 0; hh < 2; ++hh) { const int mb = 2 * kk2 + hh;
;                 if (mb <= nb) { f32x4 s = {0.f, 0.f, 0.f, 0.f};
;                     s = __builtin_amdgcn_mfma_f32_16x16x32_bf16(Kf[mb][0], Qf[nb][0], s, 0, 0, 0); s = __builtin_amdgcn_mfma_f32_16x16x32_bf16(Kf[mb][1], Qf[nb][1], s, 0, 0, 0);
; #pragma unroll
;                     for (int r = 0; r < 4; ++r) { const int m = 16 * mb + 4 * fq + r, n = 16 * nb + lo; float v = s[r];
;                         if (KIND == 0) v *= __expf((float)(n - m) * lg);
;                         if (mb == nb) v = (m <= n) ? v : 0.f;
;                         pv[4 * hh + r] = v; }
;                 } else {
; #pragma unroll
;                     for (int r = 0; r < 4; ++r) pv[4 * hh + r] = 0.f; }
;             }
;             const bf16x8 Pf = pack_frag(pv);
; #pragma unroll
;             for (int eb = 0; eb < 4; ++eb)
;                 O[eb] = __builtin_amdgcn_mfma_f32_16x16x32_bf16(tr_frag(vT, 32 * kk2 + 4 * fq, 32 * kk2 + 16 + 4 * fq, 16 * eb, lo), Pf, O[eb], 0, 0, 0);
;         }
; #pragma unroll
;         for (int kk = 0; kk < 2; ++kk)
; #pragma unroll
;             for (int eb = 0; eb < 4; ++eb) O2[eb] = __builtin_amdgcn_mfma_f32_16x16x32_bf16(Sf[eb][kk], Qf[nb][kk], O2[eb], 0, 0, 0);
;         const float osc = KIND == 0 ? __expf((float)(16 * nb + lo + 1) * lg) : 1.0f;
; #pragma unroll
;         for (int eb = 0; eb < 4; ++eb) O[eb] = O[eb] + O2[eb] * osc;
;         float ss = 0.f;
; #pragma unroll
;         for (int eb = 0; eb < 4; ++eb) ss += (O[eb][0] * O[eb][0] + O[eb][1] * O[eb][1]) + (O[eb][2] * O[eb][2] + O[eb][3] * O[eb][3]);
;         { const int ln = (fq << 4) | lo; ss += bperm_f(ln ^ 16, ss); ss += bperm_f(ln ^ 32, ss); }
;         const float rs = rsqrtf(ss * (1.0f / 64.0f) + EPS);
;         const size_t n = 16 * nb + lo;
; #pragma unroll
;         for (int eb = 0; eb < 4; ++eb) { const int e0 = 16 * eb + 4 * fq;
;             const unsigned long long gw_ = *(const unsigned long long*)(gsrc + n * NIN + e0); const f32x4 w4 = *(const f32x4*)(nw + e0);
	v_mfma_f32_16x16x32_bf16 v[114:117], v[52:55], v[0:3], v[44:47]
	v_mfma_f32_16x16x32_bf16 v[44:47], v[64:67], v[28:31], 0
	v_mfma_f32_16x16x32_bf16 v[52:55], v[72:75], v[28:31], 0
	v_mfma_f32_16x16x32_bf16 v[102:105], v[76:79], v[28:31], 0
	v_mfma_f32_16x16x32_bf16 v[28:31], v[80:83], v[28:31], 0
	v_mfma_f32_16x16x32_bf16 v[44:47], v[84:87], v[40:43], v[44:47]
	v_mfma_f32_16x16x32_bf16 v[28:31], v[96:99], v[40:43], v[28:31]
	v_mfma_f32_16x16x32_bf16 v[118:121], v[88:91], v[40:43], v[52:55]
	v_mfma_f32_16x16x32_bf16 v[122:125], v[92:95], v[40:43], v[102:105]
	s_nop 4
	v_add_f32_e64 v54, v50, v46
	v_add_f32_e64 v55, v51, v47
	v_pk_add_f32 v[0:1], v[116:117], v[30:31]
	v_pk_add_f32 v[42:43], v[114:115], v[28:29]
	v_pk_add_f32 v[102:103], v[48:49], v[44:45]
	v_pk_mul_f32 v[28:29], v[54:55], v[54:55]
	v_pk_mul_f32 v[30:31], v[102:103], v[102:103]
	v_pk_add_f32 v[50:51], v[108:109], v[120:121]
	v_pk_add_f32 v[52:53], v[106:107], v[118:119]
	v_pk_mov_b32 v[40:41], v[30:31], v[28:29] op_sel:[1,0]
	v_mov_b32_e32 v31, v29
	v_pk_add_f32 v[28:29], v[40:41], v[30:31]
	v_pk_mul_f32 v[30:31], v[50:51], v[50:51]
	v_pk_mul_f32 v[40:41], v[52:53], v[52:53]
	v_pk_add_f32 v[46:47], v[110:111], v[122:123]
	v_pk_mov_b32 v[48:49], v[40:41], v[30:31] op_sel:[1,0]
	v_mov_b32_e32 v41, v31
	v_pk_add_f32 v[30:31], v[48:49], v[40:41]
	v_mul_f32_e32 v2, v42, v42
	v_mul_f32_e32 v40, v43, v43
	v_pk_add_f32 v[28:29], v[28:29], v[28:29] op_sel:[0,1] op_sel_hi:[1,0]
	v_pk_add_f32 v[30:31], v[30:31], v[30:31] op_sel:[0,1] op_sel_hi:[1,0]
	v_pk_add_f32 v[44:45], v[112:113], v[124:125]
	v_mov_b32_e32 v29, v2
	v_mov_b32_e32 v31, v40
	v_mul_f32_e32 v2, v47, v47
	v_mul_f32_e32 v41, v0, v0
	v_pk_add_f32 v[28:29], v[28:29], v[30:31]
	v_pk_fma_f32 v[30:31], v[46:47], v[46:47], v[2:3] op_sel_hi:[1,1,0]
	v_mul_f32_e32 v2, v45, v45
	v_mul_f32_e32 v48, v1, v1
	v_mov_b32_e32 v31, v41
	v_pk_fma_f32 v[40:41], v[44:45], v[44:45], v[2:3] op_sel_hi:[1,1,0]
	s_nop 0
	v_mov_b32_e32 v41, v48
	v_pk_add_f32 v[30:31], v[30:31], v[40:41]
	s_nop 0
	v_pk_add_f32 v[28:29], v[28:29], v[30:31]
	s_nop 0
	v_add_f32_e32 v2, v28, v29
	ds_bpermute_b32 v28, v130, v2
	s_waitcnt lgkmcnt(0)
	v_add_f32_e32 v2, v2, v28
	ds_bpermute_b32 v28, v129, v2
	s_waitcnt lgkmcnt(0)
	v_add_f32_e32 v2, v2, v28
	v_fmamk_f32 v2, v2, 0x3c800000, v200
	v_cmp_gt_f32_e64 s[44:45], s29, v2
	v_mul_f32_e32 v28, 0x4b800000, v2
	s_nop 0
	v_cndmask_b32_e64 v2, v2, v28, s[44:45]
	v_rsq_f32_e32 v2, v2
	s_nop 0
	v_mul_f32_e32 v28, 0x45800000, v2
	v_cndmask_b32_e64 v40, v2, v28, s[44:45]
	v_mad_u64_u32 v[28:29], s[20:21], v127, s72, v[100:101]
	v_lshl_add_u64 v[48:49], v[28:29], 0, v[62:63]
	v_mov_b64_e32 v[106:107], v[238:239]
	v_mov_b64_e32 v[28:29], v[146:147]
	v_mov_b64_e32 v[30:31], v[148:149]
	v_lshlrev_b32_e32 v2, 11, v127
	v_lshl_add_u64 v[104:105], s[46:47], 0, v[2:3]
	v_pk_mul_f32 v[102:103], v[102:103], v[40:41] op_sel_hi:[1,0]
	v_pk_mul_f32 v[54:55], v[54:55], v[40:41] op_sel_hi:[1,0]
	v_pk_mul_f32 v[52:53], v[52:53], v[40:41] op_sel_hi:[1,0]
	v_pk_mul_f32 v[50:51], v[50:51], v[40:41] op_sel_hi:[1,0]
	s_waitcnt lgkmcnt(0)
	v_lshlrev_b32_e32 v108, 16, v106
	v_mul_f32_e32 v2, 0xbfb8aa3b, v108
	v_exp_f32_e32 v2, v2
	v_and_b32_e32 v109, 0xffff0000, v106
	v_lshlrev_b32_e32 v106, 16, v107
	v_and_b32_e32 v107, 0xffff0000, v107
	v_add_f32_e32 v2, 1.0, v2
	v_rcp_f32_e32 v110, v2
	v_mul_f32_e32 v2, 0xbfb8aa3b, v109
	v_exp_f32_e32 v2, v2
	v_pk_mul_f32 v[28:29], v[28:29], v[102:103]
	v_pk_mul_f32 v[30:31], v[30:31], v[54:55]
	v_add_f32_e32 v2, 1.0, v2
	v_rcp_f32_e32 v111, v2
	v_mul_f32_e32 v2, 0xbfb8aa3b, v106
	v_exp_f32_e32 v2, v2
	v_pk_mul_f32 v[102:103], v[110:111], v[108:109]
	s_nop 0
	v_pk_mul_f32 v[28:29], v[102:103], v[28:29]
	v_add_f32_e32 v2, 1.0, v2
	v_rcp_f32_e32 v102, v2
	v_mul_f32_e32 v2, 0xbfb8aa3b, v107
	v_exp_f32_e32 v2, v2
	s_nop 0
	v_add_f32_e32 v2, 1.0, v2
	v_rcp_f32_e32 v103, v2
	s_nop 0
	v_pk_mul_f32 v[54:55], v[102:103], v[106:107]
	s_nop 0
	v_pk_mul_f32 v[30:31], v[54:55], v[30:31]
	v_cvt_pk_bf16_f32 v54, v28, v29
	v_cvt_pk_bf16_f32 v55, v30, v31
	v_lshl_add_u64 v[28:29], v[104:105], 0, v[62:63]
	v_lshl_add_u64 v[28:29], v[28:29], 0, v[142:143]
	v_mov_b64_e32 v[196:197], v[54:55]
	v_mov_b64_e32 v[30:31], v[240:241]
	v_mov_b64_e32 v[102:103], v[150:151]
	v_mov_b64_e32 v[104:105], v[152:153]
	s_waitcnt lgkmcnt(0)
	v_lshlrev_b32_e32 v54, 16, v30
	v_mul_f32_e32 v2, 0xbfb8aa3b, v54
	v_exp_f32_e32 v2, v2
	v_and_b32_e32 v55, 0xffff0000, v30
	v_lshlrev_b32_e32 v30, 16, v31
	v_and_b32_e32 v31, 0xffff0000, v31
	v_add_f32_e32 v2, 1.0, v2
	v_rcp_f32_e32 v106, v2
	v_mul_f32_e32 v2, 0xbfb8aa3b, v55
	v_exp_f32_e32 v2, v2
	v_pk_mul_f32 v[52:53], v[102:103], v[52:53]
	v_pk_mul_f32 v[50:51], v[104:105], v[50:51]
	v_mul_f32_e32 v102, v47, v40
	v_add_f32_e32 v2, 1.0, v2
	v_rcp_f32_e32 v107, v2
	v_mul_f32_e32 v2, 0xbfb8aa3b, v30
	v_exp_f32_e32 v2, v2
	v_mul_f32_e32 v104, v44, v40
	v_pk_mul_f32 v[54:55], v[106:107], v[54:55]
	v_add_f32_e32 v2, 1.0, v2
	v_pk_mul_f32 v[52:53], v[54:55], v[52:53]
	v_rcp_f32_e32 v54, v2
	v_mul_f32_e32 v2, 0xbfb8aa3b, v31
	v_exp_f32_e32 v2, v2
	s_nop 0
	v_add_f32_e32 v2, 1.0, v2
	v_rcp_f32_e32 v55, v2
	s_nop 0
	v_pk_mul_f32 v[30:31], v[54:55], v[30:31]
	s_nop 0
	v_pk_mul_f32 v[30:31], v[30:31], v[50:51]
	v_cvt_pk_bf16_f32 v50, v52, v53
	v_cvt_pk_bf16_f32 v51, v30, v31
	v_mov_b64_e32 v[198:199], v[50:51]
	s_nop 1
	v_permlane16_swap_b32_e32 v196, v198
	v_permlane16_swap_b32_e32 v197, v199
	global_store_dwordx4 v[28:29], v[196:199], off offset:1536
	v_mov_b64_e32 v[30:31], v[242:243]
	s_nop 0
	v_mov_b64_e32 v[50:51], v[188:189]
	v_mov_b64_e32 v[52:53], v[190:191]
	v_mul_f32_e32 v54, v46, v40
	s_waitcnt lgkmcnt(0)
; template <int KIND>
; __device__ __forceinline__ void w_m3_core(const bf16x8 (&Qf)[4][2], const bf16x8 (&Kf)[4][2], const bf16x8 (&Sf)[4][2], const LAS bf16_t* vT, float lg,
;                                           const bf16_t* gsrc, const float* nw, bf16_t* ydst, int lo, int fq) {
;     ...
; #pragma unroll
;         for (int kk2 = 0; kk2 < 2; ++kk2) {
;             if (2 * kk2 > nb) continue;
;             float pv[8];
; #pragma unroll
;             for (int hh = 0; hh < 2; ++hh) { const int mb = 2 * kk2 + hh;
;                 if (mb <= nb) { f32x4 s = {0.f, 0.f, 0.f, 0.f};
;                     s = __builtin_amdgcn_mfma_f32_16x16x32_bf16(Kf[mb][0], Qf[nb][0], s, 0, 0, 0); s = __builtin_amdgcn_mfma_f32_16x16x32_bf16(Kf[mb][1], Qf[nb][1], s, 0, 0, 0);
; #pragma unroll
;                     for (int r = 0; r < 4; ++r) { const int m = 16 * mb + 4 * fq + r, n = 16 * nb + lo; float v = s[r];
;                         if (KIND == 0) v *= __expf((float)(n - m) * lg);
;                         if (mb == nb) v = (m <= n) ? v : 0.f;
;                         pv[4 * hh + r] = v; }
;                 } else {
; #pragma unroll
;                     for (int r = 0; r < 4; ++r) pv[4 * hh + r] = 0.f; }
;             }
;             const bf16x8 Pf = pack_frag(pv);
; #pragma unroll
;             for (int eb = 0; eb < 4; ++eb)
;                 O[eb] = __builtin_amdgcn_mfma_f32_16x16x32_bf16(tr_frag(vT, 32 * kk2 + 4 * fq, 32 * kk2 + 16 + 4 * fq, 16 * eb, lo), Pf, O[eb], 0, 0, 0);
;     ...
;         for (int eb = 0; eb < 4; ++eb) { const int e0 = 16 * eb + 4 * fq;
;             const unsigned long long gw_ = *(const unsigned long long*)(gsrc + n * NIN + e0); const f32x4 w4 = *(const f32x4*)(nw + e0);
;             const float g0 = __uint_as_float((unsigned)gw_ << 16), g1 = __uint_as_float((unsigned)gw_ & 0xffff0000u), g2 = __uint_as_float((unsigned)(gw_ >> 32) << 16), g3 = __uint_as_float((unsigned)(gw_ >> 32) & 0xffff0000u);
;             const float o0 = O[eb][0] * rs * w4[0] * (g0 * sigmoidf_(g0)), o1 = O[eb][1] * rs * w4[1] * (g1 * sigmoidf_(g1));
;             const float o2 = O[eb][2] * rs * w4[2] * (g2 * sigmoidf_(g2)), o3 = O[eb][3] * rs * w4[3] * (g3 * sigmoidf_(g3));
;             *(unsigned long long*)(ydst + n * DM + e0) = (unsigned long long)pk2(o0, o1) | ((unsigned long long)pk2(o2, o3) << 32); }
	v_lshlrev_b32_e32 v55, 16, v30
	v_mul_f32_e32 v2, 0xbfb8aa3b, v55
	v_exp_f32_e32 v2, v2
	v_and_b32_e32 v103, 0xffff0000, v30
	v_lshlrev_b32_e32 v105, 16, v31
	v_and_b32_e32 v31, 0xffff0000, v31
	v_add_f32_e32 v2, 1.0, v2
	v_rcp_f32_e32 v107, v2
	v_mul_f32_e32 v2, 0xbfb8aa3b, v103
	v_exp_f32_e32 v2, v2
	v_mov_b32_e32 v46, v51
	v_mul_f32_e32 v30, v45, v40
	v_mov_b32_e32 v106, v50
	v_add_f32_e32 v2, 1.0, v2
	v_rcp_f32_e32 v47, v2
	v_mul_f32_e32 v2, 0xbfb8aa3b, v105
	v_exp_f32_e32 v2, v2
	v_pk_mul_f32 v[54:55], v[106:107], v[54:55]
	v_pk_mul_f32 v[46:47], v[46:47], v[102:103]
	v_mov_b32_e32 v50, v52
	v_add_f32_e32 v2, 1.0, v2
	v_rcp_f32_e32 v51, v2
	v_mul_f32_e32 v2, 0xbfb8aa3b, v31
	v_exp_f32_e32 v2, v2
	v_mov_b32_e32 v44, v53
	v_pk_mul_f32 v[50:51], v[50:51], v[104:105]
	v_mul_f32_e32 v52, v0, v40
	v_add_f32_e32 v2, 1.0, v2
	v_rcp_f32_e32 v45, v2
	s_nop 0
	v_pk_mul_f32 v[30:31], v[44:45], v[30:31]
	v_mov_b32_e32 v44, v54
	v_mov_b32_e32 v45, v46
	v_mov_b32_e32 v46, v55
	v_pk_mul_f32 v[44:45], v[44:45], v[46:47]
	v_mov_b32_e32 v46, v50
	v_mov_b32_e32 v47, v30
	v_mov_b32_e32 v30, v51
	v_pk_mul_f32 v[30:31], v[46:47], v[30:31]
	v_cvt_pk_bf16_f32 v44, v44, v45
	v_cvt_pk_bf16_f32 v45, v30, v31
	v_mov_b64_e32 v[196:197], v[44:45]
	v_mov_b64_e32 v[30:31], v[244:245]
	s_nop 0
	v_mov_b64_e32 v[44:45], v[192:193]
	v_mov_b64_e32 v[46:47], v[194:195]
	v_mul_f32_e32 v48, v42, v40
	v_mul_f32_e32 v50, v43, v40
	s_waitcnt lgkmcnt(0)
	v_lshlrev_b32_e32 v49, 16, v30
	v_lshlrev_b32_e32 v53, 16, v31
	v_mul_f32_e32 v2, 0xbfb8aa3b, v49
	v_mul_f32_e32 v0, 0xbfb8aa3b, v53
	v_exp_f32_e32 v2, v2
	v_exp_f32_e32 v0, v0
	v_and_b32_e32 v51, 0xffff0000, v30
	v_and_b32_e32 v31, 0xffff0000, v31
	v_add_f32_e32 v2, 1.0, v2
	v_add_f32_e32 v0, 1.0, v0
	v_rcp_f32_e32 v55, v2
	v_mul_f32_e32 v2, 0xbfb8aa3b, v51
	v_mov_b32_e32 v42, v45
	v_rcp_f32_e32 v45, v0
	v_mul_f32_e32 v0, 0xbfb8aa3b, v31
	v_exp_f32_e32 v2, v2
	v_exp_f32_e32 v0, v0
	v_mul_f32_e32 v30, v1, v40
	v_mov_b32_e32 v54, v44
	v_add_f32_e32 v2, 1.0, v2
	v_add_f32_e32 v0, 1.0, v0
	v_rcp_f32_e32 v43, v2
	v_rcp_f32_e32 v1, v0
	v_mov_b32_e32 v44, v46
	v_mov_b32_e32 v0, v47
	v_pk_mul_f32 v[48:49], v[54:55], v[48:49]
	v_pk_mul_f32 v[42:43], v[42:43], v[50:51]
	v_pk_mul_f32 v[44:45], v[44:45], v[52:53]
	v_pk_mul_f32 v[0:1], v[0:1], v[30:31]
	v_mov_b32_e32 v30, v48
	v_mov_b32_e32 v31, v42
	v_mov_b32_e32 v42, v49
	v_mov_b32_e32 v40, v44
	v_mov_b32_e32 v41, v0
	v_mov_b32_e32 v0, v45
	v_pk_mul_f32 v[30:31], v[30:31], v[42:43]
	v_pk_mul_f32 v[0:1], v[40:41], v[0:1]
	v_cvt_pk_bf16_f32 v30, v30, v31
	v_cvt_pk_bf16_f32 v31, v0, v1
	v_mov_b64_e32 v[198:199], v[30:31]
	s_nop 1
	v_permlane16_swap_b32_e32 v196, v198
	v_permlane16_swap_b32_e32 v197, v199
	global_store_dwordx4 v[28:29], v[196:199], off offset:1600
	v_mfma_f32_16x16x32_bf16 v[20:23], v[20:23], v[8:11], 0
	v_mfma_f32_16x16x32_bf16 v[20:23], v[24:27], v[56:59], v[20:23]
	ds_read_b64_tr_b16 v[26:27], v131 offset:2304
	ds_read_b64_tr_b16 v[24:25], v131
	v_mfma_f32_16x16x32_bf16 v[16:19], v[16:19], v[8:11], 0
	v_mfma_f32_16x16x32_bf16 v[16:19], v[32:35], v[56:59], v[16:19]
	s_nop 3
	v_cvt_pk_bf16_f32 v20, v20, v21
	v_cvt_pk_bf16_f32 v21, v22, v23
	v_mfma_f32_16x16x32_bf16 v[12:15], v[12:15], v[8:11], 0
	v_mfma_f32_16x16x32_bf16 v[4:7], v[4:7], v[8:11], 0
	v_cvt_pk_bf16_f32 v22, v16, v17
	v_cvt_pk_bf16_f32 v23, v18, v19
	v_mfma_f32_16x16x32_bf16 v[4:7], v[68:71], v[56:59], v[4:7]
	s_waitcnt lgkmcnt(0)
	v_mfma_f32_16x16x32_bf16 v[16:19], v[24:27], v[20:23], 0
	ds_read_b64_tr_b16 v[24:25], v131 offset:32
	ds_read_b64_tr_b16 v[26:27], v131 offset:2336
	ds_read_b64_tr_b16 v[28:29], v131 offset:64
	ds_read_b64_tr_b16 v[32:33], v131 offset:96
	ds_read_b64_tr_b16 v[30:31], v131 offset:2368
	ds_read_b64_tr_b16 v[34:35], v131 offset:2400
	v_mfma_f32_16x16x32_bf16 v[12:15], v[36:39], v[56:59], v[12:15]
	v_cndmask_b32_e64 v0, v4, 0, s[40:41]
	v_cndmask_b32_e64 v1, 0, v5, s[42:43]
	ds_read_b64_tr_b16 v[36:37], v131 offset:4608
	ds_read_b64_tr_b16 v[38:39], v131 offset:6912
	s_waitcnt lgkmcnt(0)
	v_mfma_f32_16x16x32_bf16 v[24:27], v[24:27], v[20:23], 0
	s_nop 1
	v_cvt_pk_bf16_f32 v4, v12, v13
	v_cvt_pk_bf16_f32 v5, v14, v15
	v_cndmask_b32_e64 v2, v6, 0, s[38:39]
	v_mfma_f32_16x16x32_bf16 v[28:31], v[28:31], v[20:23], 0
	v_cndmask_b32_e64 v7, v7, 0, vcc
	v_cvt_pk_bf16_f32 v6, v0, v1
	v_cvt_pk_bf16_f32 v7, v2, v7
	v_mfma_f32_16x16x32_bf16 v[12:15], v[32:35], v[20:23], 0
	ds_read_b64_tr_b16 v[20:21], v131 offset:6944
	v_mad_u64_u32 v[0:1], s[20:21], v126, s72, v[100:101]
	v_mfma_f32_16x16x32_bf16 v[32:35], v[36:39], v[4:7], v[16:19]
	s_nop 2
	ds_read_b64_tr_b16 v[18:19], v131 offset:4640
	ds_read_b64_tr_b16 v[16:17], v131 offset:4672
	s_waitcnt lgkmcnt(0)
	v_mfma_f32_16x16x32_bf16 v[20:23], v[18:21], v[4:7], v[24:27]
	ds_read_b64_tr_b16 v[18:19], v131 offset:6976
	s_nop 1
	ds_read_b64_tr_b16 v[24:25], v131 offset:4704
	ds_read_b64_tr_b16 v[26:27], v131 offset:7008
	s_waitcnt lgkmcnt(0)
; __device__ __forceinline__ unsigned pk2(float lo, float hi) { const f32x2_t v = {lo, hi}; const bf16x2_t b = __builtin_convertvector(v, bf16x2_t); return __builtin_bit_cast(unsigned, b); }
; __device__ __forceinline__ float sigmoidf_(float x) { return __builtin_amdgcn_rcpf(1.0f + __expf(-x)); }
; template <int KIND>
; __device__ __forceinline__ void w_m3_core(const bf16x8 (&Qf)[4][2], const bf16x8 (&Kf)[4][2], const bf16x8 (&Sf)[4][2], const LAS bf16_t* vT, float lg,
;                                           const bf16_t* gsrc, const float* nw, bf16_t* ydst, int lo, int fq) {
;     ...
;                 O[eb] = __builtin_amdgcn_mfma_f32_16x16x32_bf16(tr_frag(vT, 32 * kk2 + 4 * fq, 32 * kk2 + 16 + 4 * fq, 16 * eb, lo), Pf, O[eb], 0, 0, 0);
;         }
; #pragma unroll
;         for (int kk = 0; kk < 2; ++kk)
; #pragma unroll
;             for (int eb = 0; eb < 4; ++eb) O2[eb] = __builtin_amdgcn_mfma_f32_16x16x32_bf16(Sf[eb][kk], Qf[nb][kk], O2[eb], 0, 0, 0);
;         const float osc = KIND == 0 ? __expf((float)(16 * nb + lo + 1) * lg) : 1.0f;
; #pragma unroll
;         for (int eb = 0; eb < 4; ++eb) O[eb] = O[eb] + O2[eb] * osc;
;         float ss = 0.f;
; #pragma unroll
;         for (int eb = 0; eb < 4; ++eb) ss += (O[eb][0] * O[eb][0] + O[eb][1] * O[eb][1]) + (O[eb][2] * O[eb][2] + O[eb][3] * O[eb][3]);
;         { const int ln = (fq << 4) | lo; ss += bperm_f(ln ^ 16, ss); ss += bperm_f(ln ^ 32, ss); }
;         const float rs = rsqrtf(ss * (1.0f / 64.0f) + EPS);
;         const size_t n = 16 * nb + lo;
; #pragma unroll
;         for (int eb = 0; eb < 4; ++eb) { const int e0 = 16 * eb + 4 * fq;
;             const unsigned long long gw_ = *(const unsigned long long*)(gsrc + n * NIN + e0); const f32x4 w4 = *(const f32x4*)(nw + e0);
;             const float g0 = __uint_as_float((unsigned)gw_ << 16), g1 = __uint_as_float((unsigned)gw_ & 0xffff0000u), g2 = __uint_as_float((unsigned)(gw_ >> 32) << 16), g3 = __uint_as_float((unsigned)(gw_ >> 32) & 0xffff0000u);
;             const float o0 = O[eb][0] * rs * w4[0] * (g0 * sigmoidf_(g0)), o1 = O[eb][1] * rs * w4[1] * (g1 * sigmoidf_(g1));
;             const float o2 = O[eb][2] * rs * w4[2] * (g2 * sigmoidf_(g2)), o3 = O[eb][3] * rs * w4[3] * (g3 * sigmoidf_(g3));
;             *(unsigned long long*)(ydst + n * DM + e0) = (unsigned long long)pk2(o0, o1) | ((unsigned long long)pk2(o2, o3) << 32); }
	v_mfma_f32_16x16x32_bf16 v[16:19], v[16:19], v[4:7], v[28:31]
	v_mfma_f32_16x16x32_bf16 v[12:15], v[24:27], v[4:7], v[12:15]
	v_lshl_add_u64 v[6:7], v[0:1], 0, v[62:63]
	v_mov_b64_e32 v[44:45], v[246:247]
	v_mov_b64_e32 v[40:41], v[146:147]
	v_mov_b64_e32 v[42:43], v[148:149]
	v_mfma_f32_16x16x32_bf16 v[24:27], v[64:67], v[8:11], 0
	v_mfma_f32_16x16x32_bf16 v[28:31], v[72:75], v[8:11], 0
	v_mfma_f32_16x16x32_bf16 v[36:39], v[76:79], v[8:11], 0
	v_mfma_f32_16x16x32_bf16 v[8:11], v[80:83], v[8:11], 0
	v_mfma_f32_16x16x32_bf16 v[24:27], v[84:87], v[56:59], v[24:27]
	v_mfma_f32_16x16x32_bf16 v[8:11], v[96:99], v[56:59], v[8:11]
	v_mfma_f32_16x16x32_bf16 v[28:31], v[88:91], v[56:59], v[28:31]
	s_nop 5
	v_add_f32_e64 v26, v34, v26
	v_add_f32_e64 v27, v35, v27
	v_pk_add_f32 v[32:33], v[32:33], v[24:25]
	v_pk_add_f32 v[0:1], v[14:15], v[10:11]
	v_pk_add_f32 v[4:5], v[12:13], v[8:9]
	v_pk_mul_f32 v[8:9], v[26:27], v[26:27]
	v_pk_mul_f32 v[10:11], v[32:33], v[32:33]
	v_pk_add_f32 v[30:31], v[22:23], v[30:31]
	v_mfma_f32_16x16x32_bf16 v[22:25], v[92:95], v[56:59], v[36:39]
	v_add_f32_e64 v20, v20, v28
	v_add_f32_e64 v21, v21, v29
	v_pk_mov_b32 v[12:13], v[10:11], v[8:9] op_sel:[1,0]
	v_mov_b32_e32 v11, v9
	v_pk_add_f32 v[8:9], v[12:13], v[10:11]
	v_pk_mul_f32 v[10:11], v[30:31], v[30:31]
	v_pk_mul_f32 v[12:13], v[20:21], v[20:21]
	s_nop 0
	v_pk_add_f32 v[16:17], v[16:17], v[22:23]
	v_pk_mov_b32 v[14:15], v[12:13], v[10:11] op_sel:[1,0]
	v_mov_b32_e32 v13, v11
	v_pk_add_f32 v[10:11], v[14:15], v[12:13]
	v_mul_f32_e32 v2, v4, v4
	v_mul_f32_e32 v12, v5, v5
	v_pk_add_f32 v[8:9], v[8:9], v[8:9] op_sel:[0,1] op_sel_hi:[1,0]
	v_pk_add_f32 v[10:11], v[10:11], v[10:11] op_sel:[0,1] op_sel_hi:[1,0]
	v_pk_add_f32 v[18:19], v[18:19], v[24:25]
	v_mov_b32_e32 v9, v2
	v_mov_b32_e32 v11, v12
	v_mul_f32_e32 v2, v17, v17
	v_mul_f32_e32 v13, v0, v0
	v_pk_add_f32 v[8:9], v[8:9], v[10:11]
	v_pk_fma_f32 v[10:11], v[16:17], v[16:17], v[2:3] op_sel_hi:[1,1,0]
	v_mul_f32_e32 v2, v19, v19
	v_mul_f32_e32 v14, v1, v1
	v_mov_b32_e32 v11, v13
	v_pk_fma_f32 v[12:13], v[18:19], v[18:19], v[2:3] op_sel_hi:[1,1,0]
	s_waitcnt lgkmcnt(0)
	v_and_b32_e32 v15, 0xffff0000, v45
	v_mov_b32_e32 v13, v14
	v_pk_add_f32 v[10:11], v[10:11], v[12:13]
	v_lshlrev_b32_e32 v12, 16, v44
	v_pk_add_f32 v[8:9], v[8:9], v[10:11]
	v_and_b32_e32 v13, 0xffff0000, v44
	v_add_f32_e32 v2, v8, v9
	ds_bpermute_b32 v8, v130, v2
	v_mul_f32_e32 v9, 0xbfb8aa3b, v13
	v_exp_f32_e32 v9, v9
	v_lshlrev_b32_e32 v14, 16, v45
	s_waitcnt lgkmcnt(0)
	v_add_f32_e32 v2, v2, v8
	ds_bpermute_b32 v8, v129, v2
	s_waitcnt lgkmcnt(0)
	v_add_f32_e32 v2, v2, v8
	v_fmamk_f32 v2, v2, 0x3c800000, v200
	v_mul_f32_e32 v8, 0x4b800000, v2
	v_cmp_gt_f32_e32 vcc, s29, v2
	s_nop 1
	v_cndmask_b32_e32 v2, v2, v8, vcc
	v_rsq_f32_e32 v2, v2
	s_nop 0
	v_mul_f32_e32 v8, 0x45800000, v2
	v_cndmask_b32_e32 v8, v2, v8, vcc
	v_lshlrev_b32_e32 v2, 11, v126
	v_lshl_add_u64 v[10:11], s[46:47], 0, v[2:3]
	v_mul_f32_e32 v2, 0xbfb8aa3b, v12
	v_exp_f32_e32 v2, v2
	v_pk_mul_f32 v[24:25], v[32:33], v[8:9] op_sel_hi:[1,0]
	v_lshl_add_u64 v[10:11], v[10:11], 0, v[62:63]
	v_lshl_add_u64 v[10:11], v[10:11], 0, v[142:143]
	v_pk_mul_f32 v[24:25], v[40:41], v[24:25]
	v_add_f32_e32 v2, 1.0, v2
	v_rcp_f32_e32 v22, v2
	v_add_f32_e32 v2, 1.0, v9
	v_rcp_f32_e32 v23, v2
	v_mul_f32_e32 v2, 0xbfb8aa3b, v14
	v_exp_f32_e32 v2, v2
	v_mul_f32_e32 v9, 0xbfb8aa3b, v15
	v_exp_f32_e32 v9, v9
	v_pk_mul_f32 v[12:13], v[22:23], v[12:13]
	v_add_f32_e32 v2, 1.0, v2
	v_rcp_f32_e32 v22, v2
	v_add_f32_e32 v2, 1.0, v9
	v_rcp_f32_e32 v23, v2
	v_pk_mul_f32 v[12:13], v[12:13], v[24:25]
	v_pk_mul_f32 v[24:25], v[26:27], v[8:9] op_sel_hi:[1,0]
	v_cvt_pk_bf16_f32 v12, v12, v13
	v_pk_mul_f32 v[24:25], v[42:43], v[24:25]
	v_pk_mul_f32 v[14:15], v[22:23], v[14:15]
	v_pk_mul_f32 v[20:21], v[20:21], v[8:9] op_sel_hi:[1,0]
	v_pk_mul_f32 v[14:15], v[14:15], v[24:25]
	v_pk_mul_f32 v[24:25], v[30:31], v[8:9] op_sel_hi:[1,0]
	v_cvt_pk_bf16_f32 v13, v14, v15
	v_mov_b64_e32 v[196:197], v[12:13]
	v_mov_b64_e32 v[22:23], v[248:249]
	s_nop 0
	v_mov_b64_e32 v[12:13], v[150:151]
	v_mov_b64_e32 v[14:15], v[152:153]
	v_mul_f32_e32 v16, v16, v8
	v_mul_f32_e32 v18, v18, v8
	v_mul_f32_e32 v4, v4, v8
	v_mul_f32_e32 v0, v0, v8
	s_waitcnt lgkmcnt(0)
; __device__ __forceinline__ unsigned pk2(float lo, float hi) { const f32x2_t v = {lo, hi}; const bf16x2_t b = __builtin_convertvector(v, bf16x2_t); return __builtin_bit_cast(unsigned, b); }
; __device__ __forceinline__ float sigmoidf_(float x) { return __builtin_amdgcn_rcpf(1.0f + __expf(-x)); }
; template <int KIND>
; __device__ __forceinline__ void w_m3_core(const bf16x8 (&Qf)[4][2], const bf16x8 (&Kf)[4][2], const bf16x8 (&Sf)[4][2], const LAS bf16_t* vT, float lg,
;                                           const bf16_t* gsrc, const float* nw, bf16_t* ydst, int lo, int fq) {
;     ...
;         for (int eb = 0; eb < 4; ++eb) { const int e0 = 16 * eb + 4 * fq;
;             const unsigned long long gw_ = *(const unsigned long long*)(gsrc + n * NIN + e0); const f32x4 w4 = *(const f32x4*)(nw + e0);
;             const float g0 = __uint_as_float((unsigned)gw_ << 16), g1 = __uint_as_float((unsigned)gw_ & 0xffff0000u), g2 = __uint_as_float((unsigned)(gw_ >> 32) << 16), g3 = __uint_as_float((unsigned)(gw_ >> 32) & 0xffff0000u);
;             const float o0 = O[eb][0] * rs * w4[0] * (g0 * sigmoidf_(g0)), o1 = O[eb][1] * rs * w4[1] * (g1 * sigmoidf_(g1));
;             const float o2 = O[eb][2] * rs * w4[2] * (g2 * sigmoidf_(g2)), o3 = O[eb][3] * rs * w4[3] * (g3 * sigmoidf_(g3));
;             *(unsigned long long*)(ydst + n * DM + e0) = (unsigned long long)pk2(o0, o1) | ((unsigned long long)pk2(o2, o3) << 32); }
	v_lshlrev_b32_e32 v26, 16, v22
	v_and_b32_e32 v27, 0xffff0000, v22
	v_lshlrev_b32_e32 v22, 16, v23
	v_and_b32_e32 v23, 0xffff0000, v23
	v_mul_f32_e32 v2, 0xbfb8aa3b, v26
	v_mul_f32_e32 v9, 0xbfb8aa3b, v27
	v_mul_f32_e32 v28, 0xbfb8aa3b, v22
	v_mul_f32_e32 v29, 0xbfb8aa3b, v23
	v_exp_f32_e32 v2, v2
	v_exp_f32_e32 v9, v9
	v_exp_f32_e32 v28, v28
	v_exp_f32_e32 v29, v29
	v_add_f32_e32 v2, 1.0, v2
	v_add_f32_e32 v9, 1.0, v9
	v_add_f32_e32 v30, 1.0, v28
	v_add_f32_e32 v31, 1.0, v29
	v_rcp_f32_e32 v28, v2
	v_rcp_f32_e32 v29, v9
	v_rcp_f32_e32 v30, v30
	v_rcp_f32_e32 v31, v31
	v_pk_mul_f32 v[12:13], v[12:13], v[20:21]
	v_pk_mul_f32 v[14:15], v[14:15], v[24:25]
	v_pk_mul_f32 v[20:21], v[28:29], v[26:27]
	v_pk_mul_f32 v[22:23], v[30:31], v[22:23]
	v_pk_mul_f32 v[12:13], v[20:21], v[12:13]
	v_pk_mul_f32 v[14:15], v[22:23], v[14:15]
	v_cvt_pk_bf16_f32 v12, v12, v13
	v_cvt_pk_bf16_f32 v13, v14, v15
	v_mov_b64_e32 v[198:199], v[12:13]
	s_nop 1
	v_permlane16_swap_b32_e32 v196, v198
	v_permlane16_swap_b32_e32 v197, v199
	global_store_dwordx4 v[10:11], v[196:199], off offset:1536
	v_mov_b64_e32 v[20:21], v[250:251]
	s_nop 0
	v_mov_b64_e32 v[12:13], v[188:189]
	v_mov_b64_e32 v[14:15], v[190:191]
	v_mul_f32_e32 v22, v17, v8
	v_mul_f32_e32 v24, v19, v8
	s_waitcnt lgkmcnt(0)
	v_lshlrev_b32_e32 v17, 16, v20
	v_and_b32_e32 v23, 0xffff0000, v20
	v_lshlrev_b32_e32 v19, 16, v21
	v_and_b32_e32 v25, 0xffff0000, v21
	v_mov_b32_e32 v20, v13
	v_mov_b32_e32 v26, v15
	v_mul_f32_e32 v2, 0xbfb8aa3b, v17
	v_mul_f32_e32 v9, 0xbfb8aa3b, v23
	v_mul_f32_e32 v13, 0xbfb8aa3b, v19
	v_mul_f32_e32 v15, 0xbfb8aa3b, v25
	v_exp_f32_e32 v2, v2
	v_exp_f32_e32 v9, v9
	v_exp_f32_e32 v13, v13
	v_exp_f32_e32 v15, v15
	v_add_f32_e32 v2, 1.0, v2
	v_add_f32_e32 v9, 1.0, v9
	v_add_f32_e32 v27, 1.0, v13
	v_add_f32_e32 v28, 1.0, v15
	v_rcp_f32_e32 v13, v2
	v_rcp_f32_e32 v21, v9
	v_rcp_f32_e32 v15, v27
	v_rcp_f32_e32 v27, v28
	v_pk_mul_f32 v[12:13], v[12:13], v[16:17]
	v_pk_mul_f32 v[16:17], v[20:21], v[22:23]
	v_pk_mul_f32 v[14:15], v[14:15], v[18:19]
	v_pk_mul_f32 v[18:19], v[26:27], v[24:25]
	v_mov_b32_e32 v20, v12
	v_mov_b32_e32 v21, v16
	v_mov_b32_e32 v16, v13
	v_mov_b32_e32 v12, v14
	v_mov_b32_e32 v13, v18
	v_mov_b32_e32 v18, v15
	v_pk_mul_f32 v[14:15], v[20:21], v[16:17]
	v_pk_mul_f32 v[12:13], v[12:13], v[18:19]
	v_cvt_pk_bf16_f32 v14, v14, v15
	v_cvt_pk_bf16_f32 v15, v12, v13
	v_mov_b64_e32 v[196:197], v[14:15]
	v_mov_b64_e32 v[6:7], v[252:253]
	s_nop 0
	v_mov_b64_e32 v[12:13], v[192:193]
	v_mov_b64_e32 v[14:15], v[194:195]
	v_mul_f32_e32 v16, v5, v8
	v_mul_f32_e32 v8, v1, v8
	s_waitcnt lgkmcnt(0)
	v_lshlrev_b32_e32 v5, 16, v6
	v_and_b32_e32 v17, 0xffff0000, v6
	v_lshlrev_b32_e32 v1, 16, v7
	v_and_b32_e32 v9, 0xffff0000, v7
	v_mov_b32_e32 v6, v12
	v_mov_b32_e32 v12, v13
	v_mov_b32_e32 v18, v15
	v_mul_f32_e32 v2, 0xbfb8aa3b, v5
	v_mul_f32_e32 v7, 0xbfb8aa3b, v17
	v_mul_f32_e32 v13, 0xbfb8aa3b, v1
	v_mul_f32_e32 v15, 0xbfb8aa3b, v9
	v_exp_f32_e32 v2, v2
	v_exp_f32_e32 v7, v7
	v_exp_f32_e32 v13, v13
	v_exp_f32_e32 v15, v15
	v_add_f32_e32 v2, 1.0, v2
	v_add_f32_e32 v19, 1.0, v7
	v_add_f32_e32 v20, 1.0, v13
	v_add_f32_e32 v21, 1.0, v15
	v_rcp_f32_e32 v7, v2
	v_rcp_f32_e32 v13, v19
	v_rcp_f32_e32 v15, v20
	v_rcp_f32_e32 v19, v21
	v_pk_mul_f32 v[4:5], v[6:7], v[4:5]
	v_pk_mul_f32 v[6:7], v[12:13], v[16:17]
	v_pk_mul_f32 v[0:1], v[14:15], v[0:1]
	v_pk_mul_f32 v[8:9], v[18:19], v[8:9]
	v_mov_b32_e32 v12, v4
	v_mov_b32_e32 v13, v6
	v_mov_b32_e32 v6, v5
	v_mov_b32_e32 v4, v0
	v_mov_b32_e32 v5, v8
	v_mov_b32_e32 v8, v1
	v_pk_mul_f32 v[0:1], v[12:13], v[6:7]
	v_pk_mul_f32 v[4:5], v[4:5], v[8:9]
	v_cvt_pk_bf16_f32 v0, v0, v1
	v_cvt_pk_bf16_f32 v1, v4, v5
	v_mov_b64_e32 v[198:199], v[0:1]
	s_nop 1
	v_permlane16_swap_b32_e32 v196, v198
	v_permlane16_swap_b32_e32 v197, v199
	global_store_dwordx4 v[10:11], v[196:199], off offset:1600
	s_waitcnt lgkmcnt(0)

; __device__ __forceinline__ void ld8bf(const bf16_t* p, float (&o)[8]) { unpack8(*(const u32x4*)p, o); }
; __device__ __forceinline__ const float* in_ptr(const Args& a, int i) { asm volatile("" : "+s"(i)); return a.in[i]; }
; __device__ __forceinline__ void w_lru_m1(const Args& a, int l, unsigned char* ws, const bf16_t* proj, bf16_t* y, LAS unsigned char* wl, int b, int ck_, int h, int lane) {
;     ...
;     const float* cw = in_ptr(a, I_LCW) + (size_t)l * 4 * 512; const float* cbias = in_ptr(a, I_LCB) + l * 512;
;     const bf16_t* gwt = (const bf16_t*)(ws + WS_GATE) + (size_t)l * 65536;
;     const bf16_t* waT = gwt + h * 4096; const bf16_t* wxT = gwt + 32768 + h * 4096;
;     const float* ba = in_ptr(a, I_BA) + l * 512 + 64 * h; const float* bx = in_ptr(a, I_BX) + l * 512 + 64 * h; const float* lam = in_ptr(a, I_LAM) + l * 512 + 64 * h;
;     bf16x8 nWa[2], nWx[2]; f32x4 nba, nbx, nlam;
; #pragma unroll
;     for (int kk = 0; kk < 2; ++kk) { nWa[kk] = *(const bf16x8*)(waT + lo * 64 + 32 * kk + 8 * fq); nWx[kk] = *(const bf16x8*)(wxT + lo * 64 + 32 * kk + 8 * fq); }
;     nba = *(const f32x4*)(ba + 4 * fq); nbx = *(const f32x4*)(bx + 4 * fq); nlam = *(const f32x4*)(lam + 4 * fq);
;     bf16x8 Xf[4][2];
; #pragma unroll
;     for (int kk = 0; kk < 2; ++kk) { const int ch0 = 64 * h + 32 * kk + 8 * fq; float w[4][8], bs[8];
; #pragma unroll
;         for (int j = 0; j < 8; ++j) { bs[j] = cbias[ch0 + j];
; #pragma unroll
;             for (int k = 0; k < 4; ++k) w[k][j] = cw[k * 512 + ch0 + j]; }
; #pragma unroll
;         for (int tb = 0; tb < 4; ++tb) { const int tok = 16 * tb + lo, t = 64 * ck_ + tok; float s[8];
; #pragma unroll
;             for (int j = 0; j < 8; ++j) s[j] = bs[j];
; #pragma unroll
;             for (int k = 0; k < 4; ++k) { const int tt = t - 3 + k; float x[8];
;                 ld8bf(proj + (size_t)(b * SEQ + (tt >= 0 ? tt : 0)) * NIN + C_LX + ch0, x);
.LBB0_520:
	s_lshr_b32 s20, s24, 8
	s_lshr_b32 s21, s24, 9
	s_add_i32 s20, s20, s24
	s_and_b32 s21, s21, 12
	s_add_i32 s20, s20, s21
	s_and_b32 s91, s20, 15
	s_cmp_gt_u32 s91, 7
	s_cbranch_scc1 .LBB0_519
	s_ashr_i32 s20, s24, 31
	s_ashr_i32 s90, s24, 4
	s_lshr_b32 s20, s20, 25
	s_add_i32 s27, s90, s20
	s_and_b32 s20, s27, 0xffffff80
	v_mov_b32_e32 v122, v144
	s_mov_b32 s34, 3
	s_sub_i32 s46, s90, s20
	s_ashr_i32 s35, s34, 31
	s_lshl_b32 s20, s46, 6
	s_lshl_b64 s[34:35], s[34:35], 3
	s_add_u32 s34, s0, s34
	s_addc_u32 s35, s1, s35
	s_load_dwordx2 s[40:41], s[34:35], 0x0
	s_mov_b32 s34, 4
	s_ashr_i32 s35, s34, 31
	s_lshl_b64 s[34:35], s[34:35], 3
	s_add_u32 s34, s0, s34
	s_addc_u32 s35, s1, s35
	s_lshl_b32 s21, s91, 13
	s_add_u32 s92, s2, s21
	s_addc_u32 s93, s3, 0
	s_load_dwordx2 s[42:43], s[34:35], 0x0
	s_add_u32 s34, s68, s21
	s_mov_b32 s44, 6
	s_addc_u32 s35, s70, 0
	s_ashr_i32 s45, s44, 31
	s_lshl_b64 s[44:45], s[44:45], 3
	s_add_u32 s44, s0, s44
	s_addc_u32 s45, s1, s45
	s_waitcnt lgkmcnt(0)
	s_mov_b32 s48, 8
	s_load_dwordx2 s[44:45], s[44:45], 0x0
	s_ashr_i32 s49, s48, 31
	s_lshl_b32 s21, s91, 6
	s_lshl_b64 s[48:49], s[48:49], 3
	s_add_u32 s48, s0, s48
	s_addc_u32 s49, s1, s49
	s_load_dwordx2 s[48:49], s[48:49], 0x0
	v_ashrrev_i32_e32 v8, 4, v122
	v_and_b32_e32 v136, 15, v122
	v_lshlrev_b32_e32 v4, 3, v8
	v_lshlrev_b32_e32 v2, 7, v136
	s_waitcnt lgkmcnt(0)
	s_add_u32 s47, s48, s88
	s_mov_b32 s48, 9
	s_addc_u32 s50, s49, s89
	s_ashr_i32 s49, s48, 31
	s_lshl_b64 s[48:49], s[48:49], 3
	s_add_u32 s48, s0, s48
	s_addc_u32 s49, s1, s49
	s_add_u32 s48, s78, 0x3b00000
	s_addc_u32 s49, s79, 0x0
	v_ashrrev_i32_e32 v5, 31, v4
	v_lshl_add_u64 v[0:1], s[92:93], 0, v[2:3]
	v_lshlrev_b64 v[100:101], 1, v[4:5]
	v_lshl_add_u64 v[0:1], v[0:1], 0, v[100:101]
	s_waitcnt lgkmcnt(0)
	s_add_u32 s51, s48, s88
	s_addc_u32 s52, s49, s89
	s_lshl_b32 s27, s27, 6
	s_and_b32 s27, s27, 0xffffe000
	s_add_u32 s48, s40, s96
	s_addc_u32 s49, s41, s97
	s_add_u32 s42, s42, s88
	s_addc_u32 s43, s43, s89
	s_add_u32 s40, s44, s88
	s_addc_u32 s41, s45, s89
	s_lshl_b32 s53, s91, 8
	s_add_u32 s40, s40, s53
	v_lshl_add_u64 v[6:7], s[34:35], 0, v[2:3]
	s_addc_u32 s41, s41, 0
	v_lshl_add_u64 v[6:7], v[6:7], 0, v[100:101]
	flat_load_dwordx4 v[52:55], v[0:1]
	flat_load_dwordx4 v[56:59], v[6:7]
	flat_load_dwordx4 v[60:63], v[0:1] offset:64
	flat_load_dwordx4 v[64:67], v[6:7] offset:64
	s_add_u32 s44, s47, s53
	v_lshlrev_b32_e32 v0, 2, v8
	s_addc_u32 s45, s50, 0
	v_ashrrev_i32_e32 v1, 31, v0
	s_add_u32 s50, s51, s53
	v_lshlrev_b64 v[6:7], 2, v[0:1]
	s_addc_u32 s51, s52, 0
	v_lshl_add_u64 v[108:109], s[40:41], 0, v[6:7]
	s_add_i32 s40, s20, -3
	v_add_u32_e32 v78, s21, v4
	v_lshl_add_u64 v[110:111], s[44:45], 0, v[6:7]
	v_lshl_add_u64 v[112:113], s[50:51], 0, v[6:7]
	v_ashrrev_i32_e32 v79, 31, v78
	v_add_u32_e32 v6, s40, v136
	v_lshlrev_b64 v[4:5], 2, v[78:79]
	v_cmp_lt_i32_e64 s[50:51], -1, v6
	v_lshl_add_u64 v[76:77], s[42:43], 0, v[4:5]
	v_lshl_add_u64 v[86:87], s[48:49], 0, v[4:5]
	s_mov_b64 s[42:43], 0x1000
	v_cndmask_b32_e64 v4, 0, v6, s[50:51]
	v_lshl_add_u64 v[36:37], v[86:87], 0, s[42:43]
	s_mov_b64 s[42:43], 0x1800
	v_lshl_add_u64 v[80:81], v[78:79], 1, s[8:9]
	v_add_u32_e32 v79, s27, v4
	v_lshl_add_u64 v[82:83], v[86:87], 0, s[42:43]
	v_max_i32_e32 v4, -1, v6
	s_or_b32 s80, s27, 1
	v_add_u32_e32 v92, s80, v4
	v_max_i32_e32 v4, -2, v6
	s_or_b32 s81, s27, 2
	v_add_u32_e32 v93, s81, v4
	s_cmp_gt_i32 s46, -1
	v_or_b32_e32 v4, s20, v136
	s_cselect_b64 s[42:43], -1, 0
	v_cndmask_b32_e64 v4, 0, v4, s[42:43]
	v_add_u32_e32 v94, s27, v4
	global_load_dwordx4 v[48:51], v[108:109], off
	global_load_dwordx4 v[44:47], v[110:111], off
	global_load_dwordx4 v[88:91], v[112:113], off
	v_lshl_add_u32 v95, v8, 5, s6
	v_cmp_lt_i32_e64 s[48:49], -2, v6
	v_cmp_lt_i32_e64 s[44:45], -3, v6
	global_load_dwordx4 v[20:23], v[76:77], off offset:16
	s_nop 0
	global_load_dwordx4 v[4:7], v[76:77], off
	global_load_dwordx4 v[24:27], v[86:87], off offset:16
	global_load_dwordx4 v[32:35], v[86:87], off
	global_load_dwordx4 v[28:31], v[86:87], off offset:2064
	global_load_dwordx4 v[40:43], v[86:87], off offset:2048
	v_add_co_u32_e32 v96, vcc, s73, v86
	v_mad_u32_u24 v121, v136, s76, v95
	s_nop 0
	v_addc_co_u32_e32 v97, vcc, 0, v87, vcc
	global_load_dwordx4 v[68:71], v[96:97], off
	s_nop 0
	global_load_dwordx4 v[36:39], v[36:37], off offset:16
	s_nop 0
	global_load_dwordx4 v[104:107], v[96:97], off offset:2048
	global_load_dwordx4 v[114:117], v[82:83], off offset:16
	v_add_u32_e32 v186, s20, v136
	v_add_u32_e32 v187, -16, v186
	v_max_i32_e32 v187, 0, v187
	v_add_u32_e32 v187, s27, v187
	v_add_u32_e32 v186, s27, v186
	v_mad_i64_i32 v[188:189], s[46:47], v187, s72, v[80:81]
	global_load_dwordx4 v[222:225], v[188:189], off
	global_load_dwordx4 v[242:245], v[188:189], off offset:64
	v_mad_i64_i32 v[188:189], s[46:47], v186, s72, v[80:81]
	global_load_dwordx4 v[226:229], v[188:189], off
	global_load_dwordx4 v[246:249], v[188:189], off offset:64
	v_add_u32_e32 v187, 16, v186
	v_mad_i64_i32 v[188:189], s[46:47], v187, s72, v[80:81]
	global_load_dwordx4 v[230:233], v[188:189], off
	global_load_dwordx4 v[250:253], v[188:189], off offset:64
	v_add_u32_e32 v187, 32, v186
	v_mad_i64_i32 v[188:189], s[46:47], v187, s72, v[80:81]
	global_load_dwordx4 v[234:237], v[188:189], off
	global_load_dwordx4 v[190:193], v[188:189], off offset:64
	v_add_u32_e32 v187, 48, v186
	v_mad_i64_i32 v[188:189], s[46:47], v187, s72, v[80:81]
	global_load_dwordx4 v[238:241], v[188:189], off
	global_load_dwordx4 v[194:197], v[188:189], off offset:64
	v_or_b32_e32 v140, 16, v136
	v_or_b32_e32 v139, 32, v136
	v_or_b32_e32 v137, 48, v136
	v_mov_b64_e32 v[102:103], s[8:9]
	s_waitcnt vmcnt(0) lgkmcnt(0)
; __device__ __forceinline__ void ld8bf(const bf16_t* p, float (&o)[8]) { unpack8(*(const u32x4*)p, o); }
; __device__ __forceinline__ bf16x8 pack_frag(const float (&v)[8]) { return __builtin_bit_cast(bf16x8, pack8(v)); }
; __device__ __forceinline__ void w_lru_m1(const Args& a, int l, unsigned char* ws, const bf16_t* proj, bf16_t* y, LAS unsigned char* wl, int b, int ck_, int h, int lane) {
;     ...
;         for (int tb = 0; tb < 4; ++tb) { const int tok = 16 * tb + lo, t = 64 * ck_ + tok; float s[8];
; #pragma unroll
;             for (int j = 0; j < 8; ++j) s[j] = bs[j];
; #pragma unroll
;             for (int k = 0; k < 4; ++k) { const int tt = t - 3 + k; float x[8];
;                 ld8bf(proj + (size_t)(b * SEQ + (tt >= 0 ? tt : 0)) * NIN + C_LX + ch0, x);
; #pragma unroll
;                 for (int j = 0; j < 8; ++j) s[j] += (tt >= 0 ? w[k][j] : 0.f) * x[j]; }
;             Xf[tb][kk] = pack_frag(s);
; #pragma unroll
;             for (int j = 0; j < 8; ++j) xcf[tok * 65 + 32 * kk + 8 * fq + j] = s[j]; }
	v_mov_b32_dpp v72, v222 row_ror:3 row_mask:0xf bank_mask:0xf
	v_mov_b32_dpp v73, v223 row_ror:3 row_mask:0xf bank_mask:0xf
	v_mov_b32_dpp v74, v224 row_ror:3 row_mask:0xf bank_mask:0xf
	v_mov_b32_dpp v75, v225 row_ror:3 row_mask:0xf bank_mask:0xf
	v_mov_b32_dpp v72, v226 row_shr:3 row_mask:0xf bank_mask:0xf
	v_mov_b32_dpp v73, v227 row_shr:3 row_mask:0xf bank_mask:0xf
	v_mov_b32_dpp v74, v228 row_shr:3 row_mask:0xf bank_mask:0xf
	v_mov_b32_dpp v75, v229 row_shr:3 row_mask:0xf bank_mask:0xf
	v_mov_b32_dpp v16, v222 row_ror:2 row_mask:0xf bank_mask:0xf
	v_mov_b32_dpp v17, v223 row_ror:2 row_mask:0xf bank_mask:0xf
	v_mov_b32_dpp v18, v224 row_ror:2 row_mask:0xf bank_mask:0xf
	v_mov_b32_dpp v19, v225 row_ror:2 row_mask:0xf bank_mask:0xf
	v_mov_b32_dpp v16, v226 row_shr:2 row_mask:0xf bank_mask:0xf
	v_mov_b32_dpp v17, v227 row_shr:2 row_mask:0xf bank_mask:0xf
	v_mov_b32_dpp v18, v228 row_shr:2 row_mask:0xf bank_mask:0xf
	v_mov_b32_dpp v19, v229 row_shr:2 row_mask:0xf bank_mask:0xf
	v_mov_b32_dpp v12, v222 row_ror:1 row_mask:0xf bank_mask:0xf
	v_mov_b32_dpp v13, v223 row_ror:1 row_mask:0xf bank_mask:0xf
	v_mov_b32_dpp v14, v224 row_ror:1 row_mask:0xf bank_mask:0xf
	v_mov_b32_dpp v15, v225 row_ror:1 row_mask:0xf bank_mask:0xf
	v_mov_b32_dpp v12, v226 row_shr:1 row_mask:0xf bank_mask:0xf
	v_mov_b32_dpp v13, v227 row_shr:1 row_mask:0xf bank_mask:0xf
	v_mov_b32_dpp v14, v228 row_shr:1 row_mask:0xf bank_mask:0xf
	v_mov_b32_dpp v15, v229 row_shr:1 row_mask:0xf bank_mask:0xf
	v_mov_b64_e32 v[8:9], v[226:227]
	v_mov_b64_e32 v[10:11], v[228:229]
	v_lshlrev_b32_e32 v82, 16, v72
	v_lshlrev_b32_e32 v84, 16, v73
	v_and_b32_e32 v83, 0xffff0000, v72
	v_and_b32_e32 v85, 0xffff0000, v73
	v_cndmask_b32_e64 v73, 0, v33, s[50:51]
	v_cndmask_b32_e64 v72, 0, v32, s[50:51]
	v_cndmask_b32_e64 v99, 0, v35, s[50:51]
	v_cndmask_b32_e64 v98, 0, v34, s[50:51]
	v_pk_fma_f32 v[84:85], v[98:99], v[84:85], v[6:7]
	v_pk_fma_f32 v[72:73], v[72:73], v[82:83], v[4:5]
	v_lshlrev_b32_e32 v82, 16, v17
	v_lshlrev_b32_e32 v98, 16, v16
	v_and_b32_e32 v83, 0xffff0000, v17
	v_and_b32_e32 v99, 0xffff0000, v16
	v_cndmask_b32_e64 v17, 0, v43, s[48:49]
	v_cndmask_b32_e64 v16, 0, v42, s[48:49]
	v_cndmask_b32_e64 v119, 0, v41, s[48:49]
	v_cndmask_b32_e64 v118, 0, v40, s[48:49]
	v_pk_fma_f32 v[72:73], v[118:119], v[98:99], v[72:73]
	v_pk_fma_f32 v[16:17], v[16:17], v[82:83], v[84:85]
	v_lshlrev_b32_e32 v82, 16, v12
	v_lshlrev_b32_e32 v84, 16, v13
	v_and_b32_e32 v83, 0xffff0000, v12
	v_and_b32_e32 v85, 0xffff0000, v13
	v_cndmask_b32_e64 v13, 0, v69, s[44:45]
	v_cndmask_b32_e64 v12, 0, v68, s[44:45]
	v_cndmask_b32_e64 v99, 0, v71, s[44:45]
	v_cndmask_b32_e64 v98, 0, v70, s[44:45]
	v_pk_fma_f32 v[16:17], v[98:99], v[84:85], v[16:17]
	v_pk_fma_f32 v[12:13], v[12:13], v[82:83], v[72:73]
	v_lshlrev_b32_e32 v84, 16, v9
	v_lshlrev_b32_e32 v98, 16, v8
	v_and_b32_e32 v85, 0xffff0000, v9
	v_and_b32_e32 v99, 0xffff0000, v8
	v_cndmask_b32_e64 v73, 0, v107, s[42:43]
	v_cndmask_b32_e64 v72, 0, v106, s[42:43]
	v_cndmask_b32_e64 v83, 0, v105, s[42:43]
	v_cndmask_b32_e64 v82, 0, v104, s[42:43]
	v_pk_fma_f32 v[8:9], v[82:83], v[98:99], v[12:13]
	v_pk_fma_f32 v[12:13], v[72:73], v[84:85], v[16:17]
	v_cvt_pk_bf16_f32 v16, v8, v9
	v_cvt_pk_bf16_f32 v17, v12, v13
	ds_write2_b32 v121, v12, v13 offset0:2 offset1:3
	ds_write2_b32 v121, v8, v9 offset1:1
	v_lshlrev_b32_e32 v8, 16, v74
	v_lshlrev_b32_e32 v12, 16, v75
	v_and_b32_e32 v9, 0xffff0000, v74
	v_and_b32_e32 v13, 0xffff0000, v75
	v_cndmask_b32_e64 v75, 0, v25, s[50:51]
	v_cndmask_b32_e64 v74, 0, v24, s[50:51]
	v_cndmask_b32_e64 v85, 0, v27, s[50:51]
	v_cndmask_b32_e64 v84, 0, v26, s[50:51]
	v_pk_fma_f32 v[12:13], v[84:85], v[12:13], v[22:23]
	v_pk_fma_f32 v[8:9], v[74:75], v[8:9], v[20:21]
	v_lshlrev_b32_e32 v74, 16, v19
	v_lshlrev_b32_e32 v84, 16, v18
	v_and_b32_e32 v75, 0xffff0000, v19
	v_and_b32_e32 v85, 0xffff0000, v18
	v_cndmask_b32_e64 v19, 0, v31, s[48:49]
	v_cndmask_b32_e64 v18, 0, v30, s[48:49]
	v_cndmask_b32_e64 v99, 0, v29, s[48:49]
	v_cndmask_b32_e64 v98, 0, v28, s[48:49]
	v_pk_fma_f32 v[8:9], v[98:99], v[84:85], v[8:9]
	v_pk_fma_f32 v[12:13], v[18:19], v[74:75], v[12:13]
	v_lshlrev_b32_e32 v18, 16, v14
	v_lshlrev_b32_e32 v74, 16, v15
	v_and_b32_e32 v19, 0xffff0000, v14
	v_and_b32_e32 v75, 0xffff0000, v15
	v_cndmask_b32_e64 v15, 0, v37, s[44:45]
	v_cndmask_b32_e64 v14, 0, v36, s[44:45]
	v_cndmask_b32_e64 v85, 0, v39, s[44:45]
	v_cndmask_b32_e64 v84, 0, v38, s[44:45]
	v_pk_fma_f32 v[12:13], v[84:85], v[74:75], v[12:13]
	v_pk_fma_f32 v[8:9], v[14:15], v[18:19], v[8:9]
	v_lshlrev_b32_e32 v14, 16, v11
	v_lshlrev_b32_e32 v18, 16, v10
	v_and_b32_e32 v15, 0xffff0000, v11
	v_and_b32_e32 v19, 0xffff0000, v10
	v_cndmask_b32_e64 v75, 0, v117, s[42:43]
	v_cndmask_b32_e64 v74, 0, v116, s[42:43]
	v_cndmask_b32_e64 v85, 0, v115, s[42:43]
	v_cndmask_b32_e64 v84, 0, v114, s[42:43]
	v_add_u32_e32 v98, s40, v140
	v_pk_fma_f32 v[8:9], v[84:85], v[18:19], v[8:9]
	v_pk_fma_f32 v[10:11], v[74:75], v[14:15], v[12:13]
	v_cmp_lt_i32_e64 s[62:63], -1, v98
	v_cvt_pk_bf16_f32 v18, v8, v9
	ds_write2_b32 v121, v10, v11 offset0:6 offset1:7
	ds_write2_b32 v121, v8, v9 offset0:4 offset1:5
	v_cndmask_b32_e64 v8, 0, v98, s[62:63]
	v_cmp_lt_i32_e64 s[60:61], -2, v98
	v_max_i32_e32 v12, -1, v98
	v_cmp_lt_i32_e64 s[58:59], -3, v98
	v_max_i32_e32 v98, -2, v98
	v_add_u32_e32 v142, s81, v98
	v_add_u32_e32 v134, s27, v8
	v_add_u32_e32 v135, s80, v12
	v_mov_b32_dpp v104, v226 row_ror:1 row_mask:0xf bank_mask:0xf
	v_mov_b32_dpp v105, v227 row_ror:1 row_mask:0xf bank_mask:0xf
	v_mov_b32_dpp v106, v228 row_ror:1 row_mask:0xf bank_mask:0xf
	v_mov_b32_dpp v107, v229 row_ror:1 row_mask:0xf bank_mask:0xf
; __device__ __forceinline__ void ld8bf(const bf16_t* p, float (&o)[8]) { unpack8(*(const u32x4*)p, o); }
; __device__ __forceinline__ bf16x8 pack_frag(const float (&v)[8]) { return __builtin_bit_cast(bf16x8, pack8(v)); }
; __device__ __forceinline__ void w_lru_m1(const Args& a, int l, unsigned char* ws, const bf16_t* proj, bf16_t* y, LAS unsigned char* wl, int b, int ck_, int h, int lane) {
;     ...
;         for (int tb = 0; tb < 4; ++tb) { const int tok = 16 * tb + lo, t = 64 * ck_ + tok; float s[8];
; #pragma unroll
;             for (int j = 0; j < 8; ++j) s[j] = bs[j];
; #pragma unroll
;             for (int k = 0; k < 4; ++k) { const int tt = t - 3 + k; float x[8];
;                 ld8bf(proj + (size_t)(b * SEQ + (tt >= 0 ? tt : 0)) * NIN + C_LX + ch0, x);
; #pragma unroll
;                 for (int j = 0; j < 8; ++j) s[j] += (tt >= 0 ? w[k][j] : 0.f) * x[j]; }
;             Xf[tb][kk] = pack_frag(s);
; #pragma unroll
;             for (int j = 0; j < 8; ++j) xcf[tok * 65 + 32 * kk + 8 * fq + j] = s[j]; }
	v_mov_b32_dpp v104, v230 row_shr:1 row_mask:0xf bank_mask:0xf
	v_mov_b32_dpp v105, v231 row_shr:1 row_mask:0xf bank_mask:0xf
	v_mov_b32_dpp v106, v232 row_shr:1 row_mask:0xf bank_mask:0xf
	v_mov_b32_dpp v107, v233 row_shr:1 row_mask:0xf bank_mask:0xf
	v_or_b32_e32 v98, s20, v140
	v_cvt_pk_bf16_f32 v19, v10, v11
	v_mov_b32_dpp v8, v226 row_ror:3 row_mask:0xf bank_mask:0xf
	v_mov_b32_dpp v9, v227 row_ror:3 row_mask:0xf bank_mask:0xf
	v_mov_b32_dpp v10, v228 row_ror:3 row_mask:0xf bank_mask:0xf
	v_mov_b32_dpp v11, v229 row_ror:3 row_mask:0xf bank_mask:0xf
	v_mov_b32_dpp v8, v230 row_shr:3 row_mask:0xf bank_mask:0xf
	v_mov_b32_dpp v9, v231 row_shr:3 row_mask:0xf bank_mask:0xf
	v_mov_b32_dpp v10, v232 row_shr:3 row_mask:0xf bank_mask:0xf
	v_mov_b32_dpp v11, v233 row_shr:3 row_mask:0xf bank_mask:0xf
	v_cndmask_b32_e64 v98, 0, v98, s[42:43]
	v_mov_b32_dpp v12, v226 row_ror:2 row_mask:0xf bank_mask:0xf
	v_mov_b32_dpp v13, v227 row_ror:2 row_mask:0xf bank_mask:0xf
	v_mov_b32_dpp v14, v228 row_ror:2 row_mask:0xf bank_mask:0xf
	v_mov_b32_dpp v15, v229 row_ror:2 row_mask:0xf bank_mask:0xf
	v_mov_b32_dpp v12, v230 row_shr:2 row_mask:0xf bank_mask:0xf
	v_mov_b32_dpp v13, v231 row_shr:2 row_mask:0xf bank_mask:0xf
	v_mov_b32_dpp v14, v232 row_shr:2 row_mask:0xf bank_mask:0xf
	v_mov_b32_dpp v15, v233 row_shr:2 row_mask:0xf bank_mask:0xf
	v_add_u32_e32 v143, s27, v98
	v_mov_b64_e32 v[114:115], v[230:231]
	v_mov_b64_e32 v[116:117], v[232:233]
	v_mov_b32_e32 v98, 0x1040
	v_mad_u32_u24 v123, v136, s76, v98
	v_cndmask_b32_e64 v127, 0, v35, s[62:63]
	v_cndmask_b32_e64 v126, 0, v34, s[62:63]
	v_cndmask_b32_e64 v129, 0, v41, s[60:61]
	v_cndmask_b32_e64 v128, 0, v40, s[60:61]
	v_add_u32_e32 v125, v95, v123
	s_waitcnt vmcnt(0) lgkmcnt(0)
	v_lshlrev_b32_e32 v98, 16, v8
	v_lshlrev_b32_e32 v118, 16, v9
	v_and_b32_e32 v99, 0xffff0000, v8
	v_and_b32_e32 v119, 0xffff0000, v9
	v_cndmask_b32_e64 v9, 0, v33, s[62:63]
	v_cndmask_b32_e64 v8, 0, v32, s[62:63]
	v_pk_fma_f32 v[118:119], v[126:127], v[118:119], v[6:7]
	v_pk_fma_f32 v[8:9], v[8:9], v[98:99], v[4:5]
	v_lshlrev_b32_e32 v98, 16, v13
	v_lshlrev_b32_e32 v126, 16, v12
	v_and_b32_e32 v99, 0xffff0000, v13
	v_and_b32_e32 v127, 0xffff0000, v12
	v_cndmask_b32_e64 v13, 0, v43, s[60:61]
	v_cndmask_b32_e64 v12, 0, v42, s[60:61]
	v_pk_fma_f32 v[8:9], v[128:129], v[126:127], v[8:9]
	v_pk_fma_f32 v[12:13], v[12:13], v[98:99], v[118:119]
	v_lshlrev_b32_e32 v98, 16, v104
	v_lshlrev_b32_e32 v118, 16, v105
	v_and_b32_e32 v99, 0xffff0000, v104
	v_and_b32_e32 v119, 0xffff0000, v105
	v_cndmask_b32_e64 v105, 0, v69, s[58:59]
	v_cndmask_b32_e64 v104, 0, v68, s[58:59]
	v_cndmask_b32_e64 v127, 0, v71, s[58:59]
	v_cndmask_b32_e64 v126, 0, v70, s[58:59]
	v_pk_fma_f32 v[12:13], v[126:127], v[118:119], v[12:13]
	v_pk_fma_f32 v[8:9], v[104:105], v[98:99], v[8:9]
	v_lshlrev_b32_e32 v98, 16, v115
	v_lshlrev_b32_e32 v104, 16, v114
	v_and_b32_e32 v99, 0xffff0000, v115
	v_and_b32_e32 v105, 0xffff0000, v114
	v_pk_fma_f32 v[8:9], v[82:83], v[104:105], v[8:9]
	v_pk_fma_f32 v[98:99], v[72:73], v[98:99], v[12:13]
	v_cvt_pk_bf16_f32 v12, v8, v9
	v_cvt_pk_bf16_f32 v13, v98, v99
	ds_write2_b32 v125, v98, v99 offset0:2 offset1:3
	ds_write2_b32 v125, v8, v9 offset1:1
	v_lshlrev_b32_e32 v8, 16, v10
	v_lshlrev_b32_e32 v98, 16, v11
	v_and_b32_e32 v9, 0xffff0000, v10
	v_and_b32_e32 v99, 0xffff0000, v11
	v_cndmask_b32_e64 v11, 0, v25, s[62:63]
	v_cndmask_b32_e64 v10, 0, v24, s[62:63]
	v_cndmask_b32_e64 v105, 0, v27, s[62:63]
	v_cndmask_b32_e64 v104, 0, v26, s[62:63]
	v_pk_fma_f32 v[98:99], v[104:105], v[98:99], v[22:23]
	v_pk_fma_f32 v[8:9], v[10:11], v[8:9], v[20:21]
	v_lshlrev_b32_e32 v10, 16, v15
	v_lshlrev_b32_e32 v104, 16, v14
	v_and_b32_e32 v11, 0xffff0000, v15
	v_and_b32_e32 v105, 0xffff0000, v14
	v_cndmask_b32_e64 v15, 0, v31, s[60:61]
	v_cndmask_b32_e64 v14, 0, v30, s[60:61]
	v_cndmask_b32_e64 v115, 0, v29, s[60:61]
	v_cndmask_b32_e64 v114, 0, v28, s[60:61]
	v_pk_fma_f32 v[8:9], v[114:115], v[104:105], v[8:9]
	v_pk_fma_f32 v[10:11], v[14:15], v[10:11], v[98:99]
	v_lshlrev_b32_e32 v14, 16, v106
	v_lshlrev_b32_e32 v98, 16, v107
	v_and_b32_e32 v15, 0xffff0000, v106
	v_and_b32_e32 v99, 0xffff0000, v107
	v_cndmask_b32_e64 v105, 0, v37, s[58:59]
	v_cndmask_b32_e64 v104, 0, v36, s[58:59]
	v_cndmask_b32_e64 v107, 0, v39, s[58:59]
	v_cndmask_b32_e64 v106, 0, v38, s[58:59]
	v_pk_fma_f32 v[10:11], v[106:107], v[98:99], v[10:11]
	v_pk_fma_f32 v[8:9], v[104:105], v[14:15], v[8:9]
	v_lshlrev_b32_e32 v14, 16, v117
	v_lshlrev_b32_e32 v98, 16, v116
	v_and_b32_e32 v15, 0xffff0000, v117
	v_and_b32_e32 v99, 0xffff0000, v116
	v_add_u32_e32 v114, s40, v139
	v_pk_fma_f32 v[8:9], v[84:85], v[98:99], v[8:9]
	v_pk_fma_f32 v[10:11], v[74:75], v[14:15], v[10:11]
	v_cmp_lt_i32_e64 s[56:57], -1, v114
	v_cvt_pk_bf16_f32 v14, v8, v9
	ds_write2_b32 v125, v10, v11 offset0:6 offset1:7
	ds_write2_b32 v125, v8, v9 offset0:4 offset1:5
	v_cndmask_b32_e64 v8, 0, v114, s[56:57]
	v_max_i32_e32 v98, -1, v114
	v_add_u32_e32 v130, s27, v8
	v_add_u32_e32 v131, s80, v98
	v_cvt_pk_bf16_f32 v15, v10, v11
	v_mov_b32_dpp v8, v230 row_ror:3 row_mask:0xf bank_mask:0xf
	v_mov_b32_dpp v9, v231 row_ror:3 row_mask:0xf bank_mask:0xf
	v_mov_b32_dpp v10, v232 row_ror:3 row_mask:0xf bank_mask:0xf
	v_mov_b32_dpp v11, v233 row_ror:3 row_mask:0xf bank_mask:0xf
	v_mov_b32_dpp v8, v234 row_shr:3 row_mask:0xf bank_mask:0xf
	v_mov_b32_dpp v9, v235 row_shr:3 row_mask:0xf bank_mask:0xf
	v_mov_b32_dpp v10, v236 row_shr:3 row_mask:0xf bank_mask:0xf
	v_mov_b32_dpp v11, v237 row_shr:3 row_mask:0xf bank_mask:0xf
	v_cmp_lt_i32_e64 s[54:55], -2, v114
	v_mov_b32_dpp v104, v230 row_ror:2 row_mask:0xf bank_mask:0xf
; __device__ __forceinline__ void ld8bf(const bf16_t* p, float (&o)[8]) { unpack8(*(const u32x4*)p, o); }
; __device__ __forceinline__ bf16x8 pack_frag(const float (&v)[8]) { return __builtin_bit_cast(bf16x8, pack8(v)); }
; __device__ __forceinline__ void w_lru_m1(const Args& a, int l, unsigned char* ws, const bf16_t* proj, bf16_t* y, LAS unsigned char* wl, int b, int ck_, int h, int lane) {
;     ...
;         for (int tb = 0; tb < 4; ++tb) { const int tok = 16 * tb + lo, t = 64 * ck_ + tok; float s[8];
; #pragma unroll
;             for (int j = 0; j < 8; ++j) s[j] = bs[j];
; #pragma unroll
;             for (int k = 0; k < 4; ++k) { const int tt = t - 3 + k; float x[8];
;                 ld8bf(proj + (size_t)(b * SEQ + (tt >= 0 ? tt : 0)) * NIN + C_LX + ch0, x);
; #pragma unroll
;                 for (int j = 0; j < 8; ++j) s[j] += (tt >= 0 ? w[k][j] : 0.f) * x[j]; }
;             Xf[tb][kk] = pack_frag(s);
; #pragma unroll
;             for (int j = 0; j < 8; ++j) xcf[tok * 65 + 32 * kk + 8 * fq + j] = s[j]; }
	v_mov_b32_dpp v105, v231 row_ror:2 row_mask:0xf bank_mask:0xf
	v_mov_b32_dpp v106, v232 row_ror:2 row_mask:0xf bank_mask:0xf
	v_mov_b32_dpp v107, v233 row_ror:2 row_mask:0xf bank_mask:0xf
	v_mov_b32_dpp v104, v234 row_shr:2 row_mask:0xf bank_mask:0xf
	v_mov_b32_dpp v105, v235 row_shr:2 row_mask:0xf bank_mask:0xf
	v_mov_b32_dpp v106, v236 row_shr:2 row_mask:0xf bank_mask:0xf
	v_mov_b32_dpp v107, v237 row_shr:2 row_mask:0xf bank_mask:0xf
	v_max_i32_e32 v98, -2, v114
	v_add_u32_e32 v132, s81, v98
	v_cmp_lt_i32_e64 s[52:53], -3, v114
	v_mov_b32_dpp v114, v230 row_ror:1 row_mask:0xf bank_mask:0xf
	v_mov_b32_dpp v115, v231 row_ror:1 row_mask:0xf bank_mask:0xf
	v_mov_b32_dpp v116, v232 row_ror:1 row_mask:0xf bank_mask:0xf
	v_mov_b32_dpp v117, v233 row_ror:1 row_mask:0xf bank_mask:0xf
	v_mov_b32_dpp v114, v234 row_shr:1 row_mask:0xf bank_mask:0xf
	v_mov_b32_dpp v115, v235 row_shr:1 row_mask:0xf bank_mask:0xf
	v_mov_b32_dpp v116, v236 row_shr:1 row_mask:0xf bank_mask:0xf
	v_mov_b32_dpp v117, v237 row_shr:1 row_mask:0xf bank_mask:0xf
	v_or_b32_e32 v98, s20, v139
	v_cndmask_b32_e64 v98, 0, v98, s[42:43]
	v_add_u32_e32 v133, s27, v98
	v_mov_b64_e32 v[126:127], v[234:235]
	v_mov_b64_e32 v[128:129], v[236:237]
	v_mov_b32_e32 v98, 0x2080
	v_mad_u32_u24 v141, v136, s76, v98
	v_cndmask_b32_e64 v147, 0, v35, s[56:57]
	v_cndmask_b32_e64 v146, 0, v34, s[56:57]
	v_cndmask_b32_e64 v149, 0, v41, s[54:55]
	v_cndmask_b32_e64 v148, 0, v40, s[54:55]
	v_add_u32_e32 v124, v95, v141
	s_waitcnt vmcnt(0) lgkmcnt(0)
	v_lshlrev_b32_e32 v98, 16, v8
	v_lshlrev_b32_e32 v118, 16, v9
	v_and_b32_e32 v99, 0xffff0000, v8
	v_and_b32_e32 v119, 0xffff0000, v9
	v_cndmask_b32_e64 v9, 0, v33, s[56:57]
	v_cndmask_b32_e64 v8, 0, v32, s[56:57]
	v_pk_fma_f32 v[118:119], v[146:147], v[118:119], v[6:7]
	v_pk_fma_f32 v[8:9], v[8:9], v[98:99], v[4:5]
	v_lshlrev_b32_e32 v98, 16, v105
	v_lshlrev_b32_e32 v146, 16, v104
	v_and_b32_e32 v99, 0xffff0000, v105
	v_and_b32_e32 v147, 0xffff0000, v104
	v_cndmask_b32_e64 v105, 0, v43, s[54:55]
	v_cndmask_b32_e64 v104, 0, v42, s[54:55]
	v_pk_fma_f32 v[8:9], v[148:149], v[146:147], v[8:9]
	v_pk_fma_f32 v[98:99], v[104:105], v[98:99], v[118:119]
	v_lshlrev_b32_e32 v104, 16, v114
	v_lshlrev_b32_e32 v118, 16, v115
	v_and_b32_e32 v105, 0xffff0000, v114
	v_and_b32_e32 v119, 0xffff0000, v115
	v_cndmask_b32_e64 v115, 0, v69, s[52:53]
	v_cndmask_b32_e64 v114, 0, v68, s[52:53]
	v_cndmask_b32_e64 v147, 0, v71, s[52:53]
	v_cndmask_b32_e64 v146, 0, v70, s[52:53]
	v_pk_fma_f32 v[98:99], v[146:147], v[118:119], v[98:99]
	v_pk_fma_f32 v[8:9], v[114:115], v[104:105], v[8:9]
	v_lshlrev_b32_e32 v104, 16, v127
	v_lshlrev_b32_e32 v114, 16, v126
	v_and_b32_e32 v105, 0xffff0000, v127
	v_and_b32_e32 v115, 0xffff0000, v126
	v_pk_fma_f32 v[114:115], v[82:83], v[114:115], v[8:9]
	v_pk_fma_f32 v[98:99], v[72:73], v[104:105], v[98:99]
	v_cvt_pk_bf16_f32 v8, v114, v115
	v_cvt_pk_bf16_f32 v9, v98, v99
	ds_write2_b32 v124, v98, v99 offset0:2 offset1:3
	ds_write2_b32 v124, v114, v115 offset1:1
	v_lshlrev_b32_e32 v98, 16, v10
	v_lshlrev_b32_e32 v104, 16, v11
	v_and_b32_e32 v99, 0xffff0000, v10
	v_and_b32_e32 v105, 0xffff0000, v11
	v_cndmask_b32_e64 v11, 0, v25, s[56:57]
	v_cndmask_b32_e64 v10, 0, v24, s[56:57]
	v_cndmask_b32_e64 v115, 0, v27, s[56:57]
	v_cndmask_b32_e64 v114, 0, v26, s[56:57]
	v_pk_fma_f32 v[104:105], v[114:115], v[104:105], v[22:23]
	v_pk_fma_f32 v[10:11], v[10:11], v[98:99], v[20:21]
	v_lshlrev_b32_e32 v98, 16, v107
	v_lshlrev_b32_e32 v114, 16, v106
	v_and_b32_e32 v99, 0xffff0000, v107
	v_and_b32_e32 v115, 0xffff0000, v106
	v_cndmask_b32_e64 v107, 0, v31, s[54:55]
	v_cndmask_b32_e64 v106, 0, v30, s[54:55]
	v_cndmask_b32_e64 v119, 0, v29, s[54:55]
	v_cndmask_b32_e64 v118, 0, v28, s[54:55]
	v_pk_fma_f32 v[10:11], v[118:119], v[114:115], v[10:11]
	v_pk_fma_f32 v[98:99], v[106:107], v[98:99], v[104:105]
	v_lshlrev_b32_e32 v104, 16, v116
	v_lshlrev_b32_e32 v106, 16, v117
	v_and_b32_e32 v105, 0xffff0000, v116
	v_and_b32_e32 v107, 0xffff0000, v117
	v_cndmask_b32_e64 v115, 0, v37, s[52:53]
	v_cndmask_b32_e64 v114, 0, v36, s[52:53]
	v_cndmask_b32_e64 v117, 0, v39, s[52:53]
	v_cndmask_b32_e64 v116, 0, v38, s[52:53]
	v_pk_fma_f32 v[98:99], v[116:117], v[106:107], v[98:99]
	v_pk_fma_f32 v[10:11], v[114:115], v[104:105], v[10:11]
	v_lshlrev_b32_e32 v104, 16, v129
	v_and_b32_e32 v105, 0xffff0000, v129
	v_add_u32_e32 v118, s40, v137
	v_lshlrev_b32_e32 v106, 16, v128
	v_and_b32_e32 v107, 0xffff0000, v128
	v_pk_fma_f32 v[98:99], v[74:75], v[104:105], v[98:99]
	v_cmp_lt_i32_e64 s[46:47], -1, v118
	v_pk_fma_f32 v[106:107], v[84:85], v[106:107], v[10:11]
	v_cvt_pk_bf16_f32 v11, v98, v99
	ds_write2_b32 v124, v98, v99 offset0:6 offset1:7
	ds_write2_b32 v124, v106, v107 offset0:4 offset1:5
	v_cndmask_b32_e64 v98, 0, v118, s[46:47]
	v_add_u32_e32 v126, s27, v98
	v_cvt_pk_bf16_f32 v10, v106, v107
	v_mov_b32_dpp v104, v234 row_ror:3 row_mask:0xf bank_mask:0xf
	v_mov_b32_dpp v105, v235 row_ror:3 row_mask:0xf bank_mask:0xf
	v_mov_b32_dpp v106, v236 row_ror:3 row_mask:0xf bank_mask:0xf
	v_mov_b32_dpp v107, v237 row_ror:3 row_mask:0xf bank_mask:0xf
	v_mov_b32_dpp v104, v238 row_shr:3 row_mask:0xf bank_mask:0xf
	v_mov_b32_dpp v105, v239 row_shr:3 row_mask:0xf bank_mask:0xf
	v_mov_b32_dpp v106, v240 row_shr:3 row_mask:0xf bank_mask:0xf
	v_mov_b32_dpp v107, v241 row_shr:3 row_mask:0xf bank_mask:0xf
	v_max_i32_e32 v98, -1, v118
	v_add_u32_e32 v127, s80, v98
	v_mov_b32_dpp v114, v234 row_ror:2 row_mask:0xf bank_mask:0xf
	v_mov_b32_dpp v115, v235 row_ror:2 row_mask:0xf bank_mask:0xf
	v_mov_b32_dpp v116, v236 row_ror:2 row_mask:0xf bank_mask:0xf
	v_mov_b32_dpp v117, v237 row_ror:2 row_mask:0xf bank_mask:0xf
; __device__ __forceinline__ void ld8bf(const bf16_t* p, float (&o)[8]) { unpack8(*(const u32x4*)p, o); }
; __device__ __forceinline__ bf16x8 pack_frag(const float (&v)[8]) { return __builtin_bit_cast(bf16x8, pack8(v)); }
; __device__ __forceinline__ void w_lru_m1(const Args& a, int l, unsigned char* ws, const bf16_t* proj, bf16_t* y, LAS unsigned char* wl, int b, int ck_, int h, int lane) {
;     ...
;         for (int tb = 0; tb < 4; ++tb) { const int tok = 16 * tb + lo, t = 64 * ck_ + tok; float s[8];
; #pragma unroll
;             for (int j = 0; j < 8; ++j) s[j] = bs[j];
; #pragma unroll
;             for (int k = 0; k < 4; ++k) { const int tt = t - 3 + k; float x[8];
;                 ld8bf(proj + (size_t)(b * SEQ + (tt >= 0 ? tt : 0)) * NIN + C_LX + ch0, x);
; #pragma unroll
;                 for (int j = 0; j < 8; ++j) s[j] += (tt >= 0 ? w[k][j] : 0.f) * x[j]; }
;             Xf[tb][kk] = pack_frag(s);
; #pragma unroll
;             for (int j = 0; j < 8; ++j) xcf[tok * 65 + 32 * kk + 8 * fq + j] = s[j]; }
	v_mov_b32_dpp v114, v238 row_shr:2 row_mask:0xf bank_mask:0xf
	v_mov_b32_dpp v115, v239 row_shr:2 row_mask:0xf bank_mask:0xf
	v_mov_b32_dpp v116, v240 row_shr:2 row_mask:0xf bank_mask:0xf
	v_mov_b32_dpp v117, v241 row_shr:2 row_mask:0xf bank_mask:0xf
	v_max_i32_e32 v98, -2, v118
	v_add_u32_e32 v128, s81, v98
	v_mov_b32_dpp v146, v234 row_ror:1 row_mask:0xf bank_mask:0xf
	v_mov_b32_dpp v147, v235 row_ror:1 row_mask:0xf bank_mask:0xf
	v_mov_b32_dpp v148, v236 row_ror:1 row_mask:0xf bank_mask:0xf
	v_mov_b32_dpp v149, v237 row_ror:1 row_mask:0xf bank_mask:0xf
	v_mov_b32_dpp v146, v238 row_shr:1 row_mask:0xf bank_mask:0xf
	v_mov_b32_dpp v147, v239 row_shr:1 row_mask:0xf bank_mask:0xf
	v_mov_b32_dpp v148, v240 row_shr:1 row_mask:0xf bank_mask:0xf
	v_mov_b32_dpp v149, v241 row_shr:1 row_mask:0xf bank_mask:0xf
	v_or_b32_e32 v98, s20, v137
	v_cndmask_b32_e64 v98, 0, v98, s[42:43]
	v_add_u32_e32 v129, s27, v98
	v_mov_b64_e32 v[150:151], v[238:239]
	v_mov_b64_e32 v[152:153], v[240:241]
	v_mov_b32_e32 v80, 0x30c0
	v_cmp_lt_i32_e64 s[40:41], -2, v118
	v_mad_u32_u24 v138, v136, s76, v80
	v_cndmask_b32_e64 v33, 0, v33, s[46:47]
	v_cndmask_b32_e64 v32, 0, v32, s[46:47]
	v_cndmask_b32_e64 v35, 0, v35, s[46:47]
	v_cndmask_b32_e64 v34, 0, v34, s[46:47]
	v_cmp_lt_i32_e32 vcc, -3, v118
	v_cndmask_b32_e64 v43, 0, v43, s[40:41]
	v_cndmask_b32_e64 v42, 0, v42, s[40:41]
	v_cndmask_b32_e64 v41, 0, v41, s[40:41]
	v_cndmask_b32_e64 v40, 0, v40, s[40:41]
	v_add_u32_e32 v120, v95, v138
	v_cndmask_b32_e64 v25, 0, v25, s[46:47]
	v_cndmask_b32_e64 v24, 0, v24, s[46:47]
	v_cndmask_b32_e64 v27, 0, v27, s[46:47]
	v_cndmask_b32_e64 v26, 0, v26, s[46:47]
	v_cndmask_b32_e64 v29, 0, v29, s[40:41]
	v_cndmask_b32_e64 v28, 0, v28, s[40:41]
	s_mov_b64 s[80:81], 0x1080
	s_waitcnt vmcnt(0) lgkmcnt(0)
	v_lshlrev_b32_e32 v80, 16, v104
	v_lshlrev_b32_e32 v98, 16, v105
	v_and_b32_e32 v81, 0xffff0000, v104
	v_and_b32_e32 v99, 0xffff0000, v105
	v_pk_fma_f32 v[6:7], v[34:35], v[98:99], v[6:7]
	v_pk_fma_f32 v[4:5], v[32:33], v[80:81], v[4:5]
	v_lshlrev_b32_e32 v32, 16, v115
	v_lshlrev_b32_e32 v34, 16, v114
	v_and_b32_e32 v33, 0xffff0000, v115
	v_and_b32_e32 v35, 0xffff0000, v114
	v_pk_fma_f32 v[4:5], v[40:41], v[34:35], v[4:5]
	v_pk_fma_f32 v[6:7], v[42:43], v[32:33], v[6:7]
	v_lshlrev_b32_e32 v32, 16, v146
	v_lshlrev_b32_e32 v34, 16, v147
	v_and_b32_e32 v33, 0xffff0000, v146
	v_and_b32_e32 v35, 0xffff0000, v147
	v_cndmask_b32_e32 v41, 0, v69, vcc
	v_cndmask_b32_e32 v40, 0, v68, vcc
	v_cndmask_b32_e32 v43, 0, v71, vcc
	v_cndmask_b32_e32 v42, 0, v70, vcc
	v_pk_fma_f32 v[6:7], v[42:43], v[34:35], v[6:7]
	v_pk_fma_f32 v[4:5], v[40:41], v[32:33], v[4:5]
	v_lshlrev_b32_e32 v32, 16, v151
	v_and_b32_e32 v33, 0xffff0000, v151
	v_lshlrev_b32_e32 v34, 16, v150
	v_and_b32_e32 v35, 0xffff0000, v150
	v_pk_fma_f32 v[6:7], v[72:73], v[32:33], v[6:7]
	v_pk_fma_f32 v[34:35], v[82:83], v[34:35], v[4:5]
	v_cvt_pk_bf16_f32 v5, v6, v7
	ds_write2_b32 v120, v6, v7 offset0:2 offset1:3
	ds_write2_b32 v120, v34, v35 offset1:1
	v_lshlrev_b32_e32 v6, 16, v106
	v_lshlrev_b32_e32 v32, 16, v107
	v_and_b32_e32 v7, 0xffff0000, v106
	v_and_b32_e32 v33, 0xffff0000, v107
	v_pk_fma_f32 v[22:23], v[26:27], v[32:33], v[22:23]
	v_pk_fma_f32 v[6:7], v[24:25], v[6:7], v[20:21]
	v_lshlrev_b32_e32 v20, 16, v117
	v_lshlrev_b32_e32 v24, 16, v116
	v_and_b32_e32 v21, 0xffff0000, v117
	v_and_b32_e32 v25, 0xffff0000, v116
	v_cndmask_b32_e64 v27, 0, v31, s[40:41]
	v_cndmask_b32_e64 v26, 0, v30, s[40:41]
	v_pk_fma_f32 v[6:7], v[28:29], v[24:25], v[6:7]
	v_pk_fma_f32 v[20:21], v[26:27], v[20:21], v[22:23]
	v_lshlrev_b32_e32 v22, 16, v148
	v_lshlrev_b32_e32 v24, 16, v149
	v_and_b32_e32 v23, 0xffff0000, v148
	v_and_b32_e32 v25, 0xffff0000, v149
	v_cndmask_b32_e32 v27, 0, v37, vcc
	v_cndmask_b32_e32 v26, 0, v36, vcc
	v_cndmask_b32_e32 v29, 0, v39, vcc
	v_cndmask_b32_e32 v28, 0, v38, vcc
	v_pk_fma_f32 v[20:21], v[28:29], v[24:25], v[20:21]
	v_pk_fma_f32 v[6:7], v[26:27], v[22:23], v[6:7]
	v_lshlrev_b32_e32 v22, 16, v153
	v_and_b32_e32 v23, 0xffff0000, v153
	v_lshlrev_b32_e32 v24, 16, v152
	v_and_b32_e32 v25, 0xffff0000, v152
	v_pk_fma_f32 v[20:21], v[74:75], v[22:23], v[20:21]
	v_pk_fma_f32 v[24:25], v[84:85], v[24:25], v[6:7]
	v_cvt_pk_bf16_f32 v7, v20, v21
	ds_write2_b32 v120, v20, v21 offset0:6 offset1:7
	ds_write2_b32 v120, v24, v25 offset0:4 offset1:5
	v_add_u32_e32 v20, 32, v78
	v_ashrrev_i32_e32 v21, 31, v20
	v_lshl_add_u64 v[84:85], v[86:87], 0, s[80:81]
	s_mov_b64 s[80:81], 0x1880
	v_lshl_add_u64 v[106:107], v[86:87], 0, s[80:81]
	v_lshlrev_b64 v[104:105], 1, v[20:21]
	v_mov_b32_dpp v80, v242 row_ror:3 row_mask:0xf bank_mask:0xf
	v_mov_b32_dpp v81, v243 row_ror:3 row_mask:0xf bank_mask:0xf
	v_mov_b32_dpp v82, v244 row_ror:3 row_mask:0xf bank_mask:0xf
	v_mov_b32_dpp v83, v245 row_ror:3 row_mask:0xf bank_mask:0xf
	v_mov_b32_dpp v80, v246 row_shr:3 row_mask:0xf bank_mask:0xf
	v_mov_b32_dpp v81, v247 row_shr:3 row_mask:0xf bank_mask:0xf
	v_mov_b32_dpp v82, v248 row_shr:3 row_mask:0xf bank_mask:0xf
	v_mov_b32_dpp v83, v249 row_shr:3 row_mask:0xf bank_mask:0xf
	v_cvt_pk_bf16_f32 v4, v34, v35
	v_mov_b32_dpp v32, v242 row_ror:2 row_mask:0xf bank_mask:0xf
	v_mov_b32_dpp v33, v243 row_ror:2 row_mask:0xf bank_mask:0xf
	v_mov_b32_dpp v34, v244 row_ror:2 row_mask:0xf bank_mask:0xf
	v_mov_b32_dpp v35, v245 row_ror:2 row_mask:0xf bank_mask:0xf
	v_mov_b32_dpp v32, v246 row_shr:2 row_mask:0xf bank_mask:0xf
	v_mov_b32_dpp v33, v247 row_shr:2 row_mask:0xf bank_mask:0xf
	v_mov_b32_dpp v34, v248 row_shr:2 row_mask:0xf bank_mask:0xf
	v_mov_b32_dpp v35, v249 row_shr:2 row_mask:0xf bank_mask:0xf
	v_mov_b32_dpp v28, v242 row_ror:1 row_mask:0xf bank_mask:0xf
	v_mov_b32_dpp v29, v243 row_ror:1 row_mask:0xf bank_mask:0xf
	v_mov_b32_dpp v30, v244 row_ror:1 row_mask:0xf bank_mask:0xf
	v_mov_b32_dpp v31, v245 row_ror:1 row_mask:0xf bank_mask:0xf
	v_mov_b32_dpp v28, v246 row_shr:1 row_mask:0xf bank_mask:0xf
	v_mov_b32_dpp v29, v247 row_shr:1 row_mask:0xf bank_mask:0xf
	v_mov_b32_dpp v30, v248 row_shr:1 row_mask:0xf bank_mask:0xf
	v_mov_b32_dpp v31, v249 row_shr:1 row_mask:0xf bank_mask:0xf
	v_cvt_pk_bf16_f32 v6, v24, v25
	v_mov_b64_e32 v[24:25], v[246:247]
	v_mov_b64_e32 v[26:27], v[248:249]
	global_load_dwordx4 v[40:43], v[76:77], off offset:144
	global_load_dwordx4 v[72:75], v[76:77], off offset:128
	global_load_dwordx4 v[68:71], v[86:87], off offset:144
	s_nop 0
	global_load_dwordx4 v[76:79], v[86:87], off offset:128
	global_load_dwordx4 v[36:39], v[86:87], off offset:2192
	global_load_dwordx4 v[20:23], v[86:87], off offset:2176
	global_load_dwordx4 v[92:95], v[96:97], off offset:128
	s_nop 0
	global_load_dwordx4 v[84:87], v[84:85], off offset:16
	s_nop 0
	global_load_dwordx4 v[96:99], v[96:97], off offset:2176
	s_nop 0
	global_load_dwordx4 v[146:149], v[106:107], off offset:16
	s_waitcnt vmcnt(0) lgkmcnt(0)
; __device__ __forceinline__ void ld8bf(const bf16_t* p, float (&o)[8]) { unpack8(*(const u32x4*)p, o); }
; __device__ __forceinline__ bf16x8 pack_frag(const float (&v)[8]) { return __builtin_bit_cast(bf16x8, pack8(v)); }
; __device__ __forceinline__ void w_lru_m1(const Args& a, int l, unsigned char* ws, const bf16_t* proj, bf16_t* y, LAS unsigned char* wl, int b, int ck_, int h, int lane) {
;     ...
;         for (int tb = 0; tb < 4; ++tb) { const int tok = 16 * tb + lo, t = 64 * ck_ + tok; float s[8];
; #pragma unroll
;             for (int j = 0; j < 8; ++j) s[j] = bs[j];
; #pragma unroll
;             for (int k = 0; k < 4; ++k) { const int tt = t - 3 + k; float x[8];
;                 ld8bf(proj + (size_t)(b * SEQ + (tt >= 0 ? tt : 0)) * NIN + C_LX + ch0, x);
; #pragma unroll
;                 for (int j = 0; j < 8; ++j) s[j] += (tt >= 0 ? w[k][j] : 0.f) * x[j]; }
;             Xf[tb][kk] = pack_frag(s);
; #pragma unroll
;             for (int j = 0; j < 8; ++j) xcf[tok * 65 + 32 * kk + 8 * fq + j] = s[j]; }
	v_lshlrev_b32_e32 v106, 16, v80
	v_lshlrev_b32_e32 v114, 16, v81
	v_and_b32_e32 v107, 0xffff0000, v80
	v_and_b32_e32 v115, 0xffff0000, v81
	v_cndmask_b32_e64 v81, 0, v77, s[50:51]
	v_cndmask_b32_e64 v80, 0, v76, s[50:51]
	v_cndmask_b32_e64 v117, 0, v79, s[50:51]
	v_cndmask_b32_e64 v116, 0, v78, s[50:51]
	v_pk_fma_f32 v[114:115], v[116:117], v[114:115], v[74:75]
	v_pk_fma_f32 v[80:81], v[80:81], v[106:107], v[72:73]
	v_lshlrev_b32_e32 v106, 16, v33
	v_lshlrev_b32_e32 v116, 16, v32
	v_and_b32_e32 v107, 0xffff0000, v33
	v_and_b32_e32 v117, 0xffff0000, v32
	v_cndmask_b32_e64 v33, 0, v23, s[48:49]
	v_cndmask_b32_e64 v32, 0, v22, s[48:49]
	v_cndmask_b32_e64 v119, 0, v21, s[48:49]
	v_cndmask_b32_e64 v118, 0, v20, s[48:49]
	v_pk_fma_f32 v[80:81], v[118:119], v[116:117], v[80:81]
	v_pk_fma_f32 v[32:33], v[32:33], v[106:107], v[114:115]
	v_lshlrev_b32_e32 v106, 16, v28
	v_lshlrev_b32_e32 v114, 16, v29
	v_and_b32_e32 v107, 0xffff0000, v28
	v_and_b32_e32 v115, 0xffff0000, v29
	v_cndmask_b32_e64 v29, 0, v93, s[44:45]
	v_cndmask_b32_e64 v28, 0, v92, s[44:45]
	v_cndmask_b32_e64 v117, 0, v95, s[44:45]
	v_cndmask_b32_e64 v116, 0, v94, s[44:45]
	v_pk_fma_f32 v[32:33], v[116:117], v[114:115], v[32:33]
	v_pk_fma_f32 v[28:29], v[28:29], v[106:107], v[80:81]
	v_lshlrev_b32_e32 v80, 16, v25
	v_lshlrev_b32_e32 v116, 16, v24
	v_and_b32_e32 v81, 0xffff0000, v25
	v_and_b32_e32 v117, 0xffff0000, v24
	v_cndmask_b32_e64 v107, 0, v99, s[42:43]
	v_cndmask_b32_e64 v106, 0, v98, s[42:43]
	v_cndmask_b32_e64 v115, 0, v97, s[42:43]
	v_cndmask_b32_e64 v114, 0, v96, s[42:43]
	v_pk_fma_f32 v[24:25], v[114:115], v[116:117], v[28:29]
	v_pk_fma_f32 v[28:29], v[106:107], v[80:81], v[32:33]
	v_cvt_pk_bf16_f32 v32, v24, v25
	v_cvt_pk_bf16_f32 v33, v28, v29
	ds_write2_b32 v121, v28, v29 offset0:34 offset1:35
	ds_write2_b32 v121, v24, v25 offset0:32 offset1:33
	v_lshlrev_b32_e32 v24, 16, v82
	v_lshlrev_b32_e32 v28, 16, v83
	v_and_b32_e32 v25, 0xffff0000, v82
	v_and_b32_e32 v29, 0xffff0000, v83
	v_cndmask_b32_e64 v81, 0, v69, s[50:51]
	v_cndmask_b32_e64 v80, 0, v68, s[50:51]
	v_cndmask_b32_e64 v83, 0, v71, s[50:51]
	v_cndmask_b32_e64 v82, 0, v70, s[50:51]
	v_pk_fma_f32 v[28:29], v[82:83], v[28:29], v[42:43]
	v_pk_fma_f32 v[24:25], v[80:81], v[24:25], v[40:41]
	v_lshlrev_b32_e32 v80, 16, v35
	v_lshlrev_b32_e32 v82, 16, v34
	v_and_b32_e32 v81, 0xffff0000, v35
	v_and_b32_e32 v83, 0xffff0000, v34
	v_cndmask_b32_e64 v35, 0, v39, s[48:49]
	v_cndmask_b32_e64 v34, 0, v38, s[48:49]
	v_cndmask_b32_e64 v97, 0, v37, s[48:49]
	v_cndmask_b32_e64 v96, 0, v36, s[48:49]
	v_pk_fma_f32 v[24:25], v[96:97], v[82:83], v[24:25]
	v_pk_fma_f32 v[28:29], v[34:35], v[80:81], v[28:29]
	v_lshlrev_b32_e32 v34, 16, v30
	v_lshlrev_b32_e32 v80, 16, v31
	v_and_b32_e32 v35, 0xffff0000, v30
	v_and_b32_e32 v81, 0xffff0000, v31
	v_cndmask_b32_e64 v31, 0, v85, s[44:45]
	v_cndmask_b32_e64 v30, 0, v84, s[44:45]
	v_cndmask_b32_e64 v83, 0, v87, s[44:45]
	v_cndmask_b32_e64 v82, 0, v86, s[44:45]
	v_pk_fma_f32 v[28:29], v[82:83], v[80:81], v[28:29]
	v_pk_fma_f32 v[24:25], v[30:31], v[34:35], v[24:25]
	v_lshlrev_b32_e32 v30, 16, v27
	v_lshlrev_b32_e32 v34, 16, v26
	v_and_b32_e32 v31, 0xffff0000, v27
	v_and_b32_e32 v35, 0xffff0000, v26
	v_cndmask_b32_e64 v117, 0, v149, s[42:43]
	v_cndmask_b32_e64 v116, 0, v148, s[42:43]
	v_cndmask_b32_e64 v119, 0, v147, s[42:43]
	v_cndmask_b32_e64 v118, 0, v146, s[42:43]
	v_pk_fma_f32 v[24:25], v[118:119], v[34:35], v[24:25]
	v_pk_fma_f32 v[26:27], v[116:117], v[30:31], v[28:29]
	v_cvt_pk_bf16_f32 v34, v24, v25
	ds_write2_b32 v121, v26, v27 offset0:38 offset1:39
	ds_write2_b32 v121, v24, v25 offset0:36 offset1:37
	v_cvt_pk_bf16_f32 v35, v26, v27
	v_mov_b32_dpp v24, v246 row_ror:3 row_mask:0xf bank_mask:0xf
	v_mov_b32_dpp v25, v247 row_ror:3 row_mask:0xf bank_mask:0xf
	v_mov_b32_dpp v26, v248 row_ror:3 row_mask:0xf bank_mask:0xf
	v_mov_b32_dpp v27, v249 row_ror:3 row_mask:0xf bank_mask:0xf
	v_mov_b32_dpp v24, v250 row_shr:3 row_mask:0xf bank_mask:0xf
	v_mov_b32_dpp v25, v251 row_shr:3 row_mask:0xf bank_mask:0xf
	v_mov_b32_dpp v26, v252 row_shr:3 row_mask:0xf bank_mask:0xf
	v_mov_b32_dpp v27, v253 row_shr:3 row_mask:0xf bank_mask:0xf
	v_mov_b32_dpp v28, v246 row_ror:2 row_mask:0xf bank_mask:0xf
	v_mov_b32_dpp v29, v247 row_ror:2 row_mask:0xf bank_mask:0xf
	v_mov_b32_dpp v30, v248 row_ror:2 row_mask:0xf bank_mask:0xf
	v_mov_b32_dpp v31, v249 row_ror:2 row_mask:0xf bank_mask:0xf
	v_mov_b32_dpp v28, v250 row_shr:2 row_mask:0xf bank_mask:0xf
	v_mov_b32_dpp v29, v251 row_shr:2 row_mask:0xf bank_mask:0xf
	v_mov_b32_dpp v30, v252 row_shr:2 row_mask:0xf bank_mask:0xf
	v_mov_b32_dpp v31, v253 row_shr:2 row_mask:0xf bank_mask:0xf
	v_mov_b32_dpp v80, v246 row_ror:1 row_mask:0xf bank_mask:0xf
	v_mov_b32_dpp v81, v247 row_ror:1 row_mask:0xf bank_mask:0xf
	v_mov_b32_dpp v82, v248 row_ror:1 row_mask:0xf bank_mask:0xf
	v_mov_b32_dpp v83, v249 row_ror:1 row_mask:0xf bank_mask:0xf
	v_mov_b32_dpp v80, v250 row_shr:1 row_mask:0xf bank_mask:0xf
	v_mov_b32_dpp v81, v251 row_shr:1 row_mask:0xf bank_mask:0xf
	v_mov_b32_dpp v82, v252 row_shr:1 row_mask:0xf bank_mask:0xf
	v_mov_b32_dpp v83, v253 row_shr:1 row_mask:0xf bank_mask:0xf
	v_mov_b64_e32 v[96:97], v[250:251]
	v_mov_b64_e32 v[98:99], v[252:253]
	v_cndmask_b32_e64 v147, 0, v79, s[62:63]
	v_cndmask_b32_e64 v146, 0, v78, s[62:63]
	v_cndmask_b32_e64 v149, 0, v21, s[60:61]
	v_cndmask_b32_e64 v148, 0, v20, s[60:61]
	s_add_i32 s48, s20, s27
	s_lshl_b32 s20, s91, 7
	s_add_u32 s44, s10, s20
	s_addc_u32 s45, s11, 0
	s_waitcnt vmcnt(0) lgkmcnt(0)
; __device__ __forceinline__ void ld8bf(const bf16_t* p, float (&o)[8]) { unpack8(*(const u32x4*)p, o); }
; __device__ __forceinline__ bf16x8 pack_frag(const float (&v)[8]) { return __builtin_bit_cast(bf16x8, pack8(v)); }
; __device__ __forceinline__ void w_lru_m1(const Args& a, int l, unsigned char* ws, const bf16_t* proj, bf16_t* y, LAS unsigned char* wl, int b, int ck_, int h, int lane) {
;     ...
;         for (int tb = 0; tb < 4; ++tb) { const int tok = 16 * tb + lo, t = 64 * ck_ + tok; float s[8];
; #pragma unroll
;             for (int j = 0; j < 8; ++j) s[j] = bs[j];
; #pragma unroll
;             for (int k = 0; k < 4; ++k) { const int tt = t - 3 + k; float x[8];
;                 ld8bf(proj + (size_t)(b * SEQ + (tt >= 0 ? tt : 0)) * NIN + C_LX + ch0, x);
; #pragma unroll
;                 for (int j = 0; j < 8; ++j) s[j] += (tt >= 0 ? w[k][j] : 0.f) * x[j]; }
;             Xf[tb][kk] = pack_frag(s);
; #pragma unroll
;             for (int j = 0; j < 8; ++j) xcf[tok * 65 + 32 * kk + 8 * fq + j] = s[j]; }
	v_lshlrev_b32_e32 v134, 16, v24
	v_lshlrev_b32_e32 v142, 16, v25
	v_and_b32_e32 v135, 0xffff0000, v24
	v_and_b32_e32 v143, 0xffff0000, v25
	v_cndmask_b32_e64 v25, 0, v77, s[62:63]
	v_cndmask_b32_e64 v24, 0, v76, s[62:63]
	v_pk_fma_f32 v[142:143], v[146:147], v[142:143], v[74:75]
	v_pk_fma_f32 v[24:25], v[24:25], v[134:135], v[72:73]
	v_lshlrev_b32_e32 v134, 16, v29
	v_lshlrev_b32_e32 v146, 16, v28
	v_and_b32_e32 v135, 0xffff0000, v29
	v_and_b32_e32 v147, 0xffff0000, v28
	v_cndmask_b32_e64 v29, 0, v23, s[60:61]
	v_cndmask_b32_e64 v28, 0, v22, s[60:61]
	v_pk_fma_f32 v[24:25], v[148:149], v[146:147], v[24:25]
	v_pk_fma_f32 v[28:29], v[28:29], v[134:135], v[142:143]
	v_lshlrev_b32_e32 v134, 16, v80
	v_lshlrev_b32_e32 v142, 16, v81
	v_and_b32_e32 v135, 0xffff0000, v80
	v_and_b32_e32 v143, 0xffff0000, v81
	v_cndmask_b32_e64 v81, 0, v93, s[58:59]
	v_cndmask_b32_e64 v80, 0, v92, s[58:59]
	v_cndmask_b32_e64 v147, 0, v95, s[58:59]
	v_cndmask_b32_e64 v146, 0, v94, s[58:59]
	v_pk_fma_f32 v[28:29], v[146:147], v[142:143], v[28:29]
	v_pk_fma_f32 v[24:25], v[80:81], v[134:135], v[24:25]
	v_lshlrev_b32_e32 v80, 16, v97
	v_lshlrev_b32_e32 v134, 16, v96
	v_and_b32_e32 v81, 0xffff0000, v97
	v_and_b32_e32 v135, 0xffff0000, v96
	v_pk_fma_f32 v[24:25], v[114:115], v[134:135], v[24:25]
	v_pk_fma_f32 v[80:81], v[106:107], v[80:81], v[28:29]
	v_cvt_pk_bf16_f32 v28, v24, v25
	v_cvt_pk_bf16_f32 v29, v80, v81
	ds_write2_b32 v125, v80, v81 offset0:34 offset1:35
	ds_write2_b32 v125, v24, v25 offset0:32 offset1:33
	v_lshlrev_b32_e32 v24, 16, v26
	v_lshlrev_b32_e32 v80, 16, v27
	v_and_b32_e32 v25, 0xffff0000, v26
	v_and_b32_e32 v81, 0xffff0000, v27
	v_cndmask_b32_e64 v27, 0, v69, s[62:63]
	v_cndmask_b32_e64 v26, 0, v68, s[62:63]
	v_cndmask_b32_e64 v97, 0, v71, s[62:63]
	v_cndmask_b32_e64 v96, 0, v70, s[62:63]
	v_pk_fma_f32 v[80:81], v[96:97], v[80:81], v[42:43]
	v_pk_fma_f32 v[24:25], v[26:27], v[24:25], v[40:41]
	v_lshlrev_b32_e32 v26, 16, v31
	v_lshlrev_b32_e32 v96, 16, v30
	v_and_b32_e32 v27, 0xffff0000, v31
	v_and_b32_e32 v97, 0xffff0000, v30
	v_cndmask_b32_e64 v31, 0, v39, s[60:61]
	v_cndmask_b32_e64 v30, 0, v38, s[60:61]
	v_cndmask_b32_e64 v135, 0, v37, s[60:61]
	v_cndmask_b32_e64 v134, 0, v36, s[60:61]
	v_pk_fma_f32 v[24:25], v[134:135], v[96:97], v[24:25]
	v_pk_fma_f32 v[26:27], v[30:31], v[26:27], v[80:81]
	v_lshlrev_b32_e32 v30, 16, v82
	v_lshlrev_b32_e32 v80, 16, v83
	v_and_b32_e32 v31, 0xffff0000, v82
	v_and_b32_e32 v81, 0xffff0000, v83
	v_cndmask_b32_e64 v83, 0, v85, s[58:59]
	v_cndmask_b32_e64 v82, 0, v84, s[58:59]
	v_cndmask_b32_e64 v97, 0, v87, s[58:59]
	v_cndmask_b32_e64 v96, 0, v86, s[58:59]
	v_pk_fma_f32 v[26:27], v[96:97], v[80:81], v[26:27]
	v_pk_fma_f32 v[24:25], v[82:83], v[30:31], v[24:25]
	v_lshlrev_b32_e32 v30, 16, v99
	v_lshlrev_b32_e32 v80, 16, v98
	v_and_b32_e32 v31, 0xffff0000, v99
	v_and_b32_e32 v81, 0xffff0000, v98
	v_pk_fma_f32 v[24:25], v[118:119], v[80:81], v[24:25]
	v_pk_fma_f32 v[26:27], v[116:117], v[30:31], v[26:27]
	v_cvt_pk_bf16_f32 v30, v24, v25
	ds_write2_b32 v125, v26, v27 offset0:38 offset1:39
	ds_write2_b32 v125, v24, v25 offset0:36 offset1:37
	v_cvt_pk_bf16_f32 v31, v26, v27
	v_mov_b32_dpp v24, v250 row_ror:3 row_mask:0xf bank_mask:0xf
	v_mov_b32_dpp v25, v251 row_ror:3 row_mask:0xf bank_mask:0xf
	v_mov_b32_dpp v26, v252 row_ror:3 row_mask:0xf bank_mask:0xf
	v_mov_b32_dpp v27, v253 row_ror:3 row_mask:0xf bank_mask:0xf
	v_mov_b32_dpp v24, v190 row_shr:3 row_mask:0xf bank_mask:0xf
	v_mov_b32_dpp v25, v191 row_shr:3 row_mask:0xf bank_mask:0xf
	v_mov_b32_dpp v26, v192 row_shr:3 row_mask:0xf bank_mask:0xf
	v_mov_b32_dpp v27, v193 row_shr:3 row_mask:0xf bank_mask:0xf
	v_mov_b32_dpp v80, v250 row_ror:2 row_mask:0xf bank_mask:0xf
	v_mov_b32_dpp v81, v251 row_ror:2 row_mask:0xf bank_mask:0xf
	v_mov_b32_dpp v82, v252 row_ror:2 row_mask:0xf bank_mask:0xf
	v_mov_b32_dpp v83, v253 row_ror:2 row_mask:0xf bank_mask:0xf
	v_mov_b32_dpp v80, v190 row_shr:2 row_mask:0xf bank_mask:0xf
	v_mov_b32_dpp v81, v191 row_shr:2 row_mask:0xf bank_mask:0xf
	v_mov_b32_dpp v82, v192 row_shr:2 row_mask:0xf bank_mask:0xf
	v_mov_b32_dpp v83, v193 row_shr:2 row_mask:0xf bank_mask:0xf
	v_mov_b32_dpp v96, v250 row_ror:1 row_mask:0xf bank_mask:0xf
	v_mov_b32_dpp v97, v251 row_ror:1 row_mask:0xf bank_mask:0xf
	v_mov_b32_dpp v98, v252 row_ror:1 row_mask:0xf bank_mask:0xf
	v_mov_b32_dpp v99, v253 row_ror:1 row_mask:0xf bank_mask:0xf
	v_mov_b32_dpp v96, v190 row_shr:1 row_mask:0xf bank_mask:0xf
	v_mov_b32_dpp v97, v191 row_shr:1 row_mask:0xf bank_mask:0xf
	v_mov_b32_dpp v98, v192 row_shr:1 row_mask:0xf bank_mask:0xf
	v_mov_b32_dpp v99, v193 row_shr:1 row_mask:0xf bank_mask:0xf
	v_mov_b64_e32 v[130:131], v[190:191]
	v_mov_b64_e32 v[132:133], v[192:193]
	v_cndmask_b32_e64 v147, 0, v79, s[56:57]
	v_cndmask_b32_e64 v146, 0, v78, s[56:57]
	v_cndmask_b32_e64 v149, 0, v21, s[54:55]
	v_cndmask_b32_e64 v148, 0, v20, s[54:55]
	v_cndmask_b32_e64 v79, 0, v79, s[46:47]
	v_cndmask_b32_e64 v78, 0, v78, s[46:47]
	v_cndmask_b32_e64 v21, 0, v21, s[40:41]
	v_cndmask_b32_e64 v20, 0, v20, s[40:41]
	s_waitcnt vmcnt(0) lgkmcnt(0)
; __device__ __forceinline__ void ld8bf(const bf16_t* p, float (&o)[8]) { unpack8(*(const u32x4*)p, o); }
; __device__ __forceinline__ bf16x8 pack_frag(const float (&v)[8]) { return __builtin_bit_cast(bf16x8, pack8(v)); }
; __device__ __forceinline__ void w_lru_m1(const Args& a, int l, unsigned char* ws, const bf16_t* proj, bf16_t* y, LAS unsigned char* wl, int b, int ck_, int h, int lane) {
;     ...
;         for (int tb = 0; tb < 4; ++tb) { const int tok = 16 * tb + lo, t = 64 * ck_ + tok; float s[8];
; #pragma unroll
;             for (int j = 0; j < 8; ++j) s[j] = bs[j];
; #pragma unroll
;             for (int k = 0; k < 4; ++k) { const int tt = t - 3 + k; float x[8];
;                 ld8bf(proj + (size_t)(b * SEQ + (tt >= 0 ? tt : 0)) * NIN + C_LX + ch0, x);
; #pragma unroll
;                 for (int j = 0; j < 8; ++j) s[j] += (tt >= 0 ? w[k][j] : 0.f) * x[j]; }
;             Xf[tb][kk] = pack_frag(s);
; #pragma unroll
;             for (int j = 0; j < 8; ++j) xcf[tok * 65 + 32 * kk + 8 * fq + j] = s[j]; }
	v_lshlrev_b32_e32 v134, 16, v24
	v_lshlrev_b32_e32 v142, 16, v25
	v_and_b32_e32 v135, 0xffff0000, v24
	v_and_b32_e32 v143, 0xffff0000, v25
	v_cndmask_b32_e64 v25, 0, v77, s[56:57]
	v_cndmask_b32_e64 v24, 0, v76, s[56:57]
	v_pk_fma_f32 v[142:143], v[146:147], v[142:143], v[74:75]
	v_pk_fma_f32 v[24:25], v[24:25], v[134:135], v[72:73]
	v_lshlrev_b32_e32 v134, 16, v81
	v_lshlrev_b32_e32 v146, 16, v80
	v_and_b32_e32 v135, 0xffff0000, v81
	v_and_b32_e32 v147, 0xffff0000, v80
	v_cndmask_b32_e64 v81, 0, v23, s[54:55]
	v_cndmask_b32_e64 v80, 0, v22, s[54:55]
	v_pk_fma_f32 v[24:25], v[148:149], v[146:147], v[24:25]
	v_pk_fma_f32 v[80:81], v[80:81], v[134:135], v[142:143]
	v_lshlrev_b32_e32 v134, 16, v96
	v_lshlrev_b32_e32 v142, 16, v97
	v_and_b32_e32 v135, 0xffff0000, v96
	v_and_b32_e32 v143, 0xffff0000, v97
	v_cndmask_b32_e64 v97, 0, v93, s[52:53]
	v_cndmask_b32_e64 v96, 0, v92, s[52:53]
	v_cndmask_b32_e64 v147, 0, v95, s[52:53]
	v_cndmask_b32_e64 v146, 0, v94, s[52:53]
	v_pk_fma_f32 v[80:81], v[146:147], v[142:143], v[80:81]
	v_pk_fma_f32 v[24:25], v[96:97], v[134:135], v[24:25]
	v_lshlrev_b32_e32 v96, 16, v131
	v_lshlrev_b32_e32 v134, 16, v130
	v_and_b32_e32 v97, 0xffff0000, v131
	v_and_b32_e32 v135, 0xffff0000, v130
	v_pk_fma_f32 v[130:131], v[114:115], v[134:135], v[24:25]
	v_pk_fma_f32 v[80:81], v[106:107], v[96:97], v[80:81]
	v_cvt_pk_bf16_f32 v24, v130, v131
	v_cvt_pk_bf16_f32 v25, v80, v81
	ds_write2_b32 v124, v80, v81 offset0:34 offset1:35
	ds_write2_b32 v124, v130, v131 offset0:32 offset1:33
	v_lshlrev_b32_e32 v80, 16, v26
	v_lshlrev_b32_e32 v96, 16, v27
	v_and_b32_e32 v81, 0xffff0000, v26
	v_and_b32_e32 v97, 0xffff0000, v27
	v_cndmask_b32_e64 v27, 0, v69, s[56:57]
	v_cndmask_b32_e64 v26, 0, v68, s[56:57]
	v_cndmask_b32_e64 v131, 0, v71, s[56:57]
	v_cndmask_b32_e64 v130, 0, v70, s[56:57]
	v_pk_fma_f32 v[96:97], v[130:131], v[96:97], v[42:43]
	v_pk_fma_f32 v[26:27], v[26:27], v[80:81], v[40:41]
	v_lshlrev_b32_e32 v80, 16, v83
	v_lshlrev_b32_e32 v130, 16, v82
	v_and_b32_e32 v81, 0xffff0000, v83
	v_and_b32_e32 v131, 0xffff0000, v82
	v_cndmask_b32_e64 v83, 0, v39, s[54:55]
	v_cndmask_b32_e64 v82, 0, v38, s[54:55]
	v_cndmask_b32_e64 v135, 0, v37, s[54:55]
	v_cndmask_b32_e64 v134, 0, v36, s[54:55]
	v_pk_fma_f32 v[26:27], v[134:135], v[130:131], v[26:27]
	v_pk_fma_f32 v[80:81], v[82:83], v[80:81], v[96:97]
	v_lshlrev_b32_e32 v82, 16, v98
	v_lshlrev_b32_e32 v96, 16, v99
	v_and_b32_e32 v83, 0xffff0000, v98
	v_and_b32_e32 v97, 0xffff0000, v99
	v_cndmask_b32_e64 v99, 0, v85, s[52:53]
	v_cndmask_b32_e64 v98, 0, v84, s[52:53]
	v_cndmask_b32_e64 v131, 0, v87, s[52:53]
	v_cndmask_b32_e64 v130, 0, v86, s[52:53]
	v_pk_fma_f32 v[80:81], v[130:131], v[96:97], v[80:81]
	v_pk_fma_f32 v[26:27], v[98:99], v[82:83], v[26:27]
	v_lshlrev_b32_e32 v82, 16, v133
	v_and_b32_e32 v83, 0xffff0000, v133
	v_lshlrev_b32_e32 v96, 16, v132
	v_and_b32_e32 v97, 0xffff0000, v132
	v_pk_fma_f32 v[80:81], v[116:117], v[82:83], v[80:81]
	v_pk_fma_f32 v[96:97], v[118:119], v[96:97], v[26:27]
	v_cvt_pk_bf16_f32 v27, v80, v81
	ds_write2_b32 v124, v80, v81 offset0:38 offset1:39
	ds_write2_b32 v124, v96, v97 offset0:36 offset1:37
	v_mov_b32_dpp v130, v190 row_ror:3 row_mask:0xf bank_mask:0xf
	v_mov_b32_dpp v131, v191 row_ror:3 row_mask:0xf bank_mask:0xf
	v_mov_b32_dpp v132, v192 row_ror:3 row_mask:0xf bank_mask:0xf
	v_mov_b32_dpp v133, v193 row_ror:3 row_mask:0xf bank_mask:0xf
	v_mov_b32_dpp v130, v194 row_shr:3 row_mask:0xf bank_mask:0xf
	v_mov_b32_dpp v131, v195 row_shr:3 row_mask:0xf bank_mask:0xf
	v_mov_b32_dpp v132, v196 row_shr:3 row_mask:0xf bank_mask:0xf
	v_mov_b32_dpp v133, v197 row_shr:3 row_mask:0xf bank_mask:0xf
	v_mov_b32_dpp v124, v190 row_ror:2 row_mask:0xf bank_mask:0xf
	v_mov_b32_dpp v125, v191 row_ror:2 row_mask:0xf bank_mask:0xf
	v_mov_b32_dpp v126, v192 row_ror:2 row_mask:0xf bank_mask:0xf
	v_mov_b32_dpp v127, v193 row_ror:2 row_mask:0xf bank_mask:0xf
	v_mov_b32_dpp v124, v194 row_shr:2 row_mask:0xf bank_mask:0xf
	v_mov_b32_dpp v125, v195 row_shr:2 row_mask:0xf bank_mask:0xf
	v_mov_b32_dpp v126, v196 row_shr:2 row_mask:0xf bank_mask:0xf
	v_mov_b32_dpp v127, v197 row_shr:2 row_mask:0xf bank_mask:0xf
	v_cvt_pk_bf16_f32 v26, v96, v97
	v_mov_b32_dpp v96, v190 row_ror:1 row_mask:0xf bank_mask:0xf
	v_mov_b32_dpp v97, v191 row_ror:1 row_mask:0xf bank_mask:0xf
	v_mov_b32_dpp v98, v192 row_ror:1 row_mask:0xf bank_mask:0xf
	v_mov_b32_dpp v99, v193 row_ror:1 row_mask:0xf bank_mask:0xf
	v_mov_b32_dpp v96, v194 row_shr:1 row_mask:0xf bank_mask:0xf
	v_mov_b32_dpp v97, v195 row_shr:1 row_mask:0xf bank_mask:0xf
	v_mov_b32_dpp v98, v196 row_shr:1 row_mask:0xf bank_mask:0xf
	v_mov_b32_dpp v99, v197 row_shr:1 row_mask:0xf bank_mask:0xf
	v_mov_b64_e32 v[80:81], v[194:195]
	v_mov_b64_e32 v[82:83], v[196:197]
	v_cndmask_b32_e64 v77, 0, v77, s[46:47]
	v_cndmask_b32_e64 v76, 0, v76, s[46:47]
	v_cndmask_b32_e64 v23, 0, v23, s[40:41]
	v_cndmask_b32_e64 v22, 0, v22, s[40:41]
	v_cndmask_b32_e64 v69, 0, v69, s[46:47]
	v_cndmask_b32_e64 v68, 0, v68, s[46:47]
	v_cndmask_b32_e64 v71, 0, v71, s[46:47]
	v_cndmask_b32_e64 v70, 0, v70, s[46:47]
	v_cndmask_b32_e64 v39, 0, v39, s[40:41]
	v_cndmask_b32_e64 v38, 0, v38, s[40:41]
	v_cndmask_b32_e64 v37, 0, v37, s[40:41]
	v_cndmask_b32_e64 v36, 0, v36, s[40:41]
	s_add_u32 s46, s71, s20
	s_addc_u32 s47, s64, 0
	s_ashr_i32 s91, s90, 31
	s_lshl_b64 s[42:43], s[90:91], 9
	s_or_b32 s42, s42, s21
	s_waitcnt vmcnt(0) lgkmcnt(0)
; __device__ __forceinline__ float sigmoidf_(float x) { return __builtin_amdgcn_rcpf(1.0f + __expf(-x)); }
; #define WAVE_LDS_FENCE() asm volatile("s_waitcnt lgkmcnt(0)" ::: "memory")
; __device__ __forceinline__ void w_lru_m1(const Args& a, int l, unsigned char* ws, const bf16_t* proj, bf16_t* y, LAS unsigned char* wl, int b, int ck_, int h, int lane) {
;     ...
;             for (int j = 0; j < 8; ++j) xcf[tok * 65 + 32 * kk + 8 * fq + j] = s[j]; }
;     }
;     WAVE_LDS_FENCE();
; #pragma unroll
;     for (int jb = 0; jb < 4; ++jb) {
;         bf16x8 WaF[2], WxF[2]; f32x4 pba, pbx, plam;
; #pragma unroll
;         for (int kk = 0; kk < 2; ++kk) { WaF[kk] = nWa[kk]; WxF[kk] = nWx[kk]; }
;         pba = nba; pbx = nbx; plam = nlam;
;         if (jb < 3) {
; #pragma unroll
;             for (int kk = 0; kk < 2; ++kk) { nWa[kk] = *(const bf16x8*)(waT + (16 * (jb + 1) + lo) * 64 + 32 * kk + 8 * fq); nWx[kk] = *(const bf16x8*)(wxT + (16 * (jb + 1) + lo) * 64 + 32 * kk + 8 * fq); }
;             nba = *(const f32x4*)(ba + 16 * (jb + 1) + 4 * fq); nbx = *(const f32x4*)(bx + 16 * (jb + 1) + 4 * fq); nlam = *(const f32x4*)(lam + 16 * (jb + 1) + 4 * fq);
;         }
;         const int j0 = 16 * jb + 4 * fq;
;         float bav[4], bxv[4], sp[4], hc[4], Pc[4];
; #pragma unroll
;         for (int r = 0; r < 4; ++r) { bav[r] = pba[r]; bxv[r] = pbx[r]; sp[r] = log1pf(__expf(-plam[r])); hc[r] = 0.f; Pc[r] = 1.f; }
; #pragma unroll
;         for (int tb = 0; tb < 4; ++tb) { const int tok = 16 * tb + lo;
;             f32x4 ga = {0.f, 0.f, 0.f, 0.f}, gx = {0.f, 0.f, 0.f, 0.f};
; #pragma unroll
;             for (int kk = 0; kk < 2; ++kk) { ga = __builtin_amdgcn_mfma_f32_16x16x32_bf16(WaF[kk], Xf[tb][kk], ga, 0, 0, 0); gx = __builtin_amdgcn_mfma_f32_16x16x32_bf16(WxF[kk], Xf[tb][kk], gx, 0, 0, 0); }
;             float hv[4], pv[4];
; #pragma unroll
;             for (int r = 0; r < 4; ++r) {
;                 const float rg = sigmoidf_(ga[r] + bav[r]), ig = sigmoidf_(gx[r] + bxv[r]);
;                 const float la = -8.0f * rg * sp[r]; float A = __expf(la);
;                 float U = __builtin_amdgcn_sqrtf(1.0f - A * A) * (ig * xcf[tok * 65 + j0 + r]);
	v_lshlrev_b32_e32 v102, 16, v130
	v_lshlrev_b32_e32 v104, 16, v131
	v_and_b32_e32 v103, 0xffff0000, v130
	v_and_b32_e32 v105, 0xffff0000, v131
	v_pk_fma_f32 v[74:75], v[78:79], v[104:105], v[74:75]
	v_pk_fma_f32 v[72:73], v[76:77], v[102:103], v[72:73]
	v_lshlrev_b32_e32 v76, 16, v125
	v_lshlrev_b32_e32 v78, 16, v124
	v_and_b32_e32 v77, 0xffff0000, v125
	v_and_b32_e32 v79, 0xffff0000, v124
	v_pk_fma_f32 v[20:21], v[20:21], v[78:79], v[72:73]
	v_pk_fma_f32 v[22:23], v[22:23], v[76:77], v[74:75]
	v_lshlrev_b32_e32 v72, 16, v96
	v_lshlrev_b32_e32 v74, 16, v97
	v_and_b32_e32 v73, 0xffff0000, v96
	v_and_b32_e32 v75, 0xffff0000, v97
	v_cndmask_b32_e32 v77, 0, v93, vcc
	v_cndmask_b32_e32 v76, 0, v92, vcc
	v_cndmask_b32_e32 v79, 0, v95, vcc
	v_cndmask_b32_e32 v78, 0, v94, vcc
	v_pk_fma_f32 v[22:23], v[78:79], v[74:75], v[22:23]
	v_pk_fma_f32 v[20:21], v[76:77], v[72:73], v[20:21]
	v_lshlrev_b32_e32 v72, 16, v81
	v_and_b32_e32 v73, 0xffff0000, v81
	v_lshlrev_b32_e32 v74, 16, v80
	v_and_b32_e32 v75, 0xffff0000, v80
	v_pk_fma_f32 v[22:23], v[106:107], v[72:73], v[22:23]
	v_pk_fma_f32 v[74:75], v[114:115], v[74:75], v[20:21]
	v_cvt_pk_bf16_f32 v21, v22, v23
	ds_write2_b32 v120, v22, v23 offset0:34 offset1:35
	ds_write2_b32 v120, v74, v75 offset0:32 offset1:33
	v_lshlrev_b32_e32 v22, 16, v132
	v_lshlrev_b32_e32 v72, 16, v133
	v_and_b32_e32 v23, 0xffff0000, v132
	v_and_b32_e32 v73, 0xffff0000, v133
	v_pk_fma_f32 v[42:43], v[70:71], v[72:73], v[42:43]
	v_pk_fma_f32 v[22:23], v[68:69], v[22:23], v[40:41]
	v_lshlrev_b32_e32 v40, 16, v127
	v_lshlrev_b32_e32 v68, 16, v126
	v_and_b32_e32 v41, 0xffff0000, v127
	v_and_b32_e32 v69, 0xffff0000, v126
	v_pk_fma_f32 v[22:23], v[36:37], v[68:69], v[22:23]
	v_pk_fma_f32 v[36:37], v[38:39], v[40:41], v[42:43]
	v_lshlrev_b32_e32 v38, 16, v98
	v_lshlrev_b32_e32 v40, 16, v99
	v_and_b32_e32 v39, 0xffff0000, v98
	v_and_b32_e32 v41, 0xffff0000, v99
	v_cndmask_b32_e32 v43, 0, v85, vcc
	v_cndmask_b32_e32 v42, 0, v84, vcc
	v_cndmask_b32_e32 v69, 0, v87, vcc
	v_cndmask_b32_e32 v68, 0, v86, vcc
	v_pk_fma_f32 v[36:37], v[68:69], v[40:41], v[36:37]
	v_pk_fma_f32 v[22:23], v[42:43], v[38:39], v[22:23]
	v_lshlrev_b32_e32 v38, 16, v83
	v_and_b32_e32 v39, 0xffff0000, v83
	v_lshlrev_b32_e32 v40, 16, v82
	v_and_b32_e32 v41, 0xffff0000, v82
	v_pk_fma_f32 v[36:37], v[116:117], v[38:39], v[36:37]
	v_pk_fma_f32 v[40:41], v[118:119], v[40:41], v[22:23]
	v_cvt_pk_bf16_f32 v23, v36, v37
	ds_write2_b32 v120, v36, v37 offset0:38 offset1:39
	ds_write2_b32 v120, v40, v41 offset0:36 offset1:37
	v_lshlrev_b32_e32 v36, 2, v122
	v_lshl_add_u64 v[118:119], s[92:93], 0, v[100:101]
	v_lshl_add_u64 v[120:121], s[34:35], 0, v[100:101]
	v_and_b32_e32 v143, 0xc0, v36
	v_lshl_add_u64 v[36:37], v[118:119], 0, v[2:3]
	v_lshl_add_u64 v[38:39], v[120:121], 0, v[2:3]
	s_nop 7
	s_waitcnt lgkmcnt(0)
	v_cvt_pk_bf16_f32 v20, v74, v75
	v_cvt_pk_bf16_f32 v22, v40, v41
	s_nop 7
	global_load_dwordx4 v[68:71], v[36:37], off offset:2048
	global_load_dwordx4 v[72:75], v[38:39], off offset:2048
	global_load_dwordx4 v[76:79], v[36:37], off offset:2112
	global_load_dwordx4 v[80:83], v[38:39], off offset:2112
	global_load_dwordx4 v[40:43], v[108:109], off offset:64
	s_nop 7
	global_load_dwordx4 v[36:39], v[110:111], off offset:64
	global_load_dwordx4 v[84:87], v[112:113], off offset:64
	s_nop 7
	v_mov_b32_e32 v104, 1.0
	s_nop 7
	v_mov_b32_e32 v105, 1.0
	s_nop 7
	v_cmp_eq_u32_e32 vcc, 0, v136
	s_nop 7
	v_mov_b32_e32 v145, v88
	s_nop 7
	v_mov_b32_e32 v147, v89
	s_nop 7
	v_mov_b32_e32 v103, 1.0
	s_nop 7
	v_mov_b32_e32 v2, v90
	s_nop 7
	v_mov_b32_e32 v100, 1.0
	s_nop 7
	v_mov_b32_e32 v101, 1.0
	s_nop 7
	v_mfma_f32_16x16x32_bf16 v[92:95], v[56:59], v[16:19], 0
	v_mov_b32_e32 v98, 1.0
	s_nop 7
	v_mfma_f32_16x16x32_bf16 v[92:95], v[64:67], v[32:35], v[92:95]
	v_mov_b32_e32 v99, 1.0
	s_nop 7
	v_mov_b32_e32 v146, v91
	v_and_b32_e32 v88, -16, v122
	v_add_u32_e32 v142, s6, v88
	v_lshlrev_b64 v[88:89], 1, v[0:1]
	v_lshl_add_u64 v[114:115], s[44:45], 0, v[88:89]
	v_lshl_add_u64 v[116:117], s[46:47], 0, v[88:89]
	v_and_b32_e32 v198, 16, v144
	v_lshrrev_b32_e32 v199, 1, v198
	v_add_u32_e32 v198, v198, v199
	v_mov_b32_e32 v199, 0
	v_lshl_add_u64 v[114:115], v[114:115], 0, v[198:199]
	v_lshl_add_u64 v[116:117], v[116:117], 0, v[198:199]
	v_mfma_f32_16x16x32_bf16 v[88:91], v[52:55], v[16:19], 0
	v_mad_u32_u24 v122, v136, s76, v142
	ds_read2_b32 v[124:125], v122 offset1:1
	ds_read2_b32 v[128:129], v122 offset0:2 offset1:3
	v_mfma_f32_16x16x32_bf16 v[88:91], v[60:63], v[32:35], v[88:91]
	v_mov_b32_e32 v102, 1.0
	v_add_u32_e32 v148, v142, v123
	v_add_u32_e32 v150, v142, v141
	s_nop 4
	v_add_f32_e32 v88, v48, v88
	v_add_f32_e32 v89, v49, v89
	v_mul_f32_e32 v88, 0xbfb8aa3b, v88
	v_mul_f32_e32 v89, 0xbfb8aa3b, v89
	v_exp_f32_e32 v88, v88
	v_exp_f32_e32 v89, v89
	v_add_f32_e32 v90, v50, v90
	v_mul_f32_e32 v90, 0xbfb8aa3b, v90
	v_add_f32_e32 v88, 1.0, v88
	v_add_f32_e32 v89, 1.0, v89
	v_rcp_f32_e32 v96, v88
	v_rcp_f32_e32 v97, v89
	v_add_f32_e32 v88, v44, v92
	v_add_f32_e32 v89, v45, v93
	v_mul_f32_e32 v92, 0xc1000000, v96
	v_mul_f32_e32 v93, 0xc1000000, v97
	v_mul_f32_e32 v88, 0xbfb8aa3b, v88
	v_mul_f32_e32 v92, v145, v92
	v_mul_f32_e32 v89, 0xbfb8aa3b, v89
	v_mul_f32_e32 v93, v147, v93
	v_exp_f32_e32 v88, v88
	v_mul_f32_e32 v92, 0x3fb8aa3b, v92
	v_exp_f32_e32 v89, v89
	v_mul_f32_e32 v93, 0x3fb8aa3b, v93
	v_exp_f32_e32 v92, v92
	v_exp_f32_e32 v93, v93
	v_add_f32_e32 v88, 1.0, v88
	v_add_f32_e32 v89, 1.0, v89
	v_rcp_f32_e32 v88, v88
	v_fma_f32 v96, -v92, v92, 1.0
	v_rcp_f32_e32 v89, v89
	v_fma_f32 v97, -v93, v93, 1.0
	v_sqrt_f32_e32 v96, v96
	v_sqrt_f32_e32 v97, v97
	s_waitcnt lgkmcnt(0)
; __device__ __forceinline__ unsigned pk2(float lo, float hi) { const f32x2_t v = {lo, hi}; const bf16x2_t b = __builtin_convertvector(v, bf16x2_t); return __builtin_bit_cast(unsigned, b); }
; __device__ __forceinline__ float sigmoidf_(float x) { return __builtin_amdgcn_rcpf(1.0f + __expf(-x)); }
; __device__ __forceinline__ float bcast15(float v, int lane) { return bperm_f((lane & 48) | 15, v); }
; __device__ __forceinline__ void w_lru_m1(const Args& a, int l, unsigned char* ws, const bf16_t* proj, bf16_t* y, LAS unsigned char* wl, int b, int ck_, int h, int lane) {
;     ...
;         for (int tb = 0; tb < 4; ++tb) { const int tok = 16 * tb + lo;
;             f32x4 ga = {0.f, 0.f, 0.f, 0.f}, gx = {0.f, 0.f, 0.f, 0.f};
; #pragma unroll
;             for (int kk = 0; kk < 2; ++kk) { ga = __builtin_amdgcn_mfma_f32_16x16x32_bf16(WaF[kk], Xf[tb][kk], ga, 0, 0, 0); gx = __builtin_amdgcn_mfma_f32_16x16x32_bf16(WxF[kk], Xf[tb][kk], gx, 0, 0, 0); }
;             float hv[4], pv[4];
; #pragma unroll
;             for (int r = 0; r < 4; ++r) {
;                 const float rg = sigmoidf_(ga[r] + bav[r]), ig = sigmoidf_(gx[r] + bxv[r]);
;                 const float la = -8.0f * rg * sp[r]; float A = __expf(la);
;                 float U = __builtin_amdgcn_sqrtf(1.0f - A * A) * (ig * xcf[tok * 65 + j0 + r]);
;                 { const float As = dpp_shr1<1>(A), Us = dpp_shr0<1>(U); U = A * Us + U; A = A * As; }
;                 { const float As = dpp_shr1<2>(A), Us = dpp_shr0<2>(U); U = A * Us + U; A = A * As; }
;                 { const float As = dpp_shr1<4>(A), Us = dpp_shr0<4>(U); U = A * Us + U; A = A * As; }
;                 { const float As = dpp_shr1<8>(A), Us = dpp_shr0<8>(U); U = A * Us + U; A = A * As; }
;                 const float hh = U + A * hc[r], PP = A * Pc[r];
;                 hc[r] = bcast15(hh, lane); Pc[r] = bcast15(PP, lane); hv[r] = hh; pv[r] = PP; }
;             *(unsigned long long*)(y + (size_t)(row0 + tok) * DM + 64 * h + j0) = (unsigned long long)pk2(hv[0], hv[1]) | ((unsigned long long)pk2(hv[2], hv[3]) << 32);
;             *(unsigned long long*)((bf16_t*)(ws + WS_P) + (size_t)(row0 + tok) * 512 + 64 * h + j0) = (unsigned long long)pk2(pv[0], pv[1]) | ((unsigned long long)pk2(pv[2], pv[3]) << 32);
	v_pk_mul_f32 v[88:89], v[124:125], v[88:89]
	v_mov_b32_dpp v98, v92 row_shr:1 row_mask:0xf bank_mask:0xf
	v_mov_b32_dpp v99, v93 row_shr:1 row_mask:0xf bank_mask:0xf
	v_pk_mul_f32 v[88:89], v[88:89], v[96:97]
	v_pk_mul_f32 v[98:99], v[92:93], v[98:99]
	v_exp_f32_e32 v90, v90
	v_mov_b32_dpp v96, v88 row_shr:1 row_mask:0xf bank_mask:0xf bound_ctrl:1
	v_mov_b32_dpp v97, v89 row_shr:1 row_mask:0xf bank_mask:0xf bound_ctrl:1
	v_pk_fma_f32 v[88:89], v[92:93], v[96:97], v[88:89]
	v_mov_b32_dpp v100, v98 row_shr:2 row_mask:0xf bank_mask:0xf
	v_mov_b32_dpp v101, v99 row_shr:2 row_mask:0xf bank_mask:0xf
	v_mov_b32_dpp v92, v88 row_shr:2 row_mask:0xf bank_mask:0xf bound_ctrl:1
	v_mov_b32_dpp v93, v89 row_shr:2 row_mask:0xf bank_mask:0xf bound_ctrl:1
	v_pk_fma_f32 v[88:89], v[98:99], v[92:93], v[88:89]
	v_pk_mul_f32 v[100:101], v[98:99], v[100:101]
	v_add_f32_e32 v90, 1.0, v90
	v_mov_b32_dpp v92, v88 row_shr:4 row_mask:0xf bank_mask:0xf bound_ctrl:1
	v_mov_b32_dpp v93, v89 row_shr:4 row_mask:0xf bank_mask:0xf bound_ctrl:1
	v_mov_b32_dpp v102, v100 row_shr:4 row_mask:0xf bank_mask:0xf
	v_mov_b32_dpp v103, v101 row_shr:4 row_mask:0xf bank_mask:0xf
	v_pk_fma_f32 v[88:89], v[100:101], v[92:93], v[88:89]
	v_pk_mul_f32 v[102:103], v[100:101], v[102:103]
	v_add_f32_e32 v91, v51, v91
	v_mov_b32_dpp v92, v88 row_shr:8 row_mask:0xf bank_mask:0xf bound_ctrl:1
	v_mov_b32_dpp v93, v89 row_shr:8 row_mask:0xf bank_mask:0xf bound_ctrl:1
	v_pk_fma_f32 v[88:89], v[102:103], v[92:93], v[88:89]
	v_rcp_f32_e32 v92, v90
	v_mul_f32_e32 v91, 0xbfb8aa3b, v91
	v_exp_f32_e32 v91, v91
	v_add_f32_e32 v90, v46, v94
	v_mul_f32_e32 v92, 0xc1000000, v92
	v_mul_f32_e32 v92, v2, v92
	v_mul_f32_e32 v92, 0x3fb8aa3b, v92
	v_exp_f32_e32 v92, v92
	v_add_f32_e32 v91, 1.0, v91
	v_mul_f32_e32 v90, 0xbfb8aa3b, v90
	v_exp_f32_e32 v90, v90
	v_fma_f32 v93, -v92, v92, 1.0
	v_sqrt_f32_e32 v94, v93
	v_rcp_f32_e32 v93, v91
	v_add_f32_e32 v91, v47, v95
	v_mul_f32_e32 v91, 0xbfb8aa3b, v91
	v_exp_f32_e32 v91, v91
	v_mul_f32_e32 v93, 0xc1000000, v93
	v_mul_f32_e32 v93, v146, v93
	v_mul_f32_e32 v93, 0x3fb8aa3b, v93
	v_exp_f32_e32 v93, v93
	v_add_f32_e32 v90, 1.0, v90
	v_add_f32_e32 v91, 1.0, v91
	v_rcp_f32_e32 v90, v90
	v_rcp_f32_e32 v91, v91
	v_fma_f32 v95, -v93, v93, 1.0
	v_sqrt_f32_e32 v95, v95
	v_mov_b32_e32 v96, 1.0
	v_pk_mul_f32 v[90:91], v[90:91], v[128:129]
	v_mov_b32_e32 v97, 1.0
	v_pk_mul_f32 v[90:91], v[94:95], v[90:91]
	v_mov_b32_dpp v96, v92 row_shr:1 row_mask:0xf bank_mask:0xf
	v_mov_b32_dpp v97, v93 row_shr:1 row_mask:0xf bank_mask:0xf
	v_mov_b32_dpp v94, v90 row_shr:1 row_mask:0xf bank_mask:0xf bound_ctrl:1
	v_mov_b32_dpp v95, v91 row_shr:1 row_mask:0xf bank_mask:0xf bound_ctrl:1
	v_pk_mul_f32 v[96:97], v[92:93], v[96:97]
	v_mov_b32_e32 v100, 1.0
	v_mov_b32_e32 v101, 1.0
	v_pk_fma_f32 v[90:91], v[92:93], v[94:95], v[90:91]
	v_mov_b32_dpp v104, v102 row_shr:8 row_mask:0xf bank_mask:0xf
	v_mov_b32_dpp v105, v103 row_shr:8 row_mask:0xf bank_mask:0xf
	v_mov_b32_dpp v100, v96 row_shr:2 row_mask:0xf bank_mask:0xf
	v_mov_b32_dpp v101, v97 row_shr:2 row_mask:0xf bank_mask:0xf
	v_mov_b32_dpp v92, v90 row_shr:2 row_mask:0xf bank_mask:0xf bound_ctrl:1
	v_mov_b32_dpp v93, v91 row_shr:2 row_mask:0xf bank_mask:0xf bound_ctrl:1
	v_pk_mul_f32 v[106:107], v[102:103], v[104:105]
	v_pk_mul_f32 v[100:101], v[96:97], v[100:101]
	v_mov_b32_e32 v102, 1.0
	v_mov_b32_e32 v103, 1.0
	v_pk_fma_f32 v[90:91], v[96:97], v[92:93], v[90:91]
	v_mov_b32_dpp v102, v100 row_shr:4 row_mask:0xf bank_mask:0xf
	v_mov_b32_dpp v103, v101 row_shr:4 row_mask:0xf bank_mask:0xf
	v_mov_b32_dpp v92, v90 row_shr:4 row_mask:0xf bank_mask:0xf bound_ctrl:1
	v_mov_b32_dpp v93, v91 row_shr:4 row_mask:0xf bank_mask:0xf bound_ctrl:1
	v_pk_mul_f32 v[102:103], v[100:101], v[102:103]
	v_mov_b32_e32 v124, 1.0
	v_mov_b32_e32 v125, 1.0
	v_pk_fma_f32 v[90:91], v[100:101], v[92:93], v[90:91]
	v_mov_b32_dpp v124, v102 row_shr:8 row_mask:0xf bank_mask:0xf
	v_mov_b32_dpp v125, v103 row_shr:8 row_mask:0xf bank_mask:0xf
	v_mov_b32_dpp v92, v90 row_shr:8 row_mask:0xf bank_mask:0xf bound_ctrl:1
	v_mov_b32_dpp v93, v91 row_shr:8 row_mask:0xf bank_mask:0xf bound_ctrl:1
	v_pk_mul_f32 v[126:127], v[102:103], v[124:125]
	v_pk_fma_f32 v[90:91], v[102:103], v[92:93], v[90:91]
	v_pk_fma_f32 v[88:89], v[106:107], 0, v[88:89] op_sel_hi:[1,0,1]
	v_pk_fma_f32 v[90:91], v[126:127], 0, v[90:91] op_sel_hi:[1,0,1]
	ds_bpermute_b32 v98, v143, v88 offset:60
	ds_bpermute_b32 v99, v143, v89 offset:60
	ds_bpermute_b32 v96, v143, v90 offset:60
	v_cvt_pk_bf16_f32 v88, v88, v89
	v_cvt_pk_bf16_f32 v89, v90, v91
	v_or_b32_e32 v90, s48, v136
	ds_bpermute_b32 v97, v143, v91 offset:60
	v_ashrrev_i32_e32 v91, 31, v90
	v_lshlrev_b64 v[92:93], 11, v[90:91]
	v_lshl_add_u64 v[100:101], v[114:115], 0, v[92:93]
	v_lshlrev_b64 v[90:91], 10, v[90:91]
	v_mov_b64_e32 v[222:223], v[88:89]
	v_cvt_pk_bf16_f32 v88, v106, v107
	v_cvt_pk_bf16_f32 v89, v126, v127
	v_lshl_add_u64 v[102:103], v[116:117], 0, v[90:91]
	v_mov_b64_e32 v[226:227], v[88:89]
	v_mfma_f32_16x16x32_bf16 v[88:91], v[52:55], v[12:15], 0
	ds_bpermute_b32 v124, v143, v126 offset:60
	ds_bpermute_b32 v125, v143, v127 offset:60
	ds_bpermute_b32 v104, v143, v106 offset:60
	v_mfma_f32_16x16x32_bf16 v[126:129], v[56:59], v[12:15], 0
	ds_bpermute_b32 v105, v143, v107 offset:60
	v_mfma_f32_16x16x32_bf16 v[92:95], v[60:63], v[28:31], v[88:91]
	v_mfma_f32_16x16x32_bf16 v[88:91], v[64:67], v[28:31], v[126:129]
	s_nop 6
	v_add_f32_e32 v92, v48, v92
	v_mul_f32_e32 v92, 0xbfb8aa3b, v92
	v_exp_f32_e32 v92, v92
	v_add_f32_e32 v88, v44, v88
	v_mul_f32_e32 v88, 0xbfb8aa3b, v88
	v_exp_f32_e32 v88, v88
	v_add_f32_e32 v92, 1.0, v92
	v_rcp_f32_e32 v92, v92
; __device__ __forceinline__ unsigned pk2(float lo, float hi) { const f32x2_t v = {lo, hi}; const bf16x2_t b = __builtin_convertvector(v, bf16x2_t); return __builtin_bit_cast(unsigned, b); }
; __device__ __forceinline__ float sigmoidf_(float x) { return __builtin_amdgcn_rcpf(1.0f + __expf(-x)); }
; __device__ __forceinline__ float bcast15(float v, int lane) { return bperm_f((lane & 48) | 15, v); }
; __device__ __forceinline__ void w_lru_m1(const Args& a, int l, unsigned char* ws, const bf16_t* proj, bf16_t* y, LAS unsigned char* wl, int b, int ck_, int h, int lane) {
;     ...
;         for (int tb = 0; tb < 4; ++tb) { const int tok = 16 * tb + lo;
;             f32x4 ga = {0.f, 0.f, 0.f, 0.f}, gx = {0.f, 0.f, 0.f, 0.f};
; #pragma unroll
;             for (int kk = 0; kk < 2; ++kk) { ga = __builtin_amdgcn_mfma_f32_16x16x32_bf16(WaF[kk], Xf[tb][kk], ga, 0, 0, 0); gx = __builtin_amdgcn_mfma_f32_16x16x32_bf16(WxF[kk], Xf[tb][kk], gx, 0, 0, 0); }
;             float hv[4], pv[4];
; #pragma unroll
;             for (int r = 0; r < 4; ++r) {
;                 const float rg = sigmoidf_(ga[r] + bav[r]), ig = sigmoidf_(gx[r] + bxv[r]);
;                 const float la = -8.0f * rg * sp[r]; float A = __expf(la);
;                 float U = __builtin_amdgcn_sqrtf(1.0f - A * A) * (ig * xcf[tok * 65 + j0 + r]);
;                 { const float As = dpp_shr1<1>(A), Us = dpp_shr0<1>(U); U = A * Us + U; A = A * As; }
;                 { const float As = dpp_shr1<2>(A), Us = dpp_shr0<2>(U); U = A * Us + U; A = A * As; }
;                 { const float As = dpp_shr1<4>(A), Us = dpp_shr0<4>(U); U = A * Us + U; A = A * As; }
;                 { const float As = dpp_shr1<8>(A), Us = dpp_shr0<8>(U); U = A * Us + U; A = A * As; }
;                 const float hh = U + A * hc[r], PP = A * Pc[r];
;                 hc[r] = bcast15(hh, lane); Pc[r] = bcast15(PP, lane); hv[r] = hh; pv[r] = PP; }
;             *(unsigned long long*)(y + (size_t)(row0 + tok) * DM + 64 * h + j0) = (unsigned long long)pk2(hv[0], hv[1]) | ((unsigned long long)pk2(hv[2], hv[3]) << 32);
;             *(unsigned long long*)((bf16_t*)(ws + WS_P) + (size_t)(row0 + tok) * 512 + 64 * h + j0) = (unsigned long long)pk2(pv[0], pv[1]) | ((unsigned long long)pk2(pv[2], pv[3]) << 32);
	v_add_f32_e32 v89, v45, v89
	v_add_f32_e32 v88, 1.0, v88
	v_rcp_f32_e32 v106, v88
	v_mul_f32_e32 v88, 0xc1000000, v92
	v_add_f32_e32 v92, v49, v93
	v_mul_f32_e32 v92, 0xbfb8aa3b, v92
	v_exp_f32_e32 v92, v92
	v_mul_f32_e32 v89, 0xbfb8aa3b, v89
	v_exp_f32_e32 v89, v89
	v_mul_f32_e32 v88, v145, v88
	v_add_f32_e32 v92, 1.0, v92
	v_rcp_f32_e32 v92, v92
	v_add_f32_e32 v89, 1.0, v89
	v_rcp_f32_e32 v107, v89
	v_mul_f32_e32 v88, 0x3fb8aa3b, v88
	v_mul_f32_e32 v89, 0xc1000000, v92
	v_mul_f32_e32 v89, v147, v89
	v_mul_f32_e32 v89, 0x3fb8aa3b, v89
	v_exp_f32_e32 v122, v88
	v_exp_f32_e32 v123, v89
	v_add_f32_e32 v94, v50, v94
	v_add_f32_e32 v95, v51, v95
	v_fma_f32 v88, -v122, v122, 1.0
	v_fma_f32 v89, -v123, v123, 1.0
	v_sqrt_f32_e32 v126, v88
	v_mov_b32_e32 v88, 1.0
	v_sqrt_f32_e32 v127, v89
	v_mov_b32_e32 v89, 1.0
	v_mov_b32_dpp v88, v122 row_shr:1 row_mask:0xf bank_mask:0xf
	v_mul_f32_e32 v94, 0xbfb8aa3b, v94
	v_mov_b32_dpp v89, v123 row_shr:1 row_mask:0xf bank_mask:0xf
	v_pk_mul_f32 v[128:129], v[122:123], v[88:89]
	v_mov_b32_e32 v88, 1.0
	v_mov_b32_e32 v89, 1.0
	v_mul_f32_e32 v95, 0xbfb8aa3b, v95
	v_mov_b32_dpp v88, v128 row_shr:2 row_mask:0xf bank_mask:0xf
	v_mov_b32_dpp v89, v129 row_shr:2 row_mask:0xf bank_mask:0xf
	v_pk_mul_f32 v[130:131], v[128:129], v[88:89]
	v_mov_b32_e32 v88, 1.0
	v_mov_b32_e32 v89, 1.0
	v_exp_f32_e32 v94, v94
	v_mov_b32_dpp v88, v130 row_shr:4 row_mask:0xf bank_mask:0xf
	v_mov_b32_dpp v89, v131 row_shr:4 row_mask:0xf bank_mask:0xf
	v_pk_mul_f32 v[132:133], v[130:131], v[88:89]
	v_mov_b32_e32 v88, 1.0
	v_mov_b32_e32 v89, 1.0
	v_exp_f32_e32 v95, v95
	v_mov_b32_dpp v88, v132 row_shr:8 row_mask:0xf bank_mask:0xf
	v_mov_b32_dpp v89, v133 row_shr:8 row_mask:0xf bank_mask:0xf
	v_pk_mul_f32 v[134:135], v[132:133], v[88:89]
	v_add_f32_e32 v90, v46, v90
	s_waitcnt lgkmcnt(0)
	v_pk_mul_f32 v[92:93], v[134:135], v[104:105]
	ds_read2_b32 v[104:105], v148 offset1:1
	v_add_f32_e32 v91, v47, v91
	v_mul_f32_e32 v90, 0xbfb8aa3b, v90
	v_mul_f32_e32 v91, 0xbfb8aa3b, v91
	v_add_f32_e32 v94, 1.0, v94
	s_waitcnt lgkmcnt(0)
	v_pk_mul_f32 v[104:105], v[104:105], v[106:107]
	v_exp_f32_e32 v90, v90
	v_pk_mul_f32 v[104:105], v[104:105], v[126:127]
	v_add_f32_e32 v95, 1.0, v95
	v_exp_f32_e32 v91, v91
	v_mov_b32_dpp v106, v104 row_shr:1 row_mask:0xf bank_mask:0xf bound_ctrl:1
	v_mov_b32_dpp v107, v105 row_shr:1 row_mask:0xf bank_mask:0xf bound_ctrl:1
	v_pk_fma_f32 v[104:105], v[122:123], v[106:107], v[104:105]
	v_rcp_f32_e32 v94, v94
	v_rcp_f32_e32 v95, v95
	v_mov_b32_dpp v106, v104 row_shr:2 row_mask:0xf bank_mask:0xf bound_ctrl:1
	v_mov_b32_dpp v107, v105 row_shr:2 row_mask:0xf bank_mask:0xf bound_ctrl:1
	v_pk_fma_f32 v[104:105], v[128:129], v[106:107], v[104:105]
	v_add_f32_e32 v90, 1.0, v90
	v_add_f32_e32 v91, 1.0, v91
	v_mov_b32_dpp v106, v104 row_shr:4 row_mask:0xf bank_mask:0xf bound_ctrl:1
	v_mov_b32_dpp v107, v105 row_shr:4 row_mask:0xf bank_mask:0xf bound_ctrl:1
	v_pk_fma_f32 v[104:105], v[130:131], v[106:107], v[104:105]
	ds_bpermute_b32 v88, v143, v92 offset:60
	ds_bpermute_b32 v89, v143, v93 offset:60
	v_mov_b32_dpp v106, v104 row_shr:8 row_mask:0xf bank_mask:0xf bound_ctrl:1
	v_mov_b32_dpp v107, v105 row_shr:8 row_mask:0xf bank_mask:0xf bound_ctrl:1
	v_pk_fma_f32 v[104:105], v[132:133], v[106:107], v[104:105]
	v_rcp_f32_e32 v106, v90
	v_mul_f32_e32 v90, 0xc1000000, v94
	v_rcp_f32_e32 v107, v91
	v_mul_f32_e32 v91, 0xc1000000, v95
	v_mul_f32_e32 v90, v2, v90
	v_mul_f32_e32 v91, v146, v91
	v_mul_f32_e32 v90, 0x3fb8aa3b, v90
	v_mul_f32_e32 v91, 0x3fb8aa3b, v91
	v_exp_f32_e32 v94, v90
	v_exp_f32_e32 v95, v91
	v_pk_fma_f32 v[104:105], v[134:135], v[98:99], v[104:105]
	ds_read2_b32 v[134:135], v148 offset0:2 offset1:3
	v_fma_f32 v90, -v94, v94, 1.0
	v_fma_f32 v91, -v95, v95, 1.0
	v_sqrt_f32_e32 v122, v90
	v_sqrt_f32_e32 v123, v91
	s_waitcnt lgkmcnt(0)
	v_pk_mul_f32 v[106:107], v[106:107], v[134:135]
	v_mov_b32_e32 v90, 1.0
	v_mov_b32_e32 v91, 1.0
	v_pk_mul_f32 v[106:107], v[122:123], v[106:107]
	v_mov_b32_dpp v90, v94 row_shr:1 row_mask:0xf bank_mask:0xf
	v_mov_b32_dpp v91, v95 row_shr:1 row_mask:0xf bank_mask:0xf
	v_mov_b32_dpp v122, v106 row_shr:1 row_mask:0xf bank_mask:0xf bound_ctrl:1
	v_mov_b32_dpp v123, v107 row_shr:1 row_mask:0xf bank_mask:0xf bound_ctrl:1
	v_pk_mul_f32 v[126:127], v[94:95], v[90:91]
	v_mov_b32_e32 v90, 1.0
	v_mov_b32_e32 v91, 1.0
	v_pk_fma_f32 v[94:95], v[94:95], v[122:123], v[106:107]
	v_mov_b32_dpp v90, v126 row_shr:2 row_mask:0xf bank_mask:0xf
	v_mov_b32_dpp v91, v127 row_shr:2 row_mask:0xf bank_mask:0xf
	v_mov_b32_dpp v106, v94 row_shr:2 row_mask:0xf bank_mask:0xf bound_ctrl:1
	v_mov_b32_dpp v107, v95 row_shr:2 row_mask:0xf bank_mask:0xf bound_ctrl:1
	v_pk_mul_f32 v[128:129], v[126:127], v[90:91]
	v_mov_b32_e32 v90, 1.0
	v_mov_b32_e32 v91, 1.0
	v_pk_fma_f32 v[94:95], v[126:127], v[106:107], v[94:95]
	v_mov_b32_dpp v90, v128 row_shr:4 row_mask:0xf bank_mask:0xf
	v_mov_b32_dpp v91, v129 row_shr:4 row_mask:0xf bank_mask:0xf
	v_mov_b32_dpp v106, v94 row_shr:4 row_mask:0xf bank_mask:0xf bound_ctrl:1
	v_mov_b32_dpp v107, v95 row_shr:4 row_mask:0xf bank_mask:0xf bound_ctrl:1
	v_pk_mul_f32 v[130:131], v[128:129], v[90:91]
	v_mov_b32_e32 v90, 1.0
	v_mov_b32_e32 v91, 1.0
	v_pk_fma_f32 v[94:95], v[128:129], v[106:107], v[94:95]
	v_mov_b32_dpp v90, v130 row_shr:8 row_mask:0xf bank_mask:0xf
	v_mov_b32_dpp v91, v131 row_shr:8 row_mask:0xf bank_mask:0xf
	v_mov_b32_dpp v106, v94 row_shr:8 row_mask:0xf bank_mask:0xf bound_ctrl:1
	v_mov_b32_dpp v107, v95 row_shr:8 row_mask:0xf bank_mask:0xf bound_ctrl:1
	v_pk_mul_f32 v[132:133], v[130:131], v[90:91]
	v_pk_fma_f32 v[94:95], v[130:131], v[106:107], v[94:95]
; __device__ __forceinline__ unsigned pk2(float lo, float hi) { const f32x2_t v = {lo, hi}; const bf16x2_t b = __builtin_convertvector(v, bf16x2_t); return __builtin_bit_cast(unsigned, b); }
; __device__ __forceinline__ float sigmoidf_(float x) { return __builtin_amdgcn_rcpf(1.0f + __expf(-x)); }
; __device__ __forceinline__ float bcast15(float v, int lane) { return bperm_f((lane & 48) | 15, v); }
; __device__ __forceinline__ void w_lru_m1(const Args& a, int l, unsigned char* ws, const bf16_t* proj, bf16_t* y, LAS unsigned char* wl, int b, int ck_, int h, int lane) {
;     ...
;         for (int tb = 0; tb < 4; ++tb) { const int tok = 16 * tb + lo;
;             f32x4 ga = {0.f, 0.f, 0.f, 0.f}, gx = {0.f, 0.f, 0.f, 0.f};
; #pragma unroll
;             for (int kk = 0; kk < 2; ++kk) { ga = __builtin_amdgcn_mfma_f32_16x16x32_bf16(WaF[kk], Xf[tb][kk], ga, 0, 0, 0); gx = __builtin_amdgcn_mfma_f32_16x16x32_bf16(WxF[kk], Xf[tb][kk], gx, 0, 0, 0); }
;             float hv[4], pv[4];
; #pragma unroll
;             for (int r = 0; r < 4; ++r) {
;                 const float rg = sigmoidf_(ga[r] + bav[r]), ig = sigmoidf_(gx[r] + bxv[r]);
;                 const float la = -8.0f * rg * sp[r]; float A = __expf(la);
;                 float U = __builtin_amdgcn_sqrtf(1.0f - A * A) * (ig * xcf[tok * 65 + j0 + r]);
;                 { const float As = dpp_shr1<1>(A), Us = dpp_shr0<1>(U); U = A * Us + U; A = A * As; }
;                 { const float As = dpp_shr1<2>(A), Us = dpp_shr0<2>(U); U = A * Us + U; A = A * As; }
;                 { const float As = dpp_shr1<4>(A), Us = dpp_shr0<4>(U); U = A * Us + U; A = A * As; }
;                 { const float As = dpp_shr1<8>(A), Us = dpp_shr0<8>(U); U = A * Us + U; A = A * As; }
;                 const float hh = U + A * hc[r], PP = A * Pc[r];
;                 hc[r] = bcast15(hh, lane); Pc[r] = bcast15(PP, lane); hv[r] = hh; pv[r] = PP; }
;             *(unsigned long long*)(y + (size_t)(row0 + tok) * DM + 64 * h + j0) = (unsigned long long)pk2(hv[0], hv[1]) | ((unsigned long long)pk2(hv[2], hv[3]) << 32);
;             *(unsigned long long*)((bf16_t*)(ws + WS_P) + (size_t)(row0 + tok) * 512 + 64 * h + j0) = (unsigned long long)pk2(pv[0], pv[1]) | ((unsigned long long)pk2(pv[2], pv[3]) << 32);
	ds_bpermute_b32 v98, v143, v104 offset:60
	v_pk_fma_f32 v[94:95], v[132:133], v[96:97], v[94:95]
	ds_bpermute_b32 v96, v143, v94 offset:60
	v_cvt_pk_bf16_f32 v107, v94, v95
	v_or_b32_e32 v94, s48, v140
	ds_bpermute_b32 v97, v143, v95 offset:60
	v_ashrrev_i32_e32 v95, 31, v94
	ds_bpermute_b32 v99, v143, v105 offset:60
	v_cvt_pk_bf16_f32 v106, v104, v105
	v_lshlrev_b64 v[104:105], 11, v[94:95]
	v_pk_mul_f32 v[124:125], v[132:133], v[124:125]
	v_lshl_add_u64 v[104:105], v[114:115], 0, v[104:105]
	v_lshlrev_b64 v[94:95], 10, v[94:95]
	v_mov_b64_e32 v[230:231], v[106:107]
	v_cvt_pk_bf16_f32 v92, v92, v93
	v_cvt_pk_bf16_f32 v93, v124, v125
	v_lshl_add_u64 v[106:107], v[116:117], 0, v[94:95]
	v_mov_b64_e32 v[234:235], v[92:93]
	v_mfma_f32_16x16x32_bf16 v[92:95], v[52:55], v[8:11], 0
	ds_bpermute_b32 v90, v143, v124 offset:60
	ds_bpermute_b32 v91, v143, v125 offset:60
	v_mfma_f32_16x16x32_bf16 v[126:129], v[60:63], v[24:27], v[92:95]
	v_mfma_f32_16x16x32_bf16 v[122:125], v[56:59], v[8:11], 0
	v_mfma_f32_16x16x32_bf16 v[122:125], v[64:67], v[24:27], v[122:125]
	s_nop 5
	v_add_f32_e32 v92, v48, v126
	v_mul_f32_e32 v92, 0xbfb8aa3b, v92
	v_exp_f32_e32 v92, v92
	v_mfma_f32_16x16x32_bf16 v[52:55], v[52:55], v[4:7], 0
	v_add_f32_e32 v92, 1.0, v92
	v_rcp_f32_e32 v93, v92
	v_add_f32_e32 v92, v44, v122
	v_mov_b32_e32 v122, 1.0
	v_mul_f32_e32 v92, 0xbfb8aa3b, v92
	v_mul_f32_e32 v93, 0xc1000000, v93
	v_mul_f32_e32 v93, v145, v93
	v_mul_f32_e32 v93, 0x3fb8aa3b, v93
	v_exp_f32_e32 v94, v93
	v_exp_f32_e32 v92, v92
	v_fma_f32 v93, -v94, v94, 1.0
	v_sqrt_f32_e32 v126, v93
	v_add_f32_e32 v93, v49, v127
	v_mul_f32_e32 v93, 0xbfb8aa3b, v93
	v_exp_f32_e32 v93, v93
	v_mov_b32_dpp v122, v94 row_shr:1 row_mask:0xf bank_mask:0xf
	v_add_f32_e32 v92, 1.0, v92
	v_rcp_f32_e32 v92, v92
	v_add_f32_e32 v93, 1.0, v93
	v_rcp_f32_e32 v95, v93
	v_add_f32_e32 v93, v45, v123
	v_mul_f32_e32 v93, 0xbfb8aa3b, v93
	v_exp_f32_e32 v93, v93
	v_mul_f32_e32 v95, 0xc1000000, v95
	v_mul_f32_e32 v95, v147, v95
	v_mul_f32_e32 v95, 0x3fb8aa3b, v95
	v_exp_f32_e32 v95, v95
	v_add_f32_e32 v93, 1.0, v93
	v_rcp_f32_e32 v93, v93
	v_fma_f32 v123, -v95, v95, 1.0
	v_sqrt_f32_e32 v127, v123
	v_mov_b32_e32 v123, 1.0
	s_nop 1
	v_mov_b32_dpp v123, v95 row_shr:1 row_mask:0xf bank_mask:0xf
	v_pk_mul_f32 v[130:131], v[94:95], v[122:123]
	v_mov_b32_e32 v122, 1.0
	v_mov_b32_e32 v123, 1.0
	s_nop 0
	v_mov_b32_dpp v122, v130 row_shr:2 row_mask:0xf bank_mask:0xf
	v_mov_b32_dpp v123, v131 row_shr:2 row_mask:0xf bank_mask:0xf
	v_pk_mul_f32 v[132:133], v[130:131], v[122:123]
	v_mov_b32_e32 v122, 1.0
	v_mov_b32_e32 v123, 1.0
	s_nop 0
	v_mov_b32_dpp v122, v132 row_shr:4 row_mask:0xf bank_mask:0xf
	v_mov_b32_dpp v123, v133 row_shr:4 row_mask:0xf bank_mask:0xf
	v_pk_mul_f32 v[134:135], v[132:133], v[122:123]
	v_mov_b32_e32 v122, 1.0
	v_mov_b32_e32 v123, 1.0
	s_nop 0
	v_mov_b32_dpp v122, v134 row_shr:8 row_mask:0xf bank_mask:0xf
	v_mov_b32_dpp v123, v135 row_shr:8 row_mask:0xf bank_mask:0xf
	v_pk_mul_f32 v[140:141], v[134:135], v[122:123]
	s_nop 0
	v_pk_mul_f32 v[148:149], v[140:141], v[88:89]
	ds_read2_b32 v[88:89], v150 offset1:1
	ds_bpermute_b32 v122, v143, v148 offset:60
	ds_bpermute_b32 v123, v143, v149 offset:60
	s_waitcnt lgkmcnt(0)
	v_pk_mul_f32 v[88:89], v[88:89], v[92:93]
	s_nop 0
	v_pk_mul_f32 v[88:89], v[88:89], v[126:127]
	s_nop 1
	v_mov_b32_dpp v92, v88 row_shr:1 row_mask:0xf bank_mask:0xf bound_ctrl:1
	v_mov_b32_dpp v93, v89 row_shr:1 row_mask:0xf bank_mask:0xf bound_ctrl:1
	v_pk_fma_f32 v[88:89], v[94:95], v[92:93], v[88:89]
	s_nop 1
	v_mov_b32_dpp v92, v88 row_shr:2 row_mask:0xf bank_mask:0xf bound_ctrl:1
	v_mov_b32_dpp v93, v89 row_shr:2 row_mask:0xf bank_mask:0xf bound_ctrl:1
	v_pk_fma_f32 v[88:89], v[130:131], v[92:93], v[88:89]
	s_nop 1
	v_mov_b32_dpp v92, v88 row_shr:4 row_mask:0xf bank_mask:0xf bound_ctrl:1
	v_mov_b32_dpp v93, v89 row_shr:4 row_mask:0xf bank_mask:0xf bound_ctrl:1
	v_pk_fma_f32 v[88:89], v[132:133], v[92:93], v[88:89]
	s_nop 1
	v_mov_b32_dpp v92, v88 row_shr:8 row_mask:0xf bank_mask:0xf bound_ctrl:1
	v_mov_b32_dpp v93, v89 row_shr:8 row_mask:0xf bank_mask:0xf bound_ctrl:1
	v_pk_fma_f32 v[88:89], v[134:135], v[92:93], v[88:89]
	v_mov_b32_e32 v92, 1.0
	v_pk_fma_f32 v[98:99], v[140:141], v[98:99], v[88:89]
	v_add_f32_e32 v88, v50, v128
	v_mul_f32_e32 v88, 0xbfb8aa3b, v88
	v_exp_f32_e32 v88, v88
	ds_read2_b32 v[140:141], v150 offset0:2 offset1:3
	ds_bpermute_b32 v94, v143, v98 offset:60
	ds_bpermute_b32 v95, v143, v99 offset:60
	v_add_f32_e32 v88, 1.0, v88
	v_rcp_f32_e32 v89, v88
	v_add_f32_e32 v88, v46, v124
	v_mul_f32_e32 v88, 0xbfb8aa3b, v88
	v_exp_f32_e32 v88, v88
	v_mul_f32_e32 v89, 0xc1000000, v89
	v_mul_f32_e32 v89, v2, v89
	v_mul_f32_e32 v89, 0x3fb8aa3b, v89
	v_exp_f32_e32 v124, v89
	v_add_f32_e32 v88, 1.0, v88
	v_rcp_f32_e32 v88, v88
	v_cvt_pk_bf16_f32 v98, v98, v99
	v_fma_f32 v89, -v124, v124, 1.0
	v_sqrt_f32_e32 v126, v89
	v_add_f32_e32 v89, v51, v129
	v_mul_f32_e32 v89, 0xbfb8aa3b, v89
	v_exp_f32_e32 v89, v89
	v_mov_b32_dpp v92, v124 row_shr:1 row_mask:0xf bank_mask:0xf
	v_add_f32_e32 v89, 1.0, v89
	v_rcp_f32_e32 v93, v89
	v_add_f32_e32 v89, v47, v125
	v_mul_f32_e32 v89, 0xbfb8aa3b, v89
	v_exp_f32_e32 v89, v89
	v_mul_f32_e32 v93, 0xc1000000, v93
	v_mul_f32_e32 v93, v146, v93
	v_mul_f32_e32 v93, 0x3fb8aa3b, v93
	v_exp_f32_e32 v125, v93
	v_add_f32_e32 v89, 1.0, v89
	v_rcp_f32_e32 v89, v89
	v_fma_f32 v93, -v125, v125, 1.0
	v_sqrt_f32_e32 v127, v93
	s_waitcnt lgkmcnt(0)
; __device__ __forceinline__ unsigned pk2(float lo, float hi) { const f32x2_t v = {lo, hi}; const bf16x2_t b = __builtin_convertvector(v, bf16x2_t); return __builtin_bit_cast(unsigned, b); }
; __device__ __forceinline__ float sigmoidf_(float x) { return __builtin_amdgcn_rcpf(1.0f + __expf(-x)); }
; __device__ __forceinline__ float bcast15(float v, int lane) { return bperm_f((lane & 48) | 15, v); }
; __device__ __forceinline__ void w_lru_m1(const Args& a, int l, unsigned char* ws, const bf16_t* proj, bf16_t* y, LAS unsigned char* wl, int b, int ck_, int h, int lane) {
;     ...
;         for (int tb = 0; tb < 4; ++tb) { const int tok = 16 * tb + lo;
;             f32x4 ga = {0.f, 0.f, 0.f, 0.f}, gx = {0.f, 0.f, 0.f, 0.f};
; #pragma unroll
;             for (int kk = 0; kk < 2; ++kk) { ga = __builtin_amdgcn_mfma_f32_16x16x32_bf16(WaF[kk], Xf[tb][kk], ga, 0, 0, 0); gx = __builtin_amdgcn_mfma_f32_16x16x32_bf16(WxF[kk], Xf[tb][kk], gx, 0, 0, 0); }
;             float hv[4], pv[4];
; #pragma unroll
;             for (int r = 0; r < 4; ++r) {
;                 const float rg = sigmoidf_(ga[r] + bav[r]), ig = sigmoidf_(gx[r] + bxv[r]);
;                 const float la = -8.0f * rg * sp[r]; float A = __expf(la);
;                 float U = __builtin_amdgcn_sqrtf(1.0f - A * A) * (ig * xcf[tok * 65 + j0 + r]);
;                 { const float As = dpp_shr1<1>(A), Us = dpp_shr0<1>(U); U = A * Us + U; A = A * As; }
;                 { const float As = dpp_shr1<2>(A), Us = dpp_shr0<2>(U); U = A * Us + U; A = A * As; }
;                 { const float As = dpp_shr1<4>(A), Us = dpp_shr0<4>(U); U = A * Us + U; A = A * As; }
;                 { const float As = dpp_shr1<8>(A), Us = dpp_shr0<8>(U); U = A * Us + U; A = A * As; }
;                 const float hh = U + A * hc[r], PP = A * Pc[r];
;                 hc[r] = bcast15(hh, lane); Pc[r] = bcast15(PP, lane); hv[r] = hh; pv[r] = PP; }
;             *(unsigned long long*)(y + (size_t)(row0 + tok) * DM + 64 * h + j0) = (unsigned long long)pk2(hv[0], hv[1]) | ((unsigned long long)pk2(hv[2], hv[3]) << 32);
;             *(unsigned long long*)((bf16_t*)(ws + WS_P) + (size_t)(row0 + tok) * 512 + 64 * h + j0) = (unsigned long long)pk2(pv[0], pv[1]) | ((unsigned long long)pk2(pv[2], pv[3]) << 32);
	v_pk_mul_f32 v[88:89], v[88:89], v[140:141]
	v_mov_b32_e32 v93, 1.0
	v_pk_mul_f32 v[88:89], v[126:127], v[88:89]
	s_nop 0
	v_mov_b32_dpp v93, v125 row_shr:1 row_mask:0xf bank_mask:0xf
	v_mov_b32_dpp v126, v88 row_shr:1 row_mask:0xf bank_mask:0xf bound_ctrl:1
	v_mov_b32_dpp v127, v89 row_shr:1 row_mask:0xf bank_mask:0xf bound_ctrl:1
	v_pk_mul_f32 v[128:129], v[124:125], v[92:93]
	v_mov_b32_e32 v92, 1.0
	v_mov_b32_e32 v93, 1.0
	v_pk_fma_f32 v[88:89], v[124:125], v[126:127], v[88:89]
	v_mov_b32_dpp v92, v128 row_shr:2 row_mask:0xf bank_mask:0xf
	v_mov_b32_dpp v93, v129 row_shr:2 row_mask:0xf bank_mask:0xf
	v_mov_b32_dpp v124, v88 row_shr:2 row_mask:0xf bank_mask:0xf bound_ctrl:1
	v_mov_b32_dpp v125, v89 row_shr:2 row_mask:0xf bank_mask:0xf bound_ctrl:1
	v_pk_mul_f32 v[130:131], v[128:129], v[92:93]
	v_mov_b32_e32 v92, 1.0
	v_mov_b32_e32 v93, 1.0
	v_pk_fma_f32 v[88:89], v[128:129], v[124:125], v[88:89]
	v_mov_b32_dpp v92, v130 row_shr:4 row_mask:0xf bank_mask:0xf
	v_mov_b32_dpp v93, v131 row_shr:4 row_mask:0xf bank_mask:0xf
	v_mov_b32_dpp v124, v88 row_shr:4 row_mask:0xf bank_mask:0xf bound_ctrl:1
	v_mov_b32_dpp v125, v89 row_shr:4 row_mask:0xf bank_mask:0xf bound_ctrl:1
	v_pk_mul_f32 v[132:133], v[130:131], v[92:93]
	v_mov_b32_e32 v92, 1.0
	v_mov_b32_e32 v93, 1.0
	v_pk_fma_f32 v[88:89], v[130:131], v[124:125], v[88:89]
	v_mov_b32_dpp v92, v132 row_shr:8 row_mask:0xf bank_mask:0xf
	v_mov_b32_dpp v93, v133 row_shr:8 row_mask:0xf bank_mask:0xf
	v_mov_b32_dpp v124, v88 row_shr:8 row_mask:0xf bank_mask:0xf bound_ctrl:1
	v_mov_b32_dpp v125, v89 row_shr:8 row_mask:0xf bank_mask:0xf bound_ctrl:1
	v_pk_mul_f32 v[134:135], v[132:133], v[92:93]
	v_pk_fma_f32 v[88:89], v[132:133], v[124:125], v[88:89]
	v_or_b32_e32 v124, s48, v139
	v_pk_fma_f32 v[96:97], v[134:135], v[96:97], v[88:89]
	v_ashrrev_i32_e32 v125, 31, v124
	v_pk_mul_f32 v[90:91], v[134:135], v[90:91]
	ds_bpermute_b32 v88, v143, v96 offset:60
	ds_bpermute_b32 v89, v143, v97 offset:60
	v_cvt_pk_bf16_f32 v99, v96, v97
	v_lshlrev_b64 v[96:97], 11, v[124:125]
	ds_bpermute_b32 v92, v143, v90 offset:60
	ds_bpermute_b32 v93, v143, v91 offset:60
	v_lshl_add_u64 v[96:97], v[114:115], 0, v[96:97]
	v_cvt_pk_bf16_f32 v127, v90, v91
	v_lshlrev_b64 v[90:91], 10, v[124:125]
	v_mov_b64_e32 v[238:239], v[98:99]
	v_cvt_pk_bf16_f32 v126, v148, v149
	v_lshl_add_u64 v[98:99], v[116:117], 0, v[90:91]
	v_mov_b64_e32 v[242:243], v[126:127]
	v_mfma_f32_16x16x32_bf16 v[124:127], v[56:59], v[4:7], 0
	v_mfma_f32_16x16x32_bf16 v[56:59], v[60:63], v[20:23], v[52:55]
	v_mfma_f32_16x16x32_bf16 v[52:55], v[64:67], v[20:23], v[124:127]
	s_nop 5
	v_add_u32_e32 v124, v142, v138
	v_add_f32_e32 v48, v48, v56
	v_add_f32_e32 v49, v49, v57
	v_mul_f32_e32 v48, 0xbfb8aa3b, v48
	v_mul_f32_e32 v49, 0xbfb8aa3b, v49
	v_exp_f32_e32 v48, v48
	v_exp_f32_e32 v49, v49
	v_add_f32_e32 v44, v44, v52
	v_add_f32_e32 v45, v45, v53
	v_mul_f32_e32 v44, 0xbfb8aa3b, v44
	v_mul_f32_e32 v45, 0xbfb8aa3b, v45
	v_add_f32_e32 v48, 1.0, v48
	v_exp_f32_e32 v44, v44
	v_add_f32_e32 v49, 1.0, v49
	v_exp_f32_e32 v45, v45
	v_rcp_f32_e32 v56, v48
	v_rcp_f32_e32 v52, v49
	v_add_f32_e32 v44, 1.0, v44
	v_add_f32_e32 v45, 1.0, v45
	v_rcp_f32_e32 v48, v44
	v_mul_f32_e32 v44, 0xc1000000, v56
	v_rcp_f32_e32 v49, v45
	v_mul_f32_e32 v45, 0xc1000000, v52
	v_mul_f32_e32 v44, v145, v44
	v_mul_f32_e32 v45, v147, v45
	v_mul_f32_e32 v44, 0x3fb8aa3b, v44
	v_mul_f32_e32 v45, 0x3fb8aa3b, v45
	v_exp_f32_e32 v56, v44
	v_exp_f32_e32 v57, v45
	v_add_f32_e32 v50, v50, v58
	v_mul_f32_e32 v50, 0xbfb8aa3b, v50
	v_fma_f32 v44, -v56, v56, 1.0
	v_fma_f32 v45, -v57, v57, 1.0
	v_sqrt_f32_e32 v60, v44
	v_mov_b32_e32 v44, 1.0
	v_sqrt_f32_e32 v61, v45
	v_mov_b32_e32 v45, 1.0
	v_exp_f32_e32 v50, v50
	v_mov_b32_dpp v44, v56 row_shr:1 row_mask:0xf bank_mask:0xf
	v_mov_b32_dpp v45, v57 row_shr:1 row_mask:0xf bank_mask:0xf
	v_pk_mul_f32 v[62:63], v[56:57], v[44:45]
	v_mov_b32_e32 v44, 1.0
	v_mov_b32_e32 v45, 1.0
	v_add_f32_e32 v46, v46, v54
	v_mov_b32_dpp v44, v62 row_shr:2 row_mask:0xf bank_mask:0xf
	v_mov_b32_dpp v45, v63 row_shr:2 row_mask:0xf bank_mask:0xf
	v_mul_f32_e32 v46, 0xbfb8aa3b, v46
	v_pk_mul_f32 v[64:65], v[62:63], v[44:45]
	v_mov_b32_e32 v44, 1.0
	v_mov_b32_e32 v45, 1.0
	v_add_f32_e32 v50, 1.0, v50
	v_exp_f32_e32 v46, v46
	v_mov_b32_dpp v44, v64 row_shr:4 row_mask:0xf bank_mask:0xf
	v_mov_b32_dpp v45, v65 row_shr:4 row_mask:0xf bank_mask:0xf
	v_rcp_f32_e32 v50, v50
	v_pk_mul_f32 v[66:67], v[64:65], v[44:45]
	v_mov_b32_e32 v44, 1.0
	v_mov_b32_e32 v45, 1.0
	v_add_f32_e32 v46, 1.0, v46
	v_mov_b32_dpp v44, v66 row_shr:8 row_mask:0xf bank_mask:0xf
	v_mov_b32_dpp v45, v67 row_shr:8 row_mask:0xf bank_mask:0xf
	v_pk_mul_f32 v[90:91], v[66:67], v[44:45]
	v_rcp_f32_e32 v54, v46
	v_pk_mul_f32 v[52:53], v[90:91], v[122:123]
	ds_read2_b32 v[122:123], v124 offset1:1
	v_mul_f32_e32 v46, 0xc1000000, v50
	v_mul_f32_e32 v2, v2, v46
	v_mul_f32_e32 v2, 0x3fb8aa3b, v2
	v_exp_f32_e32 v50, v2
	s_waitcnt lgkmcnt(0)
; __device__ __forceinline__ unsigned pk2(float lo, float hi) { const f32x2_t v = {lo, hi}; const bf16x2_t b = __builtin_convertvector(v, bf16x2_t); return __builtin_bit_cast(unsigned, b); }
; __device__ __forceinline__ float sigmoidf_(float x) { return __builtin_amdgcn_rcpf(1.0f + __expf(-x)); }
; __device__ __forceinline__ void w_lru_m1(const Args& a, int l, unsigned char* ws, const bf16_t* proj, bf16_t* y, LAS unsigned char* wl, int b, int ck_, int h, int lane) {
;     ...
;         for (int tb = 0; tb < 4; ++tb) { const int tok = 16 * tb + lo;
;             f32x4 ga = {0.f, 0.f, 0.f, 0.f}, gx = {0.f, 0.f, 0.f, 0.f};
; #pragma unroll
;             for (int kk = 0; kk < 2; ++kk) { ga = __builtin_amdgcn_mfma_f32_16x16x32_bf16(WaF[kk], Xf[tb][kk], ga, 0, 0, 0); gx = __builtin_amdgcn_mfma_f32_16x16x32_bf16(WxF[kk], Xf[tb][kk], gx, 0, 0, 0); }
;             float hv[4], pv[4];
; #pragma unroll
;             for (int r = 0; r < 4; ++r) {
;                 const float rg = sigmoidf_(ga[r] + bav[r]), ig = sigmoidf_(gx[r] + bxv[r]);
;                 const float la = -8.0f * rg * sp[r]; float A = __expf(la);
;                 float U = __builtin_amdgcn_sqrtf(1.0f - A * A) * (ig * xcf[tok * 65 + j0 + r]);
;                 { const float As = dpp_shr1<1>(A), Us = dpp_shr0<1>(U); U = A * Us + U; A = A * As; }
;                 { const float As = dpp_shr1<2>(A), Us = dpp_shr0<2>(U); U = A * Us + U; A = A * As; }
;                 { const float As = dpp_shr1<4>(A), Us = dpp_shr0<4>(U); U = A * Us + U; A = A * As; }
;                 { const float As = dpp_shr1<8>(A), Us = dpp_shr0<8>(U); U = A * Us + U; A = A * As; }
;                 const float hh = U + A * hc[r], PP = A * Pc[r];
;                 hc[r] = bcast15(hh, lane); Pc[r] = bcast15(PP, lane); hv[r] = hh; pv[r] = PP; }
;             *(unsigned long long*)(y + (size_t)(row0 + tok) * DM + 64 * h + j0) = (unsigned long long)pk2(hv[0], hv[1]) | ((unsigned long long)pk2(hv[2], hv[3]) << 32);
;             *(unsigned long long*)((bf16_t*)(ws + WS_P) + (size_t)(row0 + tok) * 512 + 64 * h + j0) = (unsigned long long)pk2(pv[0], pv[1]) | ((unsigned long long)pk2(pv[2], pv[3]) << 32);
;         }
;         if (lo == 0) { const size_t so = (size_t)(b * NCH + ck_) * 512 + 64 * h + j0;
; #pragma unroll
;             for (int r = 0; r < 4; ++r) { ((float*)(ws + WS_LRUA))[so + r] = Pc[r]; ((float*)(ws + WS_LRUH))[so + r] = hc[r]; } }
	v_pk_mul_f32 v[48:49], v[122:123], v[48:49]
	v_add_f32_e32 v47, v47, v55
	v_pk_mul_f32 v[48:49], v[48:49], v[60:61]
	v_fma_f32 v2, -v50, v50, 1.0
	v_mul_f32_e32 v47, 0xbfb8aa3b, v47
	v_mov_b32_dpp v60, v48 row_shr:1 row_mask:0xf bank_mask:0xf bound_ctrl:1
	v_mov_b32_dpp v61, v49 row_shr:1 row_mask:0xf bank_mask:0xf bound_ctrl:1
	v_pk_fma_f32 v[48:49], v[56:57], v[60:61], v[48:49]
	v_sqrt_f32_e32 v60, v2
	v_add_f32_e32 v2, v51, v59
	v_mul_f32_e32 v2, 0xbfb8aa3b, v2
	v_exp_f32_e32 v2, v2
	v_exp_f32_e32 v47, v47
	v_mov_b32_e32 v46, 1.0
	v_mov_b32_dpp v56, v48 row_shr:2 row_mask:0xf bank_mask:0xf bound_ctrl:1
	v_add_f32_e32 v2, 1.0, v2
	v_rcp_f32_e32 v2, v2
	v_add_f32_e32 v47, 1.0, v47
	v_rcp_f32_e32 v55, v47
	v_mov_b32_e32 v47, 1.0
	v_mul_f32_e32 v2, 0xc1000000, v2
	v_mul_f32_e32 v2, v146, v2
	v_mul_f32_e32 v2, 0x3fb8aa3b, v2
	v_exp_f32_e32 v51, v2
	v_mov_b32_dpp v57, v49 row_shr:2 row_mask:0xf bank_mask:0xf bound_ctrl:1
	v_mov_b32_dpp v46, v50 row_shr:1 row_mask:0xf bank_mask:0xf
	v_pk_fma_f32 v[48:49], v[62:63], v[56:57], v[48:49]
	v_mov_b32_dpp v47, v51 row_shr:1 row_mask:0xf bank_mask:0xf
	v_pk_mul_f32 v[62:63], v[50:51], v[46:47]
	v_mov_b32_e32 v46, 1.0
	v_mov_b32_e32 v47, 1.0
	v_mov_b32_dpp v56, v48 row_shr:4 row_mask:0xf bank_mask:0xf bound_ctrl:1
	v_mov_b32_dpp v57, v49 row_shr:4 row_mask:0xf bank_mask:0xf bound_ctrl:1
	v_mov_b32_dpp v46, v62 row_shr:2 row_mask:0xf bank_mask:0xf
	v_mov_b32_dpp v47, v63 row_shr:2 row_mask:0xf bank_mask:0xf
	v_pk_fma_f32 v[48:49], v[64:65], v[56:57], v[48:49]
	v_pk_mul_f32 v[64:65], v[62:63], v[46:47]
	v_mov_b32_e32 v46, 1.0
	v_mov_b32_e32 v47, 1.0
	v_mov_b32_dpp v56, v48 row_shr:8 row_mask:0xf bank_mask:0xf bound_ctrl:1
	v_mov_b32_dpp v57, v49 row_shr:8 row_mask:0xf bank_mask:0xf bound_ctrl:1
	v_mov_b32_dpp v46, v64 row_shr:4 row_mask:0xf bank_mask:0xf
	v_mov_b32_dpp v47, v65 row_shr:4 row_mask:0xf bank_mask:0xf
	v_pk_fma_f32 v[48:49], v[66:67], v[56:57], v[48:49]
	v_pk_mul_f32 v[66:67], v[64:65], v[46:47]
	v_mov_b32_e32 v46, 1.0
	v_mov_b32_e32 v47, 1.0
	v_pk_fma_f32 v[56:57], v[90:91], v[94:95], v[48:49]
	v_mov_b32_dpp v46, v66 row_shr:8 row_mask:0xf bank_mask:0xf
	v_mov_b32_dpp v47, v67 row_shr:8 row_mask:0xf bank_mask:0xf
	v_pk_mul_f32 v[90:91], v[66:67], v[46:47]
	v_fma_f32 v2, -v51, v51, 1.0
	v_pk_mul_f32 v[58:59], v[90:91], v[92:93]
	ds_read2_b32 v[92:93], v124 offset0:2 offset1:3
	v_sqrt_f32_e32 v61, v2
	ds_bpermute_b32 v44, v143, v52 offset:60
	ds_bpermute_b32 v48, v143, v56 offset:60
	ds_bpermute_b32 v49, v143, v57 offset:60
	s_waitcnt lgkmcnt(0)
	v_pk_mul_f32 v[54:55], v[54:55], v[92:93]
	ds_bpermute_b32 v45, v143, v53 offset:60
	v_pk_mul_f32 v[54:55], v[60:61], v[54:55]
	ds_bpermute_b32 v46, v143, v58 offset:60
	ds_bpermute_b32 v47, v143, v59 offset:60
	v_mov_b32_dpp v60, v54 row_shr:1 row_mask:0xf bank_mask:0xf bound_ctrl:1
	v_mov_b32_dpp v61, v55 row_shr:1 row_mask:0xf bank_mask:0xf bound_ctrl:1
	v_pk_fma_f32 v[50:51], v[50:51], v[60:61], v[54:55]
	v_cvt_pk_bf16_f32 v56, v56, v57
	v_cvt_pk_bf16_f32 v52, v52, v53
	v_mov_b32_dpp v54, v50 row_shr:2 row_mask:0xf bank_mask:0xf bound_ctrl:1
	v_mov_b32_dpp v55, v51 row_shr:2 row_mask:0xf bank_mask:0xf bound_ctrl:1
	v_pk_fma_f32 v[50:51], v[62:63], v[54:55], v[50:51]
	v_cvt_pk_bf16_f32 v53, v58, v59
	s_nop 0
	v_mov_b32_dpp v54, v50 row_shr:4 row_mask:0xf bank_mask:0xf bound_ctrl:1
	v_mov_b32_dpp v55, v51 row_shr:4 row_mask:0xf bank_mask:0xf bound_ctrl:1
	v_pk_fma_f32 v[50:51], v[64:65], v[54:55], v[50:51]
	s_nop 1
	v_mov_b32_dpp v54, v50 row_shr:8 row_mask:0xf bank_mask:0xf bound_ctrl:1
	v_mov_b32_dpp v55, v51 row_shr:8 row_mask:0xf bank_mask:0xf bound_ctrl:1
	v_pk_fma_f32 v[50:51], v[66:67], v[54:55], v[50:51]
	s_nop 0
	v_pk_fma_f32 v[54:55], v[90:91], v[88:89], v[50:51]
	ds_bpermute_b32 v50, v143, v54 offset:60
	ds_bpermute_b32 v51, v143, v55 offset:60
	v_cvt_pk_bf16_f32 v57, v54, v55
	v_or_b32_e32 v54, s48, v137
	v_ashrrev_i32_e32 v55, 31, v54
	v_lshlrev_b64 v[60:61], 11, v[54:55]
	v_lshlrev_b64 v[54:55], 10, v[54:55]
	v_lshl_add_u64 v[114:115], v[114:115], 0, v[60:61]
	v_lshl_add_u64 v[116:117], v[116:117], 0, v[54:55]
	v_mov_b64_e32 v[246:247], v[56:57]
	v_mov_b64_e32 v[250:251], v[52:53]
	s_and_saveexec_b64 s[34:35], vcc
	s_cbranch_execz .LBB0_523
	v_lshl_add_u64 v[52:53], s[42:43], 0, v[0:1]
	v_lshlrev_b64 v[52:53], 2, v[52:53]
	v_lshl_add_u64 v[54:55], s[84:85], 0, v[52:53]
	v_lshl_add_u64 v[52:53], s[86:87], 0, v[52:53]
	s_waitcnt lgkmcnt(0)
	global_store_dwordx4 v[54:55], v[44:47], off
	global_store_dwordx4 v[52:53], v[48:51], off
; __device__ __forceinline__ float sigmoidf_(float x) { return __builtin_amdgcn_rcpf(1.0f + __expf(-x)); }
; __device__ __forceinline__ void w_lru_m1(const Args& a, int l, unsigned char* ws, const bf16_t* proj, bf16_t* y, LAS unsigned char* wl, int b, int ck_, int h, int lane) {
;     ...
;     for (int jb = 0; jb < 4; ++jb) {
;         bf16x8 WaF[2], WxF[2]; f32x4 pba, pbx, plam;
; #pragma unroll
;         for (int kk = 0; kk < 2; ++kk) { WaF[kk] = nWa[kk]; WxF[kk] = nWx[kk]; }
;         pba = nba; pbx = nbx; plam = nlam;
;         if (jb < 3) {
; #pragma unroll
;             for (int kk = 0; kk < 2; ++kk) { nWa[kk] = *(const bf16x8*)(waT + (16 * (jb + 1) + lo) * 64 + 32 * kk + 8 * fq); nWx[kk] = *(const bf16x8*)(wxT + (16 * (jb + 1) + lo) * 64 + 32 * kk + 8 * fq); }
;             nba = *(const f32x4*)(ba + 16 * (jb + 1) + 4 * fq); nbx = *(const f32x4*)(bx + 16 * (jb + 1) + 4 * fq); nlam = *(const f32x4*)(lam + 16 * (jb + 1) + 4 * fq);
;         }
;         const int j0 = 16 * jb + 4 * fq;
;         float bav[4], bxv[4], sp[4], hc[4], Pc[4];
; #pragma unroll
;         for (int r = 0; r < 4; ++r) { bav[r] = pba[r]; bxv[r] = pbx[r]; sp[r] = log1pf(__expf(-plam[r])); hc[r] = 0.f; Pc[r] = 1.f; }
; #pragma unroll
;         for (int tb = 0; tb < 4; ++tb) { const int tok = 16 * tb + lo;
;             f32x4 ga = {0.f, 0.f, 0.f, 0.f}, gx = {0.f, 0.f, 0.f, 0.f};
; #pragma unroll
;             for (int kk = 0; kk < 2; ++kk) { ga = __builtin_amdgcn_mfma_f32_16x16x32_bf16(WaF[kk], Xf[tb][kk], ga, 0, 0, 0); gx = __builtin_amdgcn_mfma_f32_16x16x32_bf16(WxF[kk], Xf[tb][kk], gx, 0, 0, 0); }
;             float hv[4], pv[4];
; #pragma unroll
;             for (int r = 0; r < 4; ++r) {
;                 const float rg = sigmoidf_(ga[r] + bav[r]), ig = sigmoidf_(gx[r] + bxv[r]);
;                 const float la = -8.0f * rg * sp[r]; float A = __expf(la);
;                 float U = __builtin_amdgcn_sqrtf(1.0f - A * A) * (ig * xcf[tok * 65 + j0 + r]);
.LBB0_523:
	s_or_b64 exec, exec, s[34:35]
	v_lshlrev_b32_e32 v146, 6, v136
	v_lshl_or_b32 v2, v146, 1, v209
	s_waitcnt lgkmcnt(0)
	v_lshl_add_u64 v[44:45], v[118:119], 0, v[2:3]
	v_lshl_add_u64 v[46:47], v[120:121], 0, v[2:3]
	s_waitcnt vmcnt(2)
	s_nop 7
	v_mul_u32_u24_e32 v92, 0x104, v136
	v_add_u32_e32 v145, v142, v92
	global_load_dwordx4 v[64:67], v[44:45], off
	global_load_dwordx4 v[60:63], v[46:47], off
	global_load_dwordx4 v[56:59], v[44:45], off offset:64
	global_load_dwordx4 v[52:55], v[46:47], off offset:64
	global_load_dwordx4 v[48:51], v[108:109], off offset:128
	s_nop 7
	global_load_dwordx4 v[44:47], v[110:111], off offset:128
	global_load_dwordx4 v[88:91], v[112:113], off offset:128
	s_nop 7
	v_mov_b32_e32 v132, 1.0
	s_nop 7
	v_mov_b32_e32 v133, 1.0
	s_nop 7
	v_or_b32_e32 v1, 60, v143
	ds_read2_b32 v[136:137], v145 offset0:18 offset1:19
	s_nop 7
	v_mov_b32_e32 v147, v84
	s_nop 7
	v_mov_b32_e32 v149, v85
	s_nop 7
	v_mov_b32_e32 v130, 1.0
	s_nop 7
	v_mov_b32_e32 v131, 1.0
	s_nop 7
	v_mov_b32_e32 v2, v86
	s_nop 7
	v_mov_b32_e32 v128, 1.0
	s_nop 7
	v_mov_b32_e32 v129, 1.0
	s_nop 7
	v_mfma_f32_16x16x32_bf16 v[122:125], v[72:75], v[16:19], 0
	s_nop 7
	v_mfma_f32_16x16x32_bf16 v[124:127], v[80:83], v[32:35], v[122:125]
	s_nop 7
	v_mov_b32_e32 v148, v87
	v_mfma_f32_16x16x32_bf16 v[84:87], v[68:71], v[16:19], 0
	v_mfma_f32_16x16x32_bf16 v[84:87], v[76:79], v[32:35], v[84:87]
	s_nop 7
	v_add_f32_e32 v84, v40, v84
	v_mul_f32_e32 v84, 0xbfb8aa3b, v84
	v_exp_f32_e32 v84, v84
	v_add_f32_e32 v85, v41, v85
	v_mul_f32_e32 v85, 0xbfb8aa3b, v85
	v_exp_f32_e32 v85, v85
	v_add_f32_e32 v84, 1.0, v84
	v_rcp_f32_e32 v93, v84
	v_add_f32_e32 v84, v36, v124
	v_add_f32_e32 v85, 1.0, v85
	v_mul_f32_e32 v84, 0xbfb8aa3b, v84
	v_mul_f32_e32 v93, 0xc1000000, v93
	v_mul_f32_e32 v93, v147, v93
	v_mul_f32_e32 v93, 0x3fb8aa3b, v93
	v_exp_f32_e32 v94, v93
	v_exp_f32_e32 v84, v84
	v_mov_b32_e32 v124, 1.0
	v_add_f32_e32 v86, v42, v86
	v_fma_f32 v93, -v94, v94, 1.0
	v_sqrt_f32_e32 v122, v93
	v_rcp_f32_e32 v93, v85
	v_add_f32_e32 v85, v37, v125
	v_mul_f32_e32 v85, 0xbfb8aa3b, v85
	v_exp_f32_e32 v85, v85
	v_mul_f32_e32 v93, 0xc1000000, v93
	v_mul_f32_e32 v93, v149, v93
	v_mul_f32_e32 v93, 0x3fb8aa3b, v93
	v_exp_f32_e32 v95, v93
	v_add_f32_e32 v84, 1.0, v84
	v_add_f32_e32 v85, 1.0, v85
	v_rcp_f32_e32 v84, v84
	v_fma_f32 v93, -v95, v95, 1.0
	v_sqrt_f32_e32 v123, v93
	ds_read2_b32 v[92:93], v145 offset0:16 offset1:17
	v_rcp_f32_e32 v85, v85
	v_mov_b32_e32 v125, 1.0
	v_mov_b32_dpp v124, v94 row_shr:1 row_mask:0xf bank_mask:0xf
	v_mul_f32_e32 v86, 0xbfb8aa3b, v86
	s_waitcnt lgkmcnt(0)
	v_pk_mul_f32 v[84:85], v[92:93], v[84:85]
	v_mov_b32_dpp v125, v95 row_shr:1 row_mask:0xf bank_mask:0xf
	v_pk_mul_f32 v[84:85], v[84:85], v[122:123]
	v_pk_mul_f32 v[124:125], v[94:95], v[124:125]
	v_exp_f32_e32 v86, v86
	v_mov_b32_dpp v92, v84 row_shr:1 row_mask:0xf bank_mask:0xf bound_ctrl:1
	v_mov_b32_dpp v93, v85 row_shr:1 row_mask:0xf bank_mask:0xf bound_ctrl:1
	v_pk_fma_f32 v[84:85], v[94:95], v[92:93], v[84:85]
	v_mov_b32_dpp v128, v124 row_shr:2 row_mask:0xf bank_mask:0xf
	v_mov_b32_dpp v129, v125 row_shr:2 row_mask:0xf bank_mask:0xf
	v_mov_b32_dpp v92, v84 row_shr:2 row_mask:0xf bank_mask:0xf bound_ctrl:1
	v_mov_b32_dpp v93, v85 row_shr:2 row_mask:0xf bank_mask:0xf bound_ctrl:1
	v_pk_fma_f32 v[84:85], v[124:125], v[92:93], v[84:85]
	v_pk_mul_f32 v[128:129], v[124:125], v[128:129]
	v_add_f32_e32 v86, 1.0, v86
	v_mov_b32_dpp v92, v84 row_shr:4 row_mask:0xf bank_mask:0xf bound_ctrl:1
	v_mov_b32_dpp v93, v85 row_shr:4 row_mask:0xf bank_mask:0xf bound_ctrl:1
	v_mov_b32_dpp v130, v128 row_shr:4 row_mask:0xf bank_mask:0xf
	v_mov_b32_dpp v131, v129 row_shr:4 row_mask:0xf bank_mask:0xf
	v_pk_fma_f32 v[84:85], v[128:129], v[92:93], v[84:85]
	v_pk_mul_f32 v[130:131], v[128:129], v[130:131]
	v_add_f32_e32 v87, v43, v87
	v_mov_b32_dpp v92, v84 row_shr:8 row_mask:0xf bank_mask:0xf bound_ctrl:1
	v_mov_b32_dpp v93, v85 row_shr:8 row_mask:0xf bank_mask:0xf bound_ctrl:1
	v_pk_fma_f32 v[84:85], v[130:131], v[92:93], v[84:85]
	v_rcp_f32_e32 v92, v86
	v_mul_f32_e32 v87, 0xbfb8aa3b, v87
	v_exp_f32_e32 v87, v87
	v_add_f32_e32 v86, v38, v126
	v_mul_f32_e32 v92, 0xc1000000, v92
	v_mul_f32_e32 v92, v2, v92
	v_mul_f32_e32 v92, 0x3fb8aa3b, v92
	v_exp_f32_e32 v92, v92
	v_add_f32_e32 v87, 1.0, v87
	v_mul_f32_e32 v86, 0xbfb8aa3b, v86
	v_exp_f32_e32 v86, v86
	v_fma_f32 v93, -v92, v92, 1.0
	v_sqrt_f32_e32 v94, v93
	v_rcp_f32_e32 v93, v87
	v_add_f32_e32 v87, v39, v127
	v_mul_f32_e32 v87, 0xbfb8aa3b, v87
	v_exp_f32_e32 v87, v87
	v_mul_f32_e32 v93, 0xc1000000, v93
	v_mul_f32_e32 v93, v148, v93
	v_mul_f32_e32 v93, 0x3fb8aa3b, v93
	v_exp_f32_e32 v93, v93
	v_add_f32_e32 v86, 1.0, v86
	v_add_f32_e32 v87, 1.0, v87
	v_rcp_f32_e32 v86, v86
	v_rcp_f32_e32 v87, v87
	v_fma_f32 v95, -v93, v93, 1.0
	v_sqrt_f32_e32 v95, v95
	v_mov_b32_e32 v122, 1.0
	v_pk_mul_f32 v[86:87], v[86:87], v[136:137]
	v_mov_b32_e32 v123, 1.0
	v_pk_mul_f32 v[86:87], v[94:95], v[86:87]
	v_mov_b32_dpp v122, v92 row_shr:1 row_mask:0xf bank_mask:0xf
	v_mov_b32_dpp v123, v93 row_shr:1 row_mask:0xf bank_mask:0xf
	v_mov_b32_dpp v94, v86 row_shr:1 row_mask:0xf bank_mask:0xf bound_ctrl:1
	v_mov_b32_dpp v95, v87 row_shr:1 row_mask:0xf bank_mask:0xf bound_ctrl:1
	v_pk_mul_f32 v[122:123], v[92:93], v[122:123]
	v_mov_b32_e32 v126, 1.0
	v_mov_b32_e32 v127, 1.0
	v_pk_fma_f32 v[86:87], v[92:93], v[94:95], v[86:87]
	v_mov_b32_dpp v126, v122 row_shr:2 row_mask:0xf bank_mask:0xf
	v_mov_b32_dpp v127, v123 row_shr:2 row_mask:0xf bank_mask:0xf
	v_mov_b32_dpp v92, v86 row_shr:2 row_mask:0xf bank_mask:0xf bound_ctrl:1
	v_mov_b32_dpp v93, v87 row_shr:2 row_mask:0xf bank_mask:0xf bound_ctrl:1
; __device__ __forceinline__ unsigned pk2(float lo, float hi) { const f32x2_t v = {lo, hi}; const bf16x2_t b = __builtin_convertvector(v, bf16x2_t); return __builtin_bit_cast(unsigned, b); }
; __device__ __forceinline__ float sigmoidf_(float x) { return __builtin_amdgcn_rcpf(1.0f + __expf(-x)); }
; __device__ __forceinline__ float bcast15(float v, int lane) { return bperm_f((lane & 48) | 15, v); }
; __device__ __forceinline__ void w_lru_m1(const Args& a, int l, unsigned char* ws, const bf16_t* proj, bf16_t* y, LAS unsigned char* wl, int b, int ck_, int h, int lane) {
;     ...
;         for (int tb = 0; tb < 4; ++tb) { const int tok = 16 * tb + lo;
;             f32x4 ga = {0.f, 0.f, 0.f, 0.f}, gx = {0.f, 0.f, 0.f, 0.f};
; #pragma unroll
;             for (int kk = 0; kk < 2; ++kk) { ga = __builtin_amdgcn_mfma_f32_16x16x32_bf16(WaF[kk], Xf[tb][kk], ga, 0, 0, 0); gx = __builtin_amdgcn_mfma_f32_16x16x32_bf16(WxF[kk], Xf[tb][kk], gx, 0, 0, 0); }
;             float hv[4], pv[4];
; #pragma unroll
;             for (int r = 0; r < 4; ++r) {
;                 const float rg = sigmoidf_(ga[r] + bav[r]), ig = sigmoidf_(gx[r] + bxv[r]);
;                 const float la = -8.0f * rg * sp[r]; float A = __expf(la);
;                 float U = __builtin_amdgcn_sqrtf(1.0f - A * A) * (ig * xcf[tok * 65 + j0 + r]);
;                 { const float As = dpp_shr1<1>(A), Us = dpp_shr0<1>(U); U = A * Us + U; A = A * As; }
;                 { const float As = dpp_shr1<2>(A), Us = dpp_shr0<2>(U); U = A * Us + U; A = A * As; }
;                 { const float As = dpp_shr1<4>(A), Us = dpp_shr0<4>(U); U = A * Us + U; A = A * As; }
;                 { const float As = dpp_shr1<8>(A), Us = dpp_shr0<8>(U); U = A * Us + U; A = A * As; }
;                 const float hh = U + A * hc[r], PP = A * Pc[r];
;                 hc[r] = bcast15(hh, lane); Pc[r] = bcast15(PP, lane); hv[r] = hh; pv[r] = PP; }
;             *(unsigned long long*)(y + (size_t)(row0 + tok) * DM + 64 * h + j0) = (unsigned long long)pk2(hv[0], hv[1]) | ((unsigned long long)pk2(hv[2], hv[3]) << 32);
;             *(unsigned long long*)((bf16_t*)(ws + WS_P) + (size_t)(row0 + tok) * 512 + 64 * h + j0) = (unsigned long long)pk2(pv[0], pv[1]) | ((unsigned long long)pk2(pv[2], pv[3]) << 32);
	v_pk_mul_f32 v[126:127], v[122:123], v[126:127]
	v_mov_b32_e32 v128, 1.0
	v_mov_b32_e32 v129, 1.0
	v_pk_fma_f32 v[86:87], v[122:123], v[92:93], v[86:87]
	v_mov_b32_dpp v132, v130 row_shr:8 row_mask:0xf bank_mask:0xf
	v_mov_b32_dpp v133, v131 row_shr:8 row_mask:0xf bank_mask:0xf
	v_mov_b32_dpp v128, v126 row_shr:4 row_mask:0xf bank_mask:0xf
	v_mov_b32_dpp v129, v127 row_shr:4 row_mask:0xf bank_mask:0xf
	v_mov_b32_dpp v92, v86 row_shr:4 row_mask:0xf bank_mask:0xf bound_ctrl:1
	v_mov_b32_dpp v93, v87 row_shr:4 row_mask:0xf bank_mask:0xf bound_ctrl:1
	v_pk_mul_f32 v[134:135], v[130:131], v[132:133]
	v_pk_mul_f32 v[128:129], v[126:127], v[128:129]
	v_mov_b32_e32 v130, 1.0
	v_mov_b32_e32 v131, 1.0
	v_pk_fma_f32 v[86:87], v[126:127], v[92:93], v[86:87]
	v_mov_b32_dpp v130, v128 row_shr:8 row_mask:0xf bank_mask:0xf
	v_mov_b32_dpp v131, v129 row_shr:8 row_mask:0xf bank_mask:0xf
	v_mov_b32_dpp v92, v86 row_shr:8 row_mask:0xf bank_mask:0xf bound_ctrl:1
	v_mov_b32_dpp v93, v87 row_shr:8 row_mask:0xf bank_mask:0xf bound_ctrl:1
	v_pk_mul_f32 v[130:131], v[128:129], v[130:131]
	v_pk_fma_f32 v[86:87], v[128:129], v[92:93], v[86:87]
	v_pk_fma_f32 v[84:85], v[134:135], 0, v[84:85] op_sel_hi:[1,0,1]
	v_pk_fma_f32 v[86:87], v[130:131], 0, v[86:87] op_sel_hi:[1,0,1]
	ds_bpermute_b32 v124, v1, v84
	ds_bpermute_b32 v125, v1, v85
	v_cvt_pk_bf16_f32 v84, v84, v85
	v_cvt_pk_bf16_f32 v85, v86, v87
	v_mov_b64_e32 v[224:225], v[84:85]
	s_nop 1
	v_permlane16_swap_b32_e32 v222, v224
	v_permlane16_swap_b32_e32 v223, v225
	global_store_dwordx4 v[100:101], v[222:225], off
	v_cvt_pk_bf16_f32 v84, v134, v135
	v_cvt_pk_bf16_f32 v85, v130, v131
	ds_bpermute_b32 v122, v1, v86
	ds_bpermute_b32 v123, v1, v87
	v_mov_b64_e32 v[228:229], v[84:85]
	s_nop 1
	v_permlane16_swap_b32_e32 v226, v228
	v_permlane16_swap_b32_e32 v227, v229
	global_store_dwordx4 v[102:103], v[226:229], off
	v_mfma_f32_16x16x32_bf16 v[84:87], v[68:71], v[12:15], 0
	ds_bpermute_b32 v132, v1, v130
	ds_bpermute_b32 v133, v1, v131
	ds_bpermute_b32 v150, v1, v134
	v_mfma_f32_16x16x32_bf16 v[126:129], v[72:75], v[12:15], 0
	ds_bpermute_b32 v151, v1, v135
	v_mfma_f32_16x16x32_bf16 v[92:95], v[76:79], v[28:31], v[84:87]
	v_mfma_f32_16x16x32_bf16 v[84:87], v[80:83], v[28:31], v[126:129]
	s_nop 6
	v_add_f32_e32 v92, v40, v92
	v_mul_f32_e32 v92, 0xbfb8aa3b, v92
	v_exp_f32_e32 v92, v92
	v_add_f32_e32 v84, v36, v84
	v_mul_f32_e32 v84, 0xbfb8aa3b, v84
	v_exp_f32_e32 v84, v84
	v_add_f32_e32 v92, 1.0, v92
	v_rcp_f32_e32 v92, v92
	v_add_f32_e32 v85, v37, v85
	v_add_f32_e32 v84, 1.0, v84
	v_rcp_f32_e32 v126, v84
	v_mul_f32_e32 v84, 0xc1000000, v92
	v_add_f32_e32 v92, v41, v93
	v_mul_f32_e32 v92, 0xbfb8aa3b, v92
	v_exp_f32_e32 v92, v92
	v_mul_f32_e32 v85, 0xbfb8aa3b, v85
	v_exp_f32_e32 v85, v85
	v_mul_f32_e32 v84, v147, v84
	v_add_f32_e32 v92, 1.0, v92
	v_rcp_f32_e32 v92, v92
	v_add_f32_e32 v85, 1.0, v85
	v_rcp_f32_e32 v127, v85
	v_mul_f32_e32 v84, 0x3fb8aa3b, v84
	v_mul_f32_e32 v85, 0xc1000000, v92
	v_mul_f32_e32 v85, v149, v85
	v_mul_f32_e32 v85, 0x3fb8aa3b, v85
	v_exp_f32_e32 v128, v84
	v_exp_f32_e32 v129, v85
	v_add_f32_e32 v94, v42, v94
	v_add_f32_e32 v95, v43, v95
	v_fma_f32 v84, -v128, v128, 1.0
	v_fma_f32 v85, -v129, v129, 1.0
	v_sqrt_f32_e32 v130, v84
	v_mov_b32_e32 v84, 1.0
	v_sqrt_f32_e32 v131, v85
	v_mov_b32_e32 v85, 1.0
	v_mov_b32_dpp v84, v128 row_shr:1 row_mask:0xf bank_mask:0xf
	v_mul_f32_e32 v94, 0xbfb8aa3b, v94
	v_mov_b32_dpp v85, v129 row_shr:1 row_mask:0xf bank_mask:0xf
	v_pk_mul_f32 v[134:135], v[128:129], v[84:85]
	v_mov_b32_e32 v84, 1.0
	v_mov_b32_e32 v85, 1.0
	v_mul_f32_e32 v95, 0xbfb8aa3b, v95
	v_mov_b32_dpp v84, v134 row_shr:2 row_mask:0xf bank_mask:0xf
	v_mov_b32_dpp v85, v135 row_shr:2 row_mask:0xf bank_mask:0xf
	v_pk_mul_f32 v[136:137], v[134:135], v[84:85]
	v_mov_b32_e32 v84, 1.0
	v_mov_b32_e32 v85, 1.0
	v_exp_f32_e32 v94, v94
	v_mov_b32_dpp v84, v136 row_shr:4 row_mask:0xf bank_mask:0xf
	v_mov_b32_dpp v85, v137 row_shr:4 row_mask:0xf bank_mask:0xf
	v_pk_mul_f32 v[138:139], v[136:137], v[84:85]
	v_mov_b32_e32 v84, 1.0
	v_mov_b32_e32 v85, 1.0
	v_exp_f32_e32 v95, v95
	v_mov_b32_dpp v84, v138 row_shr:8 row_mask:0xf bank_mask:0xf
	v_mov_b32_dpp v85, v139 row_shr:8 row_mask:0xf bank_mask:0xf
	v_pk_mul_f32 v[140:141], v[138:139], v[84:85]
	v_add_u32_e32 v85, 0x1080, v145
	ds_read2_b32 v[142:143], v85 offset1:1
	v_add_f32_e32 v86, v38, v86
	v_add_f32_e32 v87, v39, v87
	v_mul_f32_e32 v86, 0xbfb8aa3b, v86
	v_mul_f32_e32 v87, 0xbfb8aa3b, v87
	s_waitcnt lgkmcnt(0)
; __device__ __forceinline__ unsigned pk2(float lo, float hi) { const f32x2_t v = {lo, hi}; const bf16x2_t b = __builtin_convertvector(v, bf16x2_t); return __builtin_bit_cast(unsigned, b); }
; __device__ __forceinline__ float sigmoidf_(float x) { return __builtin_amdgcn_rcpf(1.0f + __expf(-x)); }
; __device__ __forceinline__ float bcast15(float v, int lane) { return bperm_f((lane & 48) | 15, v); }
; __device__ __forceinline__ void w_lru_m1(const Args& a, int l, unsigned char* ws, const bf16_t* proj, bf16_t* y, LAS unsigned char* wl, int b, int ck_, int h, int lane) {
;     ...
;         for (int tb = 0; tb < 4; ++tb) { const int tok = 16 * tb + lo;
;             f32x4 ga = {0.f, 0.f, 0.f, 0.f}, gx = {0.f, 0.f, 0.f, 0.f};
; #pragma unroll
;             for (int kk = 0; kk < 2; ++kk) { ga = __builtin_amdgcn_mfma_f32_16x16x32_bf16(WaF[kk], Xf[tb][kk], ga, 0, 0, 0); gx = __builtin_amdgcn_mfma_f32_16x16x32_bf16(WxF[kk], Xf[tb][kk], gx, 0, 0, 0); }
;             float hv[4], pv[4];
; #pragma unroll
;             for (int r = 0; r < 4; ++r) {
;                 const float rg = sigmoidf_(ga[r] + bav[r]), ig = sigmoidf_(gx[r] + bxv[r]);
;                 const float la = -8.0f * rg * sp[r]; float A = __expf(la);
;                 float U = __builtin_amdgcn_sqrtf(1.0f - A * A) * (ig * xcf[tok * 65 + j0 + r]);
;                 { const float As = dpp_shr1<1>(A), Us = dpp_shr0<1>(U); U = A * Us + U; A = A * As; }
;                 { const float As = dpp_shr1<2>(A), Us = dpp_shr0<2>(U); U = A * Us + U; A = A * As; }
;                 { const float As = dpp_shr1<4>(A), Us = dpp_shr0<4>(U); U = A * Us + U; A = A * As; }
;                 { const float As = dpp_shr1<8>(A), Us = dpp_shr0<8>(U); U = A * Us + U; A = A * As; }
;                 const float hh = U + A * hc[r], PP = A * Pc[r];
;                 hc[r] = bcast15(hh, lane); Pc[r] = bcast15(PP, lane); hv[r] = hh; pv[r] = PP; }
;             *(unsigned long long*)(y + (size_t)(row0 + tok) * DM + 64 * h + j0) = (unsigned long long)pk2(hv[0], hv[1]) | ((unsigned long long)pk2(hv[2], hv[3]) << 32);
;             *(unsigned long long*)((bf16_t*)(ws + WS_P) + (size_t)(row0 + tok) * 512 + 64 * h + j0) = (unsigned long long)pk2(pv[0], pv[1]) | ((unsigned long long)pk2(pv[2], pv[3]) << 32);
	v_pk_mul_f32 v[126:127], v[142:143], v[126:127]
	v_add_f32_e32 v94, 1.0, v94
	v_pk_mul_f32 v[126:127], v[126:127], v[130:131]
	v_exp_f32_e32 v86, v86
	v_add_f32_e32 v95, 1.0, v95
	v_mov_b32_dpp v130, v126 row_shr:1 row_mask:0xf bank_mask:0xf bound_ctrl:1
	v_mov_b32_dpp v131, v127 row_shr:1 row_mask:0xf bank_mask:0xf bound_ctrl:1
	v_pk_fma_f32 v[126:127], v[128:129], v[130:131], v[126:127]
	v_exp_f32_e32 v87, v87
	v_rcp_f32_e32 v94, v94
	v_mov_b32_dpp v128, v126 row_shr:2 row_mask:0xf bank_mask:0xf bound_ctrl:1
	v_mov_b32_dpp v129, v127 row_shr:2 row_mask:0xf bank_mask:0xf bound_ctrl:1
	v_pk_fma_f32 v[126:127], v[134:135], v[128:129], v[126:127]
	v_rcp_f32_e32 v95, v95
	v_add_f32_e32 v86, 1.0, v86
	v_mov_b32_dpp v128, v126 row_shr:4 row_mask:0xf bank_mask:0xf bound_ctrl:1
	v_mov_b32_dpp v129, v127 row_shr:4 row_mask:0xf bank_mask:0xf bound_ctrl:1
	v_pk_fma_f32 v[126:127], v[136:137], v[128:129], v[126:127]
	v_add_f32_e32 v87, 1.0, v87
	v_pk_mul_f32 v[92:93], v[140:141], v[150:151]
	v_mov_b32_dpp v128, v126 row_shr:8 row_mask:0xf bank_mask:0xf bound_ctrl:1
	v_mov_b32_dpp v129, v127 row_shr:8 row_mask:0xf bank_mask:0xf bound_ctrl:1
	v_pk_fma_f32 v[126:127], v[138:139], v[128:129], v[126:127]
	v_rcp_f32_e32 v128, v86
	v_mul_f32_e32 v86, 0xc1000000, v94
	v_rcp_f32_e32 v129, v87
	v_mul_f32_e32 v87, 0xc1000000, v95
	v_mul_f32_e32 v86, v2, v86
	v_mul_f32_e32 v87, v148, v87
	v_mul_f32_e32 v86, 0x3fb8aa3b, v86
	v_mul_f32_e32 v87, 0x3fb8aa3b, v87
	v_exp_f32_e32 v94, v86
	v_exp_f32_e32 v95, v87
	v_pk_fma_f32 v[126:127], v[140:141], v[124:125], v[126:127]
	ds_bpermute_b32 v84, v1, v92
	v_fma_f32 v86, -v94, v94, 1.0
	v_fma_f32 v87, -v95, v95, 1.0
	v_sqrt_f32_e32 v130, v86
	v_mov_b32_e32 v86, 1.0
	v_sqrt_f32_e32 v131, v87
	v_mov_b32_e32 v87, 1.0
	v_mov_b32_dpp v86, v94 row_shr:1 row_mask:0xf bank_mask:0xf
	ds_bpermute_b32 v124, v1, v126
	v_mov_b32_dpp v87, v95 row_shr:1 row_mask:0xf bank_mask:0xf
	v_pk_mul_f32 v[134:135], v[94:95], v[86:87]
	v_mov_b32_e32 v86, 1.0
	v_mov_b32_e32 v87, 1.0
	ds_bpermute_b32 v125, v1, v127
	v_mov_b32_dpp v86, v134 row_shr:2 row_mask:0xf bank_mask:0xf
	v_mov_b32_dpp v87, v135 row_shr:2 row_mask:0xf bank_mask:0xf
	v_pk_mul_f32 v[136:137], v[134:135], v[86:87]
	v_mov_b32_e32 v86, 1.0
	v_mov_b32_e32 v87, 1.0
	ds_bpermute_b32 v85, v1, v93
	v_mov_b32_dpp v86, v136 row_shr:4 row_mask:0xf bank_mask:0xf
	v_mov_b32_dpp v87, v137 row_shr:4 row_mask:0xf bank_mask:0xf
	v_pk_mul_f32 v[138:139], v[136:137], v[86:87]
	v_mov_b32_e32 v86, 1.0
	v_mov_b32_e32 v87, 1.0
	v_cvt_pk_bf16_f32 v126, v126, v127
	v_mov_b32_dpp v86, v138 row_shr:8 row_mask:0xf bank_mask:0xf
	v_mov_b32_dpp v87, v139 row_shr:8 row_mask:0xf bank_mask:0xf
	v_pk_mul_f32 v[140:141], v[138:139], v[86:87]
	v_add_u32_e32 v87, 0x1088, v145
	ds_read2_b32 v[142:143], v87 offset1:1
	v_pk_mul_f32 v[132:133], v[140:141], v[132:133]
	v_cvt_pk_bf16_f32 v92, v92, v93
	v_cvt_pk_bf16_f32 v93, v132, v133
	ds_bpermute_b32 v86, v1, v132
	s_waitcnt lgkmcnt(0)
	v_pk_mul_f32 v[128:129], v[128:129], v[142:143]
	ds_bpermute_b32 v87, v1, v133
	v_pk_mul_f32 v[128:129], v[130:131], v[128:129]
	s_nop 1
	v_mov_b32_dpp v130, v128 row_shr:1 row_mask:0xf bank_mask:0xf bound_ctrl:1
	v_mov_b32_dpp v131, v129 row_shr:1 row_mask:0xf bank_mask:0xf bound_ctrl:1
	v_pk_fma_f32 v[94:95], v[94:95], v[130:131], v[128:129]
	s_nop 1
	v_mov_b32_dpp v128, v94 row_shr:2 row_mask:0xf bank_mask:0xf bound_ctrl:1
	v_mov_b32_dpp v129, v95 row_shr:2 row_mask:0xf bank_mask:0xf bound_ctrl:1
	v_pk_fma_f32 v[94:95], v[134:135], v[128:129], v[94:95]
	s_nop 1
	v_mov_b32_dpp v128, v94 row_shr:4 row_mask:0xf bank_mask:0xf bound_ctrl:1
	v_mov_b32_dpp v129, v95 row_shr:4 row_mask:0xf bank_mask:0xf bound_ctrl:1
	v_pk_fma_f32 v[94:95], v[136:137], v[128:129], v[94:95]
	s_nop 1
	v_mov_b32_dpp v128, v94 row_shr:8 row_mask:0xf bank_mask:0xf bound_ctrl:1
	v_mov_b32_dpp v129, v95 row_shr:8 row_mask:0xf bank_mask:0xf bound_ctrl:1
	v_pk_fma_f32 v[94:95], v[138:139], v[128:129], v[94:95]
	s_nop 0
	v_pk_fma_f32 v[94:95], v[140:141], v[122:123], v[94:95]
	ds_bpermute_b32 v122, v1, v94
	v_cvt_pk_bf16_f32 v127, v94, v95
	ds_bpermute_b32 v123, v1, v95
	v_mov_b64_e32 v[232:233], v[126:127]
	s_nop 1
	v_permlane16_swap_b32_e32 v230, v232
	v_permlane16_swap_b32_e32 v231, v233
	global_store_dwordx4 v[104:105], v[230:233], off
	v_mov_b64_e32 v[236:237], v[92:93]
	s_nop 1
	v_permlane16_swap_b32_e32 v234, v236
	v_permlane16_swap_b32_e32 v235, v237
	global_store_dwordx4 v[106:107], v[234:237], off
	v_mfma_f32_16x16x32_bf16 v[92:95], v[68:71], v[8:11], 0
	v_mfma_f32_16x16x32_bf16 v[130:133], v[76:79], v[24:27], v[92:95]
	v_mfma_f32_16x16x32_bf16 v[126:129], v[72:75], v[8:11], 0
	v_mfma_f32_16x16x32_bf16 v[134:137], v[80:83], v[24:27], v[126:129]
	s_nop 5
	v_add_f32_e32 v92, v40, v130
	v_mul_f32_e32 v92, 0xbfb8aa3b, v92
	v_exp_f32_e32 v92, v92
	v_mov_b32_e32 v126, 1.0
	v_mfma_f32_16x16x32_bf16 v[68:71], v[68:71], v[4:7], 0
	v_add_f32_e32 v92, 1.0, v92
	v_rcp_f32_e32 v93, v92
	v_add_f32_e32 v92, v36, v134
	v_mul_f32_e32 v92, 0xbfb8aa3b, v92
	v_exp_f32_e32 v92, v92
	v_mul_f32_e32 v93, 0xc1000000, v93
	v_mul_f32_e32 v93, v147, v93
	v_mul_f32_e32 v93, 0x3fb8aa3b, v93
	v_exp_f32_e32 v94, v93
	v_add_f32_e32 v92, 1.0, v92
	v_rcp_f32_e32 v92, v92
	v_fma_f32 v93, -v94, v94, 1.0
	v_sqrt_f32_e32 v130, v93
	v_add_f32_e32 v93, v41, v131
	v_mul_f32_e32 v93, 0xbfb8aa3b, v93
	v_exp_f32_e32 v93, v93
	v_mov_b32_dpp v126, v94 row_shr:1 row_mask:0xf bank_mask:0xf
	v_add_f32_e32 v93, 1.0, v93
	v_rcp_f32_e32 v95, v93
	v_add_f32_e32 v93, v37, v135
	v_mul_f32_e32 v93, 0xbfb8aa3b, v93
	v_exp_f32_e32 v93, v93
	v_mul_f32_e32 v95, 0xc1000000, v95
	v_mul_f32_e32 v95, v149, v95
	v_mul_f32_e32 v95, 0x3fb8aa3b, v95
	v_exp_f32_e32 v95, v95
	v_add_f32_e32 v93, 1.0, v93
	v_rcp_f32_e32 v93, v93
	v_fma_f32 v127, -v95, v95, 1.0
	v_sqrt_f32_e32 v131, v127
	v_mov_b32_e32 v127, 1.0
	s_nop 1
	v_mov_b32_dpp v127, v95 row_shr:1 row_mask:0xf bank_mask:0xf
	v_pk_mul_f32 v[134:135], v[94:95], v[126:127]
	v_mov_b32_e32 v126, 1.0
	v_mov_b32_e32 v127, 1.0
	s_nop 0
	v_mov_b32_dpp v126, v134 row_shr:2 row_mask:0xf bank_mask:0xf
	v_mov_b32_dpp v127, v135 row_shr:2 row_mask:0xf bank_mask:0xf
	v_pk_mul_f32 v[138:139], v[134:135], v[126:127]
	v_mov_b32_e32 v126, 1.0
	v_mov_b32_e32 v127, 1.0
	s_nop 0
	v_mov_b32_dpp v126, v138 row_shr:4 row_mask:0xf bank_mask:0xf
	v_mov_b32_dpp v127, v139 row_shr:4 row_mask:0xf bank_mask:0xf
	v_pk_mul_f32 v[140:141], v[138:139], v[126:127]
	v_mov_b32_e32 v126, 1.0
	v_mov_b32_e32 v127, 1.0
	s_nop 0
	v_mov_b32_dpp v126, v140 row_shr:8 row_mask:0xf bank_mask:0xf
	v_mov_b32_dpp v127, v141 row_shr:8 row_mask:0xf bank_mask:0xf
	v_pk_mul_f32 v[142:143], v[140:141], v[126:127]
	s_nop 0
	v_pk_mul_f32 v[128:129], v[142:143], v[84:85]
	v_add_u32_e32 v84, 0x20c0, v145
	ds_read2_b32 v[84:85], v84 offset1:1
	ds_bpermute_b32 v126, v1, v128
	ds_bpermute_b32 v127, v1, v129
	s_waitcnt lgkmcnt(0)
; __device__ __forceinline__ unsigned pk2(float lo, float hi) { const f32x2_t v = {lo, hi}; const bf16x2_t b = __builtin_convertvector(v, bf16x2_t); return __builtin_bit_cast(unsigned, b); }
; __device__ __forceinline__ float sigmoidf_(float x) { return __builtin_amdgcn_rcpf(1.0f + __expf(-x)); }
; __device__ __forceinline__ float bcast15(float v, int lane) { return bperm_f((lane & 48) | 15, v); }
; __device__ __forceinline__ void w_lru_m1(const Args& a, int l, unsigned char* ws, const bf16_t* proj, bf16_t* y, LAS unsigned char* wl, int b, int ck_, int h, int lane) {
;     ...
;         for (int tb = 0; tb < 4; ++tb) { const int tok = 16 * tb + lo;
;             f32x4 ga = {0.f, 0.f, 0.f, 0.f}, gx = {0.f, 0.f, 0.f, 0.f};
; #pragma unroll
;             for (int kk = 0; kk < 2; ++kk) { ga = __builtin_amdgcn_mfma_f32_16x16x32_bf16(WaF[kk], Xf[tb][kk], ga, 0, 0, 0); gx = __builtin_amdgcn_mfma_f32_16x16x32_bf16(WxF[kk], Xf[tb][kk], gx, 0, 0, 0); }
;             float hv[4], pv[4];
; #pragma unroll
;             for (int r = 0; r < 4; ++r) {
;                 const float rg = sigmoidf_(ga[r] + bav[r]), ig = sigmoidf_(gx[r] + bxv[r]);
;                 const float la = -8.0f * rg * sp[r]; float A = __expf(la);
;                 float U = __builtin_amdgcn_sqrtf(1.0f - A * A) * (ig * xcf[tok * 65 + j0 + r]);
;                 { const float As = dpp_shr1<1>(A), Us = dpp_shr0<1>(U); U = A * Us + U; A = A * As; }
;                 { const float As = dpp_shr1<2>(A), Us = dpp_shr0<2>(U); U = A * Us + U; A = A * As; }
;                 { const float As = dpp_shr1<4>(A), Us = dpp_shr0<4>(U); U = A * Us + U; A = A * As; }
;                 { const float As = dpp_shr1<8>(A), Us = dpp_shr0<8>(U); U = A * Us + U; A = A * As; }
;                 const float hh = U + A * hc[r], PP = A * Pc[r];
;                 hc[r] = bcast15(hh, lane); Pc[r] = bcast15(PP, lane); hv[r] = hh; pv[r] = PP; }
;             *(unsigned long long*)(y + (size_t)(row0 + tok) * DM + 64 * h + j0) = (unsigned long long)pk2(hv[0], hv[1]) | ((unsigned long long)pk2(hv[2], hv[3]) << 32);
;             *(unsigned long long*)((bf16_t*)(ws + WS_P) + (size_t)(row0 + tok) * 512 + 64 * h + j0) = (unsigned long long)pk2(pv[0], pv[1]) | ((unsigned long long)pk2(pv[2], pv[3]) << 32);
	v_pk_mul_f32 v[84:85], v[84:85], v[92:93]
	s_nop 0
	v_pk_mul_f32 v[84:85], v[84:85], v[130:131]
	s_nop 1
	v_mov_b32_dpp v92, v84 row_shr:1 row_mask:0xf bank_mask:0xf bound_ctrl:1
	v_mov_b32_dpp v93, v85 row_shr:1 row_mask:0xf bank_mask:0xf bound_ctrl:1
	v_pk_fma_f32 v[84:85], v[94:95], v[92:93], v[84:85]
	s_nop 1
	v_mov_b32_dpp v92, v84 row_shr:2 row_mask:0xf bank_mask:0xf bound_ctrl:1
	v_mov_b32_dpp v93, v85 row_shr:2 row_mask:0xf bank_mask:0xf bound_ctrl:1
	v_pk_fma_f32 v[84:85], v[134:135], v[92:93], v[84:85]
	s_nop 1
	v_mov_b32_dpp v92, v84 row_shr:4 row_mask:0xf bank_mask:0xf bound_ctrl:1
	v_mov_b32_dpp v93, v85 row_shr:4 row_mask:0xf bank_mask:0xf bound_ctrl:1
	v_pk_fma_f32 v[84:85], v[138:139], v[92:93], v[84:85]
	s_nop 1
	v_mov_b32_dpp v92, v84 row_shr:8 row_mask:0xf bank_mask:0xf bound_ctrl:1
	v_mov_b32_dpp v93, v85 row_shr:8 row_mask:0xf bank_mask:0xf bound_ctrl:1
	v_pk_fma_f32 v[84:85], v[140:141], v[92:93], v[84:85]
	v_mov_b32_e32 v92, 1.0
	v_pk_fma_f32 v[124:125], v[142:143], v[124:125], v[84:85]
	v_add_f32_e32 v84, v42, v132
	v_mul_f32_e32 v84, 0xbfb8aa3b, v84
	v_exp_f32_e32 v84, v84
	ds_bpermute_b32 v94, v1, v124
	ds_bpermute_b32 v95, v1, v125
	v_cvt_pk_bf16_f32 v124, v124, v125
	v_add_f32_e32 v84, 1.0, v84
	v_rcp_f32_e32 v85, v84
	v_add_f32_e32 v84, v38, v136
	v_mul_f32_e32 v84, 0xbfb8aa3b, v84
	v_exp_f32_e32 v84, v84
	v_mul_f32_e32 v85, 0xc1000000, v85
	v_mul_f32_e32 v85, v2, v85
	v_mul_f32_e32 v85, 0x3fb8aa3b, v85
	v_exp_f32_e32 v130, v85
	v_add_f32_e32 v84, 1.0, v84
	v_rcp_f32_e32 v84, v84
	v_fma_f32 v85, -v130, v130, 1.0
	v_sqrt_f32_e32 v132, v85
	v_add_f32_e32 v85, v43, v133
	v_mul_f32_e32 v85, 0xbfb8aa3b, v85
	v_exp_f32_e32 v85, v85
	v_mov_b32_dpp v92, v130 row_shr:1 row_mask:0xf bank_mask:0xf
	v_add_f32_e32 v85, 1.0, v85
	v_rcp_f32_e32 v93, v85
	v_add_f32_e32 v85, v39, v137
	v_mul_f32_e32 v85, 0xbfb8aa3b, v85
	v_exp_f32_e32 v85, v85
	v_mul_f32_e32 v93, 0xc1000000, v93
	v_mul_f32_e32 v93, v148, v93
	v_mul_f32_e32 v93, 0x3fb8aa3b, v93
	v_exp_f32_e32 v131, v93
	v_add_f32_e32 v85, 1.0, v85
	v_rcp_f32_e32 v85, v85
	v_fma_f32 v93, -v131, v131, 1.0
	v_sqrt_f32_e32 v133, v93
	v_mov_b32_e32 v93, 1.0
	s_nop 1
	v_mov_b32_dpp v93, v131 row_shr:1 row_mask:0xf bank_mask:0xf
	v_pk_mul_f32 v[134:135], v[130:131], v[92:93]
	v_mov_b32_e32 v92, 1.0
	v_mov_b32_e32 v93, 1.0
	s_nop 0
	v_mov_b32_dpp v92, v134 row_shr:2 row_mask:0xf bank_mask:0xf
	v_mov_b32_dpp v93, v135 row_shr:2 row_mask:0xf bank_mask:0xf
	v_pk_mul_f32 v[136:137], v[134:135], v[92:93]
	v_mov_b32_e32 v92, 1.0
	v_mov_b32_e32 v93, 1.0
	s_nop 0
	v_mov_b32_dpp v92, v136 row_shr:4 row_mask:0xf bank_mask:0xf
	v_mov_b32_dpp v93, v137 row_shr:4 row_mask:0xf bank_mask:0xf
	v_pk_mul_f32 v[138:139], v[136:137], v[92:93]
	v_mov_b32_e32 v92, 1.0
	v_mov_b32_e32 v93, 1.0
	s_nop 0
	v_mov_b32_dpp v92, v138 row_shr:8 row_mask:0xf bank_mask:0xf
	v_mov_b32_dpp v93, v139 row_shr:8 row_mask:0xf bank_mask:0xf
	v_pk_mul_f32 v[140:141], v[138:139], v[92:93]
	v_add_u32_e32 v93, 0x20c8, v145
	ds_read2_b32 v[142:143], v93 offset1:1
	v_pk_mul_f32 v[86:87], v[140:141], v[86:87]
	ds_bpermute_b32 v92, v1, v86
	ds_bpermute_b32 v93, v1, v87
	s_waitcnt lgkmcnt(0)
	v_pk_mul_f32 v[84:85], v[84:85], v[142:143]
	s_nop 0
	v_pk_mul_f32 v[84:85], v[132:133], v[84:85]
	s_nop 1
	v_mov_b32_dpp v132, v84 row_shr:1 row_mask:0xf bank_mask:0xf bound_ctrl:1
	v_mov_b32_dpp v133, v85 row_shr:1 row_mask:0xf bank_mask:0xf bound_ctrl:1
	v_pk_fma_f32 v[84:85], v[130:131], v[132:133], v[84:85]
	s_nop 1
	v_mov_b32_dpp v130, v84 row_shr:2 row_mask:0xf bank_mask:0xf bound_ctrl:1
	v_mov_b32_dpp v131, v85 row_shr:2 row_mask:0xf bank_mask:0xf bound_ctrl:1
	v_pk_fma_f32 v[84:85], v[134:135], v[130:131], v[84:85]
	s_nop 1
	v_mov_b32_dpp v130, v84 row_shr:4 row_mask:0xf bank_mask:0xf bound_ctrl:1
	v_mov_b32_dpp v131, v85 row_shr:4 row_mask:0xf bank_mask:0xf bound_ctrl:1
	v_pk_fma_f32 v[84:85], v[136:137], v[130:131], v[84:85]
	s_nop 1
	v_mov_b32_dpp v130, v84 row_shr:8 row_mask:0xf bank_mask:0xf bound_ctrl:1
	v_mov_b32_dpp v131, v85 row_shr:8 row_mask:0xf bank_mask:0xf bound_ctrl:1
	v_pk_fma_f32 v[84:85], v[138:139], v[130:131], v[84:85]
	s_nop 0
	v_pk_fma_f32 v[122:123], v[140:141], v[122:123], v[84:85]
	ds_bpermute_b32 v84, v1, v122
	ds_bpermute_b32 v85, v1, v123
	v_cvt_pk_bf16_f32 v125, v122, v123
	v_cvt_pk_bf16_f32 v122, v128, v129
	v_cvt_pk_bf16_f32 v123, v86, v87
	v_mov_b64_e32 v[240:241], v[124:125]
	s_nop 1
	v_permlane16_swap_b32_e32 v238, v240
	v_permlane16_swap_b32_e32 v239, v241
	global_store_dwordx4 v[96:97], v[238:241], off
	v_mov_b64_e32 v[244:245], v[122:123]
	s_nop 1
	v_permlane16_swap_b32_e32 v242, v244
	v_permlane16_swap_b32_e32 v243, v245
	global_store_dwordx4 v[98:99], v[242:245], off
	v_mfma_f32_16x16x32_bf16 v[122:125], v[72:75], v[4:7], 0
	v_mfma_f32_16x16x32_bf16 v[72:75], v[76:79], v[20:23], v[68:71]
	v_mfma_f32_16x16x32_bf16 v[68:71], v[80:83], v[20:23], v[122:125]
	s_nop 6
	v_add_f32_e32 v40, v40, v72
	v_add_f32_e32 v41, v41, v73
	v_add_f32_e32 v42, v42, v74
	v_mul_f32_e32 v40, 0xbfb8aa3b, v40
	v_mul_f32_e32 v41, 0xbfb8aa3b, v41
	v_mul_f32_e32 v42, 0xbfb8aa3b, v42
	v_exp_f32_e32 v40, v40
	v_exp_f32_e32 v41, v41
	v_exp_f32_e32 v42, v42
	v_add_f32_e32 v36, v36, v68
	v_add_f32_e32 v37, v37, v69
	v_add_f32_e32 v38, v38, v70
	v_mul_f32_e32 v36, 0xbfb8aa3b, v36
	v_mul_f32_e32 v37, 0xbfb8aa3b, v37
	v_mul_f32_e32 v38, 0xbfb8aa3b, v38
	v_add_f32_e32 v40, 1.0, v40
	v_exp_f32_e32 v36, v36
	v_add_f32_e32 v41, 1.0, v41
	v_exp_f32_e32 v37, v37
	v_add_f32_e32 v42, 1.0, v42
	v_exp_f32_e32 v38, v38
	v_rcp_f32_e32 v72, v40
	v_rcp_f32_e32 v68, v41
	v_rcp_f32_e32 v42, v42
	v_add_f32_e32 v36, 1.0, v36
	v_add_f32_e32 v37, 1.0, v37
; __device__ __forceinline__ unsigned pk2(float lo, float hi) { const f32x2_t v = {lo, hi}; const bf16x2_t b = __builtin_convertvector(v, bf16x2_t); return __builtin_bit_cast(unsigned, b); }
; __device__ __forceinline__ float sigmoidf_(float x) { return __builtin_amdgcn_rcpf(1.0f + __expf(-x)); }
; __device__ __forceinline__ void w_lru_m1(const Args& a, int l, unsigned char* ws, const bf16_t* proj, bf16_t* y, LAS unsigned char* wl, int b, int ck_, int h, int lane) {
;     ...
;         for (int tb = 0; tb < 4; ++tb) { const int tok = 16 * tb + lo;
;             f32x4 ga = {0.f, 0.f, 0.f, 0.f}, gx = {0.f, 0.f, 0.f, 0.f};
; #pragma unroll
;             for (int kk = 0; kk < 2; ++kk) { ga = __builtin_amdgcn_mfma_f32_16x16x32_bf16(WaF[kk], Xf[tb][kk], ga, 0, 0, 0); gx = __builtin_amdgcn_mfma_f32_16x16x32_bf16(WxF[kk], Xf[tb][kk], gx, 0, 0, 0); }
;             float hv[4], pv[4];
; #pragma unroll
;             for (int r = 0; r < 4; ++r) {
;                 const float rg = sigmoidf_(ga[r] + bav[r]), ig = sigmoidf_(gx[r] + bxv[r]);
;                 const float la = -8.0f * rg * sp[r]; float A = __expf(la);
;                 float U = __builtin_amdgcn_sqrtf(1.0f - A * A) * (ig * xcf[tok * 65 + j0 + r]);
;                 { const float As = dpp_shr1<1>(A), Us = dpp_shr0<1>(U); U = A * Us + U; A = A * As; }
;                 { const float As = dpp_shr1<2>(A), Us = dpp_shr0<2>(U); U = A * Us + U; A = A * As; }
;                 { const float As = dpp_shr1<4>(A), Us = dpp_shr0<4>(U); U = A * Us + U; A = A * As; }
;                 { const float As = dpp_shr1<8>(A), Us = dpp_shr0<8>(U); U = A * Us + U; A = A * As; }
;                 const float hh = U + A * hc[r], PP = A * Pc[r];
;                 hc[r] = bcast15(hh, lane); Pc[r] = bcast15(PP, lane); hv[r] = hh; pv[r] = PP; }
;             *(unsigned long long*)(y + (size_t)(row0 + tok) * DM + 64 * h + j0) = (unsigned long long)pk2(hv[0], hv[1]) | ((unsigned long long)pk2(hv[2], hv[3]) << 32);
;             *(unsigned long long*)((bf16_t*)(ws + WS_P) + (size_t)(row0 + tok) * 512 + 64 * h + j0) = (unsigned long long)pk2(pv[0], pv[1]) | ((unsigned long long)pk2(pv[2], pv[3]) << 32);
;         }
;         if (lo == 0) { const size_t so = (size_t)(b * NCH + ck_) * 512 + 64 * h + j0;
; #pragma unroll
;             for (int r = 0; r < 4; ++r) { ((float*)(ws + WS_LRUA))[so + r] = Pc[r]; ((float*)(ws + WS_LRUH))[so + r] = hc[r]; } }
	v_add_f32_e32 v38, 1.0, v38
	v_rcp_f32_e32 v40, v36
	v_mul_f32_e32 v36, 0xc1000000, v72
	v_rcp_f32_e32 v41, v37
	v_mul_f32_e32 v37, 0xc1000000, v68
	v_rcp_f32_e32 v70, v38
	v_mul_f32_e32 v38, 0xc1000000, v42
	v_mul_f32_e32 v36, v147, v36
	v_mul_f32_e32 v37, v149, v37
	v_mul_f32_e32 v2, v2, v38
	v_mul_f32_e32 v36, 0x3fb8aa3b, v36
	v_mul_f32_e32 v37, 0x3fb8aa3b, v37
	v_mul_f32_e32 v2, 0x3fb8aa3b, v2
	v_exp_f32_e32 v72, v36
	v_exp_f32_e32 v73, v37
	v_exp_f32_e32 v42, v2
	v_add_f32_e32 v39, v39, v71
	v_fma_f32 v36, -v72, v72, 1.0
	v_fma_f32 v37, -v73, v73, 1.0
	v_fma_f32 v2, -v42, v42, 1.0
	v_sqrt_f32_e32 v76, v36
	v_mov_b32_e32 v36, 1.0
	v_sqrt_f32_e32 v77, v37
	v_mov_b32_e32 v37, 1.0
	v_sqrt_f32_e32 v74, v2
	v_add_f32_e32 v2, v43, v75
	v_mov_b32_dpp v36, v72 row_shr:1 row_mask:0xf bank_mask:0xf
	v_mov_b32_dpp v37, v73 row_shr:1 row_mask:0xf bank_mask:0xf
	v_mul_f32_e32 v2, 0xbfb8aa3b, v2
	v_pk_mul_f32 v[78:79], v[72:73], v[36:37]
	v_mov_b32_e32 v36, 1.0
	v_mov_b32_e32 v37, 1.0
	v_exp_f32_e32 v2, v2
	v_mov_b32_dpp v36, v78 row_shr:2 row_mask:0xf bank_mask:0xf
	v_mov_b32_dpp v37, v79 row_shr:2 row_mask:0xf bank_mask:0xf
	v_pk_mul_f32 v[80:81], v[78:79], v[36:37]
	v_mov_b32_e32 v36, 1.0
	v_mov_b32_e32 v37, 1.0
	v_add_f32_e32 v2, 1.0, v2
	v_mov_b32_dpp v36, v80 row_shr:4 row_mask:0xf bank_mask:0xf
	v_mov_b32_dpp v37, v81 row_shr:4 row_mask:0xf bank_mask:0xf
	v_pk_mul_f32 v[82:83], v[80:81], v[36:37]
	v_mov_b32_e32 v36, 1.0
	v_mov_b32_e32 v37, 1.0
	v_rcp_f32_e32 v2, v2
	v_mov_b32_dpp v36, v82 row_shr:8 row_mask:0xf bank_mask:0xf
	v_mov_b32_dpp v37, v83 row_shr:8 row_mask:0xf bank_mask:0xf
	v_pk_mul_f32 v[86:87], v[82:83], v[36:37]
	v_add_u32_e32 v37, 0x3100, v145
	ds_read2_b32 v[122:123], v37 offset1:1
	v_mul_f32_e32 v39, 0xbfb8aa3b, v39
	v_mul_f32_e32 v2, 0xc1000000, v2
	v_exp_f32_e32 v39, v39
	v_mul_f32_e32 v2, v148, v2
	v_mul_f32_e32 v2, 0x3fb8aa3b, v2
	s_waitcnt lgkmcnt(0)
	v_pk_mul_f32 v[40:41], v[122:123], v[40:41]
	v_exp_f32_e32 v43, v2
	v_pk_mul_f32 v[40:41], v[40:41], v[76:77]
	v_add_f32_e32 v39, 1.0, v39
	v_mov_b32_e32 v38, 1.0
	v_mov_b32_dpp v76, v40 row_shr:1 row_mask:0xf bank_mask:0xf bound_ctrl:1
	v_mov_b32_dpp v77, v41 row_shr:1 row_mask:0xf bank_mask:0xf bound_ctrl:1
	v_pk_fma_f32 v[40:41], v[72:73], v[76:77], v[40:41]
	v_rcp_f32_e32 v71, v39
	v_mov_b32_e32 v39, 1.0
	v_mov_b32_dpp v72, v40 row_shr:2 row_mask:0xf bank_mask:0xf bound_ctrl:1
	v_mov_b32_dpp v73, v41 row_shr:2 row_mask:0xf bank_mask:0xf bound_ctrl:1
	v_mov_b32_dpp v38, v42 row_shr:1 row_mask:0xf bank_mask:0xf
	v_mov_b32_dpp v39, v43 row_shr:1 row_mask:0xf bank_mask:0xf
	v_pk_fma_f32 v[40:41], v[78:79], v[72:73], v[40:41]
	v_pk_mul_f32 v[78:79], v[42:43], v[38:39]
	v_mov_b32_e32 v38, 1.0
	v_mov_b32_e32 v39, 1.0
	v_mov_b32_dpp v72, v40 row_shr:4 row_mask:0xf bank_mask:0xf bound_ctrl:1
	v_mov_b32_dpp v73, v41 row_shr:4 row_mask:0xf bank_mask:0xf bound_ctrl:1
	v_mov_b32_dpp v38, v78 row_shr:2 row_mask:0xf bank_mask:0xf
	v_mov_b32_dpp v39, v79 row_shr:2 row_mask:0xf bank_mask:0xf
	v_pk_fma_f32 v[40:41], v[80:81], v[72:73], v[40:41]
	v_pk_mul_f32 v[80:81], v[78:79], v[38:39]
	v_mov_b32_e32 v38, 1.0
	v_mov_b32_e32 v39, 1.0
	v_mov_b32_dpp v72, v40 row_shr:8 row_mask:0xf bank_mask:0xf bound_ctrl:1
	v_mov_b32_dpp v73, v41 row_shr:8 row_mask:0xf bank_mask:0xf bound_ctrl:1
	v_mov_b32_dpp v38, v80 row_shr:4 row_mask:0xf bank_mask:0xf
	v_mov_b32_dpp v39, v81 row_shr:4 row_mask:0xf bank_mask:0xf
	v_pk_fma_f32 v[40:41], v[82:83], v[72:73], v[40:41]
	v_pk_mul_f32 v[82:83], v[80:81], v[38:39]
	v_mov_b32_e32 v38, 1.0
	v_mov_b32_e32 v39, 1.0
	v_fma_f32 v2, -v43, v43, 1.0
	v_mov_b32_dpp v38, v82 row_shr:8 row_mask:0xf bank_mask:0xf
	v_mov_b32_dpp v39, v83 row_shr:8 row_mask:0xf bank_mask:0xf
	v_pk_mul_f32 v[68:69], v[86:87], v[126:127]
	v_pk_fma_f32 v[72:73], v[86:87], v[94:95], v[40:41]
	v_sqrt_f32_e32 v75, v2
	v_pk_mul_f32 v[86:87], v[82:83], v[38:39]
	v_add_u32_e32 v2, 0x3108, v145
	v_pk_mul_f32 v[76:77], v[86:87], v[92:93]
	ds_read2_b32 v[92:93], v2 offset1:1
	ds_bpermute_b32 v36, v1, v68
	ds_bpermute_b32 v40, v1, v72
	ds_bpermute_b32 v41, v1, v73
	ds_bpermute_b32 v37, v1, v69
	s_waitcnt lgkmcnt(0)
	v_pk_mul_f32 v[70:71], v[70:71], v[92:93]
	ds_bpermute_b32 v38, v1, v76
	v_pk_mul_f32 v[70:71], v[74:75], v[70:71]
	ds_bpermute_b32 v39, v1, v77
	v_cvt_pk_bf16_f32 v72, v72, v73
	v_mov_b32_dpp v74, v70 row_shr:1 row_mask:0xf bank_mask:0xf bound_ctrl:1
	v_mov_b32_dpp v75, v71 row_shr:1 row_mask:0xf bank_mask:0xf bound_ctrl:1
	v_pk_fma_f32 v[42:43], v[42:43], v[74:75], v[70:71]
	v_cvt_pk_bf16_f32 v68, v68, v69
	v_cvt_pk_bf16_f32 v69, v76, v77
	v_mov_b32_dpp v70, v42 row_shr:2 row_mask:0xf bank_mask:0xf bound_ctrl:1
	v_mov_b32_dpp v71, v43 row_shr:2 row_mask:0xf bank_mask:0xf bound_ctrl:1
	v_pk_fma_f32 v[42:43], v[78:79], v[70:71], v[42:43]
	s_nop 1
	v_mov_b32_dpp v70, v42 row_shr:4 row_mask:0xf bank_mask:0xf bound_ctrl:1
	v_mov_b32_dpp v71, v43 row_shr:4 row_mask:0xf bank_mask:0xf bound_ctrl:1
	v_pk_fma_f32 v[42:43], v[80:81], v[70:71], v[42:43]
	s_nop 1
	v_mov_b32_dpp v70, v42 row_shr:8 row_mask:0xf bank_mask:0xf bound_ctrl:1
	v_mov_b32_dpp v71, v43 row_shr:8 row_mask:0xf bank_mask:0xf bound_ctrl:1
	v_pk_fma_f32 v[42:43], v[82:83], v[70:71], v[42:43]
	s_nop 0
	v_pk_fma_f32 v[70:71], v[86:87], v[84:85], v[42:43]
	ds_bpermute_b32 v42, v1, v70
	ds_bpermute_b32 v43, v1, v71
	v_cvt_pk_bf16_f32 v73, v70, v71
	v_mov_b64_e32 v[248:249], v[72:73]
	s_nop 1
	v_permlane16_swap_b32_e32 v246, v248
	v_permlane16_swap_b32_e32 v247, v249
	global_store_dwordx4 v[114:115], v[246:249], off
	v_mov_b64_e32 v[252:253], v[68:69]
	s_nop 1
	v_permlane16_swap_b32_e32 v250, v252
	v_permlane16_swap_b32_e32 v251, v253
	global_store_dwordx4 v[116:117], v[250:253], off
	s_and_saveexec_b64 s[34:35], vcc
	s_cbranch_execz .LBB0_525
	v_add_u32_e32 v68, 16, v0
	v_ashrrev_i32_e32 v69, 31, v68
	v_lshl_add_u64 v[68:69], s[42:43], 0, v[68:69]
	v_lshlrev_b64 v[68:69], 2, v[68:69]
	v_lshl_add_u64 v[70:71], s[84:85], 0, v[68:69]
	v_lshl_add_u64 v[68:69], s[86:87], 0, v[68:69]
	s_waitcnt lgkmcnt(0)
	global_store_dwordx4 v[70:71], v[36:39], off
	global_store_dwordx4 v[68:69], v[40:43], off
; __device__ __forceinline__ void w_lru_m1(const Args& a, int l, unsigned char* ws, const bf16_t* proj, bf16_t* y, LAS unsigned char* wl, int b, int ck_, int h, int lane) {
;     ...
;     for (int jb = 0; jb < 4; ++jb) {
;         bf16x8 WaF[2], WxF[2]; f32x4 pba, pbx, plam;
; #pragma unroll
;         for (int kk = 0; kk < 2; ++kk) { WaF[kk] = nWa[kk]; WxF[kk] = nWx[kk]; }
;         pba = nba; pbx = nbx; plam = nlam;
;         if (jb < 3) {
; #pragma unroll
;             for (int kk = 0; kk < 2; ++kk) { nWa[kk] = *(const bf16x8*)(waT + (16 * (jb + 1) + lo) * 64 + 32 * kk + 8 * fq); nWx[kk] = *(const bf16x8*)(wxT + (16 * (jb + 1) + lo) * 64 + 32 * kk + 8 * fq); }
;             nba = *(const f32x4*)(ba + 16 * (jb + 1) + 4 * fq); nbx = *(const f32x4*)(bx + 16 * (jb + 1) + 4 * fq); nlam = *(const f32x4*)(lam + 16 * (jb + 1) + 4 * fq);
;         }
;         const int j0 = 16 * jb + 4 * fq;
;         float bav[4], bxv[4], sp[4], hc[4], Pc[4];
; #pragma unroll
;         for (int r = 0; r < 4; ++r) { bav[r] = pba[r]; bxv[r] = pbx[r]; sp[r] = log1pf(__expf(-plam[r])); hc[r] = 0.f; Pc[r] = 1.f; }
; #pragma unroll
;         for (int tb = 0; tb < 4; ++tb) { const int tok = 16 * tb + lo;
;             f32x4 ga = {0.f, 0.f, 0.f, 0.f}, gx = {0.f, 0.f, 0.f, 0.f};
; #pragma unroll
;             for (int kk = 0; kk < 2; ++kk) { ga = __builtin_amdgcn_mfma_f32_16x16x32_bf16(WaF[kk], Xf[tb][kk], ga, 0, 0, 0); gx = __builtin_amdgcn_mfma_f32_16x16x32_bf16(WxF[kk], Xf[tb][kk], gx, 0, 0, 0); }
;             float hv[4], pv[4];
; #pragma unroll
;             for (int r = 0; r < 4; ++r) {
;                 const float rg = sigmoidf_(ga[r] + bav[r]), ig = sigmoidf_(gx[r] + bxv[r]);
;                 const float la = -8.0f * rg * sp[r]; float A = __expf(la);
;                 float U = __builtin_amdgcn_sqrtf(1.0f - A * A) * (ig * xcf[tok * 65 + j0 + r]);
;                 { const float As = dpp_shr1<1>(A), Us = dpp_shr0<1>(U); U = A * Us + U; A = A * As; }
;                 { const float As = dpp_shr1<2>(A), Us = dpp_shr0<2>(U); U = A * Us + U; A = A * As; }
;                 { const float As = dpp_shr1<4>(A), Us = dpp_shr0<4>(U); U = A * Us + U; A = A * As; }
;                 { const float As = dpp_shr1<8>(A), Us = dpp_shr0<8>(U); U = A * Us + U; A = A * As; }
;                 const float hh = U + A * hc[r], PP = A * Pc[r];
.LBB0_525:
	s_or_b64 exec, exec, s[34:35]
	v_lshl_or_b32 v2, v146, 1, v210
	v_lshl_add_u64 v[36:37], v[118:119], 0, v[2:3]
	s_waitcnt lgkmcnt(0)
	v_lshl_add_u64 v[38:39], v[120:121], 0, v[2:3]
	s_waitcnt vmcnt(10)
	s_nop 7
	global_load_dwordx4 v[68:71], v[36:37], off
	global_load_dwordx4 v[72:75], v[38:39], off
	global_load_dwordx4 v[76:79], v[36:37], off offset:64
	global_load_dwordx4 v[80:83], v[38:39], off offset:64
	global_load_dwordx4 v[40:43], v[108:109], off offset:192
	s_nop 7
	global_load_dwordx4 v[36:39], v[110:111], off offset:192
	global_load_dwordx4 v[84:87], v[112:113], off offset:192
	ds_read2_b32 v[124:125], v145 offset0:32 offset1:33
	ds_read2_b32 v[128:129], v145 offset0:34 offset1:35
	s_nop 7
	v_mov_b32_e32 v2, v88
	s_nop 7
	v_mov_b32_e32 v134, v89
	s_nop 7
	v_mov_b32_e32 v135, v90
	s_nop 7
	v_mfma_f32_16x16x32_bf16 v[92:95], v[60:63], v[16:19], 0
	s_nop 7
	v_mfma_f32_16x16x32_bf16 v[110:113], v[52:55], v[32:35], v[92:95]
	s_nop 7
	v_mov_b32_e32 v136, v91
	v_mfma_f32_16x16x32_bf16 v[88:91], v[64:67], v[16:19], 0
	s_nop 0
	v_add_f32_e32 v92, v44, v110
	v_add_f32_e32 v93, v45, v111
	v_mul_f32_e32 v92, 0xbfb8aa3b, v92
	v_mfma_f32_16x16x32_bf16 v[88:91], v[56:59], v[32:35], v[88:91]
	v_mul_f32_e32 v93, 0xbfb8aa3b, v93
	v_exp_f32_e32 v92, v92
	v_exp_f32_e32 v93, v93
	v_add_f32_e32 v92, 1.0, v92
	v_add_f32_e32 v93, 1.0, v93
	s_nop 2
	v_add_f32_e32 v88, v48, v88
	v_add_f32_e32 v89, v49, v89
	v_mul_f32_e32 v88, 0xbfb8aa3b, v88
	v_mul_f32_e32 v89, 0xbfb8aa3b, v89
	v_exp_f32_e32 v88, v88
	v_exp_f32_e32 v89, v89
	v_rcp_f32_e32 v92, v92
	v_rcp_f32_e32 v93, v93
	v_add_f32_e32 v88, 1.0, v88
	v_add_f32_e32 v89, 1.0, v89
	v_rcp_f32_e32 v88, v88
	v_rcp_f32_e32 v89, v89
	s_waitcnt lgkmcnt(0)
	v_pk_mul_f32 v[92:93], v[124:125], v[92:93]
	v_add_f32_e32 v90, v50, v90
	v_mul_f32_e32 v88, 0xc1000000, v88
	v_mul_f32_e32 v89, 0xc1000000, v89
	v_mul_f32_e32 v88, v2, v88
	v_mul_f32_e32 v89, v134, v89
	v_mul_f32_e32 v88, 0x3fb8aa3b, v88
	v_mul_f32_e32 v89, 0x3fb8aa3b, v89
	v_exp_f32_e32 v108, v88
	v_exp_f32_e32 v109, v89
	v_add_f32_e32 v91, v51, v91
	v_mul_f32_e32 v90, 0xbfb8aa3b, v90
	v_fma_f32 v88, -v108, v108, 1.0
	v_fma_f32 v89, -v109, v109, 1.0
	v_sqrt_f32_e32 v110, v88
	v_sqrt_f32_e32 v111, v89
	v_mov_b32_e32 v88, 1.0
	v_mov_b32_e32 v89, 1.0
	v_mul_f32_e32 v91, 0xbfb8aa3b, v91
	v_pk_mul_f32 v[92:93], v[92:93], v[110:111]
	v_mov_b32_dpp v88, v108 row_shr:1 row_mask:0xf bank_mask:0xf
	v_mov_b32_dpp v89, v109 row_shr:1 row_mask:0xf bank_mask:0xf
	v_mov_b32_dpp v110, v92 row_shr:1 row_mask:0xf bank_mask:0xf bound_ctrl:1
	v_mov_b32_dpp v111, v93 row_shr:1 row_mask:0xf bank_mask:0xf bound_ctrl:1
	v_pk_fma_f32 v[92:93], v[108:109], v[110:111], v[92:93]
	v_pk_mul_f32 v[118:119], v[108:109], v[88:89]
	v_mov_b32_e32 v88, 1.0
	v_mov_b32_e32 v89, 1.0
	v_mov_b32_dpp v108, v92 row_shr:2 row_mask:0xf bank_mask:0xf bound_ctrl:1
	v_mov_b32_dpp v109, v93 row_shr:2 row_mask:0xf bank_mask:0xf bound_ctrl:1
	v_exp_f32_e32 v90, v90
	v_exp_f32_e32 v91, v91
	v_mov_b32_dpp v88, v118 row_shr:2 row_mask:0xf bank_mask:0xf
	v_mov_b32_dpp v89, v119 row_shr:2 row_mask:0xf bank_mask:0xf
	v_pk_fma_f32 v[92:93], v[118:119], v[108:109], v[92:93]
	v_pk_mul_f32 v[120:121], v[118:119], v[88:89]
	v_mov_b32_e32 v88, 1.0
	v_mov_b32_e32 v89, 1.0
	v_mov_b32_dpp v108, v92 row_shr:4 row_mask:0xf bank_mask:0xf bound_ctrl:1
	v_mov_b32_dpp v109, v93 row_shr:4 row_mask:0xf bank_mask:0xf bound_ctrl:1
	v_mov_b32_dpp v88, v120 row_shr:4 row_mask:0xf bank_mask:0xf
	v_mov_b32_dpp v89, v121 row_shr:4 row_mask:0xf bank_mask:0xf
	v_pk_fma_f32 v[92:93], v[120:121], v[108:109], v[92:93]
	v_pk_mul_f32 v[122:123], v[120:121], v[88:89]
	v_add_f32_e32 v90, 1.0, v90
	v_mov_b32_dpp v108, v92 row_shr:8 row_mask:0xf bank_mask:0xf bound_ctrl:1
	v_mov_b32_dpp v109, v93 row_shr:8 row_mask:0xf bank_mask:0xf bound_ctrl:1
	v_add_f32_e32 v91, 1.0, v91
	v_pk_fma_f32 v[92:93], v[122:123], v[108:109], v[92:93]
	v_rcp_f32_e32 v90, v90
	v_add_f32_e32 v108, v46, v112
	v_rcp_f32_e32 v91, v91
	v_add_f32_e32 v109, v47, v113
	v_mul_f32_e32 v108, 0xbfb8aa3b, v108
	v_mul_f32_e32 v109, 0xbfb8aa3b, v109
	v_exp_f32_e32 v108, v108
	v_exp_f32_e32 v109, v109
	v_mul_f32_e32 v90, 0xc1000000, v90
	v_mul_f32_e32 v91, 0xc1000000, v91
	v_mul_f32_e32 v90, v135, v90
	v_mul_f32_e32 v91, v136, v91
	v_add_f32_e32 v108, 1.0, v108
	v_mul_f32_e32 v90, 0x3fb8aa3b, v90
	v_add_f32_e32 v109, 1.0, v109
	v_mul_f32_e32 v91, 0x3fb8aa3b, v91
	v_rcp_f32_e32 v112, v108
	v_exp_f32_e32 v108, v90
	v_rcp_f32_e32 v113, v109
	v_exp_f32_e32 v109, v91
	v_mov_b32_e32 v88, 1.0
	v_fma_f32 v90, -v108, v108, 1.0
	v_sqrt_f32_e32 v118, v90
	v_fma_f32 v91, -v109, v109, 1.0
	v_sqrt_f32_e32 v119, v91
	v_pk_mul_f32 v[112:113], v[112:113], v[128:129]
	v_mov_b32_e32 v89, 1.0
	v_mov_b32_e32 v90, 1.0
	v_mov_b32_e32 v91, 1.0
	v_pk_mul_f32 v[112:113], v[118:119], v[112:113]
	v_mov_b32_dpp v88, v122 row_shr:8 row_mask:0xf bank_mask:0xf
	v_mov_b32_dpp v89, v123 row_shr:8 row_mask:0xf bank_mask:0xf
	v_mov_b32_dpp v90, v108 row_shr:1 row_mask:0xf bank_mask:0xf
	v_mov_b32_dpp v91, v109 row_shr:1 row_mask:0xf bank_mask:0xf
	v_mov_b32_dpp v118, v112 row_shr:1 row_mask:0xf bank_mask:0xf bound_ctrl:1
	v_mov_b32_dpp v119, v113 row_shr:1 row_mask:0xf bank_mask:0xf bound_ctrl:1
	v_pk_mul_f32 v[94:95], v[122:123], v[88:89]
	v_pk_mul_f32 v[122:123], v[108:109], v[90:91]
	v_mov_b32_e32 v90, 1.0
	v_mov_b32_e32 v91, 1.0
	v_pk_fma_f32 v[108:109], v[108:109], v[118:119], v[112:113]
	v_mov_b32_dpp v90, v122 row_shr:2 row_mask:0xf bank_mask:0xf
	v_mov_b32_dpp v91, v123 row_shr:2 row_mask:0xf bank_mask:0xf
	v_mov_b32_dpp v112, v108 row_shr:2 row_mask:0xf bank_mask:0xf bound_ctrl:1
; __device__ __forceinline__ unsigned pk2(float lo, float hi) { const f32x2_t v = {lo, hi}; const bf16x2_t b = __builtin_convertvector(v, bf16x2_t); return __builtin_bit_cast(unsigned, b); }
; __device__ __forceinline__ float sigmoidf_(float x) { return __builtin_amdgcn_rcpf(1.0f + __expf(-x)); }
; __device__ __forceinline__ float bcast15(float v, int lane) { return bperm_f((lane & 48) | 15, v); }
; __device__ __forceinline__ void w_lru_m1(const Args& a, int l, unsigned char* ws, const bf16_t* proj, bf16_t* y, LAS unsigned char* wl, int b, int ck_, int h, int lane) {
;     ...
;         for (int tb = 0; tb < 4; ++tb) { const int tok = 16 * tb + lo;
;             f32x4 ga = {0.f, 0.f, 0.f, 0.f}, gx = {0.f, 0.f, 0.f, 0.f};
; #pragma unroll
;             for (int kk = 0; kk < 2; ++kk) { ga = __builtin_amdgcn_mfma_f32_16x16x32_bf16(WaF[kk], Xf[tb][kk], ga, 0, 0, 0); gx = __builtin_amdgcn_mfma_f32_16x16x32_bf16(WxF[kk], Xf[tb][kk], gx, 0, 0, 0); }
;             float hv[4], pv[4];
; #pragma unroll
;             for (int r = 0; r < 4; ++r) {
;                 const float rg = sigmoidf_(ga[r] + bav[r]), ig = sigmoidf_(gx[r] + bxv[r]);
;                 const float la = -8.0f * rg * sp[r]; float A = __expf(la);
;                 float U = __builtin_amdgcn_sqrtf(1.0f - A * A) * (ig * xcf[tok * 65 + j0 + r]);
;                 { const float As = dpp_shr1<1>(A), Us = dpp_shr0<1>(U); U = A * Us + U; A = A * As; }
;                 { const float As = dpp_shr1<2>(A), Us = dpp_shr0<2>(U); U = A * Us + U; A = A * As; }
;                 { const float As = dpp_shr1<4>(A), Us = dpp_shr0<4>(U); U = A * Us + U; A = A * As; }
;                 { const float As = dpp_shr1<8>(A), Us = dpp_shr0<8>(U); U = A * Us + U; A = A * As; }
;                 const float hh = U + A * hc[r], PP = A * Pc[r];
;                 hc[r] = bcast15(hh, lane); Pc[r] = bcast15(PP, lane); hv[r] = hh; pv[r] = PP; }
;             *(unsigned long long*)(y + (size_t)(row0 + tok) * DM + 64 * h + j0) = (unsigned long long)pk2(hv[0], hv[1]) | ((unsigned long long)pk2(hv[2], hv[3]) << 32);
;             *(unsigned long long*)((bf16_t*)(ws + WS_P) + (size_t)(row0 + tok) * 512 + 64 * h + j0) = (unsigned long long)pk2(pv[0], pv[1]) | ((unsigned long long)pk2(pv[2], pv[3]) << 32);
	v_mov_b32_dpp v113, v109 row_shr:2 row_mask:0xf bank_mask:0xf bound_ctrl:1
	v_pk_mul_f32 v[124:125], v[122:123], v[90:91]
	v_mov_b32_e32 v90, 1.0
	v_mov_b32_e32 v91, 1.0
	v_pk_fma_f32 v[108:109], v[122:123], v[112:113], v[108:109]
	v_mov_b32_dpp v90, v124 row_shr:4 row_mask:0xf bank_mask:0xf
	v_mov_b32_dpp v91, v125 row_shr:4 row_mask:0xf bank_mask:0xf
	v_mov_b32_dpp v112, v108 row_shr:4 row_mask:0xf bank_mask:0xf bound_ctrl:1
	v_mov_b32_dpp v113, v109 row_shr:4 row_mask:0xf bank_mask:0xf bound_ctrl:1
	v_pk_mul_f32 v[126:127], v[124:125], v[90:91]
	v_mov_b32_e32 v90, 1.0
	v_mov_b32_e32 v91, 1.0
	v_pk_fma_f32 v[108:109], v[124:125], v[112:113], v[108:109]
	v_mov_b32_dpp v90, v126 row_shr:8 row_mask:0xf bank_mask:0xf
	v_mov_b32_dpp v91, v127 row_shr:8 row_mask:0xf bank_mask:0xf
	v_mov_b32_dpp v112, v108 row_shr:8 row_mask:0xf bank_mask:0xf bound_ctrl:1
	v_mov_b32_dpp v113, v109 row_shr:8 row_mask:0xf bank_mask:0xf bound_ctrl:1
	v_pk_mul_f32 v[120:121], v[126:127], v[90:91]
	v_pk_fma_f32 v[108:109], v[126:127], v[112:113], v[108:109]
	v_pk_fma_f32 v[110:111], v[94:95], 0, v[92:93] op_sel_hi:[1,0,1]
	v_pk_fma_f32 v[112:113], v[120:121], 0, v[108:109] op_sel_hi:[1,0,1]
	ds_bpermute_b32 v92, v1, v110
	ds_bpermute_b32 v93, v1, v111
	v_cvt_pk_bf16_f32 v110, v110, v111
	v_cvt_pk_bf16_f32 v111, v112, v113
	ds_bpermute_b32 v108, v1, v112
	ds_bpermute_b32 v109, v1, v113
	v_mov_b64_e32 v[222:223], v[110:111]
	v_mfma_f32_16x16x32_bf16 v[110:113], v[64:67], v[12:15], 0
	ds_bpermute_b32 v88, v1, v94
	ds_bpermute_b32 v89, v1, v95
	v_cvt_pk_bf16_f32 v94, v94, v95
	v_mfma_f32_16x16x32_bf16 v[122:125], v[56:59], v[28:31], v[110:113]
	v_cvt_pk_bf16_f32 v95, v120, v121
	v_mov_b64_e32 v[226:227], v[94:95]
	ds_bpermute_b32 v90, v1, v120
	ds_bpermute_b32 v91, v1, v121
	v_mfma_f32_16x16x32_bf16 v[118:121], v[60:63], v[12:15], 0
	s_nop 2
	v_add_f32_e32 v94, v48, v122
	v_mul_f32_e32 v94, 0xbfb8aa3b, v94
	v_exp_f32_e32 v94, v94
	v_mfma_f32_16x16x32_bf16 v[118:121], v[52:55], v[28:31], v[118:121]
	v_mov_b32_e32 v112, 1.0
	v_add_f32_e32 v94, 1.0, v94
	v_rcp_f32_e32 v95, v94
	s_nop 0
	v_mul_f32_e32 v95, 0xc1000000, v95
	v_mul_f32_e32 v95, v2, v95
	v_mul_f32_e32 v95, 0x3fb8aa3b, v95
	v_exp_f32_e32 v110, v95
	v_add_f32_e32 v94, v44, v118
	v_mul_f32_e32 v94, 0xbfb8aa3b, v94
	v_exp_f32_e32 v94, v94
	v_fma_f32 v95, -v110, v110, 1.0
	v_sqrt_f32_e32 v118, v95
	v_add_f32_e32 v95, v49, v123
	v_mul_f32_e32 v95, 0xbfb8aa3b, v95
	v_exp_f32_e32 v95, v95
	v_mov_b32_dpp v112, v110 row_shr:1 row_mask:0xf bank_mask:0xf
	v_add_f32_e32 v94, 1.0, v94
	v_rcp_f32_e32 v94, v94
	v_add_f32_e32 v95, 1.0, v95
	v_rcp_f32_e32 v111, v95
	v_add_f32_e32 v95, v45, v119
	v_mul_f32_e32 v95, 0xbfb8aa3b, v95
	v_exp_f32_e32 v95, v95
	v_mul_f32_e32 v111, 0xc1000000, v111
	v_mul_f32_e32 v111, v134, v111
	v_mul_f32_e32 v111, 0x3fb8aa3b, v111
	v_exp_f32_e32 v111, v111
	v_add_f32_e32 v95, 1.0, v95
	v_rcp_f32_e32 v95, v95
	v_fma_f32 v113, -v111, v111, 1.0
	v_sqrt_f32_e32 v119, v113
	v_mov_b32_e32 v113, 1.0
	s_nop 1
	v_mov_b32_dpp v113, v111 row_shr:1 row_mask:0xf bank_mask:0xf
	v_pk_mul_f32 v[122:123], v[110:111], v[112:113]
	v_mov_b32_e32 v112, 1.0
	v_mov_b32_e32 v113, 1.0
	s_nop 0
	v_mov_b32_dpp v112, v122 row_shr:2 row_mask:0xf bank_mask:0xf
	v_mov_b32_dpp v113, v123 row_shr:2 row_mask:0xf bank_mask:0xf
	v_pk_mul_f32 v[126:127], v[122:123], v[112:113]
	v_mov_b32_e32 v112, 1.0
	v_mov_b32_e32 v113, 1.0
	s_nop 0
	v_mov_b32_dpp v112, v126 row_shr:4 row_mask:0xf bank_mask:0xf
	v_mov_b32_dpp v113, v127 row_shr:4 row_mask:0xf bank_mask:0xf
	v_pk_mul_f32 v[128:129], v[126:127], v[112:113]
	v_mov_b32_e32 v112, 1.0
	v_mov_b32_e32 v113, 1.0
	s_nop 0
	v_mov_b32_dpp v112, v128 row_shr:8 row_mask:0xf bank_mask:0xf
	v_mov_b32_dpp v113, v129 row_shr:8 row_mask:0xf bank_mask:0xf
	v_pk_mul_f32 v[130:131], v[128:129], v[112:113]
	v_add_u32_e32 v113, 0x10c0, v145
	ds_read2_b32 v[132:133], v113 offset1:1
	s_waitcnt lgkmcnt(0)
	v_pk_mul_f32 v[88:89], v[130:131], v[88:89]
	ds_bpermute_b32 v112, v1, v88
	ds_bpermute_b32 v113, v1, v89
	v_cvt_pk_bf16_f32 v88, v88, v89
	v_pk_mul_f32 v[94:95], v[132:133], v[94:95]
	s_nop 0
	v_pk_mul_f32 v[94:95], v[94:95], v[118:119]
	s_nop 1
	v_mov_b32_dpp v118, v94 row_shr:1 row_mask:0xf bank_mask:0xf bound_ctrl:1
	v_mov_b32_dpp v119, v95 row_shr:1 row_mask:0xf bank_mask:0xf bound_ctrl:1
	v_pk_fma_f32 v[94:95], v[110:111], v[118:119], v[94:95]
	s_nop 1
	v_mov_b32_dpp v110, v94 row_shr:2 row_mask:0xf bank_mask:0xf bound_ctrl:1
	v_mov_b32_dpp v111, v95 row_shr:2 row_mask:0xf bank_mask:0xf bound_ctrl:1
	v_pk_fma_f32 v[94:95], v[122:123], v[110:111], v[94:95]
	v_mov_b32_e32 v122, 1.0
	v_mov_b32_e32 v123, 1.0
	v_mov_b32_dpp v110, v94 row_shr:4 row_mask:0xf bank_mask:0xf bound_ctrl:1
	v_mov_b32_dpp v111, v95 row_shr:4 row_mask:0xf bank_mask:0xf bound_ctrl:1
	v_pk_fma_f32 v[94:95], v[126:127], v[110:111], v[94:95]
	s_nop 1
	v_mov_b32_dpp v110, v94 row_shr:8 row_mask:0xf bank_mask:0xf bound_ctrl:1
	v_mov_b32_dpp v111, v95 row_shr:8 row_mask:0xf bank_mask:0xf bound_ctrl:1
	v_pk_fma_f32 v[94:95], v[128:129], v[110:111], v[94:95]
	s_nop 0
	v_pk_fma_f32 v[92:93], v[130:131], v[92:93], v[94:95]
	v_add_f32_e32 v94, v50, v124
	v_mul_f32_e32 v94, 0xbfb8aa3b, v94
	v_exp_f32_e32 v94, v94
	ds_bpermute_b32 v110, v1, v92
	ds_bpermute_b32 v111, v1, v93
	v_cvt_pk_bf16_f32 v92, v92, v93
	v_add_f32_e32 v94, 1.0, v94
	v_rcp_f32_e32 v95, v94
	v_add_f32_e32 v94, v46, v120
	v_mul_f32_e32 v94, 0xbfb8aa3b, v94
	v_exp_f32_e32 v94, v94
	v_mul_f32_e32 v95, 0xc1000000, v95
	v_mul_f32_e32 v95, v135, v95
	v_mul_f32_e32 v95, 0x3fb8aa3b, v95
	v_exp_f32_e32 v118, v95
	v_add_f32_e32 v94, 1.0, v94
	v_rcp_f32_e32 v94, v94
	v_fma_f32 v95, -v118, v118, 1.0
; __device__ __forceinline__ float sigmoidf_(float x) { return __builtin_amdgcn_rcpf(1.0f + __expf(-x)); }
; __device__ __forceinline__ float bcast15(float v, int lane) { return bperm_f((lane & 48) | 15, v); }
; __device__ __forceinline__ void w_lru_m1(const Args& a, int l, unsigned char* ws, const bf16_t* proj, bf16_t* y, LAS unsigned char* wl, int b, int ck_, int h, int lane) {
;     ...
;         for (int tb = 0; tb < 4; ++tb) { const int tok = 16 * tb + lo;
;             f32x4 ga = {0.f, 0.f, 0.f, 0.f}, gx = {0.f, 0.f, 0.f, 0.f};
; #pragma unroll
;             for (int kk = 0; kk < 2; ++kk) { ga = __builtin_amdgcn_mfma_f32_16x16x32_bf16(WaF[kk], Xf[tb][kk], ga, 0, 0, 0); gx = __builtin_amdgcn_mfma_f32_16x16x32_bf16(WxF[kk], Xf[tb][kk], gx, 0, 0, 0); }
;             float hv[4], pv[4];
; #pragma unroll
;             for (int r = 0; r < 4; ++r) {
;                 const float rg = sigmoidf_(ga[r] + bav[r]), ig = sigmoidf_(gx[r] + bxv[r]);
;                 const float la = -8.0f * rg * sp[r]; float A = __expf(la);
;                 float U = __builtin_amdgcn_sqrtf(1.0f - A * A) * (ig * xcf[tok * 65 + j0 + r]);
;                 { const float As = dpp_shr1<1>(A), Us = dpp_shr0<1>(U); U = A * Us + U; A = A * As; }
;                 { const float As = dpp_shr1<2>(A), Us = dpp_shr0<2>(U); U = A * Us + U; A = A * As; }
;                 { const float As = dpp_shr1<4>(A), Us = dpp_shr0<4>(U); U = A * Us + U; A = A * As; }
;                 { const float As = dpp_shr1<8>(A), Us = dpp_shr0<8>(U); U = A * Us + U; A = A * As; }
;                 const float hh = U + A * hc[r], PP = A * Pc[r];
;                 hc[r] = bcast15(hh, lane); Pc[r] = bcast15(PP, lane); hv[r] = hh; pv[r] = PP; }
	v_sqrt_f32_e32 v120, v95
	v_add_f32_e32 v95, v51, v125
	v_mul_f32_e32 v95, 0xbfb8aa3b, v95
	v_exp_f32_e32 v95, v95
	v_mov_b32_dpp v122, v118 row_shr:1 row_mask:0xf bank_mask:0xf
	v_add_f32_e32 v95, 1.0, v95
	v_rcp_f32_e32 v119, v95
	v_add_f32_e32 v95, v47, v121
	v_mul_f32_e32 v95, 0xbfb8aa3b, v95
	v_exp_f32_e32 v95, v95
	v_mul_f32_e32 v119, 0xc1000000, v119
	v_mul_f32_e32 v119, v136, v119
	v_mul_f32_e32 v119, 0x3fb8aa3b, v119
	v_exp_f32_e32 v119, v119
	v_add_f32_e32 v95, 1.0, v95
	v_rcp_f32_e32 v95, v95
	v_mov_b32_dpp v123, v119 row_shr:1 row_mask:0xf bank_mask:0xf
	v_pk_mul_f32 v[124:125], v[118:119], v[122:123]
	v_mov_b32_e32 v122, 1.0
	v_mov_b32_e32 v123, 1.0
	v_fma_f32 v121, -v119, v119, 1.0
	v_mov_b32_dpp v122, v124 row_shr:2 row_mask:0xf bank_mask:0xf
	v_mov_b32_dpp v123, v125 row_shr:2 row_mask:0xf bank_mask:0xf
	v_pk_mul_f32 v[126:127], v[124:125], v[122:123]
	v_mov_b32_e32 v122, 1.0
	v_mov_b32_e32 v123, 1.0
	v_sqrt_f32_e32 v121, v121
	v_mov_b32_dpp v122, v126 row_shr:4 row_mask:0xf bank_mask:0xf
	v_mov_b32_dpp v123, v127 row_shr:4 row_mask:0xf bank_mask:0xf
	v_pk_mul_f32 v[128:129], v[126:127], v[122:123]
	v_mov_b32_e32 v122, 1.0
	v_mov_b32_e32 v123, 1.0
	s_nop 0
	v_mov_b32_dpp v122, v128 row_shr:8 row_mask:0xf bank_mask:0xf
	v_mov_b32_dpp v123, v129 row_shr:8 row_mask:0xf bank_mask:0xf
	v_pk_mul_f32 v[130:131], v[128:129], v[122:123]
	v_add_u32_e32 v123, 0x10c8, v145
	ds_read2_b32 v[132:133], v123 offset1:1
	v_pk_mul_f32 v[90:91], v[130:131], v[90:91]
	ds_bpermute_b32 v122, v1, v90
	v_cvt_pk_bf16_f32 v89, v90, v91
	ds_bpermute_b32 v123, v1, v91
	s_waitcnt lgkmcnt(0)
	v_pk_mul_f32 v[94:95], v[94:95], v[132:133]
	s_nop 0
	v_pk_mul_f32 v[94:95], v[120:121], v[94:95]
	s_nop 1
	v_mov_b32_dpp v120, v94 row_shr:1 row_mask:0xf bank_mask:0xf bound_ctrl:1
	v_mov_b32_dpp v121, v95 row_shr:1 row_mask:0xf bank_mask:0xf bound_ctrl:1
	v_pk_fma_f32 v[94:95], v[118:119], v[120:121], v[94:95]
	s_nop 1
	v_mov_b32_dpp v118, v94 row_shr:2 row_mask:0xf bank_mask:0xf bound_ctrl:1
	v_mov_b32_dpp v119, v95 row_shr:2 row_mask:0xf bank_mask:0xf bound_ctrl:1
	v_pk_fma_f32 v[94:95], v[124:125], v[118:119], v[94:95]
	s_nop 1
	v_mov_b32_dpp v118, v94 row_shr:4 row_mask:0xf bank_mask:0xf bound_ctrl:1
	v_mov_b32_dpp v119, v95 row_shr:4 row_mask:0xf bank_mask:0xf bound_ctrl:1
	v_pk_fma_f32 v[94:95], v[126:127], v[118:119], v[94:95]
	s_nop 1
	v_mov_b32_dpp v118, v94 row_shr:8 row_mask:0xf bank_mask:0xf bound_ctrl:1
	v_mov_b32_dpp v119, v95 row_shr:8 row_mask:0xf bank_mask:0xf bound_ctrl:1
	v_pk_fma_f32 v[94:95], v[128:129], v[118:119], v[94:95]
	v_mfma_f32_16x16x32_bf16 v[118:121], v[60:63], v[8:11], 0
	v_fma_f32 v94, v130, v108, v94
	v_fma_f32 v95, v131, v109, v95
	ds_bpermute_b32 v108, v1, v94
	v_cvt_pk_bf16_f32 v93, v94, v95
	v_mov_b64_e32 v[230:231], v[92:93]
	v_mov_b64_e32 v[234:235], v[88:89]
	v_mfma_f32_16x16x32_bf16 v[88:91], v[64:67], v[8:11], 0
	ds_bpermute_b32 v109, v1, v95
	v_mfma_f32_16x16x32_bf16 v[92:95], v[56:59], v[24:27], v[88:91]
	v_mfma_f32_16x16x32_bf16 v[88:91], v[52:55], v[24:27], v[118:121]
	v_mfma_f32_16x16x32_bf16 v[64:67], v[64:67], v[4:7], 0
	s_nop 5
	v_add_f32_e32 v92, v48, v92
	v_mul_f32_e32 v92, 0xbfb8aa3b, v92
	v_exp_f32_e32 v92, v92
	v_add_f32_e32 v88, v44, v88
	v_mul_f32_e32 v88, 0xbfb8aa3b, v88
	v_exp_f32_e32 v88, v88
	v_add_f32_e32 v92, 1.0, v92
	v_rcp_f32_e32 v92, v92
	v_add_f32_e32 v89, v45, v89
	v_add_f32_e32 v88, 1.0, v88
	v_rcp_f32_e32 v118, v88
	v_mul_f32_e32 v88, 0xc1000000, v92
	v_add_f32_e32 v92, v49, v93
	v_mul_f32_e32 v92, 0xbfb8aa3b, v92
	v_exp_f32_e32 v92, v92
	v_mul_f32_e32 v89, 0xbfb8aa3b, v89
	v_exp_f32_e32 v89, v89
	v_mul_f32_e32 v88, v2, v88
	v_add_f32_e32 v92, 1.0, v92
	v_rcp_f32_e32 v92, v92
	v_add_f32_e32 v89, 1.0, v89
	v_rcp_f32_e32 v119, v89
	v_mul_f32_e32 v88, 0x3fb8aa3b, v88
	v_mul_f32_e32 v89, 0xc1000000, v92
	v_mul_f32_e32 v89, v134, v89
	v_mul_f32_e32 v89, 0x3fb8aa3b, v89
	v_exp_f32_e32 v120, v88
	v_exp_f32_e32 v121, v89
	v_mfma_f32_16x16x32_bf16 v[60:63], v[60:63], v[4:7], 0
	v_add_f32_e32 v94, v50, v94
	v_fma_f32 v88, -v120, v120, 1.0
	v_fma_f32 v89, -v121, v121, 1.0
	v_sqrt_f32_e32 v124, v88
	v_mov_b32_e32 v88, 1.0
	v_sqrt_f32_e32 v125, v89
	v_mov_b32_e32 v89, 1.0
	v_mov_b32_dpp v88, v120 row_shr:1 row_mask:0xf bank_mask:0xf
	v_mfma_f32_16x16x32_bf16 v[56:59], v[56:59], v[20:23], v[64:67]
	v_mov_b32_dpp v89, v121 row_shr:1 row_mask:0xf bank_mask:0xf
	v_pk_mul_f32 v[126:127], v[120:121], v[88:89]
	v_mov_b32_e32 v88, 1.0
	v_mov_b32_e32 v89, 1.0
	v_add_f32_e32 v95, v51, v95
	v_mov_b32_dpp v88, v126 row_shr:2 row_mask:0xf bank_mask:0xf
	v_mov_b32_dpp v89, v127 row_shr:2 row_mask:0xf bank_mask:0xf
	v_pk_mul_f32 v[128:129], v[126:127], v[88:89]
	v_mov_b32_e32 v88, 1.0
	v_mov_b32_e32 v89, 1.0
	v_mul_f32_e32 v94, 0xbfb8aa3b, v94
	v_mov_b32_dpp v88, v128 row_shr:4 row_mask:0xf bank_mask:0xf
	v_mov_b32_dpp v89, v129 row_shr:4 row_mask:0xf bank_mask:0xf
	v_pk_mul_f32 v[130:131], v[128:129], v[88:89]
	v_mov_b32_e32 v88, 1.0
	v_mov_b32_e32 v89, 1.0
	v_mul_f32_e32 v95, 0xbfb8aa3b, v95
	v_mov_b32_dpp v88, v130 row_shr:8 row_mask:0xf bank_mask:0xf
	v_mov_b32_dpp v89, v131 row_shr:8 row_mask:0xf bank_mask:0xf
	v_pk_mul_f32 v[132:133], v[130:131], v[88:89]
	v_add_u32_e32 v89, 0x2100, v145
	v_pk_mul_f32 v[92:93], v[132:133], v[112:113]
	ds_read2_b32 v[112:113], v89 offset1:1
	v_mfma_f32_16x16x32_bf16 v[60:63], v[52:55], v[20:23], v[60:63]
	v_add_f32_e32 v48, v48, v56
	v_exp_f32_e32 v94, v94
	v_exp_f32_e32 v95, v95
	s_waitcnt lgkmcnt(0)
; __device__ __forceinline__ float sigmoidf_(float x) { return __builtin_amdgcn_rcpf(1.0f + __expf(-x)); }
; __device__ __forceinline__ float bcast15(float v, int lane) { return bperm_f((lane & 48) | 15, v); }
; __device__ __forceinline__ void w_lru_m1(const Args& a, int l, unsigned char* ws, const bf16_t* proj, bf16_t* y, LAS unsigned char* wl, int b, int ck_, int h, int lane) {
;     ...
;         for (int tb = 0; tb < 4; ++tb) { const int tok = 16 * tb + lo;
;             f32x4 ga = {0.f, 0.f, 0.f, 0.f}, gx = {0.f, 0.f, 0.f, 0.f};
; #pragma unroll
;             for (int kk = 0; kk < 2; ++kk) { ga = __builtin_amdgcn_mfma_f32_16x16x32_bf16(WaF[kk], Xf[tb][kk], ga, 0, 0, 0); gx = __builtin_amdgcn_mfma_f32_16x16x32_bf16(WxF[kk], Xf[tb][kk], gx, 0, 0, 0); }
;             float hv[4], pv[4];
; #pragma unroll
;             for (int r = 0; r < 4; ++r) {
;                 const float rg = sigmoidf_(ga[r] + bav[r]), ig = sigmoidf_(gx[r] + bxv[r]);
;                 const float la = -8.0f * rg * sp[r]; float A = __expf(la);
;                 float U = __builtin_amdgcn_sqrtf(1.0f - A * A) * (ig * xcf[tok * 65 + j0 + r]);
;                 { const float As = dpp_shr1<1>(A), Us = dpp_shr0<1>(U); U = A * Us + U; A = A * As; }
;                 { const float As = dpp_shr1<2>(A), Us = dpp_shr0<2>(U); U = A * Us + U; A = A * As; }
;                 { const float As = dpp_shr1<4>(A), Us = dpp_shr0<4>(U); U = A * Us + U; A = A * As; }
;                 { const float As = dpp_shr1<8>(A), Us = dpp_shr0<8>(U); U = A * Us + U; A = A * As; }
;                 const float hh = U + A * hc[r], PP = A * Pc[r];
;                 hc[r] = bcast15(hh, lane); Pc[r] = bcast15(PP, lane); hv[r] = hh; pv[r] = PP; }
	v_pk_mul_f32 v[112:113], v[112:113], v[118:119]
	v_mul_f32_e32 v48, 0xbfb8aa3b, v48
	v_pk_mul_f32 v[112:113], v[112:113], v[124:125]
	v_exp_f32_e32 v48, v48
	v_add_f32_e32 v90, v46, v90
	v_mov_b32_dpp v118, v112 row_shr:1 row_mask:0xf bank_mask:0xf bound_ctrl:1
	v_mov_b32_dpp v119, v113 row_shr:1 row_mask:0xf bank_mask:0xf bound_ctrl:1
	v_add_f32_e32 v91, v47, v91
	v_pk_fma_f32 v[112:113], v[120:121], v[118:119], v[112:113]
	v_mul_f32_e32 v90, 0xbfb8aa3b, v90
	v_mul_f32_e32 v91, 0xbfb8aa3b, v91
	v_add_f32_e32 v44, v44, v60
	v_mov_b32_dpp v118, v112 row_shr:2 row_mask:0xf bank_mask:0xf bound_ctrl:1
	v_mov_b32_dpp v119, v113 row_shr:2 row_mask:0xf bank_mask:0xf bound_ctrl:1
	v_add_f32_e32 v94, 1.0, v94
	v_exp_f32_e32 v90, v90
	v_add_f32_e32 v95, 1.0, v95
	v_exp_f32_e32 v91, v91
	v_mul_f32_e32 v44, 0xbfb8aa3b, v44
	v_pk_fma_f32 v[112:113], v[126:127], v[118:119], v[112:113]
	v_rcp_f32_e32 v94, v94
	v_rcp_f32_e32 v95, v95
	v_add_f32_e32 v48, 1.0, v48
	v_exp_f32_e32 v44, v44
	v_mov_b32_dpp v118, v112 row_shr:4 row_mask:0xf bank_mask:0xf bound_ctrl:1
	v_mov_b32_dpp v119, v113 row_shr:4 row_mask:0xf bank_mask:0xf bound_ctrl:1
	v_rcp_f32_e32 v52, v48
	v_pk_fma_f32 v[112:113], v[128:129], v[118:119], v[112:113]
	v_add_f32_e32 v90, 1.0, v90
	v_add_f32_e32 v91, 1.0, v91
	v_mov_b32_dpp v118, v112 row_shr:8 row_mask:0xf bank_mask:0xf bound_ctrl:1
	v_mov_b32_dpp v119, v113 row_shr:8 row_mask:0xf bank_mask:0xf bound_ctrl:1
	v_pk_fma_f32 v[112:113], v[130:131], v[118:119], v[112:113]
	v_rcp_f32_e32 v118, v90
	v_mul_f32_e32 v90, 0xc1000000, v94
	v_rcp_f32_e32 v119, v91
	v_mul_f32_e32 v91, 0xc1000000, v95
	v_add_f32_e32 v44, 1.0, v44
	v_mul_f32_e32 v90, v135, v90
	v_mul_f32_e32 v91, v136, v91
	v_rcp_f32_e32 v48, v44
	v_mul_f32_e32 v44, 0xc1000000, v52
	v_mul_f32_e32 v90, 0x3fb8aa3b, v90
	v_mul_f32_e32 v91, 0x3fb8aa3b, v91
	v_mul_f32_e32 v2, v2, v44
	v_exp_f32_e32 v94, v90
	v_exp_f32_e32 v95, v91
	v_mul_f32_e32 v2, 0x3fb8aa3b, v2
	v_exp_f32_e32 v54, v2
	v_fma_f32 v90, -v94, v94, 1.0
	v_fma_f32 v91, -v95, v95, 1.0
	v_sqrt_f32_e32 v120, v90
	v_mov_b32_e32 v90, 1.0
	v_sqrt_f32_e32 v121, v91
	v_mov_b32_e32 v91, 1.0
	v_fma_f32 v2, -v54, v54, 1.0
	v_mov_b32_dpp v90, v94 row_shr:1 row_mask:0xf bank_mask:0xf
	v_mov_b32_dpp v91, v95 row_shr:1 row_mask:0xf bank_mask:0xf
	v_sqrt_f32_e32 v56, v2
	v_add_f32_e32 v2, v49, v57
	v_pk_mul_f32 v[124:125], v[94:95], v[90:91]
	v_mov_b32_e32 v90, 1.0
	v_mov_b32_e32 v91, 1.0
	v_mul_f32_e32 v2, 0xbfb8aa3b, v2
	v_mov_b32_dpp v90, v124 row_shr:2 row_mask:0xf bank_mask:0xf
	v_mov_b32_dpp v91, v125 row_shr:2 row_mask:0xf bank_mask:0xf
	v_exp_f32_e32 v2, v2
	v_pk_mul_f32 v[126:127], v[124:125], v[90:91]
	v_mov_b32_e32 v90, 1.0
	v_mov_b32_e32 v91, 1.0
	v_add_f32_e32 v2, 1.0, v2
	v_mov_b32_dpp v90, v126 row_shr:4 row_mask:0xf bank_mask:0xf
	v_mov_b32_dpp v91, v127 row_shr:4 row_mask:0xf bank_mask:0xf
	v_pk_mul_f32 v[128:129], v[126:127], v[90:91]
	v_mov_b32_e32 v90, 1.0
	v_mov_b32_e32 v91, 1.0
	v_rcp_f32_e32 v2, v2
	v_mov_b32_dpp v90, v128 row_shr:8 row_mask:0xf bank_mask:0xf
	v_mov_b32_dpp v91, v129 row_shr:8 row_mask:0xf bank_mask:0xf
	v_pk_mul_f32 v[130:131], v[128:129], v[90:91]
	v_add_u32_e32 v91, 0x2108, v145
	v_pk_fma_f32 v[112:113], v[132:133], v[110:111], v[112:113]
	ds_read2_b32 v[132:133], v91 offset1:1
	v_add_f32_e32 v45, v45, v61
	v_mul_f32_e32 v45, 0xbfb8aa3b, v45
	v_mul_f32_e32 v2, 0xc1000000, v2
	v_exp_f32_e32 v45, v45
	v_mul_f32_e32 v2, v134, v2
	s_waitcnt lgkmcnt(0)
	v_pk_mul_f32 v[118:119], v[118:119], v[132:133]
	v_mul_f32_e32 v2, 0x3fb8aa3b, v2
	v_pk_mul_f32 v[118:119], v[120:121], v[118:119]
	v_exp_f32_e32 v55, v2
	v_add_f32_e32 v45, 1.0, v45
	v_mov_b32_dpp v120, v118 row_shr:1 row_mask:0xf bank_mask:0xf bound_ctrl:1
	v_mov_b32_dpp v121, v119 row_shr:1 row_mask:0xf bank_mask:0xf bound_ctrl:1
	v_pk_fma_f32 v[94:95], v[94:95], v[120:121], v[118:119]
	v_mov_b32_e32 v44, 1.0
	v_rcp_f32_e32 v49, v45
	v_mov_b32_dpp v118, v94 row_shr:2 row_mask:0xf bank_mask:0xf bound_ctrl:1
	v_mov_b32_dpp v119, v95 row_shr:2 row_mask:0xf bank_mask:0xf bound_ctrl:1
	v_mov_b32_e32 v45, 1.0
	v_pk_fma_f32 v[94:95], v[124:125], v[118:119], v[94:95]
	v_mov_b32_dpp v44, v54 row_shr:1 row_mask:0xf bank_mask:0xf
	v_mov_b32_dpp v45, v55 row_shr:1 row_mask:0xf bank_mask:0xf
	v_mov_b32_dpp v118, v94 row_shr:4 row_mask:0xf bank_mask:0xf bound_ctrl:1
	v_mov_b32_dpp v119, v95 row_shr:4 row_mask:0xf bank_mask:0xf bound_ctrl:1
	v_pk_mul_f32 v[60:61], v[54:55], v[44:45]
	v_mov_b32_e32 v44, 1.0
	v_mov_b32_e32 v45, 1.0
	v_pk_fma_f32 v[94:95], v[126:127], v[118:119], v[94:95]
	v_mov_b32_dpp v44, v60 row_shr:2 row_mask:0xf bank_mask:0xf
	v_mov_b32_dpp v45, v61 row_shr:2 row_mask:0xf bank_mask:0xf
	ds_bpermute_b32 v88, v1, v92
	ds_bpermute_b32 v89, v1, v93
	v_mov_b32_dpp v118, v94 row_shr:8 row_mask:0xf bank_mask:0xf bound_ctrl:1
	v_mov_b32_dpp v119, v95 row_shr:8 row_mask:0xf bank_mask:0xf bound_ctrl:1
	v_pk_mul_f32 v[64:65], v[60:61], v[44:45]
	v_mov_b32_e32 v44, 1.0
	v_mov_b32_e32 v45, 1.0
	v_pk_fma_f32 v[94:95], v[128:129], v[118:119], v[94:95]
	v_mov_b32_dpp v44, v64 row_shr:4 row_mask:0xf bank_mask:0xf
	v_mov_b32_dpp v45, v65 row_shr:4 row_mask:0xf bank_mask:0xf
	v_pk_mul_f32 v[122:123], v[130:131], v[122:123]
	v_pk_fma_f32 v[108:109], v[130:131], v[108:109], v[94:95]
	v_pk_mul_f32 v[66:67], v[64:65], v[44:45]
	v_mov_b32_e32 v44, 1.0
	v_mov_b32_e32 v45, 1.0
	ds_bpermute_b32 v110, v1, v112
	ds_bpermute_b32 v111, v1, v113
	v_cvt_pk_bf16_f32 v112, v112, v113
	v_cvt_pk_bf16_f32 v113, v108, v109
	v_cvt_pk_bf16_f32 v92, v92, v93
	v_cvt_pk_bf16_f32 v93, v122, v123
	v_fma_f32 v2, -v55, v55, 1.0
	v_mov_b32_dpp v44, v66 row_shr:8 row_mask:0xf bank_mask:0xf
	v_mov_b32_dpp v45, v67 row_shr:8 row_mask:0xf bank_mask:0xf
	v_mov_b64_e32 v[238:239], v[112:113]
	v_mov_b64_e32 v[242:243], v[92:93]
	v_sqrt_f32_e32 v57, v2
	v_pk_mul_f32 v[92:93], v[66:67], v[44:45]
	v_add_u32_e32 v2, 0x3140, v145
	s_waitcnt lgkmcnt(0)
; __device__ __forceinline__ unsigned pk2(float lo, float hi) { const f32x2_t v = {lo, hi}; const bf16x2_t b = __builtin_convertvector(v, bf16x2_t); return __builtin_bit_cast(unsigned, b); }
; __device__ __forceinline__ float sigmoidf_(float x) { return __builtin_amdgcn_rcpf(1.0f + __expf(-x)); }
; __device__ __forceinline__ void w_lru_m1(const Args& a, int l, unsigned char* ws, const bf16_t* proj, bf16_t* y, LAS unsigned char* wl, int b, int ck_, int h, int lane) {
;     ...
;         for (int tb = 0; tb < 4; ++tb) { const int tok = 16 * tb + lo;
;             f32x4 ga = {0.f, 0.f, 0.f, 0.f}, gx = {0.f, 0.f, 0.f, 0.f};
; #pragma unroll
;             for (int kk = 0; kk < 2; ++kk) { ga = __builtin_amdgcn_mfma_f32_16x16x32_bf16(WaF[kk], Xf[tb][kk], ga, 0, 0, 0); gx = __builtin_amdgcn_mfma_f32_16x16x32_bf16(WxF[kk], Xf[tb][kk], gx, 0, 0, 0); }
;             float hv[4], pv[4];
; #pragma unroll
;             for (int r = 0; r < 4; ++r) {
;                 const float rg = sigmoidf_(ga[r] + bav[r]), ig = sigmoidf_(gx[r] + bxv[r]);
;                 const float la = -8.0f * rg * sp[r]; float A = __expf(la);
;                 float U = __builtin_amdgcn_sqrtf(1.0f - A * A) * (ig * xcf[tok * 65 + j0 + r]);
;                 { const float As = dpp_shr1<1>(A), Us = dpp_shr0<1>(U); U = A * Us + U; A = A * As; }
;                 { const float As = dpp_shr1<2>(A), Us = dpp_shr0<2>(U); U = A * Us + U; A = A * As; }
;                 { const float As = dpp_shr1<4>(A), Us = dpp_shr0<4>(U); U = A * Us + U; A = A * As; }
;                 { const float As = dpp_shr1<8>(A), Us = dpp_shr0<8>(U); U = A * Us + U; A = A * As; }
;                 const float hh = U + A * hc[r], PP = A * Pc[r];
;                 hc[r] = bcast15(hh, lane); Pc[r] = bcast15(PP, lane); hv[r] = hh; pv[r] = PP; }
;             *(unsigned long long*)(y + (size_t)(row0 + tok) * DM + 64 * h + j0) = (unsigned long long)pk2(hv[0], hv[1]) | ((unsigned long long)pk2(hv[2], hv[3]) << 32);
;             *(unsigned long long*)((bf16_t*)(ws + WS_P) + (size_t)(row0 + tok) * 512 + 64 * h + j0) = (unsigned long long)pk2(pv[0], pv[1]) | ((unsigned long long)pk2(pv[2], pv[3]) << 32);
;         }
;         if (lo == 0) { const size_t so = (size_t)(b * NCH + ck_) * 512 + 64 * h + j0;
; #pragma unroll
;             for (int r = 0; r < 4; ++r) { ((float*)(ws + WS_LRUA))[so + r] = Pc[r]; ((float*)(ws + WS_LRUH))[so + r] = hc[r]; } }
	v_pk_mul_f32 v[52:53], v[92:93], v[88:89]
	ds_read2_b32 v[88:89], v2 offset1:1
	v_add_f32_e32 v2, v50, v58
	v_mul_f32_e32 v2, 0xbfb8aa3b, v2
	v_exp_f32_e32 v2, v2
	v_add_f32_e32 v46, v46, v62
	v_add_f32_e32 v47, v47, v63
	v_mul_f32_e32 v46, 0xbfb8aa3b, v46
	v_add_f32_e32 v2, 1.0, v2
	v_rcp_f32_e32 v2, v2
	v_mul_f32_e32 v47, 0xbfb8aa3b, v47
	v_exp_f32_e32 v46, v46
	v_exp_f32_e32 v47, v47
	v_mul_f32_e32 v2, 0xc1000000, v2
	v_mul_f32_e32 v2, v135, v2
	v_mul_f32_e32 v2, 0x3fb8aa3b, v2
	v_exp_f32_e32 v50, v2
	s_waitcnt lgkmcnt(0)
	v_pk_mul_f32 v[48:49], v[88:89], v[48:49]
	v_add_f32_e32 v46, 1.0, v46
	v_pk_mul_f32 v[48:49], v[48:49], v[56:57]
	v_fma_f32 v2, -v50, v50, 1.0
	v_sqrt_f32_e32 v58, v2
	v_add_f32_e32 v2, v51, v59
	v_mul_f32_e32 v2, 0xbfb8aa3b, v2
	v_exp_f32_e32 v2, v2
	v_mov_b32_dpp v56, v48 row_shr:1 row_mask:0xf bank_mask:0xf bound_ctrl:1
	v_mov_b32_dpp v57, v49 row_shr:1 row_mask:0xf bank_mask:0xf bound_ctrl:1
	v_add_f32_e32 v47, 1.0, v47
	v_add_f32_e32 v2, 1.0, v2
	v_rcp_f32_e32 v2, v2
	v_pk_fma_f32 v[48:49], v[54:55], v[56:57], v[48:49]
	v_rcp_f32_e32 v56, v46
	v_mov_b32_e32 v46, 1.0
	v_mul_f32_e32 v2, 0xc1000000, v2
	v_mul_f32_e32 v2, v136, v2
	v_mul_f32_e32 v2, 0x3fb8aa3b, v2
	v_exp_f32_e32 v51, v2
	v_rcp_f32_e32 v57, v47
	v_mov_b32_e32 v47, 1.0
	v_mov_b32_dpp v54, v48 row_shr:2 row_mask:0xf bank_mask:0xf bound_ctrl:1
	v_mov_b32_dpp v55, v49 row_shr:2 row_mask:0xf bank_mask:0xf bound_ctrl:1
	v_mov_b32_dpp v46, v50 row_shr:1 row_mask:0xf bank_mask:0xf
	v_mov_b32_dpp v47, v51 row_shr:1 row_mask:0xf bank_mask:0xf
	v_pk_fma_f32 v[48:49], v[60:61], v[54:55], v[48:49]
	v_pk_mul_f32 v[62:63], v[50:51], v[46:47]
	v_mov_b32_e32 v46, 1.0
	v_mov_b32_e32 v47, 1.0
	v_mov_b32_dpp v54, v48 row_shr:4 row_mask:0xf bank_mask:0xf bound_ctrl:1
	v_mov_b32_dpp v55, v49 row_shr:4 row_mask:0xf bank_mask:0xf bound_ctrl:1
	v_mov_b32_dpp v46, v62 row_shr:2 row_mask:0xf bank_mask:0xf
	v_mov_b32_dpp v47, v63 row_shr:2 row_mask:0xf bank_mask:0xf
	ds_bpermute_b32 v90, v1, v122
	ds_bpermute_b32 v91, v1, v123
	v_pk_fma_f32 v[48:49], v[64:65], v[54:55], v[48:49]
	v_pk_mul_f32 v[64:65], v[62:63], v[46:47]
	v_mov_b32_e32 v46, 1.0
	v_mov_b32_e32 v47, 1.0
	v_mov_b32_dpp v54, v48 row_shr:8 row_mask:0xf bank_mask:0xf bound_ctrl:1
	v_mov_b32_dpp v55, v49 row_shr:8 row_mask:0xf bank_mask:0xf bound_ctrl:1
	v_mov_b32_dpp v46, v64 row_shr:4 row_mask:0xf bank_mask:0xf
	v_mov_b32_dpp v47, v65 row_shr:4 row_mask:0xf bank_mask:0xf
	v_pk_fma_f32 v[48:49], v[66:67], v[54:55], v[48:49]
	v_pk_mul_f32 v[66:67], v[64:65], v[46:47]
	v_mov_b32_e32 v46, 1.0
	v_mov_b32_e32 v47, 1.0
	v_fma_f32 v2, -v51, v51, 1.0
	v_mov_b32_dpp v46, v66 row_shr:8 row_mask:0xf bank_mask:0xf
	v_mov_b32_dpp v47, v67 row_shr:8 row_mask:0xf bank_mask:0xf
	v_sqrt_f32_e32 v59, v2
	v_pk_mul_f32 v[88:89], v[66:67], v[46:47]
	v_add_u32_e32 v2, 0x3148, v145
	s_waitcnt lgkmcnt(0)
	v_pk_mul_f32 v[60:61], v[88:89], v[90:91]
	ds_read2_b32 v[90:91], v2 offset1:1
	ds_bpermute_b32 v94, v1, v108
	ds_bpermute_b32 v95, v1, v109
	v_pk_fma_f32 v[54:55], v[92:93], v[110:111], v[48:49]
	ds_bpermute_b32 v44, v1, v52
	s_waitcnt lgkmcnt(0)
	v_pk_mul_f32 v[56:57], v[56:57], v[90:91]
	ds_bpermute_b32 v48, v1, v54
	v_pk_mul_f32 v[56:57], v[58:59], v[56:57]
	ds_bpermute_b32 v49, v1, v55
	ds_bpermute_b32 v45, v1, v53
	v_mov_b32_dpp v58, v56 row_shr:1 row_mask:0xf bank_mask:0xf bound_ctrl:1
	v_mov_b32_dpp v59, v57 row_shr:1 row_mask:0xf bank_mask:0xf bound_ctrl:1
	v_pk_fma_f32 v[50:51], v[50:51], v[58:59], v[56:57]
	ds_bpermute_b32 v46, v1, v60
	ds_bpermute_b32 v47, v1, v61
	v_mov_b32_dpp v56, v50 row_shr:2 row_mask:0xf bank_mask:0xf bound_ctrl:1
	v_mov_b32_dpp v57, v51 row_shr:2 row_mask:0xf bank_mask:0xf bound_ctrl:1
	v_pk_fma_f32 v[50:51], v[62:63], v[56:57], v[50:51]
	v_cvt_pk_bf16_f32 v54, v54, v55
	v_cvt_pk_bf16_f32 v52, v52, v53
	v_mov_b32_dpp v56, v50 row_shr:4 row_mask:0xf bank_mask:0xf bound_ctrl:1
	v_mov_b32_dpp v57, v51 row_shr:4 row_mask:0xf bank_mask:0xf bound_ctrl:1
	v_pk_fma_f32 v[50:51], v[64:65], v[56:57], v[50:51]
	v_cvt_pk_bf16_f32 v53, v60, v61
	s_nop 0
	v_mov_b32_dpp v56, v50 row_shr:8 row_mask:0xf bank_mask:0xf bound_ctrl:1
	v_mov_b32_dpp v57, v51 row_shr:8 row_mask:0xf bank_mask:0xf bound_ctrl:1
	v_pk_fma_f32 v[50:51], v[66:67], v[56:57], v[50:51]
	s_nop 0
	v_pk_fma_f32 v[56:57], v[88:89], v[94:95], v[50:51]
	ds_bpermute_b32 v50, v1, v56
	ds_bpermute_b32 v51, v1, v57
	v_cvt_pk_bf16_f32 v55, v56, v57
	v_mov_b64_e32 v[246:247], v[54:55]
	v_mov_b64_e32 v[250:251], v[52:53]
	s_and_saveexec_b64 s[34:35], vcc
	s_cbranch_execz .LBB0_527
	v_add_u32_e32 v52, 32, v0
	v_ashrrev_i32_e32 v53, 31, v52
	v_lshl_add_u64 v[52:53], s[42:43], 0, v[52:53]
	v_lshlrev_b64 v[52:53], 2, v[52:53]
	v_lshl_add_u64 v[54:55], s[84:85], 0, v[52:53]
	v_lshl_add_u64 v[52:53], s[86:87], 0, v[52:53]
	s_waitcnt lgkmcnt(0)
	global_store_dwordx4 v[54:55], v[44:47], off
	global_store_dwordx4 v[52:53], v[48:51], off
; __device__ __forceinline__ float sigmoidf_(float x) { return __builtin_amdgcn_rcpf(1.0f + __expf(-x)); }
; __device__ __forceinline__ float bcast15(float v, int lane) { return bperm_f((lane & 48) | 15, v); }
; __device__ __forceinline__ void w_lru_m1(const Args& a, int l, unsigned char* ws, const bf16_t* proj, bf16_t* y, LAS unsigned char* wl, int b, int ck_, int h, int lane) {
;     ...
;         const int j0 = 16 * jb + 4 * fq;
;         float bav[4], bxv[4], sp[4], hc[4], Pc[4];
; #pragma unroll
;         for (int r = 0; r < 4; ++r) { bav[r] = pba[r]; bxv[r] = pbx[r]; sp[r] = log1pf(__expf(-plam[r])); hc[r] = 0.f; Pc[r] = 1.f; }
; #pragma unroll
;         for (int tb = 0; tb < 4; ++tb) { const int tok = 16 * tb + lo;
;             f32x4 ga = {0.f, 0.f, 0.f, 0.f}, gx = {0.f, 0.f, 0.f, 0.f};
; #pragma unroll
;             for (int kk = 0; kk < 2; ++kk) { ga = __builtin_amdgcn_mfma_f32_16x16x32_bf16(WaF[kk], Xf[tb][kk], ga, 0, 0, 0); gx = __builtin_amdgcn_mfma_f32_16x16x32_bf16(WxF[kk], Xf[tb][kk], gx, 0, 0, 0); }
;             float hv[4], pv[4];
; #pragma unroll
;             for (int r = 0; r < 4; ++r) {
;                 const float rg = sigmoidf_(ga[r] + bav[r]), ig = sigmoidf_(gx[r] + bxv[r]);
;                 const float la = -8.0f * rg * sp[r]; float A = __expf(la);
;                 float U = __builtin_amdgcn_sqrtf(1.0f - A * A) * (ig * xcf[tok * 65 + j0 + r]);
;                 { const float As = dpp_shr1<1>(A), Us = dpp_shr0<1>(U); U = A * Us + U; A = A * As; }
;                 { const float As = dpp_shr1<2>(A), Us = dpp_shr0<2>(U); U = A * Us + U; A = A * As; }
;                 { const float As = dpp_shr1<4>(A), Us = dpp_shr0<4>(U); U = A * Us + U; A = A * As; }
;                 { const float As = dpp_shr1<8>(A), Us = dpp_shr0<8>(U); U = A * Us + U; A = A * As; }
;                 const float hh = U + A * hc[r], PP = A * Pc[r];
;                 hc[r] = bcast15(hh, lane); Pc[r] = bcast15(PP, lane); hv[r] = hh; pv[r] = PP; }
.LBB0_527:
	s_or_b64 exec, exec, s[34:35]
	s_waitcnt vmcnt(2)
	s_nop 7
	ds_read2_b32 v[64:65], v145 offset0:50 offset1:51
	s_waitcnt lgkmcnt(0)
	s_nop 7
	v_mov_b32_e32 v58, v84
	s_nop 7
	v_mov_b32_e32 v60, v85
	s_nop 7
	v_mov_b32_e32 v2, v86
	s_nop 7
	ds_read2_b32 v[54:55], v145 offset0:48 offset1:49
	v_mov_b32_e32 v48, 1.0
	s_nop 7
	v_mov_b32_e32 v49, 1.0
	v_mov_b32_e32 v50, 1.0
	s_nop 7
	v_mov_b32_e32 v51, 1.0
	v_mov_b32_e32 v52, 1.0
	v_mov_b32_e32 v59, v87
	v_mfma_f32_16x16x32_bf16 v[44:47], v[68:71], v[16:19], 0
	v_mov_b32_e32 v53, 1.0
	v_mfma_f32_16x16x32_bf16 v[16:19], v[72:75], v[16:19], 0
	v_mfma_f32_16x16x32_bf16 v[44:47], v[76:79], v[32:35], v[44:47]
	v_mfma_f32_16x16x32_bf16 v[16:19], v[80:83], v[32:35], v[16:19]
	s_nop 6
	v_add_f32_e32 v32, v40, v44
	v_mul_f32_e32 v32, 0xbfb8aa3b, v32
	v_exp_f32_e32 v32, v32
	v_add_f32_e32 v16, v36, v16
	v_add_f32_e32 v17, v37, v17
	v_mul_f32_e32 v16, 0xbfb8aa3b, v16
	v_add_f32_e32 v32, 1.0, v32
	v_rcp_f32_e32 v32, v32
	v_mul_f32_e32 v17, 0xbfb8aa3b, v17
	v_exp_f32_e32 v16, v16
	v_exp_f32_e32 v17, v17
	v_mul_f32_e32 v32, 0xc1000000, v32
	v_mul_f32_e32 v32, v58, v32
	v_mul_f32_e32 v32, 0x3fb8aa3b, v32
	v_exp_f32_e32 v32, v32
	v_add_f32_e32 v16, 1.0, v16
	v_add_f32_e32 v17, 1.0, v17
	v_rcp_f32_e32 v16, v16
	v_fma_f32 v33, -v32, v32, 1.0
	v_sqrt_f32_e32 v34, v33
	v_add_f32_e32 v33, v41, v45
	v_mul_f32_e32 v33, 0xbfb8aa3b, v33
	v_exp_f32_e32 v33, v33
	v_rcp_f32_e32 v17, v17
	v_mov_b32_e32 v44, 1.0
	v_mov_b32_e32 v45, 1.0
	v_add_f32_e32 v33, 1.0, v33
	v_rcp_f32_e32 v33, v33
	s_waitcnt lgkmcnt(0)
	v_pk_mul_f32 v[16:17], v[54:55], v[16:17]
	v_mov_b32_dpp v44, v32 row_shr:1 row_mask:0xf bank_mask:0xf
	v_add_f32_e32 v18, v38, v18
	v_mul_f32_e32 v33, 0xc1000000, v33
	v_mul_f32_e32 v33, v60, v33
	v_mul_f32_e32 v33, 0x3fb8aa3b, v33
	v_exp_f32_e32 v33, v33
	v_add_f32_e32 v19, v39, v19
	v_mul_f32_e32 v18, 0xbfb8aa3b, v18
	v_mul_f32_e32 v19, 0xbfb8aa3b, v19
	v_fma_f32 v35, -v33, v33, 1.0
	v_sqrt_f32_e32 v35, v35
	v_mov_b32_dpp v45, v33 row_shr:1 row_mask:0xf bank_mask:0xf
	v_pk_mul_f32 v[44:45], v[32:33], v[44:45]
	v_exp_f32_e32 v18, v18
	v_pk_mul_f32 v[16:17], v[16:17], v[34:35]
	v_mov_b32_dpp v48, v44 row_shr:2 row_mask:0xf bank_mask:0xf
	v_mov_b32_dpp v49, v45 row_shr:2 row_mask:0xf bank_mask:0xf
	v_mov_b32_dpp v34, v16 row_shr:1 row_mask:0xf bank_mask:0xf bound_ctrl:1
	v_mov_b32_dpp v35, v17 row_shr:1 row_mask:0xf bank_mask:0xf bound_ctrl:1
	v_pk_fma_f32 v[16:17], v[32:33], v[34:35], v[16:17]
	v_pk_mul_f32 v[48:49], v[44:45], v[48:49]
	v_exp_f32_e32 v19, v19
	v_mov_b32_dpp v32, v16 row_shr:2 row_mask:0xf bank_mask:0xf bound_ctrl:1
	v_mov_b32_dpp v33, v17 row_shr:2 row_mask:0xf bank_mask:0xf bound_ctrl:1
	v_pk_fma_f32 v[16:17], v[44:45], v[32:33], v[16:17]
	v_mov_b32_dpp v50, v48 row_shr:4 row_mask:0xf bank_mask:0xf
	v_mov_b32_dpp v51, v49 row_shr:4 row_mask:0xf bank_mask:0xf
	v_mov_b32_dpp v32, v16 row_shr:4 row_mask:0xf bank_mask:0xf bound_ctrl:1
	v_mov_b32_dpp v33, v17 row_shr:4 row_mask:0xf bank_mask:0xf bound_ctrl:1
	v_pk_fma_f32 v[16:17], v[48:49], v[32:33], v[16:17]
	v_pk_mul_f32 v[50:51], v[48:49], v[50:51]
	v_add_f32_e32 v18, 1.0, v18
	v_mov_b32_dpp v32, v16 row_shr:8 row_mask:0xf bank_mask:0xf bound_ctrl:1
	v_mov_b32_dpp v33, v17 row_shr:8 row_mask:0xf bank_mask:0xf bound_ctrl:1
	v_pk_fma_f32 v[16:17], v[50:51], v[32:33], v[16:17]
	v_add_f32_e32 v32, v42, v46
	v_mul_f32_e32 v32, 0xbfb8aa3b, v32
	v_exp_f32_e32 v32, v32
	v_add_f32_e32 v19, 1.0, v19
	v_rcp_f32_e32 v18, v18
	v_rcp_f32_e32 v19, v19
	v_add_f32_e32 v32, 1.0, v32
	v_rcp_f32_e32 v32, v32
	v_mov_b32_e32 v46, 1.0
	v_pk_mul_f32 v[18:19], v[18:19], v[64:65]
	v_mov_b32_dpp v52, v50 row_shr:8 row_mask:0xf bank_mask:0xf
	v_mul_f32_e32 v32, 0xc1000000, v32
	v_mul_f32_e32 v32, v2, v32
	v_mul_f32_e32 v32, 0x3fb8aa3b, v32
	v_exp_f32_e32 v32, v32
	v_mov_b32_dpp v53, v51 row_shr:8 row_mask:0xf bank_mask:0xf
	v_pk_mul_f32 v[52:53], v[50:51], v[52:53]
	ds_bpermute_b32 v56, v1, v52
	v_fma_f32 v33, -v32, v32, 1.0
	v_sqrt_f32_e32 v44, v33
	v_add_f32_e32 v33, v43, v47
	v_mul_f32_e32 v33, 0xbfb8aa3b, v33
	v_exp_f32_e32 v33, v33
	v_mov_b32_e32 v47, 1.0
	v_mov_b32_dpp v46, v32 row_shr:1 row_mask:0xf bank_mask:0xf
	v_pk_fma_f32 v[16:17], v[52:53], 0, v[16:17] op_sel_hi:[1,0,1]
	v_add_f32_e32 v33, 1.0, v33
	v_rcp_f32_e32 v33, v33
	ds_bpermute_b32 v34, v1, v16
	ds_bpermute_b32 v35, v1, v17
	v_cvt_pk_bf16_f32 v16, v16, v17
	v_mul_f32_e32 v33, 0xc1000000, v33
	v_mul_f32_e32 v33, v59, v33
	v_mul_f32_e32 v33, 0x3fb8aa3b, v33
	v_exp_f32_e32 v33, v33
	ds_bpermute_b32 v57, v1, v53
	v_fma_f32 v45, -v33, v33, 1.0
	v_sqrt_f32_e32 v45, v45
	v_mov_b32_dpp v47, v33 row_shr:1 row_mask:0xf bank_mask:0xf
	v_pk_mul_f32 v[48:49], v[32:33], v[46:47]
	v_mov_b32_e32 v46, 1.0
	v_pk_mul_f32 v[18:19], v[44:45], v[18:19]
	v_mov_b32_e32 v47, 1.0
	v_mov_b32_dpp v46, v48 row_shr:2 row_mask:0xf bank_mask:0xf
	v_mov_b32_dpp v44, v18 row_shr:1 row_mask:0xf bank_mask:0xf bound_ctrl:1
	v_mov_b32_dpp v45, v19 row_shr:1 row_mask:0xf bank_mask:0xf bound_ctrl:1
	v_pk_fma_f32 v[18:19], v[32:33], v[44:45], v[18:19]
	v_mov_b32_dpp v47, v49 row_shr:2 row_mask:0xf bank_mask:0xf
	v_pk_mul_f32 v[50:51], v[48:49], v[46:47]
	v_mov_b32_dpp v32, v18 row_shr:2 row_mask:0xf bank_mask:0xf bound_ctrl:1
	v_mov_b32_dpp v33, v19 row_shr:2 row_mask:0xf bank_mask:0xf bound_ctrl:1
	v_mov_b32_e32 v46, 1.0
	v_mov_b32_e32 v47, 1.0
	v_pk_fma_f32 v[18:19], v[48:49], v[32:33], v[18:19]
	v_mov_b32_dpp v46, v50 row_shr:4 row_mask:0xf bank_mask:0xf
	v_mov_b32_dpp v47, v51 row_shr:4 row_mask:0xf bank_mask:0xf
	v_mov_b32_dpp v32, v18 row_shr:4 row_mask:0xf bank_mask:0xf bound_ctrl:1
	v_mov_b32_dpp v33, v19 row_shr:4 row_mask:0xf bank_mask:0xf bound_ctrl:1
; __device__ __forceinline__ unsigned pk2(float lo, float hi) { const f32x2_t v = {lo, hi}; const bf16x2_t b = __builtin_convertvector(v, bf16x2_t); return __builtin_bit_cast(unsigned, b); }
; __device__ __forceinline__ float sigmoidf_(float x) { return __builtin_amdgcn_rcpf(1.0f + __expf(-x)); }
; __device__ __forceinline__ float bcast15(float v, int lane) { return bperm_f((lane & 48) | 15, v); }
; __device__ __forceinline__ void w_lru_m1(const Args& a, int l, unsigned char* ws, const bf16_t* proj, bf16_t* y, LAS unsigned char* wl, int b, int ck_, int h, int lane) {
;     ...
;         for (int tb = 0; tb < 4; ++tb) { const int tok = 16 * tb + lo;
;             f32x4 ga = {0.f, 0.f, 0.f, 0.f}, gx = {0.f, 0.f, 0.f, 0.f};
; #pragma unroll
;             for (int kk = 0; kk < 2; ++kk) { ga = __builtin_amdgcn_mfma_f32_16x16x32_bf16(WaF[kk], Xf[tb][kk], ga, 0, 0, 0); gx = __builtin_amdgcn_mfma_f32_16x16x32_bf16(WxF[kk], Xf[tb][kk], gx, 0, 0, 0); }
;             float hv[4], pv[4];
; #pragma unroll
;             for (int r = 0; r < 4; ++r) {
;                 const float rg = sigmoidf_(ga[r] + bav[r]), ig = sigmoidf_(gx[r] + bxv[r]);
;                 const float la = -8.0f * rg * sp[r]; float A = __expf(la);
;                 float U = __builtin_amdgcn_sqrtf(1.0f - A * A) * (ig * xcf[tok * 65 + j0 + r]);
;                 { const float As = dpp_shr1<1>(A), Us = dpp_shr0<1>(U); U = A * Us + U; A = A * As; }
;                 { const float As = dpp_shr1<2>(A), Us = dpp_shr0<2>(U); U = A * Us + U; A = A * As; }
;                 { const float As = dpp_shr1<4>(A), Us = dpp_shr0<4>(U); U = A * Us + U; A = A * As; }
;                 { const float As = dpp_shr1<8>(A), Us = dpp_shr0<8>(U); U = A * Us + U; A = A * As; }
;                 const float hh = U + A * hc[r], PP = A * Pc[r];
;                 hc[r] = bcast15(hh, lane); Pc[r] = bcast15(PP, lane); hv[r] = hh; pv[r] = PP; }
;             *(unsigned long long*)(y + (size_t)(row0 + tok) * DM + 64 * h + j0) = (unsigned long long)pk2(hv[0], hv[1]) | ((unsigned long long)pk2(hv[2], hv[3]) << 32);
;             *(unsigned long long*)((bf16_t*)(ws + WS_P) + (size_t)(row0 + tok) * 512 + 64 * h + j0) = (unsigned long long)pk2(pv[0], pv[1]) | ((unsigned long long)pk2(pv[2], pv[3]) << 32);
	v_pk_mul_f32 v[54:55], v[50:51], v[46:47]
	v_mov_b32_e32 v46, 1.0
	v_mov_b32_e32 v47, 1.0
	v_pk_fma_f32 v[18:19], v[50:51], v[32:33], v[18:19]
	v_mov_b32_dpp v46, v54 row_shr:8 row_mask:0xf bank_mask:0xf
	v_mov_b32_dpp v47, v55 row_shr:8 row_mask:0xf bank_mask:0xf
	v_mov_b32_dpp v32, v18 row_shr:8 row_mask:0xf bank_mask:0xf bound_ctrl:1
	v_mov_b32_dpp v33, v19 row_shr:8 row_mask:0xf bank_mask:0xf bound_ctrl:1
	v_pk_mul_f32 v[62:63], v[54:55], v[46:47]
	v_pk_fma_f32 v[18:19], v[54:55], v[32:33], v[18:19]
	ds_bpermute_b32 v46, v1, v62
	v_pk_fma_f32 v[18:19], v[62:63], 0, v[18:19] op_sel_hi:[1,0,1]
	ds_bpermute_b32 v32, v1, v18
	v_cvt_pk_bf16_f32 v17, v18, v19
	v_mov_b64_e32 v[224:225], v[16:17]
	s_nop 1
	v_permlane16_swap_b32_e32 v222, v224
	v_permlane16_swap_b32_e32 v223, v225
	global_store_dwordx4 v[100:101], v[222:225], off offset:64
	v_cvt_pk_bf16_f32 v16, v52, v53
	v_cvt_pk_bf16_f32 v17, v62, v63
	ds_bpermute_b32 v33, v1, v19
	v_mov_b64_e32 v[228:229], v[16:17]
	s_nop 1
	v_permlane16_swap_b32_e32 v226, v228
	v_permlane16_swap_b32_e32 v227, v229
	global_store_dwordx4 v[102:103], v[226:229], off offset:64
	v_mfma_f32_16x16x32_bf16 v[16:19], v[68:71], v[12:15], 0
	ds_bpermute_b32 v47, v1, v63
	v_mfma_f32_16x16x32_bf16 v[12:15], v[72:75], v[12:15], 0
	v_mfma_f32_16x16x32_bf16 v[16:19], v[76:79], v[28:31], v[16:19]
	v_mfma_f32_16x16x32_bf16 v[12:15], v[80:83], v[28:31], v[12:15]
	s_nop 6
	v_add_f32_e32 v16, v40, v16
	v_mul_f32_e32 v16, 0xbfb8aa3b, v16
	v_exp_f32_e32 v16, v16
	v_add_f32_e32 v12, v36, v12
	v_mul_f32_e32 v12, 0xbfb8aa3b, v12
	v_exp_f32_e32 v12, v12
	v_add_f32_e32 v16, 1.0, v16
	v_rcp_f32_e32 v16, v16
	v_add_f32_e32 v13, v37, v13
	v_add_f32_e32 v12, 1.0, v12
	v_rcp_f32_e32 v28, v12
	v_mul_f32_e32 v12, 0xc1000000, v16
	v_add_f32_e32 v16, v41, v17
	v_mul_f32_e32 v16, 0xbfb8aa3b, v16
	v_exp_f32_e32 v16, v16
	v_mul_f32_e32 v13, 0xbfb8aa3b, v13
	v_exp_f32_e32 v13, v13
	v_mul_f32_e32 v12, v58, v12
	v_add_f32_e32 v16, 1.0, v16
	v_rcp_f32_e32 v16, v16
	v_add_f32_e32 v13, 1.0, v13
	v_rcp_f32_e32 v29, v13
	v_mul_f32_e32 v12, 0x3fb8aa3b, v12
	v_mul_f32_e32 v13, 0xc1000000, v16
	v_mul_f32_e32 v13, v60, v13
	v_mul_f32_e32 v13, 0x3fb8aa3b, v13
	v_exp_f32_e32 v30, v12
	v_exp_f32_e32 v31, v13
	v_add_f32_e32 v18, v42, v18
	v_add_f32_e32 v19, v43, v19
	v_fma_f32 v12, -v30, v30, 1.0
	v_fma_f32 v13, -v31, v31, 1.0
	v_sqrt_f32_e32 v44, v12
	v_mov_b32_e32 v12, 1.0
	v_sqrt_f32_e32 v45, v13
	v_mov_b32_e32 v13, 1.0
	v_mov_b32_dpp v12, v30 row_shr:1 row_mask:0xf bank_mask:0xf
	v_mul_f32_e32 v18, 0xbfb8aa3b, v18
	v_mov_b32_dpp v13, v31 row_shr:1 row_mask:0xf bank_mask:0xf
	v_pk_mul_f32 v[48:49], v[30:31], v[12:13]
	v_mov_b32_e32 v12, 1.0
	v_mov_b32_e32 v13, 1.0
	v_mul_f32_e32 v19, 0xbfb8aa3b, v19
	v_mov_b32_dpp v12, v48 row_shr:2 row_mask:0xf bank_mask:0xf
	v_mov_b32_dpp v13, v49 row_shr:2 row_mask:0xf bank_mask:0xf
	v_pk_mul_f32 v[50:51], v[48:49], v[12:13]
	v_mov_b32_e32 v12, 1.0
	v_mov_b32_e32 v13, 1.0
	v_exp_f32_e32 v18, v18
	v_mov_b32_dpp v12, v50 row_shr:4 row_mask:0xf bank_mask:0xf
	v_mov_b32_dpp v13, v51 row_shr:4 row_mask:0xf bank_mask:0xf
	v_pk_mul_f32 v[52:53], v[50:51], v[12:13]
	v_mov_b32_e32 v12, 1.0
	v_mov_b32_e32 v13, 1.0
	v_exp_f32_e32 v19, v19
	v_mov_b32_dpp v12, v52 row_shr:8 row_mask:0xf bank_mask:0xf
	v_mov_b32_dpp v13, v53 row_shr:8 row_mask:0xf bank_mask:0xf
	v_pk_mul_f32 v[54:55], v[52:53], v[12:13]
	v_add_u32_e32 v13, 0x1100, v145
	s_waitcnt lgkmcnt(0)
	v_pk_mul_f32 v[16:17], v[54:55], v[56:57]
	ds_read2_b32 v[56:57], v13 offset1:1
	v_add_f32_e32 v14, v38, v14
	v_add_f32_e32 v15, v39, v15
	v_mul_f32_e32 v14, 0xbfb8aa3b, v14
	v_mul_f32_e32 v15, 0xbfb8aa3b, v15
	s_waitcnt lgkmcnt(0)
	v_pk_mul_f32 v[28:29], v[56:57], v[28:29]
	v_add_f32_e32 v18, 1.0, v18
	v_pk_mul_f32 v[28:29], v[28:29], v[44:45]
	v_exp_f32_e32 v14, v14
	v_add_f32_e32 v19, 1.0, v19
	v_mov_b32_dpp v44, v28 row_shr:1 row_mask:0xf bank_mask:0xf bound_ctrl:1
	v_mov_b32_dpp v45, v29 row_shr:1 row_mask:0xf bank_mask:0xf bound_ctrl:1
	v_pk_fma_f32 v[28:29], v[30:31], v[44:45], v[28:29]
	v_exp_f32_e32 v15, v15
	v_rcp_f32_e32 v18, v18
	v_mov_b32_dpp v30, v28 row_shr:2 row_mask:0xf bank_mask:0xf bound_ctrl:1
	v_mov_b32_dpp v31, v29 row_shr:2 row_mask:0xf bank_mask:0xf bound_ctrl:1
	v_pk_fma_f32 v[28:29], v[48:49], v[30:31], v[28:29]
	v_rcp_f32_e32 v19, v19
	v_add_f32_e32 v14, 1.0, v14
	v_mov_b32_dpp v30, v28 row_shr:4 row_mask:0xf bank_mask:0xf bound_ctrl:1
	v_mov_b32_dpp v31, v29 row_shr:4 row_mask:0xf bank_mask:0xf bound_ctrl:1
	v_pk_fma_f32 v[28:29], v[50:51], v[30:31], v[28:29]
	v_add_f32_e32 v15, 1.0, v15
	ds_bpermute_b32 v12, v1, v16
	v_mov_b32_dpp v30, v28 row_shr:8 row_mask:0xf bank_mask:0xf bound_ctrl:1
	v_mov_b32_dpp v31, v29 row_shr:8 row_mask:0xf bank_mask:0xf bound_ctrl:1
	v_pk_fma_f32 v[28:29], v[52:53], v[30:31], v[28:29]
	ds_bpermute_b32 v13, v1, v17
	v_pk_fma_f32 v[30:31], v[54:55], v[34:35], v[28:29]
	v_rcp_f32_e32 v34, v14
	v_mul_f32_e32 v14, 0xc1000000, v18
	v_rcp_f32_e32 v35, v15
	v_mul_f32_e32 v15, 0xc1000000, v19
	v_mul_f32_e32 v14, v2, v14
	v_mul_f32_e32 v15, v59, v15
	v_mul_f32_e32 v14, 0x3fb8aa3b, v14
	v_mul_f32_e32 v15, 0x3fb8aa3b, v15
	v_exp_f32_e32 v18, v14
	v_exp_f32_e32 v19, v15
	ds_bpermute_b32 v28, v1, v30
	ds_bpermute_b32 v29, v1, v31
	v_fma_f32 v14, -v18, v18, 1.0
	v_fma_f32 v15, -v19, v19, 1.0
	v_sqrt_f32_e32 v44, v14
	v_mov_b32_e32 v14, 1.0
	v_sqrt_f32_e32 v45, v15
	v_mov_b32_e32 v15, 1.0
	v_mov_b32_dpp v14, v18 row_shr:1 row_mask:0xf bank_mask:0xf
	v_cvt_pk_bf16_f32 v30, v30, v31
	v_mov_b32_dpp v15, v19 row_shr:1 row_mask:0xf bank_mask:0xf
	v_pk_mul_f32 v[48:49], v[18:19], v[14:15]
	v_mov_b32_e32 v14, 1.0
	v_mov_b32_e32 v15, 1.0
	v_cvt_pk_bf16_f32 v16, v16, v17
	v_mov_b32_dpp v14, v48 row_shr:2 row_mask:0xf bank_mask:0xf
	v_mov_b32_dpp v15, v49 row_shr:2 row_mask:0xf bank_mask:0xf
	v_pk_mul_f32 v[50:51], v[48:49], v[14:15]
	v_mov_b32_e32 v14, 1.0
	v_mov_b32_e32 v15, 1.0
	s_nop 0
	v_mov_b32_dpp v14, v50 row_shr:4 row_mask:0xf bank_mask:0xf
	v_mov_b32_dpp v15, v51 row_shr:4 row_mask:0xf bank_mask:0xf
	v_pk_mul_f32 v[52:53], v[50:51], v[14:15]
	v_mov_b32_e32 v14, 1.0
	v_mov_b32_e32 v15, 1.0
	s_nop 0
	v_mov_b32_dpp v14, v52 row_shr:8 row_mask:0xf bank_mask:0xf
	v_mov_b32_dpp v15, v53 row_shr:8 row_mask:0xf bank_mask:0xf
	v_pk_mul_f32 v[54:55], v[52:53], v[14:15]
	v_add_u32_e32 v15, 0x1108, v145
	ds_read2_b32 v[56:57], v15 offset1:1
	v_pk_mul_f32 v[46:47], v[54:55], v[46:47]
	ds_bpermute_b32 v14, v1, v46
	v_cvt_pk_bf16_f32 v17, v46, v47
	ds_bpermute_b32 v15, v1, v47
	s_waitcnt lgkmcnt(0)
; __device__ __forceinline__ unsigned pk2(float lo, float hi) { const f32x2_t v = {lo, hi}; const bf16x2_t b = __builtin_convertvector(v, bf16x2_t); return __builtin_bit_cast(unsigned, b); }
; __device__ __forceinline__ float sigmoidf_(float x) { return __builtin_amdgcn_rcpf(1.0f + __expf(-x)); }
; __device__ __forceinline__ float bcast15(float v, int lane) { return bperm_f((lane & 48) | 15, v); }
; __device__ __forceinline__ void w_lru_m1(const Args& a, int l, unsigned char* ws, const bf16_t* proj, bf16_t* y, LAS unsigned char* wl, int b, int ck_, int h, int lane) {
;     ...
;         for (int tb = 0; tb < 4; ++tb) { const int tok = 16 * tb + lo;
;             f32x4 ga = {0.f, 0.f, 0.f, 0.f}, gx = {0.f, 0.f, 0.f, 0.f};
; #pragma unroll
;             for (int kk = 0; kk < 2; ++kk) { ga = __builtin_amdgcn_mfma_f32_16x16x32_bf16(WaF[kk], Xf[tb][kk], ga, 0, 0, 0); gx = __builtin_amdgcn_mfma_f32_16x16x32_bf16(WxF[kk], Xf[tb][kk], gx, 0, 0, 0); }
;             float hv[4], pv[4];
; #pragma unroll
;             for (int r = 0; r < 4; ++r) {
;                 const float rg = sigmoidf_(ga[r] + bav[r]), ig = sigmoidf_(gx[r] + bxv[r]);
;                 const float la = -8.0f * rg * sp[r]; float A = __expf(la);
;                 float U = __builtin_amdgcn_sqrtf(1.0f - A * A) * (ig * xcf[tok * 65 + j0 + r]);
;                 { const float As = dpp_shr1<1>(A), Us = dpp_shr0<1>(U); U = A * Us + U; A = A * As; }
;                 { const float As = dpp_shr1<2>(A), Us = dpp_shr0<2>(U); U = A * Us + U; A = A * As; }
;                 { const float As = dpp_shr1<4>(A), Us = dpp_shr0<4>(U); U = A * Us + U; A = A * As; }
;                 { const float As = dpp_shr1<8>(A), Us = dpp_shr0<8>(U); U = A * Us + U; A = A * As; }
;                 const float hh = U + A * hc[r], PP = A * Pc[r];
;                 hc[r] = bcast15(hh, lane); Pc[r] = bcast15(PP, lane); hv[r] = hh; pv[r] = PP; }
;             *(unsigned long long*)(y + (size_t)(row0 + tok) * DM + 64 * h + j0) = (unsigned long long)pk2(hv[0], hv[1]) | ((unsigned long long)pk2(hv[2], hv[3]) << 32);
;             *(unsigned long long*)((bf16_t*)(ws + WS_P) + (size_t)(row0 + tok) * 512 + 64 * h + j0) = (unsigned long long)pk2(pv[0], pv[1]) | ((unsigned long long)pk2(pv[2], pv[3]) << 32);
	v_pk_mul_f32 v[34:35], v[34:35], v[56:57]
	s_nop 0
	v_pk_mul_f32 v[34:35], v[44:45], v[34:35]
	s_nop 1
	v_mov_b32_dpp v44, v34 row_shr:1 row_mask:0xf bank_mask:0xf bound_ctrl:1
	v_mov_b32_dpp v45, v35 row_shr:1 row_mask:0xf bank_mask:0xf bound_ctrl:1
	v_pk_fma_f32 v[18:19], v[18:19], v[44:45], v[34:35]
	s_nop 1
	v_mov_b32_dpp v34, v18 row_shr:2 row_mask:0xf bank_mask:0xf bound_ctrl:1
	v_mov_b32_dpp v35, v19 row_shr:2 row_mask:0xf bank_mask:0xf bound_ctrl:1
	v_pk_fma_f32 v[18:19], v[48:49], v[34:35], v[18:19]
	s_nop 1
	v_mov_b32_dpp v34, v18 row_shr:4 row_mask:0xf bank_mask:0xf bound_ctrl:1
	v_mov_b32_dpp v35, v19 row_shr:4 row_mask:0xf bank_mask:0xf bound_ctrl:1
	v_pk_fma_f32 v[18:19], v[50:51], v[34:35], v[18:19]
	s_nop 1
	v_mov_b32_dpp v34, v18 row_shr:8 row_mask:0xf bank_mask:0xf bound_ctrl:1
	v_mov_b32_dpp v35, v19 row_shr:8 row_mask:0xf bank_mask:0xf bound_ctrl:1
	v_pk_fma_f32 v[18:19], v[52:53], v[34:35], v[18:19]
	s_nop 0
	v_pk_fma_f32 v[32:33], v[54:55], v[32:33], v[18:19]
	ds_bpermute_b32 v18, v1, v32
	v_cvt_pk_bf16_f32 v31, v32, v33
	ds_bpermute_b32 v19, v1, v33
	v_mov_b64_e32 v[232:233], v[30:31]
	s_nop 1
	v_permlane16_swap_b32_e32 v230, v232
	v_permlane16_swap_b32_e32 v231, v233
	global_store_dwordx4 v[104:105], v[230:233], off offset:64
	v_mfma_f32_16x16x32_bf16 v[30:33], v[68:71], v[8:11], 0
	v_mov_b64_e32 v[236:237], v[16:17]
	s_nop 1
	v_permlane16_swap_b32_e32 v234, v236
	v_permlane16_swap_b32_e32 v235, v237
	global_store_dwordx4 v[106:107], v[234:237], off offset:64
	v_mfma_f32_16x16x32_bf16 v[8:11], v[72:75], v[8:11], 0
	v_mfma_f32_16x16x32_bf16 v[30:33], v[76:79], v[24:27], v[30:33]
	v_mfma_f32_16x16x32_bf16 v[24:27], v[80:83], v[24:27], v[8:11]
	s_nop 6
	v_add_f32_e32 v8, v40, v30
	v_add_f32_e32 v9, v36, v24
	v_mul_f32_e32 v9, 0xbfb8aa3b, v9
	v_exp_f32_e32 v9, v9
	v_mul_f32_e32 v8, 0xbfb8aa3b, v8
	v_exp_f32_e32 v8, v8
	v_add_f32_e32 v11, v37, v25
	v_add_f32_e32 v9, 1.0, v9
	v_rcp_f32_e32 v10, v9
	v_add_f32_e32 v9, v41, v31
	v_mul_f32_e32 v9, 0xbfb8aa3b, v9
	v_exp_f32_e32 v9, v9
	v_add_f32_e32 v8, 1.0, v8
	v_rcp_f32_e32 v8, v8
	v_mul_f32_e32 v11, 0xbfb8aa3b, v11
	v_add_f32_e32 v9, 1.0, v9
	v_rcp_f32_e32 v9, v9
	v_mul_f32_e32 v8, 0xc1000000, v8
	v_mul_f32_e32 v8, v58, v8
	v_mul_f32_e32 v8, 0x3fb8aa3b, v8
	v_mul_f32_e32 v9, 0xc1000000, v9
	v_mul_f32_e32 v9, v60, v9
	v_mul_f32_e32 v9, 0x3fb8aa3b, v9
	v_exp_f32_e32 v16, v8
	v_exp_f32_e32 v17, v9
	v_exp_f32_e32 v11, v11
	v_fma_f32 v8, -v16, v16, 1.0
	v_fma_f32 v9, -v17, v17, 1.0
	v_sqrt_f32_e32 v30, v8
	v_mov_b32_e32 v8, 1.0
	v_sqrt_f32_e32 v31, v9
	v_mov_b32_e32 v9, 1.0
	v_mov_b32_dpp v8, v16 row_shr:1 row_mask:0xf bank_mask:0xf
	v_add_f32_e32 v11, 1.0, v11
	v_mov_b32_dpp v9, v17 row_shr:1 row_mask:0xf bank_mask:0xf
	v_pk_mul_f32 v[34:35], v[16:17], v[8:9]
	v_mov_b32_e32 v8, 1.0
	v_mov_b32_e32 v9, 1.0
	v_rcp_f32_e32 v11, v11
	v_mov_b32_dpp v8, v34 row_shr:2 row_mask:0xf bank_mask:0xf
	v_mov_b32_dpp v9, v35 row_shr:2 row_mask:0xf bank_mask:0xf
	v_pk_mul_f32 v[44:45], v[34:35], v[8:9]
	v_mov_b32_e32 v8, 1.0
	v_mov_b32_e32 v9, 1.0
	s_nop 0
	v_mov_b32_dpp v8, v44 row_shr:4 row_mask:0xf bank_mask:0xf
	v_mov_b32_dpp v9, v45 row_shr:4 row_mask:0xf bank_mask:0xf
	v_pk_mul_f32 v[46:47], v[44:45], v[8:9]
	v_mov_b32_e32 v8, 1.0
	v_mov_b32_e32 v9, 1.0
	s_nop 0
	v_mov_b32_dpp v8, v46 row_shr:8 row_mask:0xf bank_mask:0xf
	v_mov_b32_dpp v9, v47 row_shr:8 row_mask:0xf bank_mask:0xf
	v_pk_mul_f32 v[48:49], v[46:47], v[8:9]
	s_nop 0
	v_pk_mul_f32 v[8:9], v[48:49], v[12:13]
	v_add_u32_e32 v12, 0x2140, v145
	ds_read2_b32 v[12:13], v12 offset1:1
	ds_bpermute_b32 v24, v1, v8
	ds_bpermute_b32 v25, v1, v9
	v_cvt_pk_bf16_f32 v8, v8, v9
	s_waitcnt lgkmcnt(0)
	v_pk_mul_f32 v[10:11], v[12:13], v[10:11]
	s_nop 0
	v_pk_mul_f32 v[10:11], v[10:11], v[30:31]
	v_mov_b32_e32 v30, 1.0
	v_mov_b32_e32 v31, 1.0
	v_mov_b32_dpp v12, v10 row_shr:1 row_mask:0xf bank_mask:0xf bound_ctrl:1
	v_mov_b32_dpp v13, v11 row_shr:1 row_mask:0xf bank_mask:0xf bound_ctrl:1
	v_pk_fma_f32 v[10:11], v[16:17], v[12:13], v[10:11]
	s_nop 1
	v_mov_b32_dpp v12, v10 row_shr:2 row_mask:0xf bank_mask:0xf bound_ctrl:1
	v_mov_b32_dpp v13, v11 row_shr:2 row_mask:0xf bank_mask:0xf bound_ctrl:1
	v_pk_fma_f32 v[10:11], v[34:35], v[12:13], v[10:11]
	s_nop 1
	v_mov_b32_dpp v12, v10 row_shr:4 row_mask:0xf bank_mask:0xf bound_ctrl:1
	v_mov_b32_dpp v13, v11 row_shr:4 row_mask:0xf bank_mask:0xf bound_ctrl:1
	v_pk_fma_f32 v[10:11], v[44:45], v[12:13], v[10:11]
	s_nop 1
	v_mov_b32_dpp v12, v10 row_shr:8 row_mask:0xf bank_mask:0xf bound_ctrl:1
	v_mov_b32_dpp v13, v11 row_shr:8 row_mask:0xf bank_mask:0xf bound_ctrl:1
	v_pk_fma_f32 v[10:11], v[46:47], v[12:13], v[10:11]
	v_add_f32_e32 v12, v42, v32
	v_mul_f32_e32 v12, 0xbfb8aa3b, v12
	v_exp_f32_e32 v12, v12
	v_pk_fma_f32 v[10:11], v[48:49], v[28:29], v[10:11]
	v_mov_b32_e32 v32, 1.0
	ds_bpermute_b32 v16, v1, v10
	v_add_f32_e32 v12, 1.0, v12
	v_rcp_f32_e32 v13, v12
	v_add_f32_e32 v12, v38, v26
	v_mul_f32_e32 v12, 0xbfb8aa3b, v12
	v_exp_f32_e32 v12, v12
	v_mul_f32_e32 v13, 0xc1000000, v13
	v_mul_f32_e32 v13, v2, v13
	v_mul_f32_e32 v13, 0x3fb8aa3b, v13
	v_exp_f32_e32 v26, v13
	v_add_f32_e32 v12, 1.0, v12
	v_rcp_f32_e32 v12, v12
	ds_bpermute_b32 v17, v1, v11
	v_fma_f32 v13, -v26, v26, 1.0
	v_sqrt_f32_e32 v28, v13
	v_add_f32_e32 v13, v43, v33
	v_mul_f32_e32 v13, 0xbfb8aa3b, v13
	v_exp_f32_e32 v13, v13
	v_mov_b32_dpp v30, v26 row_shr:1 row_mask:0xf bank_mask:0xf
	v_mov_b32_e32 v33, 1.0
	v_cvt_pk_bf16_f32 v10, v10, v11
	v_add_f32_e32 v13, 1.0, v13
	v_rcp_f32_e32 v29, v13
	v_add_f32_e32 v13, v39, v27
	v_mul_f32_e32 v13, 0xbfb8aa3b, v13
	v_exp_f32_e32 v13, v13
	v_mul_f32_e32 v27, 0xc1000000, v29
	v_mul_f32_e32 v27, v59, v27
	v_mul_f32_e32 v27, 0x3fb8aa3b, v27
	v_exp_f32_e32 v27, v27
	v_add_f32_e32 v13, 1.0, v13
	v_rcp_f32_e32 v13, v13
	v_mov_b32_dpp v31, v27 row_shr:1 row_mask:0xf bank_mask:0xf
	v_pk_mul_f32 v[30:31], v[26:27], v[30:31]
	v_fma_f32 v29, -v27, v27, 1.0
	v_sqrt_f32_e32 v29, v29
	v_mov_b32_dpp v32, v30 row_shr:2 row_mask:0xf bank_mask:0xf
	v_mov_b32_dpp v33, v31 row_shr:2 row_mask:0xf bank_mask:0xf
	v_pk_mul_f32 v[34:35], v[30:31], v[32:33]
	v_mov_b32_e32 v32, 1.0
	v_mov_b32_e32 v33, 1.0
	s_nop 0
	v_mov_b32_dpp v32, v34 row_shr:4 row_mask:0xf bank_mask:0xf
	v_mov_b32_dpp v33, v35 row_shr:4 row_mask:0xf bank_mask:0xf
	v_pk_mul_f32 v[44:45], v[34:35], v[32:33]
	v_mov_b32_e32 v32, 1.0
	v_mov_b32_e32 v33, 1.0
	s_nop 0
	v_mov_b32_dpp v32, v44 row_shr:8 row_mask:0xf bank_mask:0xf
	v_mov_b32_dpp v33, v45 row_shr:8 row_mask:0xf bank_mask:0xf
	v_pk_mul_f32 v[46:47], v[44:45], v[32:33]
	v_add_u32_e32 v33, 0x2148, v145
	ds_read2_b32 v[48:49], v33 offset1:1
	v_pk_mul_f32 v[14:15], v[46:47], v[14:15]
	ds_bpermute_b32 v32, v1, v14
	v_cvt_pk_bf16_f32 v9, v14, v15
	ds_bpermute_b32 v33, v1, v15
	s_waitcnt lgkmcnt(0)
; __device__ __forceinline__ unsigned pk2(float lo, float hi) { const f32x2_t v = {lo, hi}; const bf16x2_t b = __builtin_convertvector(v, bf16x2_t); return __builtin_bit_cast(unsigned, b); }
; __device__ __forceinline__ float sigmoidf_(float x) { return __builtin_amdgcn_rcpf(1.0f + __expf(-x)); }
; __device__ __forceinline__ float bcast15(float v, int lane) { return bperm_f((lane & 48) | 15, v); }
; __device__ __forceinline__ void w_lru_m1(const Args& a, int l, unsigned char* ws, const bf16_t* proj, bf16_t* y, LAS unsigned char* wl, int b, int ck_, int h, int lane) {
;     ...
;         for (int tb = 0; tb < 4; ++tb) { const int tok = 16 * tb + lo;
;             f32x4 ga = {0.f, 0.f, 0.f, 0.f}, gx = {0.f, 0.f, 0.f, 0.f};
; #pragma unroll
;             for (int kk = 0; kk < 2; ++kk) { ga = __builtin_amdgcn_mfma_f32_16x16x32_bf16(WaF[kk], Xf[tb][kk], ga, 0, 0, 0); gx = __builtin_amdgcn_mfma_f32_16x16x32_bf16(WxF[kk], Xf[tb][kk], gx, 0, 0, 0); }
;             float hv[4], pv[4];
; #pragma unroll
;             for (int r = 0; r < 4; ++r) {
;                 const float rg = sigmoidf_(ga[r] + bav[r]), ig = sigmoidf_(gx[r] + bxv[r]);
;                 const float la = -8.0f * rg * sp[r]; float A = __expf(la);
;                 float U = __builtin_amdgcn_sqrtf(1.0f - A * A) * (ig * xcf[tok * 65 + j0 + r]);
;                 { const float As = dpp_shr1<1>(A), Us = dpp_shr0<1>(U); U = A * Us + U; A = A * As; }
;                 { const float As = dpp_shr1<2>(A), Us = dpp_shr0<2>(U); U = A * Us + U; A = A * As; }
;                 { const float As = dpp_shr1<4>(A), Us = dpp_shr0<4>(U); U = A * Us + U; A = A * As; }
;                 { const float As = dpp_shr1<8>(A), Us = dpp_shr0<8>(U); U = A * Us + U; A = A * As; }
;                 const float hh = U + A * hc[r], PP = A * Pc[r];
;                 hc[r] = bcast15(hh, lane); Pc[r] = bcast15(PP, lane); hv[r] = hh; pv[r] = PP; }
;             *(unsigned long long*)(y + (size_t)(row0 + tok) * DM + 64 * h + j0) = (unsigned long long)pk2(hv[0], hv[1]) | ((unsigned long long)pk2(hv[2], hv[3]) << 32);
;             *(unsigned long long*)((bf16_t*)(ws + WS_P) + (size_t)(row0 + tok) * 512 + 64 * h + j0) = (unsigned long long)pk2(pv[0], pv[1]) | ((unsigned long long)pk2(pv[2], pv[3]) << 32);
	v_pk_mul_f32 v[12:13], v[12:13], v[48:49]
	s_nop 0
	v_pk_mul_f32 v[12:13], v[28:29], v[12:13]
	s_nop 1
	v_mov_b32_dpp v28, v12 row_shr:1 row_mask:0xf bank_mask:0xf bound_ctrl:1
	v_mov_b32_dpp v29, v13 row_shr:1 row_mask:0xf bank_mask:0xf bound_ctrl:1
	v_pk_fma_f32 v[12:13], v[26:27], v[28:29], v[12:13]
	s_nop 1
	v_mov_b32_dpp v26, v12 row_shr:2 row_mask:0xf bank_mask:0xf bound_ctrl:1
	v_mov_b32_dpp v27, v13 row_shr:2 row_mask:0xf bank_mask:0xf bound_ctrl:1
	v_pk_fma_f32 v[12:13], v[30:31], v[26:27], v[12:13]
	s_nop 1
	v_mov_b32_dpp v26, v12 row_shr:4 row_mask:0xf bank_mask:0xf bound_ctrl:1
	v_mov_b32_dpp v27, v13 row_shr:4 row_mask:0xf bank_mask:0xf bound_ctrl:1
	v_pk_fma_f32 v[12:13], v[34:35], v[26:27], v[12:13]
	s_nop 1
	v_mov_b32_dpp v26, v12 row_shr:8 row_mask:0xf bank_mask:0xf bound_ctrl:1
	v_mov_b32_dpp v27, v13 row_shr:8 row_mask:0xf bank_mask:0xf bound_ctrl:1
	v_pk_fma_f32 v[12:13], v[44:45], v[26:27], v[12:13]
	s_nop 0
	v_pk_fma_f32 v[18:19], v[46:47], v[18:19], v[12:13]
	ds_bpermute_b32 v12, v1, v18
	v_cvt_pk_bf16_f32 v11, v18, v19
	v_mov_b64_e32 v[240:241], v[10:11]
	s_nop 1
	v_permlane16_swap_b32_e32 v238, v240
	v_permlane16_swap_b32_e32 v239, v241
	global_store_dwordx4 v[96:97], v[238:241], off offset:64
	v_mov_b64_e32 v[244:245], v[8:9]
	s_nop 1
	v_permlane16_swap_b32_e32 v242, v244
	v_permlane16_swap_b32_e32 v243, v245
	global_store_dwordx4 v[98:99], v[242:245], off offset:64
	v_mfma_f32_16x16x32_bf16 v[8:11], v[68:71], v[4:7], 0
	ds_bpermute_b32 v13, v1, v19
	v_mfma_f32_16x16x32_bf16 v[4:7], v[72:75], v[4:7], 0
	v_mfma_f32_16x16x32_bf16 v[8:11], v[76:79], v[20:23], v[8:11]
	v_mfma_f32_16x16x32_bf16 v[4:7], v[80:83], v[20:23], v[4:7]
	s_nop 6
	v_add_f32_e32 v8, v40, v8
	v_mul_f32_e32 v8, 0xbfb8aa3b, v8
	v_exp_f32_e32 v8, v8
	v_add_f32_e32 v4, v36, v4
	v_add_f32_e32 v9, v41, v9
	v_mul_f32_e32 v4, 0xbfb8aa3b, v4
	v_mul_f32_e32 v9, 0xbfb8aa3b, v9
	v_add_f32_e32 v8, 1.0, v8
	v_exp_f32_e32 v4, v4
	v_exp_f32_e32 v9, v9
	v_rcp_f32_e32 v14, v8
	v_add_f32_e32 v5, v37, v5
	v_mul_f32_e32 v5, 0xbfb8aa3b, v5
	v_add_f32_e32 v4, 1.0, v4
	v_add_f32_e32 v9, 1.0, v9
	v_exp_f32_e32 v5, v5
	v_rcp_f32_e32 v8, v4
	v_mul_f32_e32 v4, 0xc1000000, v14
	v_rcp_f32_e32 v14, v9
	v_add_f32_e32 v5, 1.0, v5
	v_rcp_f32_e32 v9, v5
	v_mul_f32_e32 v4, v58, v4
	v_mul_f32_e32 v5, 0xc1000000, v14
	v_mul_f32_e32 v5, v60, v5
	v_mul_f32_e32 v4, 0x3fb8aa3b, v4
	v_mul_f32_e32 v5, 0x3fb8aa3b, v5
	v_exp_f32_e32 v18, v4
	v_exp_f32_e32 v19, v5
	v_add_f32_e32 v10, v42, v10
	v_mul_f32_e32 v10, 0xbfb8aa3b, v10
	v_fma_f32 v4, -v18, v18, 1.0
	v_fma_f32 v5, -v19, v19, 1.0
	v_sqrt_f32_e32 v20, v4
	v_mov_b32_e32 v4, 1.0
	v_sqrt_f32_e32 v21, v5
	v_mov_b32_e32 v5, 1.0
	v_mov_b32_dpp v4, v18 row_shr:1 row_mask:0xf bank_mask:0xf
	v_exp_f32_e32 v10, v10
	v_mov_b32_dpp v5, v19 row_shr:1 row_mask:0xf bank_mask:0xf
	v_pk_mul_f32 v[22:23], v[18:19], v[4:5]
	v_mov_b32_e32 v4, 1.0
	v_mov_b32_e32 v5, 1.0
	v_add_f32_e32 v6, v38, v6
	v_mov_b32_dpp v4, v22 row_shr:2 row_mask:0xf bank_mask:0xf
	v_mov_b32_dpp v5, v23 row_shr:2 row_mask:0xf bank_mask:0xf
	v_pk_mul_f32 v[26:27], v[22:23], v[4:5]
	v_mov_b32_e32 v4, 1.0
	v_mov_b32_e32 v5, 1.0
	v_mul_f32_e32 v6, 0xbfb8aa3b, v6
	v_mov_b32_dpp v4, v26 row_shr:4 row_mask:0xf bank_mask:0xf
	v_mov_b32_dpp v5, v27 row_shr:4 row_mask:0xf bank_mask:0xf
	v_pk_mul_f32 v[28:29], v[26:27], v[4:5]
	v_mov_b32_e32 v4, 1.0
	v_mov_b32_e32 v5, 1.0
	v_add_f32_e32 v10, 1.0, v10
	v_mov_b32_dpp v4, v28 row_shr:8 row_mask:0xf bank_mask:0xf
	v_mov_b32_dpp v5, v29 row_shr:8 row_mask:0xf bank_mask:0xf
	v_pk_mul_f32 v[30:31], v[28:29], v[4:5]
	v_add_u32_e32 v5, 0x3180, v145
	v_pk_mul_f32 v[14:15], v[30:31], v[24:25]
	ds_read2_b32 v[24:25], v5 offset1:1
	v_exp_f32_e32 v6, v6
	v_rcp_f32_e32 v10, v10
	v_add_f32_e32 v7, v39, v7
	v_mul_f32_e32 v7, 0xbfb8aa3b, v7
	s_waitcnt lgkmcnt(0)
; __device__ __forceinline__ unsigned pk2(float lo, float hi) { const f32x2_t v = {lo, hi}; const bf16x2_t b = __builtin_convertvector(v, bf16x2_t); return __builtin_bit_cast(unsigned, b); }
; __device__ __forceinline__ float sigmoidf_(float x) { return __builtin_amdgcn_rcpf(1.0f + __expf(-x)); }
; __device__ __forceinline__ void w_lru_m1(const Args& a, int l, unsigned char* ws, const bf16_t* proj, bf16_t* y, LAS unsigned char* wl, int b, int ck_, int h, int lane) {
;     ...
;         for (int tb = 0; tb < 4; ++tb) { const int tok = 16 * tb + lo;
;             f32x4 ga = {0.f, 0.f, 0.f, 0.f}, gx = {0.f, 0.f, 0.f, 0.f};
; #pragma unroll
;             for (int kk = 0; kk < 2; ++kk) { ga = __builtin_amdgcn_mfma_f32_16x16x32_bf16(WaF[kk], Xf[tb][kk], ga, 0, 0, 0); gx = __builtin_amdgcn_mfma_f32_16x16x32_bf16(WxF[kk], Xf[tb][kk], gx, 0, 0, 0); }
;             float hv[4], pv[4];
; #pragma unroll
;             for (int r = 0; r < 4; ++r) {
;                 const float rg = sigmoidf_(ga[r] + bav[r]), ig = sigmoidf_(gx[r] + bxv[r]);
;                 const float la = -8.0f * rg * sp[r]; float A = __expf(la);
;                 float U = __builtin_amdgcn_sqrtf(1.0f - A * A) * (ig * xcf[tok * 65 + j0 + r]);
;                 { const float As = dpp_shr1<1>(A), Us = dpp_shr0<1>(U); U = A * Us + U; A = A * As; }
;                 { const float As = dpp_shr1<2>(A), Us = dpp_shr0<2>(U); U = A * Us + U; A = A * As; }
;                 { const float As = dpp_shr1<4>(A), Us = dpp_shr0<4>(U); U = A * Us + U; A = A * As; }
;                 { const float As = dpp_shr1<8>(A), Us = dpp_shr0<8>(U); U = A * Us + U; A = A * As; }
;                 const float hh = U + A * hc[r], PP = A * Pc[r];
;                 hc[r] = bcast15(hh, lane); Pc[r] = bcast15(PP, lane); hv[r] = hh; pv[r] = PP; }
;             *(unsigned long long*)(y + (size_t)(row0 + tok) * DM + 64 * h + j0) = (unsigned long long)pk2(hv[0], hv[1]) | ((unsigned long long)pk2(hv[2], hv[3]) << 32);
;             *(unsigned long long*)((bf16_t*)(ws + WS_P) + (size_t)(row0 + tok) * 512 + 64 * h + j0) = (unsigned long long)pk2(pv[0], pv[1]) | ((unsigned long long)pk2(pv[2], pv[3]) << 32);
;         }
;         if (lo == 0) { const size_t so = (size_t)(b * NCH + ck_) * 512 + 64 * h + j0;
; #pragma unroll
;             for (int r = 0; r < 4; ++r) { ((float*)(ws + WS_LRUA))[so + r] = Pc[r]; ((float*)(ws + WS_LRUH))[so + r] = hc[r]; } }
	v_pk_mul_f32 v[8:9], v[24:25], v[8:9]
	v_add_f32_e32 v6, 1.0, v6
	v_pk_mul_f32 v[8:9], v[8:9], v[20:21]
	v_exp_f32_e32 v7, v7
	ds_bpermute_b32 v4, v1, v14
	v_mov_b32_dpp v20, v8 row_shr:1 row_mask:0xf bank_mask:0xf bound_ctrl:1
	v_mov_b32_dpp v21, v9 row_shr:1 row_mask:0xf bank_mask:0xf bound_ctrl:1
	v_pk_fma_f32 v[8:9], v[18:19], v[20:21], v[8:9]
	v_add_f32_e32 v7, 1.0, v7
	ds_bpermute_b32 v5, v1, v15
	v_mov_b32_dpp v18, v8 row_shr:2 row_mask:0xf bank_mask:0xf bound_ctrl:1
	v_mov_b32_dpp v19, v9 row_shr:2 row_mask:0xf bank_mask:0xf bound_ctrl:1
	v_pk_fma_f32 v[8:9], v[22:23], v[18:19], v[8:9]
	s_nop 1
	v_mov_b32_dpp v18, v8 row_shr:4 row_mask:0xf bank_mask:0xf bound_ctrl:1
	v_mov_b32_dpp v19, v9 row_shr:4 row_mask:0xf bank_mask:0xf bound_ctrl:1
	v_pk_fma_f32 v[8:9], v[26:27], v[18:19], v[8:9]
	s_nop 1
	v_mov_b32_dpp v18, v8 row_shr:8 row_mask:0xf bank_mask:0xf bound_ctrl:1
	v_mov_b32_dpp v19, v9 row_shr:8 row_mask:0xf bank_mask:0xf bound_ctrl:1
	v_pk_fma_f32 v[8:9], v[28:29], v[18:19], v[8:9]
	v_rcp_f32_e32 v18, v6
	v_mul_f32_e32 v6, 0xc1000000, v10
	v_mul_f32_e32 v2, v2, v6
	v_mul_f32_e32 v2, 0x3fb8aa3b, v2
	v_exp_f32_e32 v10, v2
	v_mov_b32_e32 v6, 1.0
	v_rcp_f32_e32 v19, v7
	v_mov_b32_e32 v7, 1.0
	v_fma_f32 v2, -v10, v10, 1.0
	v_sqrt_f32_e32 v20, v2
	v_add_f32_e32 v2, v43, v11
	v_mul_f32_e32 v2, 0xbfb8aa3b, v2
	v_exp_f32_e32 v2, v2
	v_mov_b32_dpp v6, v10 row_shr:1 row_mask:0xf bank_mask:0xf
	v_pk_fma_f32 v[16:17], v[30:31], v[16:17], v[8:9]
	ds_bpermute_b32 v8, v1, v16
	v_add_f32_e32 v2, 1.0, v2
	v_rcp_f32_e32 v2, v2
	ds_bpermute_b32 v9, v1, v17
	v_cvt_pk_bf16_f32 v16, v16, v17
	v_mul_f32_e32 v2, 0xc1000000, v2
	v_mul_f32_e32 v2, v59, v2
	v_mul_f32_e32 v2, 0x3fb8aa3b, v2
	v_exp_f32_e32 v11, v2
	s_nop 0
	v_fma_f32 v2, -v11, v11, 1.0
	v_mov_b32_dpp v7, v11 row_shr:1 row_mask:0xf bank_mask:0xf
	v_pk_mul_f32 v[24:25], v[10:11], v[6:7]
	v_mov_b32_e32 v6, 1.0
	v_mov_b32_e32 v7, 1.0
	v_sqrt_f32_e32 v21, v2
	v_mov_b32_dpp v6, v24 row_shr:2 row_mask:0xf bank_mask:0xf
	v_mov_b32_dpp v7, v25 row_shr:2 row_mask:0xf bank_mask:0xf
	v_pk_mul_f32 v[26:27], v[24:25], v[6:7]
	v_mov_b32_e32 v6, 1.0
	v_mov_b32_e32 v7, 1.0
	v_add_u32_e32 v2, 0x3188, v145
	v_mov_b32_dpp v6, v26 row_shr:4 row_mask:0xf bank_mask:0xf
	v_mov_b32_dpp v7, v27 row_shr:4 row_mask:0xf bank_mask:0xf
	v_pk_mul_f32 v[28:29], v[26:27], v[6:7]
	v_mov_b32_e32 v6, 1.0
	v_mov_b32_e32 v7, 1.0
	s_nop 0
	v_mov_b32_dpp v6, v28 row_shr:8 row_mask:0xf bank_mask:0xf
	v_mov_b32_dpp v7, v29 row_shr:8 row_mask:0xf bank_mask:0xf
	v_pk_mul_f32 v[30:31], v[28:29], v[6:7]
	s_nop 0
	v_pk_mul_f32 v[22:23], v[30:31], v[32:33]
	ds_read2_b32 v[32:33], v2 offset1:1
	ds_bpermute_b32 v6, v1, v22
	ds_bpermute_b32 v7, v1, v23
	s_waitcnt lgkmcnt(0)
	v_pk_mul_f32 v[18:19], v[18:19], v[32:33]
	s_nop 0
	v_pk_mul_f32 v[18:19], v[20:21], v[18:19]
	s_nop 1
	v_mov_b32_dpp v20, v18 row_shr:1 row_mask:0xf bank_mask:0xf bound_ctrl:1
	v_mov_b32_dpp v21, v19 row_shr:1 row_mask:0xf bank_mask:0xf bound_ctrl:1
	v_pk_fma_f32 v[10:11], v[10:11], v[20:21], v[18:19]
	s_nop 1
	v_mov_b32_dpp v18, v10 row_shr:2 row_mask:0xf bank_mask:0xf bound_ctrl:1
	v_mov_b32_dpp v19, v11 row_shr:2 row_mask:0xf bank_mask:0xf bound_ctrl:1
	v_pk_fma_f32 v[10:11], v[24:25], v[18:19], v[10:11]
	s_nop 1
	v_mov_b32_dpp v18, v10 row_shr:4 row_mask:0xf bank_mask:0xf bound_ctrl:1
	v_mov_b32_dpp v19, v11 row_shr:4 row_mask:0xf bank_mask:0xf bound_ctrl:1
	v_pk_fma_f32 v[10:11], v[26:27], v[18:19], v[10:11]
	s_nop 1
	v_mov_b32_dpp v18, v10 row_shr:8 row_mask:0xf bank_mask:0xf bound_ctrl:1
	v_mov_b32_dpp v19, v11 row_shr:8 row_mask:0xf bank_mask:0xf bound_ctrl:1
	v_pk_fma_f32 v[10:11], v[28:29], v[18:19], v[10:11]
	s_nop 0
	v_pk_fma_f32 v[12:13], v[30:31], v[12:13], v[10:11]
	ds_bpermute_b32 v10, v1, v12
	ds_bpermute_b32 v11, v1, v13
	v_cvt_pk_bf16_f32 v17, v12, v13
	v_cvt_pk_bf16_f32 v12, v14, v15
	v_cvt_pk_bf16_f32 v13, v22, v23
	v_mov_b64_e32 v[248:249], v[16:17]
	s_nop 1
	v_permlane16_swap_b32_e32 v246, v248
	v_permlane16_swap_b32_e32 v247, v249
	global_store_dwordx4 v[114:115], v[246:249], off offset:64
	v_mov_b64_e32 v[252:253], v[12:13]
	s_nop 1
	v_permlane16_swap_b32_e32 v250, v252
	v_permlane16_swap_b32_e32 v251, v253
	global_store_dwordx4 v[116:117], v[250:253], off offset:64
	s_and_saveexec_b64 s[34:35], vcc
	s_cbranch_execz .LBB0_518
	v_add_u32_e32 v0, 48, v0
	v_ashrrev_i32_e32 v1, 31, v0
	v_lshl_add_u64 v[0:1], s[42:43], 0, v[0:1]
	v_lshlrev_b64 v[0:1], 2, v[0:1]
	v_lshl_add_u64 v[12:13], s[84:85], 0, v[0:1]
	v_lshl_add_u64 v[0:1], s[86:87], 0, v[0:1]
	global_store_dwordx4 v[12:13], v[4:7], off
	s_waitcnt lgkmcnt(0)
	global_store_dwordx4 v[0:1], v[8:11], off
	s_branch .LBB0_518
